# GEMM K loops: one static s_setprio 1 for waves 4-7 before each K loop, per-MFMA-block priority flips removed
# speedup vs baseline: 1.0213x; 1.0031x over previous
; template <class Epi, class Sched, bool ALIGN_EPI = false, bool SP2 = false>
; __device__ __forceinline__ void gemm_phase(PG8_LAS unsigned char* lds, const Gemm g, const Sched& S, const Epi& E) {
;     ...
;     f32x4 acc[2][2][4][2];
; #pragma unroll
;     for (int a = 0; a < 2; ++a)
; #pragma unroll
;         for (int b = 0; b < 2; ++b)
; #pragma unroll
;             for (int m = 0; m < 4; ++m)
; #pragma unroll
;                 for (int n = 0; n < 2; ++n) acc[a][b][m][n] = (f32x4){0.f, 0.f, 0.f, 0.f};
;     ...
;     for (;;) {
;         const bool has_next = S.next(ui + 1, nxt);
;         const char* nA = has_next ? (const char*)g.A + (size_t)nxt.pm * tstep : cA; const char* nB = has_next ? (const char*)g.Bt + (size_t)nxt.pn * tstep : cB;
;         for (int t = 0; t < nt; t += 2) {
.LBB0_115:
	v_mov_b32_e32 v135, 0
	s_andn2_b64 vcc, exec, s[18:19]
	v_mov_b32_e32 v134, 0
	v_mov_b32_e32 v137, 0
	v_mov_b32_e32 v136, 0
	v_mov_b32_e32 v127, 0
	v_mov_b32_e32 v126, 0
	v_mov_b32_e32 v125, 0
	v_mov_b32_e32 v124, 0
	v_mov_b32_e32 v119, 0
	v_mov_b32_e32 v118, 0
	v_mov_b32_e32 v117, 0
	v_mov_b32_e32 v116, 0
	v_mov_b32_e32 v111, 0
	v_mov_b32_e32 v110, 0
	v_mov_b32_e32 v109, 0
	v_mov_b32_e32 v108, 0
	v_mov_b32_e32 v103, 0
	v_mov_b32_e32 v102, 0
	v_mov_b32_e32 v101, 0
	v_mov_b32_e32 v100, 0
	v_mov_b32_e32 v95, 0
	v_mov_b32_e32 v94, 0
	v_mov_b32_e32 v93, 0
	v_mov_b32_e32 v92, 0
	v_mov_b32_e32 v87, 0
	v_mov_b32_e32 v86, 0
	v_mov_b32_e32 v85, 0
	v_mov_b32_e32 v84, 0
	v_mov_b32_e32 v75, 0
	v_mov_b32_e32 v74, 0
	v_mov_b32_e32 v73, 0
	v_mov_b32_e32 v72, 0
	v_mov_b32_e32 v145, 0
	v_mov_b32_e32 v144, 0
	v_mov_b32_e32 v143, 0
	v_mov_b32_e32 v142, 0
	v_mov_b32_e32 v141, 0
	v_mov_b32_e32 v140, 0
	v_mov_b32_e32 v139, 0
	v_mov_b32_e32 v138, 0
	v_mov_b32_e32 v123, 0
	v_mov_b32_e32 v122, 0
	v_mov_b32_e32 v121, 0
	v_mov_b32_e32 v120, 0
	v_mov_b32_e32 v115, 0
	v_mov_b32_e32 v114, 0
	v_mov_b32_e32 v113, 0
	v_mov_b32_e32 v112, 0
	v_mov_b32_e32 v107, 0
	v_mov_b32_e32 v106, 0
	v_mov_b32_e32 v105, 0
	v_mov_b32_e32 v104, 0
	v_mov_b32_e32 v99, 0
	v_mov_b32_e32 v98, 0
	v_mov_b32_e32 v97, 0
	v_mov_b32_e32 v96, 0
	v_mov_b32_e32 v91, 0
	v_mov_b32_e32 v90, 0
	v_mov_b32_e32 v89, 0
	v_mov_b32_e32 v88, 0
	v_mov_b32_e32 v83, 0
	v_mov_b32_e32 v82, 0
	v_mov_b32_e32 v81, 0
	v_mov_b32_e32 v80, 0
	v_mov_b32_e32 v67, 0
	v_mov_b32_e32 v66, 0
	v_mov_b32_e32 v65, 0
	v_mov_b32_e32 v64, 0
	v_mov_b32_e32 v63, 0
	v_mov_b32_e32 v62, 0
	v_mov_b32_e32 v61, 0
	v_mov_b32_e32 v60, 0
	v_mov_b32_e32 v55, 0
	v_mov_b32_e32 v54, 0
	v_mov_b32_e32 v53, 0
	v_mov_b32_e32 v52, 0
	v_mov_b32_e32 v47, 0
	v_mov_b32_e32 v46, 0
	v_mov_b32_e32 v45, 0
	v_mov_b32_e32 v44, 0
	v_mov_b32_e32 v31, 0
	v_mov_b32_e32 v30, 0
	v_mov_b32_e32 v29, 0
	v_mov_b32_e32 v28, 0
	v_mov_b32_e32 v23, 0
	v_mov_b32_e32 v22, 0
	v_mov_b32_e32 v21, 0
	v_mov_b32_e32 v20, 0
	v_mov_b32_e32 v15, 0
	v_mov_b32_e32 v14, 0
	v_mov_b32_e32 v13, 0
	v_mov_b32_e32 v12, 0
	v_mov_b32_e32 v11, 0
	v_mov_b32_e32 v10, 0
	v_mov_b32_e32 v9, 0
	v_mov_b32_e32 v8, 0
	v_mov_b32_e32 v79, 0
	v_mov_b32_e32 v78, 0
	v_mov_b32_e32 v77, 0
	v_mov_b32_e32 v76, 0
	v_mov_b32_e32 v71, 0
	v_mov_b32_e32 v70, 0
	v_mov_b32_e32 v69, 0
	v_mov_b32_e32 v68, 0
	v_mov_b32_e32 v59, 0
	v_mov_b32_e32 v58, 0
	v_mov_b32_e32 v57, 0
	v_mov_b32_e32 v56, 0
	v_mov_b32_e32 v51, 0
	v_mov_b32_e32 v50, 0
	v_mov_b32_e32 v49, 0
	v_mov_b32_e32 v48, 0
	v_mov_b32_e32 v39, 0
	v_mov_b32_e32 v38, 0
	v_mov_b32_e32 v37, 0
	v_mov_b32_e32 v36, 0
	v_mov_b32_e32 v35, 0
	v_mov_b32_e32 v34, 0
	v_mov_b32_e32 v33, 0
	v_mov_b32_e32 v32, 0
	v_mov_b32_e32 v7, 0
	v_mov_b32_e32 v6, 0
	v_mov_b32_e32 v5, 0
	v_mov_b32_e32 v4, 0
	v_mov_b32_e32 v3, 0
	v_mov_b32_e32 v2, 0
	v_mov_b32_e32 v1, 0
	v_mov_b32_e32 v0, 0
	s_cbranch_vccnz .LBB0_119
	s_add_u32 s0, s0, 0x80
	s_addc_u32 s1, s1, 0
	s_add_u32 s34, s2, 0x100
	v_mov_b32_e32 v0, 0
	s_addc_u32 s35, s3, 0
	s_mov_b32 s2, 0
	v_mov_b32_e32 v1, v0
	v_mov_b32_e32 v2, v0
	v_mov_b32_e32 v3, v0
	v_mov_b32_e32 v4, v0
	v_mov_b32_e32 v5, v0
	v_mov_b32_e32 v6, v0
	v_mov_b32_e32 v7, v0
	v_mov_b32_e32 v8, v0
	v_mov_b32_e32 v9, v0
	v_mov_b32_e32 v10, v0
	v_mov_b32_e32 v11, v0
	v_mov_b32_e32 v12, v0
	v_mov_b32_e32 v13, v0
	v_mov_b32_e32 v14, v0
	v_mov_b32_e32 v15, v0
	v_mov_b32_e32 v20, v0
	v_mov_b32_e32 v21, v0
	v_mov_b32_e32 v22, v0
	v_mov_b32_e32 v23, v0
	v_mov_b32_e32 v28, v0
	v_mov_b32_e32 v29, v0
	v_mov_b32_e32 v30, v0
	v_mov_b32_e32 v31, v0
	v_mov_b32_e32 v36, v0
	v_mov_b32_e32 v37, v0
	v_mov_b32_e32 v38, v0
	v_mov_b32_e32 v39, v0
	v_mov_b32_e32 v44, v0
	v_mov_b32_e32 v45, v0
	v_mov_b32_e32 v46, v0
	v_mov_b32_e32 v47, v0
	v_mov_b32_e32 v16, v0
	v_mov_b32_e32 v17, v0
	v_mov_b32_e32 v18, v0
	v_mov_b32_e32 v19, v0
	v_mov_b32_e32 v24, v0
	v_mov_b32_e32 v25, v0
	v_mov_b32_e32 v26, v0
	v_mov_b32_e32 v27, v0
	v_mov_b32_e32 v32, v0
	v_mov_b32_e32 v33, v0
	v_mov_b32_e32 v34, v0
	v_mov_b32_e32 v35, v0
	v_mov_b32_e32 v40, v0
	v_mov_b32_e32 v41, v0
	v_mov_b32_e32 v42, v0
	v_mov_b32_e32 v43, v0
	v_mov_b32_e32 v48, v0
	v_mov_b32_e32 v49, v0
	v_mov_b32_e32 v50, v0
	v_mov_b32_e32 v51, v0
	v_mov_b32_e32 v52, v0
	v_mov_b32_e32 v53, v0
	v_mov_b32_e32 v54, v0
	v_mov_b32_e32 v55, v0
	v_mov_b32_e32 v56, v0
	v_mov_b32_e32 v57, v0
	v_mov_b32_e32 v58, v0
	v_mov_b32_e32 v59, v0
	v_mov_b32_e32 v60, v0
	v_mov_b32_e32 v61, v0
	v_mov_b32_e32 v62, v0
	v_mov_b32_e32 v63, v0
	v_mov_b32_e32 v64, v0
	v_mov_b32_e32 v65, v0
	v_mov_b32_e32 v66, v0
	v_mov_b32_e32 v67, v0
	v_mov_b32_e32 v68, v0
	v_mov_b32_e32 v69, v0
	v_mov_b32_e32 v70, v0
	v_mov_b32_e32 v71, v0
	v_mov_b32_e32 v72, v0
	v_mov_b32_e32 v73, v0
	v_mov_b32_e32 v74, v0
	v_mov_b32_e32 v75, v0
	v_mov_b32_e32 v76, v0
	v_mov_b32_e32 v77, v0
	v_mov_b32_e32 v78, v0
	v_mov_b32_e32 v79, v0
	v_mov_b32_e32 v84, v0
	v_mov_b32_e32 v85, v0
	v_mov_b32_e32 v86, v0
	v_mov_b32_e32 v87, v0
	v_mov_b32_e32 v92, v0
	v_mov_b32_e32 v93, v0
	v_mov_b32_e32 v94, v0
	v_mov_b32_e32 v95, v0
	v_mov_b32_e32 v100, v0
	v_mov_b32_e32 v101, v0
	v_mov_b32_e32 v102, v0
	v_mov_b32_e32 v103, v0
	v_mov_b32_e32 v108, v0
	v_mov_b32_e32 v109, v0
	v_mov_b32_e32 v110, v0
	v_mov_b32_e32 v111, v0
	v_mov_b32_e32 v80, v0
	v_mov_b32_e32 v81, v0
	v_mov_b32_e32 v82, v0
	v_mov_b32_e32 v83, v0
	v_mov_b32_e32 v88, v0
	v_mov_b32_e32 v89, v0
	v_mov_b32_e32 v90, v0
	v_mov_b32_e32 v91, v0
	v_mov_b32_e32 v96, v0
	v_mov_b32_e32 v97, v0
	v_mov_b32_e32 v98, v0
	v_mov_b32_e32 v99, v0
	v_mov_b32_e32 v104, v0
	v_mov_b32_e32 v105, v0
	v_mov_b32_e32 v106, v0
	v_mov_b32_e32 v107, v0
	v_mov_b32_e32 v112, v0
	v_mov_b32_e32 v113, v0
	v_mov_b32_e32 v114, v0
	v_mov_b32_e32 v115, v0
	v_mov_b32_e32 v116, v0
	v_mov_b32_e32 v117, v0
	v_mov_b32_e32 v118, v0
	v_mov_b32_e32 v119, v0
	v_mov_b32_e32 v120, v0
	v_mov_b32_e32 v121, v0
	v_mov_b32_e32 v122, v0
	v_mov_b32_e32 v123, v0
	v_mov_b32_e32 v124, v0
	v_mov_b32_e32 v125, v0
	v_mov_b32_e32 v126, v0
	v_mov_b32_e32 v127, v0
	v_readfirstlane_b32 s100, v211
	s_cmp_ge_u32 s100, 0x100
	s_cbranch_scc0 .Lprio_skip12
	s_setprio 1
; #define PG8_STAGE(bufoff, gbase, voff) do { _Pragma("unroll") for (int _i = 0; _i < 2; ++_i) \
;         __builtin_amdgcn_global_load_lds((const unsigned*)((const char*)(gbase) + (voff)[_i]), (PG8_LAS unsigned*)(lds + (bufoff) + ldsw + _i * 8192), 16, 0, 0); } while (0)
; #define PG8_LDA(dst, b, h) do { _Pragma("unroll") for (int m = 0; m < 4; ++m) _Pragma("unroll") for (int k = 0; k < 2; ++k) dst[m][k] = *(const PG8_LAS bf16x8*)(lds + PG8_SA(b, h) + aoff + m * 2048 + k * 1024); } while (0)
; #define PG8_LDB(dst, b, h) do { _Pragma("unroll") for (int n = 0; n < 2; ++n) _Pragma("unroll") for (int k = 0; k < 2; ++k) dst[n][k] = *(const PG8_LAS bf16x8*)(lds + PG8_SB(b, h) + boff + n * 2048 + k * 1024); } while (0)
; #define PG8_MMA(ai, bj, At, Bt) do { __builtin_amdgcn_s_setprio(1); _Pragma("unroll") for (int m = 0; m < 4; ++m) _Pragma("unroll") for (int n = 0; n < 2; ++n) _Pragma("unroll") for (int k = 0; k < 2; ++k) \
;         acc[ai][bj][m][n] = __builtin_amdgcn_mfma_f32_16x16x32_bf16(Bt[n][k], At[m][k], acc[ai][bj][m][n], 0, 0, 0); __builtin_amdgcn_s_setprio(0); } while (0)
; #define PG8_WAIT_V(n) asm volatile("s_waitcnt vmcnt(" #n ")" ::: "memory")
; #define PG8_WAIT_L(n) asm volatile("s_waitcnt lgkmcnt(" #n ")" ::: "memory")
; #define PG8_BAR __builtin_amdgcn_s_barrier()
; #define PG8_SCHED __builtin_amdgcn_sched_barrier(0)
; template <class Epi, class Sched, bool ALIGN_EPI = false, bool SP2 = false>
; __device__ __forceinline__ void gemm_phase(PG8_LAS unsigned char* lds, const Gemm g, const Sched& S, const Epi& E) {
;     ...
;             PG8_LDB(B0, 0, 0); PG8_LDB(B1, 0, 1); PG8_SCHED; PG8_LDA(At, 0, 0); PG8_STAGE(PG8_SA(1, 1), a1 + hstep, voffA);
;             PG8_WAIT_V(8); PG8_WAIT_L(0); PG8_BAR; PG8_MMA(0, 0, At, B0); PG8_MMA(0, 1, At, B1); PG8_BAR; PG8_SCHED;
;             PG8_LDA(At, 0, 1); PG8_STAGE(PG8_SB(0, 0), b2, voffB); PG8_STAGE(PG8_SB(0, 1), b2 + hstep, voffB); PG8_STAGE(PG8_SA(0, 0), a2, voffA);
.Lprio_skip12:
.LBB0_117:
	s_add_i32 s36, s2, 2
	s_add_u32 s37, s0, 0x80
	s_addc_u32 s3, s1, 0
	s_add_i32 s40, 0, 0x10000
	s_cmp_eq_u32 s24, s2
	s_cselect_b32 s3, s7, s3
	s_cselect_b32 s2, s6, s37
	v_add_u32_e32 v150, s40, v147
	s_cselect_b32 s39, s47, s35
	s_cselect_b32 s38, s46, s34
	s_add_i32 s37, 0, 0x14000
	ds_read_b128 v[134:137], v150
	ds_read_b128 v[138:141], v150 offset:1024
	ds_read_b128 v[142:145], v150 offset:2048
	ds_read_b128 v[168:171], v150 offset:3072
	v_add_u32_e32 v150, s37, v147
	ds_read_b128 v[172:175], v150
	ds_read_b128 v[176:179], v150 offset:1024
	ds_read_b128 v[180:183], v150 offset:2048
	ds_read_b128 v[184:187], v150 offset:3072
	v_lshl_add_u64 v[150:151], s[0:1], 0, v[130:131]
	s_add_i32 m0, s9, 0xc000
	ds_read_b128 v[188:191], v149
	ds_read_b128 v[192:195], v149 offset:1024
	ds_read_b128 v[196:199], v149 offset:2048
	ds_read_b128 v[200:203], v149 offset:3072
	ds_read_b128 v[204:207], v149 offset:4096
	ds_read_b128 v[212:215], v149 offset:5120
	ds_read_b128 v[230:233], v149 offset:6144
	ds_read_b128 v[234:237], v149 offset:7168
	global_load_lds_dwordx4 v[150:151], off
	v_lshl_add_u64 v[150:151], s[0:1], 0, v[132:133]
	s_add_i32 m0, s9, 0xe000
	s_nop 0
	global_load_lds_dwordx4 v[150:151], off
	s_waitcnt vmcnt(8)
	s_waitcnt lgkmcnt(0)
	s_barrier
	s_waitcnt lgkmcnt(0)
	v_mfma_f32_16x16x32_bf16 v[124:127], v[134:137], v[188:191], v[124:127]
	v_mfma_f32_16x16x32_bf16 v[120:123], v[142:145], v[188:191], v[120:123]
	v_mfma_f32_16x16x32_bf16 v[116:119], v[134:137], v[196:199], v[116:119]
	v_mfma_f32_16x16x32_bf16 v[112:115], v[142:145], v[196:199], v[112:115]
	v_mfma_f32_16x16x32_bf16 v[104:107], v[134:137], v[204:207], v[104:107]
	v_mfma_f32_16x16x32_bf16 v[96:99], v[142:145], v[204:207], v[96:99]
	v_mfma_f32_16x16x32_bf16 v[88:91], v[134:137], v[230:233], v[88:91]
	v_mfma_f32_16x16x32_bf16 v[80:83], v[142:145], v[230:233], v[80:83]
	v_mfma_f32_16x16x32_bf16 v[124:127], v[138:141], v[192:195], v[124:127]
	v_mfma_f32_16x16x32_bf16 v[120:123], v[168:171], v[192:195], v[120:123]
	v_mfma_f32_16x16x32_bf16 v[116:119], v[138:141], v[200:203], v[116:119]
	v_mfma_f32_16x16x32_bf16 v[112:115], v[168:171], v[200:203], v[112:115]
	v_mfma_f32_16x16x32_bf16 v[104:107], v[138:141], v[212:215], v[104:107]
	v_mfma_f32_16x16x32_bf16 v[96:99], v[168:171], v[212:215], v[96:99]
	v_mfma_f32_16x16x32_bf16 v[88:91], v[138:141], v[234:237], v[88:91]
	v_mfma_f32_16x16x32_bf16 v[80:83], v[168:171], v[234:237], v[80:83]
	v_mfma_f32_16x16x32_bf16 v[108:111], v[172:175], v[188:191], v[108:111]
	v_mfma_f32_16x16x32_bf16 v[100:103], v[180:183], v[188:191], v[100:103]
	v_mfma_f32_16x16x32_bf16 v[92:95], v[172:175], v[196:199], v[92:95]
	v_mfma_f32_16x16x32_bf16 v[84:87], v[180:183], v[196:199], v[84:87]
	v_mfma_f32_16x16x32_bf16 v[76:79], v[172:175], v[204:207], v[76:79]
	v_mfma_f32_16x16x32_bf16 v[72:75], v[180:183], v[204:207], v[72:75]
	v_mfma_f32_16x16x32_bf16 v[68:71], v[172:175], v[230:233], v[68:71]
	v_mfma_f32_16x16x32_bf16 v[64:67], v[180:183], v[230:233], v[64:67]
	v_mfma_f32_16x16x32_bf16 v[108:111], v[176:179], v[192:195], v[108:111]
	v_mfma_f32_16x16x32_bf16 v[100:103], v[184:187], v[192:195], v[100:103]
	v_mfma_f32_16x16x32_bf16 v[92:95], v[176:179], v[200:203], v[92:95]
	v_mfma_f32_16x16x32_bf16 v[84:87], v[184:187], v[200:203], v[84:87]
	v_mfma_f32_16x16x32_bf16 v[76:79], v[176:179], v[212:215], v[76:79]
	v_mfma_f32_16x16x32_bf16 v[72:75], v[184:187], v[212:215], v[72:75]
	v_mfma_f32_16x16x32_bf16 v[68:71], v[176:179], v[234:237], v[68:71]
	v_mfma_f32_16x16x32_bf16 v[64:67], v[184:187], v[234:237], v[64:67]
	s_barrier
	s_add_i32 s40, s40, s8
	v_lshl_add_u64 v[150:151], s[38:39], 0, v[152:153]
	s_mov_b32 m0, s40
	ds_read_b128 v[188:191], v149 offset:16384
	ds_read_b128 v[192:195], v149 offset:17408
	ds_read_b128 v[196:199], v149 offset:18432
	ds_read_b128 v[200:203], v149 offset:19456
	ds_read_b128 v[204:207], v149 offset:20480
	ds_read_b128 v[212:215], v149 offset:21504
	ds_read_b128 v[230:233], v149 offset:22528
	ds_read_b128 v[234:237], v149 offset:23552
	global_load_lds_dwordx4 v[150:151], off
	s_add_i32 m0, s40, 0x2000
	v_lshl_add_u64 v[158:159], s[38:39], 0, v[128:129]
	s_add_u32 s38, s38, s12
	s_addc_u32 s39, s39, s13
	s_add_i32 s37, s37, s8
	global_load_lds_dwordx4 v[158:159], off
	v_lshl_add_u64 v[160:161], s[38:39], 0, v[152:153]
	s_mov_b32 m0, s37
	v_lshl_add_u64 v[162:163], s[38:39], 0, v[128:129]
	global_load_lds_dwordx4 v[160:161], off
	s_add_i32 m0, s37, 0x2000
	v_lshl_add_u64 v[164:165], s[2:3], 0, v[152:153]
	global_load_lds_dwordx4 v[162:163], off
	s_mov_b32 m0, s9
	v_lshl_add_u64 v[208:209], s[2:3], 0, v[128:129]
	global_load_lds_dwordx4 v[164:165], off
	s_mov_b32 m0, s10
	s_nop 0
	global_load_lds_dwordx4 v[208:209], off
	s_waitcnt vmcnt(8)
	s_waitcnt lgkmcnt(0)
	s_barrier
; #define PG8_STAGE(bufoff, gbase, voff) do { _Pragma("unroll") for (int _i = 0; _i < 2; ++_i) \
;         __builtin_amdgcn_global_load_lds((const unsigned*)((const char*)(gbase) + (voff)[_i]), (PG8_LAS unsigned*)(lds + (bufoff) + ldsw + _i * 8192), 16, 0, 0); } while (0)
; #define PG8_LDA(dst, b, h) do { _Pragma("unroll") for (int m = 0; m < 4; ++m) _Pragma("unroll") for (int k = 0; k < 2; ++k) dst[m][k] = *(const PG8_LAS bf16x8*)(lds + PG8_SA(b, h) + aoff + m * 2048 + k * 1024); } while (0)
; #define PG8_LDB(dst, b, h) do { _Pragma("unroll") for (int n = 0; n < 2; ++n) _Pragma("unroll") for (int k = 0; k < 2; ++k) dst[n][k] = *(const PG8_LAS bf16x8*)(lds + PG8_SB(b, h) + boff + n * 2048 + k * 1024); } while (0)
; #define PG8_MMA(ai, bj, At, Bt) do { __builtin_amdgcn_s_setprio(1); _Pragma("unroll") for (int m = 0; m < 4; ++m) _Pragma("unroll") for (int n = 0; n < 2; ++n) _Pragma("unroll") for (int k = 0; k < 2; ++k) \
;         acc[ai][bj][m][n] = __builtin_amdgcn_mfma_f32_16x16x32_bf16(Bt[n][k], At[m][k], acc[ai][bj][m][n], 0, 0, 0); __builtin_amdgcn_s_setprio(0); } while (0)
; #define PG8_WAIT_V(n) asm volatile("s_waitcnt vmcnt(" #n ")" ::: "memory")
; #define PG8_WAIT_L(n) asm volatile("s_waitcnt lgkmcnt(" #n ")" ::: "memory")
; #define PG8_BAR __builtin_amdgcn_s_barrier()
; #define PG8_SCHED __builtin_amdgcn_sched_barrier(0)
; template <class Epi, class Sched, bool ALIGN_EPI = false, bool SP2 = false>
; __device__ __forceinline__ void gemm_phase(PG8_LAS unsigned char* lds, const Gemm g, const Sched& S, const Epi& E) {
;     ...
;             PG8_WAIT_V(8); PG8_WAIT_L(0); PG8_BAR; PG8_MMA(1, 0, At, B0); PG8_MMA(1, 1, At, B1); PG8_BAR; PG8_SCHED;
;             PG8_LDB(B0, 1, 0); PG8_LDB(B1, 1, 1); PG8_SCHED; PG8_LDA(At, 1, 0); PG8_STAGE(PG8_SA(0, 1), a2 + hstep, voffA);
;             PG8_WAIT_V(8); PG8_WAIT_L(0); PG8_BAR; PG8_MMA(0, 0, At, B0); PG8_MMA(0, 1, At, B1); PG8_BAR; PG8_SCHED;
	s_waitcnt lgkmcnt(0)
	v_mfma_f32_16x16x32_bf16 v[60:63], v[134:137], v[188:191], v[60:63]
	v_mfma_f32_16x16x32_bf16 v[56:59], v[142:145], v[188:191], v[56:59]
	v_mfma_f32_16x16x32_bf16 v[52:55], v[134:137], v[196:199], v[52:55]
	v_mfma_f32_16x16x32_bf16 v[48:51], v[142:145], v[196:199], v[48:51]
	v_mfma_f32_16x16x32_bf16 v[40:43], v[134:137], v[204:207], v[40:43]
	v_mfma_f32_16x16x32_bf16 v[32:35], v[142:145], v[204:207], v[32:35]
	v_mfma_f32_16x16x32_bf16 v[24:27], v[134:137], v[230:233], v[24:27]
	v_mfma_f32_16x16x32_bf16 v[16:19], v[142:145], v[230:233], v[16:19]
	v_mfma_f32_16x16x32_bf16 v[60:63], v[138:141], v[192:195], v[60:63]
	v_mfma_f32_16x16x32_bf16 v[56:59], v[168:171], v[192:195], v[56:59]
	v_mfma_f32_16x16x32_bf16 v[52:55], v[138:141], v[200:203], v[52:55]
	v_mfma_f32_16x16x32_bf16 v[48:51], v[168:171], v[200:203], v[48:51]
	v_mfma_f32_16x16x32_bf16 v[40:43], v[138:141], v[212:215], v[40:43]
	v_mfma_f32_16x16x32_bf16 v[32:35], v[168:171], v[212:215], v[32:35]
	v_mfma_f32_16x16x32_bf16 v[24:27], v[138:141], v[234:237], v[24:27]
	v_mfma_f32_16x16x32_bf16 v[16:19], v[168:171], v[234:237], v[16:19]
	v_mfma_f32_16x16x32_bf16 v[44:47], v[172:175], v[188:191], v[44:47]
	v_mfma_f32_16x16x32_bf16 v[36:39], v[180:183], v[188:191], v[36:39]
	v_mfma_f32_16x16x32_bf16 v[28:31], v[172:175], v[196:199], v[28:31]
	v_mfma_f32_16x16x32_bf16 v[20:23], v[180:183], v[196:199], v[20:23]
	v_mfma_f32_16x16x32_bf16 v[12:15], v[172:175], v[204:207], v[12:15]
	v_mfma_f32_16x16x32_bf16 v[8:11], v[180:183], v[204:207], v[8:11]
	v_mfma_f32_16x16x32_bf16 v[4:7], v[172:175], v[230:233], v[4:7]
	v_mfma_f32_16x16x32_bf16 v[0:3], v[180:183], v[230:233], v[0:3]
	v_mfma_f32_16x16x32_bf16 v[44:47], v[176:179], v[192:195], v[44:47]
	v_mfma_f32_16x16x32_bf16 v[36:39], v[184:187], v[192:195], v[36:39]
	v_mfma_f32_16x16x32_bf16 v[28:31], v[176:179], v[200:203], v[28:31]
	v_mfma_f32_16x16x32_bf16 v[20:23], v[184:187], v[200:203], v[20:23]
	v_mfma_f32_16x16x32_bf16 v[12:15], v[176:179], v[212:215], v[12:15]
	v_mfma_f32_16x16x32_bf16 v[8:11], v[184:187], v[212:215], v[8:11]
	v_mfma_f32_16x16x32_bf16 v[4:7], v[176:179], v[234:237], v[4:7]
	v_mfma_f32_16x16x32_bf16 v[0:3], v[184:187], v[234:237], v[0:3]
	s_barrier
	s_add_i32 s37, 0, 0x18000
	v_add_u32_e32 v167, s37, v147
	s_add_i32 s38, 0, 0x1c000
	ds_read_b128 v[134:137], v167
	ds_read_b128 v[138:141], v167 offset:1024
	ds_read_b128 v[142:145], v167 offset:2048
	ds_read_b128 v[168:171], v167 offset:3072
	v_add_u32_e32 v167, s38, v147
	ds_read_b128 v[172:175], v167
	ds_read_b128 v[176:179], v167 offset:1024
	ds_read_b128 v[180:183], v167 offset:2048
	ds_read_b128 v[184:187], v167 offset:3072
	s_add_u32 s2, s2, s12
	s_addc_u32 s3, s3, s13
	s_mov_b32 m0, s11
	v_lshl_add_u64 v[216:217], s[2:3], 0, v[152:153]
	ds_read_b128 v[188:191], v149 offset:32768
	ds_read_b128 v[192:195], v149 offset:33792
	ds_read_b128 v[196:199], v149 offset:34816
	ds_read_b128 v[200:203], v149 offset:35840
	ds_read_b128 v[204:207], v149 offset:36864
	ds_read_b128 v[212:215], v149 offset:37888
	ds_read_b128 v[230:233], v149 offset:38912
	ds_read_b128 v[234:237], v149 offset:39936
	global_load_lds_dwordx4 v[216:217], off
	v_lshl_add_u64 v[216:217], s[2:3], 0, v[128:129]
	s_mov_b32 m0, s20
	s_nop 0
	global_load_lds_dwordx4 v[216:217], off
	s_waitcnt vmcnt(8)
	s_waitcnt lgkmcnt(0)
	s_barrier
	s_waitcnt lgkmcnt(0)
	v_mfma_f32_16x16x32_bf16 v[124:127], v[134:137], v[188:191], v[124:127]
	v_mfma_f32_16x16x32_bf16 v[120:123], v[142:145], v[188:191], v[120:123]
	v_mfma_f32_16x16x32_bf16 v[116:119], v[134:137], v[196:199], v[116:119]
	v_mfma_f32_16x16x32_bf16 v[112:115], v[142:145], v[196:199], v[112:115]
	v_mfma_f32_16x16x32_bf16 v[104:107], v[134:137], v[204:207], v[104:107]
	v_mfma_f32_16x16x32_bf16 v[96:99], v[142:145], v[204:207], v[96:99]
	v_mfma_f32_16x16x32_bf16 v[88:91], v[134:137], v[230:233], v[88:91]
	v_mfma_f32_16x16x32_bf16 v[80:83], v[142:145], v[230:233], v[80:83]
	v_mfma_f32_16x16x32_bf16 v[124:127], v[138:141], v[192:195], v[124:127]
	v_mfma_f32_16x16x32_bf16 v[120:123], v[168:171], v[192:195], v[120:123]
	v_mfma_f32_16x16x32_bf16 v[116:119], v[138:141], v[200:203], v[116:119]
	v_mfma_f32_16x16x32_bf16 v[112:115], v[168:171], v[200:203], v[112:115]
	v_mfma_f32_16x16x32_bf16 v[104:107], v[138:141], v[212:215], v[104:107]
	v_mfma_f32_16x16x32_bf16 v[96:99], v[168:171], v[212:215], v[96:99]
	v_mfma_f32_16x16x32_bf16 v[88:91], v[138:141], v[234:237], v[88:91]
	v_mfma_f32_16x16x32_bf16 v[80:83], v[168:171], v[234:237], v[80:83]
	v_mfma_f32_16x16x32_bf16 v[108:111], v[172:175], v[188:191], v[108:111]
	v_mfma_f32_16x16x32_bf16 v[100:103], v[180:183], v[188:191], v[100:103]
	v_mfma_f32_16x16x32_bf16 v[92:95], v[172:175], v[196:199], v[92:95]
	v_mfma_f32_16x16x32_bf16 v[84:87], v[180:183], v[196:199], v[84:87]
	v_mfma_f32_16x16x32_bf16 v[76:79], v[172:175], v[204:207], v[76:79]
	v_mfma_f32_16x16x32_bf16 v[72:75], v[180:183], v[204:207], v[72:75]
	v_mfma_f32_16x16x32_bf16 v[68:71], v[172:175], v[230:233], v[68:71]
	v_mfma_f32_16x16x32_bf16 v[64:67], v[180:183], v[230:233], v[64:67]
	v_mfma_f32_16x16x32_bf16 v[108:111], v[176:179], v[192:195], v[108:111]
	v_mfma_f32_16x16x32_bf16 v[100:103], v[184:187], v[192:195], v[100:103]
	v_mfma_f32_16x16x32_bf16 v[92:95], v[176:179], v[200:203], v[92:95]
	v_mfma_f32_16x16x32_bf16 v[84:87], v[184:187], v[200:203], v[84:87]
	v_mfma_f32_16x16x32_bf16 v[76:79], v[176:179], v[212:215], v[76:79]
	v_mfma_f32_16x16x32_bf16 v[72:75], v[184:187], v[212:215], v[72:75]
	v_mfma_f32_16x16x32_bf16 v[68:71], v[176:179], v[234:237], v[68:71]
	v_mfma_f32_16x16x32_bf16 v[64:67], v[184:187], v[234:237], v[64:67]
	s_barrier
; #define PG8_STAGE(bufoff, gbase, voff) do { _Pragma("unroll") for (int _i = 0; _i < 2; ++_i) \
;         __builtin_amdgcn_global_load_lds((const unsigned*)((const char*)(gbase) + (voff)[_i]), (PG8_LAS unsigned*)(lds + (bufoff) + ldsw + _i * 8192), 16, 0, 0); } while (0)
; #define PG8_LDA(dst, b, h) do { _Pragma("unroll") for (int m = 0; m < 4; ++m) _Pragma("unroll") for (int k = 0; k < 2; ++k) dst[m][k] = *(const PG8_LAS bf16x8*)(lds + PG8_SA(b, h) + aoff + m * 2048 + k * 1024); } while (0)
; #define PG8_MMA(ai, bj, At, Bt) do { __builtin_amdgcn_s_setprio(1); _Pragma("unroll") for (int m = 0; m < 4; ++m) _Pragma("unroll") for (int n = 0; n < 2; ++n) _Pragma("unroll") for (int k = 0; k < 2; ++k) \
;         acc[ai][bj][m][n] = __builtin_amdgcn_mfma_f32_16x16x32_bf16(Bt[n][k], At[m][k], acc[ai][bj][m][n], 0, 0, 0); __builtin_amdgcn_s_setprio(0); } while (0)
; #define PG8_WAIT_V(n) asm volatile("s_waitcnt vmcnt(" #n ")" ::: "memory")
; #define PG8_WAIT_L(n) asm volatile("s_waitcnt lgkmcnt(" #n ")" ::: "memory")
; #define PG8_BAR __builtin_amdgcn_s_barrier()
; #define PG8_SCHED __builtin_amdgcn_sched_barrier(0)
; template <class Epi, class Sched, bool ALIGN_EPI = false, bool SP2 = false>
; __device__ __forceinline__ void gemm_phase(PG8_LAS unsigned char* lds, const Gemm g, const Sched& S, const Epi& E) {
;     ...
;         for (int t = 0; t < nt; t += 2) {
;     ...
;             PG8_LDA(At, 1, 1); PG8_STAGE(PG8_SB(1, 0), b3, voffB); PG8_STAGE(PG8_SB(1, 1), b3 + hstep, voffB); PG8_STAGE(PG8_SA(1, 0), a3, voffA);
;             PG8_WAIT_V(8); PG8_WAIT_L(0); PG8_BAR; PG8_MMA(1, 0, At, B0); PG8_MMA(1, 1, At, B1); PG8_BAR; PG8_SCHED;
	s_add_i32 s2, s37, s8
	v_lshl_add_u64 v[150:151], v[150:151], 0, s[82:83]
	s_mov_b32 m0, s2
	ds_read_b128 v[188:191], v149 offset:49152
	ds_read_b128 v[192:195], v149 offset:50176
	ds_read_b128 v[196:199], v149 offset:51200
	ds_read_b128 v[200:203], v149 offset:52224
	ds_read_b128 v[204:207], v149 offset:53248
	ds_read_b128 v[212:215], v149 offset:54272
	ds_read_b128 v[230:233], v149 offset:55296
	ds_read_b128 v[234:237], v149 offset:56320
	global_load_lds_dwordx4 v[150:151], off
	v_lshl_add_u64 v[150:151], v[158:159], 0, s[82:83]
	s_add_i32 m0, s2, 0x2000
	s_add_i32 s2, s38, s8
	global_load_lds_dwordx4 v[150:151], off
	v_lshl_add_u64 v[150:151], v[160:161], 0, s[82:83]
	s_mov_b32 m0, s2
	s_nop 0
	global_load_lds_dwordx4 v[150:151], off
	v_lshl_add_u64 v[150:151], v[162:163], 0, s[82:83]
	s_add_i32 m0, s2, 0x2000
	s_nop 0
	global_load_lds_dwordx4 v[150:151], off
	v_lshl_add_u64 v[150:151], v[164:165], 0, s[82:83]
	s_mov_b32 m0, s21
	s_nop 0
	global_load_lds_dwordx4 v[150:151], off
	v_lshl_add_u64 v[150:151], v[208:209], 0, s[82:83]
	s_mov_b32 m0, s22
	s_nop 0
	global_load_lds_dwordx4 v[150:151], off
	s_waitcnt vmcnt(8)
	s_waitcnt lgkmcnt(0)
	s_barrier
	s_waitcnt lgkmcnt(0)
	v_mfma_f32_16x16x32_bf16 v[60:63], v[134:137], v[188:191], v[60:63]
	v_mfma_f32_16x16x32_bf16 v[56:59], v[142:145], v[188:191], v[56:59]
	v_mfma_f32_16x16x32_bf16 v[52:55], v[134:137], v[196:199], v[52:55]
	v_mfma_f32_16x16x32_bf16 v[48:51], v[142:145], v[196:199], v[48:51]
	v_mfma_f32_16x16x32_bf16 v[40:43], v[134:137], v[204:207], v[40:43]
	v_mfma_f32_16x16x32_bf16 v[32:35], v[142:145], v[204:207], v[32:35]
	v_mfma_f32_16x16x32_bf16 v[24:27], v[134:137], v[230:233], v[24:27]
	v_mfma_f32_16x16x32_bf16 v[16:19], v[142:145], v[230:233], v[16:19]
	v_mfma_f32_16x16x32_bf16 v[60:63], v[138:141], v[192:195], v[60:63]
	v_mfma_f32_16x16x32_bf16 v[56:59], v[168:171], v[192:195], v[56:59]
	v_mfma_f32_16x16x32_bf16 v[52:55], v[138:141], v[200:203], v[52:55]
	v_mfma_f32_16x16x32_bf16 v[48:51], v[168:171], v[200:203], v[48:51]
	v_mfma_f32_16x16x32_bf16 v[40:43], v[138:141], v[212:215], v[40:43]
	v_mfma_f32_16x16x32_bf16 v[32:35], v[168:171], v[212:215], v[32:35]
	v_mfma_f32_16x16x32_bf16 v[24:27], v[138:141], v[234:237], v[24:27]
	v_mfma_f32_16x16x32_bf16 v[16:19], v[168:171], v[234:237], v[16:19]
	v_mfma_f32_16x16x32_bf16 v[44:47], v[172:175], v[188:191], v[44:47]
	v_mfma_f32_16x16x32_bf16 v[36:39], v[180:183], v[188:191], v[36:39]
	v_mfma_f32_16x16x32_bf16 v[28:31], v[172:175], v[196:199], v[28:31]
	v_mfma_f32_16x16x32_bf16 v[20:23], v[180:183], v[196:199], v[20:23]
	v_mfma_f32_16x16x32_bf16 v[12:15], v[172:175], v[204:207], v[12:15]
	v_mfma_f32_16x16x32_bf16 v[8:11], v[180:183], v[204:207], v[8:11]
	v_mfma_f32_16x16x32_bf16 v[4:7], v[172:175], v[230:233], v[4:7]
	v_mfma_f32_16x16x32_bf16 v[0:3], v[180:183], v[230:233], v[0:3]
	v_mfma_f32_16x16x32_bf16 v[44:47], v[176:179], v[192:195], v[44:47]
	v_mfma_f32_16x16x32_bf16 v[36:39], v[184:187], v[192:195], v[36:39]
	v_mfma_f32_16x16x32_bf16 v[28:31], v[176:179], v[200:203], v[28:31]
	v_mfma_f32_16x16x32_bf16 v[20:23], v[184:187], v[200:203], v[20:23]
	v_mfma_f32_16x16x32_bf16 v[12:15], v[176:179], v[212:215], v[12:15]
	v_mfma_f32_16x16x32_bf16 v[8:11], v[184:187], v[212:215], v[8:11]
	v_mfma_f32_16x16x32_bf16 v[4:7], v[176:179], v[234:237], v[4:7]
	v_mfma_f32_16x16x32_bf16 v[0:3], v[184:187], v[234:237], v[0:3]
	s_barrier
	s_add_u32 s0, s0, 0x100
	s_addc_u32 s1, s1, 0
	s_add_u32 s34, s34, 0x100
	s_addc_u32 s35, s35, 0
	s_cmp_ge_i32 s36, s23
	s_mov_b32 s2, s36
	s_cbranch_scc0 .LBB0_117
; #define PG8_BAR __builtin_amdgcn_s_barrier()
; template <class Epi, class Sched, bool ALIGN_EPI = false, bool SP2 = false>
; __device__ __forceinline__ void gemm_phase(PG8_LAS unsigned char* lds, const Gemm g, const Sched& S, const Epi& E) {
;     ...
;         if constexpr (ALIGN_EPI) { if (wr == 0) PG8_BAR; }
;         if constexpr (!Epi::AFTER_DRAIN) { E(acc, cur, wr, wc, fr, fq); S.done(cur); }
;     __device__ __forceinline__ void operator()(const f32x4 (&acc)[2][2][4][2], const pg8::Unit& u, int wr, int wc, int fr, int fq) const {
;         const int row0 = u.pm * 256 + wr * 64 + fr, col0 = u.pn * 256 + wc * 32 + 4 * fq;
; #pragma unroll
;         for (int ai = 0; ai < 2; ++ai)
; #pragma unroll
;             for (int mh = 0; mh < 2; ++mh) {
;                 f32x4 xi[2][2][2];
; #pragma unroll
;                 for (int m = 0; m < 2; ++m)
; #pragma unroll
;                     for (int bj = 0; bj < 2; ++bj)
; #pragma unroll
;                         for (int n = 0; n < 2; ++n) xi[m][bj][n] = *(const f32x4*)(Xin + (size_t)(row0 + ai * 128 + (2 * mh + m) * 16) * D + col0 + bj * 128 + n * 16);
;                 __builtin_amdgcn_sched_barrier(0);
; #pragma unroll
;                 for (int m = 0; m < 2; ++m)
; #pragma unroll
;                     for (int bj = 0; bj < 2; ++bj)
; #pragma unroll
;                         for (int n = 0; n < 2; ++n) *(f32x4*)(Xout + (size_t)(row0 + ai * 128 + (2 * mh + m) * 16) * D + col0 + bj * 128 + n * 16) = xi[m][bj][n] + acc[ai][bj][2 * mh + m][n] * scale;
	s_setprio 0
	v_pk_mul_f32 v[134:135], v[126:127], 0.5 op_sel_hi:[1,0]
	v_pk_mul_f32 v[136:137], v[124:125], 0.5 op_sel_hi:[1,0]
	v_pk_mul_f32 v[126:127], v[122:123], 0.5 op_sel_hi:[1,0]
	v_pk_mul_f32 v[124:125], v[120:121], 0.5 op_sel_hi:[1,0]
	v_pk_mul_f32 v[144:145], v[110:111], 0.5 op_sel_hi:[1,0]
	v_pk_mul_f32 v[142:143], v[108:109], 0.5 op_sel_hi:[1,0]
	v_pk_mul_f32 v[140:141], v[102:103], 0.5 op_sel_hi:[1,0]
	v_pk_mul_f32 v[138:139], v[100:101], 0.5 op_sel_hi:[1,0]
	v_pk_mul_f32 v[118:119], v[118:119], 0.5 op_sel_hi:[1,0]
	v_pk_mul_f32 v[116:117], v[116:117], 0.5 op_sel_hi:[1,0]
	v_pk_mul_f32 v[110:111], v[114:115], 0.5 op_sel_hi:[1,0]
	v_pk_mul_f32 v[108:109], v[112:113], 0.5 op_sel_hi:[1,0]
	v_pk_mul_f32 v[122:123], v[94:95], 0.5 op_sel_hi:[1,0]
	v_pk_mul_f32 v[120:121], v[92:93], 0.5 op_sel_hi:[1,0]
	v_pk_mul_f32 v[114:115], v[86:87], 0.5 op_sel_hi:[1,0]
	v_pk_mul_f32 v[112:113], v[84:85], 0.5 op_sel_hi:[1,0]
	v_pk_mul_f32 v[102:103], v[106:107], 0.5 op_sel_hi:[1,0]
	v_pk_mul_f32 v[100:101], v[104:105], 0.5 op_sel_hi:[1,0]
	v_pk_mul_f32 v[94:95], v[98:99], 0.5 op_sel_hi:[1,0]
	v_pk_mul_f32 v[92:93], v[96:97], 0.5 op_sel_hi:[1,0]
	v_pk_mul_f32 v[106:107], v[78:79], 0.5 op_sel_hi:[1,0]
	v_pk_mul_f32 v[104:105], v[76:77], 0.5 op_sel_hi:[1,0]
	v_pk_mul_f32 v[98:99], v[74:75], 0.5 op_sel_hi:[1,0]
	v_pk_mul_f32 v[96:97], v[72:73], 0.5 op_sel_hi:[1,0]
	v_pk_mul_f32 v[86:87], v[90:91], 0.5 op_sel_hi:[1,0]
	v_pk_mul_f32 v[84:85], v[88:89], 0.5 op_sel_hi:[1,0]
	v_pk_mul_f32 v[74:75], v[82:83], 0.5 op_sel_hi:[1,0]
	v_pk_mul_f32 v[72:73], v[80:81], 0.5 op_sel_hi:[1,0]
	v_pk_mul_f32 v[90:91], v[70:71], 0.5 op_sel_hi:[1,0]
	v_pk_mul_f32 v[88:89], v[68:69], 0.5 op_sel_hi:[1,0]
	v_pk_mul_f32 v[82:83], v[66:67], 0.5 op_sel_hi:[1,0]
	v_pk_mul_f32 v[80:81], v[64:65], 0.5 op_sel_hi:[1,0]
	v_pk_mul_f32 v[66:67], v[62:63], 0.5 op_sel_hi:[1,0]
	v_pk_mul_f32 v[64:65], v[60:61], 0.5 op_sel_hi:[1,0]
	v_pk_mul_f32 v[62:63], v[58:59], 0.5 op_sel_hi:[1,0]
	v_pk_mul_f32 v[60:61], v[56:57], 0.5 op_sel_hi:[1,0]
	v_pk_mul_f32 v[78:79], v[46:47], 0.5 op_sel_hi:[1,0]
	v_pk_mul_f32 v[76:77], v[44:45], 0.5 op_sel_hi:[1,0]
	v_pk_mul_f32 v[70:71], v[38:39], 0.5 op_sel_hi:[1,0]
	v_pk_mul_f32 v[68:69], v[36:37], 0.5 op_sel_hi:[1,0]
	v_pk_mul_f32 v[54:55], v[54:55], 0.5 op_sel_hi:[1,0]
	v_pk_mul_f32 v[52:53], v[52:53], 0.5 op_sel_hi:[1,0]
	v_pk_mul_f32 v[46:47], v[50:51], 0.5 op_sel_hi:[1,0]
	v_pk_mul_f32 v[44:45], v[48:49], 0.5 op_sel_hi:[1,0]
	v_pk_mul_f32 v[58:59], v[30:31], 0.5 op_sel_hi:[1,0]
	v_pk_mul_f32 v[56:57], v[28:29], 0.5 op_sel_hi:[1,0]
	v_pk_mul_f32 v[50:51], v[22:23], 0.5 op_sel_hi:[1,0]
	v_pk_mul_f32 v[48:49], v[20:21], 0.5 op_sel_hi:[1,0]
	v_pk_mul_f32 v[30:31], v[42:43], 0.5 op_sel_hi:[1,0]
	v_pk_mul_f32 v[28:29], v[40:41], 0.5 op_sel_hi:[1,0]
	v_pk_mul_f32 v[22:23], v[34:35], 0.5 op_sel_hi:[1,0]
	v_pk_mul_f32 v[20:21], v[32:33], 0.5 op_sel_hi:[1,0]
	v_pk_mul_f32 v[38:39], v[14:15], 0.5 op_sel_hi:[1,0]
	v_pk_mul_f32 v[36:37], v[12:13], 0.5 op_sel_hi:[1,0]
	v_pk_mul_f32 v[34:35], v[10:11], 0.5 op_sel_hi:[1,0]
	v_pk_mul_f32 v[32:33], v[8:9], 0.5 op_sel_hi:[1,0]
	v_pk_mul_f32 v[14:15], v[26:27], 0.5 op_sel_hi:[1,0]
	v_pk_mul_f32 v[12:13], v[24:25], 0.5 op_sel_hi:[1,0]
	v_pk_mul_f32 v[10:11], v[18:19], 0.5 op_sel_hi:[1,0]
	v_pk_mul_f32 v[8:9], v[16:17], 0.5 op_sel_hi:[1,0]
	v_pk_mul_f32 v[6:7], v[6:7], 0.5 op_sel_hi:[1,0]
	v_pk_mul_f32 v[4:5], v[4:5], 0.5 op_sel_hi:[1,0]
	v_pk_mul_f32 v[2:3], v[2:3], 0.5 op_sel_hi:[1,0]
	v_pk_mul_f32 v[0:1], v[0:1], 0.5 op_sel_hi:[1,0]
	s_mov_b64 s[34:35], 0x4000

; template <class Epi, class Sched, bool ALIGN_EPI = false, bool SP2 = false>
; __device__ __forceinline__ void gemm_phase(PG8_LAS unsigned char* lds, const Gemm g, const Sched& S, const Epi& E) {
;     ...
;     f32x4 acc[2][2][4][2];
; #pragma unroll
;     for (int a = 0; a < 2; ++a)
; #pragma unroll
;         for (int b = 0; b < 2; ++b)
; #pragma unroll
;             for (int m = 0; m < 4; ++m)
; #pragma unroll
;                 for (int n = 0; n < 2; ++n) acc[a][b][m][n] = (f32x4){0.f, 0.f, 0.f, 0.f};
;     ...
;     for (;;) {
;         const bool has_next = S.next(ui + 1, nxt);
;         const char* nA = has_next ? (const char*)g.A + (size_t)nxt.pm * tstep : cA; const char* nB = has_next ? (const char*)g.Bt + (size_t)nxt.pn * tstep : cB;
;         for (int t = 0; t < nt; t += 2) {
.LBB0_156:
	v_mov_b32_e32 v127, 0
	s_andn2_b64 vcc, exec, s[18:19]
	v_mov_b32_e32 v126, v127
	v_mov_b32_e32 v125, v127
	v_mov_b32_e32 v124, v127
	v_mov_b32_e32 v123, v127
	v_mov_b32_e32 v122, v127
	v_mov_b32_e32 v121, v127
	v_mov_b32_e32 v120, v127
	v_mov_b32_e32 v111, v127
	v_mov_b32_e32 v110, v127
	v_mov_b32_e32 v109, v127
	v_mov_b32_e32 v108, v127
	v_mov_b32_e32 v107, v127
	v_mov_b32_e32 v106, v127
	v_mov_b32_e32 v105, v127
	v_mov_b32_e32 v104, v127
	v_mov_b32_e32 v95, v127
	v_mov_b32_e32 v94, v127
	v_mov_b32_e32 v93, v127
	v_mov_b32_e32 v92, v127
	v_mov_b32_e32 v91, v127
	v_mov_b32_e32 v90, v127
	v_mov_b32_e32 v89, v127
	v_mov_b32_e32 v88, v127
	v_mov_b32_e32 v79, v127
	v_mov_b32_e32 v78, v127
	v_mov_b32_e32 v77, v127
	v_mov_b32_e32 v76, v127
	v_mov_b32_e32 v75, v127
	v_mov_b32_e32 v74, v127
	v_mov_b32_e32 v73, v127
	v_mov_b32_e32 v72, v127
	v_mov_b32_e32 v119, v127
	v_mov_b32_e32 v118, v127
	v_mov_b32_e32 v117, v127
	v_mov_b32_e32 v116, v127
	v_mov_b32_e32 v115, v127
	v_mov_b32_e32 v114, v127
	v_mov_b32_e32 v113, v127
	v_mov_b32_e32 v112, v127
	v_mov_b32_e32 v103, v127
	v_mov_b32_e32 v102, v127
	v_mov_b32_e32 v101, v127
	v_mov_b32_e32 v100, v127
	v_mov_b32_e32 v99, v127
	v_mov_b32_e32 v98, v127
	v_mov_b32_e32 v97, v127
	v_mov_b32_e32 v96, v127
	v_mov_b32_e32 v87, v127
	v_mov_b32_e32 v86, v127
	v_mov_b32_e32 v85, v127
	v_mov_b32_e32 v84, v127
	v_mov_b32_e32 v83, v127
	v_mov_b32_e32 v82, v127
	v_mov_b32_e32 v81, v127
	v_mov_b32_e32 v80, v127
	v_mov_b32_e32 v71, v127
	v_mov_b32_e32 v70, v127
	v_mov_b32_e32 v69, v127
	v_mov_b32_e32 v68, v127
	v_mov_b32_e32 v67, v127
	v_mov_b32_e32 v66, v127
	v_mov_b32_e32 v65, v127
	v_mov_b32_e32 v64, v127
	v_mov_b32_e32 v63, v127
	v_mov_b32_e32 v62, v127
	v_mov_b32_e32 v61, v127
	v_mov_b32_e32 v60, v127
	v_mov_b32_e32 v59, v127
	v_mov_b32_e32 v58, v127
	v_mov_b32_e32 v57, v127
	v_mov_b32_e32 v56, v127
	v_mov_b32_e32 v47, v127
	v_mov_b32_e32 v46, v127
	v_mov_b32_e32 v45, v127
	v_mov_b32_e32 v44, v127
	v_mov_b32_e32 v43, v127
	v_mov_b32_e32 v42, v127
	v_mov_b32_e32 v41, v127
	v_mov_b32_e32 v40, v127
	v_mov_b32_e32 v31, v127
	v_mov_b32_e32 v30, v127
	v_mov_b32_e32 v29, v127
	v_mov_b32_e32 v28, v127
	v_mov_b32_e32 v27, v127
	v_mov_b32_e32 v26, v127
	v_mov_b32_e32 v25, v127
	v_mov_b32_e32 v24, v127
	v_mov_b32_e32 v15, v127
	v_mov_b32_e32 v14, v127
	v_mov_b32_e32 v13, v127
	v_mov_b32_e32 v12, v127
	v_mov_b32_e32 v11, v127
	v_mov_b32_e32 v10, v127
	v_mov_b32_e32 v9, v127
	v_mov_b32_e32 v8, v127
	v_mov_b32_e32 v55, v127
	v_mov_b32_e32 v54, v127
	v_mov_b32_e32 v53, v127
	v_mov_b32_e32 v52, v127
	v_mov_b32_e32 v51, v127
	v_mov_b32_e32 v50, v127
	v_mov_b32_e32 v49, v127
	v_mov_b32_e32 v48, v127
	v_mov_b32_e32 v39, v127
	v_mov_b32_e32 v38, v127
	v_mov_b32_e32 v37, v127
	v_mov_b32_e32 v36, v127
	v_mov_b32_e32 v35, v127
	v_mov_b32_e32 v34, v127
	v_mov_b32_e32 v33, v127
	v_mov_b32_e32 v32, v127
	v_mov_b32_e32 v23, v127
	v_mov_b32_e32 v22, v127
	v_mov_b32_e32 v21, v127
	v_mov_b32_e32 v20, v127
	v_mov_b32_e32 v19, v127
	v_mov_b32_e32 v18, v127
	v_mov_b32_e32 v17, v127
	v_mov_b32_e32 v16, v127
	v_mov_b32_e32 v7, v127
	v_mov_b32_e32 v6, v127
	v_mov_b32_e32 v5, v127
	v_mov_b32_e32 v4, v127
	v_mov_b32_e32 v3, v127
	v_mov_b32_e32 v2, v127
	v_mov_b32_e32 v1, v127
	v_mov_b32_e32 v0, v127
	s_cbranch_vccnz .LBB0_159
	s_add_u32 s0, s0, 0x80
	s_addc_u32 s1, s1, 0
	s_add_u32 s36, s2, 0x100
	v_mov_b32_e32 v0, 0
	s_addc_u32 s37, s3, 0
	s_mov_b32 s2, 0
	v_mov_b32_e32 v1, v0
	v_mov_b32_e32 v2, v0
	v_mov_b32_e32 v3, v0
	v_mov_b32_e32 v4, v0
	v_mov_b32_e32 v5, v0
	v_mov_b32_e32 v6, v0
	v_mov_b32_e32 v7, v0
	v_mov_b32_e32 v16, v0
	v_mov_b32_e32 v17, v0
	v_mov_b32_e32 v18, v0
	v_mov_b32_e32 v19, v0
	v_mov_b32_e32 v20, v0
	v_mov_b32_e32 v21, v0
	v_mov_b32_e32 v22, v0
	v_mov_b32_e32 v23, v0
	v_mov_b32_e32 v32, v0
	v_mov_b32_e32 v33, v0
	v_mov_b32_e32 v34, v0
	v_mov_b32_e32 v35, v0
	v_mov_b32_e32 v36, v0
	v_mov_b32_e32 v37, v0
	v_mov_b32_e32 v38, v0
	v_mov_b32_e32 v39, v0
	v_mov_b32_e32 v48, v0
	v_mov_b32_e32 v49, v0
	v_mov_b32_e32 v50, v0
	v_mov_b32_e32 v51, v0
	v_mov_b32_e32 v52, v0
	v_mov_b32_e32 v53, v0
	v_mov_b32_e32 v54, v0
	v_mov_b32_e32 v55, v0
	v_mov_b32_e32 v8, v0
	v_mov_b32_e32 v9, v0
	v_mov_b32_e32 v10, v0
	v_mov_b32_e32 v11, v0
	v_mov_b32_e32 v12, v0
	v_mov_b32_e32 v13, v0
	v_mov_b32_e32 v14, v0
	v_mov_b32_e32 v15, v0
	v_mov_b32_e32 v24, v0
	v_mov_b32_e32 v25, v0
	v_mov_b32_e32 v26, v0
	v_mov_b32_e32 v27, v0
	v_mov_b32_e32 v28, v0
	v_mov_b32_e32 v29, v0
	v_mov_b32_e32 v30, v0
	v_mov_b32_e32 v31, v0
	v_mov_b32_e32 v40, v0
	v_mov_b32_e32 v41, v0
	v_mov_b32_e32 v42, v0
	v_mov_b32_e32 v43, v0
	v_mov_b32_e32 v44, v0
	v_mov_b32_e32 v45, v0
	v_mov_b32_e32 v46, v0
	v_mov_b32_e32 v47, v0
	v_mov_b32_e32 v56, v0
	v_mov_b32_e32 v57, v0
	v_mov_b32_e32 v58, v0
	v_mov_b32_e32 v59, v0
	v_mov_b32_e32 v60, v0
	v_mov_b32_e32 v61, v0
	v_mov_b32_e32 v62, v0
	v_mov_b32_e32 v63, v0
	v_mov_b32_e32 v64, v0
	v_mov_b32_e32 v65, v0
	v_mov_b32_e32 v66, v0
	v_mov_b32_e32 v67, v0
	v_mov_b32_e32 v68, v0
	v_mov_b32_e32 v69, v0
	v_mov_b32_e32 v70, v0
	v_mov_b32_e32 v71, v0
	v_mov_b32_e32 v80, v0
	v_mov_b32_e32 v81, v0
	v_mov_b32_e32 v82, v0
	v_mov_b32_e32 v83, v0
	v_mov_b32_e32 v84, v0
	v_mov_b32_e32 v85, v0
	v_mov_b32_e32 v86, v0
	v_mov_b32_e32 v87, v0
	v_mov_b32_e32 v96, v0
	v_mov_b32_e32 v97, v0
	v_mov_b32_e32 v98, v0
	v_mov_b32_e32 v99, v0
	v_mov_b32_e32 v100, v0
	v_mov_b32_e32 v101, v0
	v_mov_b32_e32 v102, v0
	v_mov_b32_e32 v103, v0
	v_mov_b32_e32 v112, v0
	v_mov_b32_e32 v113, v0
	v_mov_b32_e32 v114, v0
	v_mov_b32_e32 v115, v0
	v_mov_b32_e32 v116, v0
	v_mov_b32_e32 v117, v0
	v_mov_b32_e32 v118, v0
	v_mov_b32_e32 v119, v0
	v_mov_b32_e32 v72, v0
	v_mov_b32_e32 v73, v0
	v_mov_b32_e32 v74, v0
	v_mov_b32_e32 v75, v0
	v_mov_b32_e32 v76, v0
	v_mov_b32_e32 v77, v0
	v_mov_b32_e32 v78, v0
	v_mov_b32_e32 v79, v0
	v_mov_b32_e32 v88, v0
	v_mov_b32_e32 v89, v0
	v_mov_b32_e32 v90, v0
	v_mov_b32_e32 v91, v0
	v_mov_b32_e32 v92, v0
	v_mov_b32_e32 v93, v0
	v_mov_b32_e32 v94, v0
	v_mov_b32_e32 v95, v0
	v_mov_b32_e32 v104, v0
	v_mov_b32_e32 v105, v0
	v_mov_b32_e32 v106, v0
	v_mov_b32_e32 v107, v0
	v_mov_b32_e32 v108, v0
	v_mov_b32_e32 v109, v0
	v_mov_b32_e32 v110, v0
	v_mov_b32_e32 v111, v0
	v_mov_b32_e32 v120, v0
	v_mov_b32_e32 v121, v0
	v_mov_b32_e32 v122, v0
	v_mov_b32_e32 v123, v0
	v_mov_b32_e32 v124, v0
	v_mov_b32_e32 v125, v0
	v_mov_b32_e32 v126, v0
	v_mov_b32_e32 v127, v0
	v_readfirstlane_b32 s100, v211
	s_cmp_ge_u32 s100, 0x100
	s_cbranch_scc0 .Lprio_skip11
	s_setprio 1
; #define PG8_STAGE(bufoff, gbase, voff) do { _Pragma("unroll") for (int _i = 0; _i < 2; ++_i) \
;         __builtin_amdgcn_global_load_lds((const unsigned*)((const char*)(gbase) + (voff)[_i]), (PG8_LAS unsigned*)(lds + (bufoff) + ldsw + _i * 8192), 16, 0, 0); } while (0)
; #define PG8_LDA(dst, b, h) do { _Pragma("unroll") for (int m = 0; m < 4; ++m) _Pragma("unroll") for (int k = 0; k < 2; ++k) dst[m][k] = *(const PG8_LAS bf16x8*)(lds + PG8_SA(b, h) + aoff + m * 2048 + k * 1024); } while (0)
; #define PG8_LDB(dst, b, h) do { _Pragma("unroll") for (int n = 0; n < 2; ++n) _Pragma("unroll") for (int k = 0; k < 2; ++k) dst[n][k] = *(const PG8_LAS bf16x8*)(lds + PG8_SB(b, h) + boff + n * 2048 + k * 1024); } while (0)
; #define PG8_MMA(ai, bj, At, Bt) do { __builtin_amdgcn_s_setprio(1); _Pragma("unroll") for (int m = 0; m < 4; ++m) _Pragma("unroll") for (int n = 0; n < 2; ++n) _Pragma("unroll") for (int k = 0; k < 2; ++k) \
;         acc[ai][bj][m][n] = __builtin_amdgcn_mfma_f32_16x16x32_bf16(Bt[n][k], At[m][k], acc[ai][bj][m][n], 0, 0, 0); __builtin_amdgcn_s_setprio(0); } while (0)
; #define PG8_WAIT_V(n) asm volatile("s_waitcnt vmcnt(" #n ")" ::: "memory")
; #define PG8_WAIT_L(n) asm volatile("s_waitcnt lgkmcnt(" #n ")" ::: "memory")
; #define PG8_BAR __builtin_amdgcn_s_barrier()
; #define PG8_SCHED __builtin_amdgcn_sched_barrier(0)
; template <class Epi, class Sched, bool ALIGN_EPI = false, bool SP2 = false>
; __device__ __forceinline__ void gemm_phase(PG8_LAS unsigned char* lds, const Gemm g, const Sched& S, const Epi& E) {
;     ...
;             PG8_LDB(B0, 0, 0); PG8_LDB(B1, 0, 1); PG8_SCHED; PG8_LDA(At, 0, 0); PG8_STAGE(PG8_SA(1, 1), a1 + hstep, voffA);
;             PG8_WAIT_V(8); PG8_WAIT_L(0); PG8_BAR; PG8_MMA(0, 0, At, B0); PG8_MMA(0, 1, At, B1); PG8_BAR; PG8_SCHED;
;             PG8_LDA(At, 0, 1); PG8_STAGE(PG8_SB(0, 0), b2, voffB); PG8_STAGE(PG8_SB(0, 1), b2 + hstep, voffB); PG8_STAGE(PG8_SA(0, 0), a2, voffA);
.Lprio_skip11:
.LBB0_158:
	s_add_i32 s38, s2, 2
	s_add_u32 s39, s0, 0x80
	s_addc_u32 s3, s1, 0
	s_add_i32 s42, 0, 0x10000
	s_cmp_eq_u32 s28, s2
	s_cselect_b32 s3, s7, s3
	s_cselect_b32 s2, s6, s39
	v_add_u32_e32 v138, s42, v141
	s_cselect_b32 s41, s47, s37
	s_cselect_b32 s40, s46, s36
	s_add_i32 s39, 0, 0x14000
	ds_read_b128 v[134:137], v138
	ds_read_b128 v[144:147], v138 offset:1024
	ds_read_b128 v[148:151], v138 offset:2048
	ds_read_b128 v[158:161], v138 offset:3072
	v_add_u32_e32 v138, s39, v141
	ds_read_b128 v[162:165], v138
	ds_read_b128 v[168:171], v138 offset:1024
	ds_read_b128 v[172:175], v138 offset:2048
	ds_read_b128 v[176:179], v138 offset:3072
	v_lshl_add_u64 v[138:139], s[0:1], 0, v[130:131]
	s_add_i32 m0, s11, 0xc000
	ds_read_b128 v[180:183], v143
	ds_read_b128 v[184:187], v143 offset:1024
	ds_read_b128 v[188:191], v143 offset:2048
	ds_read_b128 v[192:195], v143 offset:3072
	ds_read_b128 v[196:199], v143 offset:4096
	ds_read_b128 v[200:203], v143 offset:5120
	ds_read_b128 v[204:207], v143 offset:6144
	ds_read_b128 v[212:215], v143 offset:7168
	global_load_lds_dwordx4 v[138:139], off
	v_lshl_add_u64 v[138:139], s[0:1], 0, v[132:133]
	s_add_i32 m0, s11, 0xe000
	s_nop 0
	global_load_lds_dwordx4 v[138:139], off
	s_waitcnt vmcnt(8)
	s_waitcnt lgkmcnt(0)
	s_barrier
	s_waitcnt lgkmcnt(0)
	v_mfma_f32_16x16x32_bf16 v[124:127], v[134:137], v[180:183], v[124:127]
	v_mfma_f32_16x16x32_bf16 v[120:123], v[148:151], v[180:183], v[120:123]
	v_mfma_f32_16x16x32_bf16 v[108:111], v[134:137], v[188:191], v[108:111]
	v_mfma_f32_16x16x32_bf16 v[104:107], v[148:151], v[188:191], v[104:107]
	v_mfma_f32_16x16x32_bf16 v[92:95], v[134:137], v[196:199], v[92:95]
	v_mfma_f32_16x16x32_bf16 v[88:91], v[148:151], v[196:199], v[88:91]
	v_mfma_f32_16x16x32_bf16 v[76:79], v[134:137], v[204:207], v[76:79]
	v_mfma_f32_16x16x32_bf16 v[72:75], v[148:151], v[204:207], v[72:75]
	v_mfma_f32_16x16x32_bf16 v[124:127], v[144:147], v[184:187], v[124:127]
	v_mfma_f32_16x16x32_bf16 v[120:123], v[158:161], v[184:187], v[120:123]
	v_mfma_f32_16x16x32_bf16 v[108:111], v[144:147], v[192:195], v[108:111]
	v_mfma_f32_16x16x32_bf16 v[104:107], v[158:161], v[192:195], v[104:107]
	v_mfma_f32_16x16x32_bf16 v[92:95], v[144:147], v[200:203], v[92:95]
	v_mfma_f32_16x16x32_bf16 v[88:91], v[158:161], v[200:203], v[88:91]
	v_mfma_f32_16x16x32_bf16 v[76:79], v[144:147], v[212:215], v[76:79]
	v_mfma_f32_16x16x32_bf16 v[72:75], v[158:161], v[212:215], v[72:75]
	v_mfma_f32_16x16x32_bf16 v[116:119], v[162:165], v[180:183], v[116:119]
	v_mfma_f32_16x16x32_bf16 v[112:115], v[172:175], v[180:183], v[112:115]
	v_mfma_f32_16x16x32_bf16 v[100:103], v[162:165], v[188:191], v[100:103]
	v_mfma_f32_16x16x32_bf16 v[96:99], v[172:175], v[188:191], v[96:99]
	v_mfma_f32_16x16x32_bf16 v[84:87], v[162:165], v[196:199], v[84:87]
	v_mfma_f32_16x16x32_bf16 v[80:83], v[172:175], v[196:199], v[80:83]
	v_mfma_f32_16x16x32_bf16 v[68:71], v[162:165], v[204:207], v[68:71]
	v_mfma_f32_16x16x32_bf16 v[64:67], v[172:175], v[204:207], v[64:67]
	v_mfma_f32_16x16x32_bf16 v[116:119], v[168:171], v[184:187], v[116:119]
	v_mfma_f32_16x16x32_bf16 v[112:115], v[176:179], v[184:187], v[112:115]
	v_mfma_f32_16x16x32_bf16 v[100:103], v[168:171], v[192:195], v[100:103]
	v_mfma_f32_16x16x32_bf16 v[96:99], v[176:179], v[192:195], v[96:99]
	v_mfma_f32_16x16x32_bf16 v[84:87], v[168:171], v[200:203], v[84:87]
	v_mfma_f32_16x16x32_bf16 v[80:83], v[176:179], v[200:203], v[80:83]
	v_mfma_f32_16x16x32_bf16 v[68:71], v[168:171], v[212:215], v[68:71]
	v_mfma_f32_16x16x32_bf16 v[64:67], v[176:179], v[212:215], v[64:67]
	s_barrier
	s_add_i32 s42, s42, s10
	v_lshl_add_u64 v[138:139], s[40:41], 0, v[152:153]
	s_mov_b32 m0, s42
	ds_read_b128 v[180:183], v143 offset:16384
	ds_read_b128 v[184:187], v143 offset:17408
	ds_read_b128 v[188:191], v143 offset:18432
	ds_read_b128 v[192:195], v143 offset:19456
	ds_read_b128 v[196:199], v143 offset:20480
	ds_read_b128 v[200:203], v143 offset:21504
	ds_read_b128 v[204:207], v143 offset:22528
	ds_read_b128 v[212:215], v143 offset:23552
	global_load_lds_dwordx4 v[138:139], off
	s_add_i32 m0, s42, 0x2000
	v_lshl_add_u64 v[208:209], s[40:41], 0, v[128:129]
	s_add_u32 s40, s40, s12
	s_addc_u32 s41, s41, s13
	s_add_i32 s39, s39, s10
	global_load_lds_dwordx4 v[208:209], off
	v_lshl_add_u64 v[216:217], s[40:41], 0, v[152:153]
	s_mov_b32 m0, s39
	v_lshl_add_u64 v[230:231], s[40:41], 0, v[128:129]
	global_load_lds_dwordx4 v[216:217], off
	s_add_i32 m0, s39, 0x2000
	v_lshl_add_u64 v[232:233], s[2:3], 0, v[152:153]
	global_load_lds_dwordx4 v[230:231], off
	s_mov_b32 m0, s11
	v_lshl_add_u64 v[234:235], s[2:3], 0, v[128:129]
	global_load_lds_dwordx4 v[232:233], off
	s_mov_b32 m0, s20
	s_nop 0
	global_load_lds_dwordx4 v[234:235], off
	s_waitcnt vmcnt(8)
	s_waitcnt lgkmcnt(0)
	s_barrier
; #define PG8_STAGE(bufoff, gbase, voff) do { _Pragma("unroll") for (int _i = 0; _i < 2; ++_i) \
;         __builtin_amdgcn_global_load_lds((const unsigned*)((const char*)(gbase) + (voff)[_i]), (PG8_LAS unsigned*)(lds + (bufoff) + ldsw + _i * 8192), 16, 0, 0); } while (0)
; #define PG8_LDA(dst, b, h) do { _Pragma("unroll") for (int m = 0; m < 4; ++m) _Pragma("unroll") for (int k = 0; k < 2; ++k) dst[m][k] = *(const PG8_LAS bf16x8*)(lds + PG8_SA(b, h) + aoff + m * 2048 + k * 1024); } while (0)
; #define PG8_LDB(dst, b, h) do { _Pragma("unroll") for (int n = 0; n < 2; ++n) _Pragma("unroll") for (int k = 0; k < 2; ++k) dst[n][k] = *(const PG8_LAS bf16x8*)(lds + PG8_SB(b, h) + boff + n * 2048 + k * 1024); } while (0)
; #define PG8_MMA(ai, bj, At, Bt) do { __builtin_amdgcn_s_setprio(1); _Pragma("unroll") for (int m = 0; m < 4; ++m) _Pragma("unroll") for (int n = 0; n < 2; ++n) _Pragma("unroll") for (int k = 0; k < 2; ++k) \
;         acc[ai][bj][m][n] = __builtin_amdgcn_mfma_f32_16x16x32_bf16(Bt[n][k], At[m][k], acc[ai][bj][m][n], 0, 0, 0); __builtin_amdgcn_s_setprio(0); } while (0)
; #define PG8_WAIT_V(n) asm volatile("s_waitcnt vmcnt(" #n ")" ::: "memory")
; #define PG8_WAIT_L(n) asm volatile("s_waitcnt lgkmcnt(" #n ")" ::: "memory")
; #define PG8_BAR __builtin_amdgcn_s_barrier()
; #define PG8_SCHED __builtin_amdgcn_sched_barrier(0)
; template <class Epi, class Sched, bool ALIGN_EPI = false, bool SP2 = false>
; __device__ __forceinline__ void gemm_phase(PG8_LAS unsigned char* lds, const Gemm g, const Sched& S, const Epi& E) {
;     ...
;             PG8_WAIT_V(8); PG8_WAIT_L(0); PG8_BAR; PG8_MMA(1, 0, At, B0); PG8_MMA(1, 1, At, B1); PG8_BAR; PG8_SCHED;
;             PG8_LDB(B0, 1, 0); PG8_LDB(B1, 1, 1); PG8_SCHED; PG8_LDA(At, 1, 0); PG8_STAGE(PG8_SA(0, 1), a2 + hstep, voffA);
;             PG8_WAIT_V(8); PG8_WAIT_L(0); PG8_BAR; PG8_MMA(0, 0, At, B0); PG8_MMA(0, 1, At, B1); PG8_BAR; PG8_SCHED;
	s_waitcnt lgkmcnt(0)
	v_mfma_f32_16x16x32_bf16 v[60:63], v[134:137], v[180:183], v[60:63]
	v_mfma_f32_16x16x32_bf16 v[56:59], v[148:151], v[180:183], v[56:59]
	v_mfma_f32_16x16x32_bf16 v[44:47], v[134:137], v[188:191], v[44:47]
	v_mfma_f32_16x16x32_bf16 v[40:43], v[148:151], v[188:191], v[40:43]
	v_mfma_f32_16x16x32_bf16 v[28:31], v[134:137], v[196:199], v[28:31]
	v_mfma_f32_16x16x32_bf16 v[24:27], v[148:151], v[196:199], v[24:27]
	v_mfma_f32_16x16x32_bf16 v[12:15], v[134:137], v[204:207], v[12:15]
	v_mfma_f32_16x16x32_bf16 v[8:11], v[148:151], v[204:207], v[8:11]
	v_mfma_f32_16x16x32_bf16 v[60:63], v[144:147], v[184:187], v[60:63]
	v_mfma_f32_16x16x32_bf16 v[56:59], v[158:161], v[184:187], v[56:59]
	v_mfma_f32_16x16x32_bf16 v[44:47], v[144:147], v[192:195], v[44:47]
	v_mfma_f32_16x16x32_bf16 v[40:43], v[158:161], v[192:195], v[40:43]
	v_mfma_f32_16x16x32_bf16 v[28:31], v[144:147], v[200:203], v[28:31]
	v_mfma_f32_16x16x32_bf16 v[24:27], v[158:161], v[200:203], v[24:27]
	v_mfma_f32_16x16x32_bf16 v[12:15], v[144:147], v[212:215], v[12:15]
	v_mfma_f32_16x16x32_bf16 v[8:11], v[158:161], v[212:215], v[8:11]
	v_mfma_f32_16x16x32_bf16 v[52:55], v[162:165], v[180:183], v[52:55]
	v_mfma_f32_16x16x32_bf16 v[48:51], v[172:175], v[180:183], v[48:51]
	v_mfma_f32_16x16x32_bf16 v[36:39], v[162:165], v[188:191], v[36:39]
	v_mfma_f32_16x16x32_bf16 v[32:35], v[172:175], v[188:191], v[32:35]
	v_mfma_f32_16x16x32_bf16 v[20:23], v[162:165], v[196:199], v[20:23]
	v_mfma_f32_16x16x32_bf16 v[16:19], v[172:175], v[196:199], v[16:19]
	v_mfma_f32_16x16x32_bf16 v[4:7], v[162:165], v[204:207], v[4:7]
	v_mfma_f32_16x16x32_bf16 v[0:3], v[172:175], v[204:207], v[0:3]
	v_mfma_f32_16x16x32_bf16 v[52:55], v[168:171], v[184:187], v[52:55]
	v_mfma_f32_16x16x32_bf16 v[48:51], v[176:179], v[184:187], v[48:51]
	v_mfma_f32_16x16x32_bf16 v[36:39], v[168:171], v[192:195], v[36:39]
	v_mfma_f32_16x16x32_bf16 v[32:35], v[176:179], v[192:195], v[32:35]
	v_mfma_f32_16x16x32_bf16 v[20:23], v[168:171], v[200:203], v[20:23]
	v_mfma_f32_16x16x32_bf16 v[16:19], v[176:179], v[200:203], v[16:19]
	v_mfma_f32_16x16x32_bf16 v[4:7], v[168:171], v[212:215], v[4:7]
	v_mfma_f32_16x16x32_bf16 v[0:3], v[176:179], v[212:215], v[0:3]
	s_barrier
	s_add_i32 s39, 0, 0x18000
	s_add_i32 s40, 0, 0x1c000
	v_add_u32_e32 v158, s39, v141
	v_add_u32_e32 v167, s40, v141
	ds_read_b128 v[134:137], v158
	ds_read_b128 v[144:147], v158 offset:1024
	ds_read_b128 v[148:151], v158 offset:2048
	ds_read_b128 v[158:161], v158 offset:3072
	ds_read_b128 v[162:165], v167
	ds_read_b128 v[168:171], v167 offset:1024
	ds_read_b128 v[172:175], v167 offset:2048
	ds_read_b128 v[176:179], v167 offset:3072
	s_add_u32 s2, s2, s12
	s_addc_u32 s3, s3, s13
	s_mov_b32 m0, s21
	v_lshl_add_u64 v[236:237], s[2:3], 0, v[152:153]
	ds_read_b128 v[180:183], v143 offset:32768
	ds_read_b128 v[184:187], v143 offset:33792
	ds_read_b128 v[188:191], v143 offset:34816
	ds_read_b128 v[192:195], v143 offset:35840
	ds_read_b128 v[196:199], v143 offset:36864
	ds_read_b128 v[200:203], v143 offset:37888
	ds_read_b128 v[204:207], v143 offset:38912
	ds_read_b128 v[212:215], v143 offset:39936
	global_load_lds_dwordx4 v[236:237], off
	v_lshl_add_u64 v[236:237], s[2:3], 0, v[128:129]
	s_mov_b32 m0, s22
	s_nop 0
	global_load_lds_dwordx4 v[236:237], off
	s_waitcnt vmcnt(8)
	s_waitcnt lgkmcnt(0)
	s_barrier
	s_waitcnt lgkmcnt(0)
	v_mfma_f32_16x16x32_bf16 v[124:127], v[134:137], v[180:183], v[124:127]
	v_mfma_f32_16x16x32_bf16 v[120:123], v[148:151], v[180:183], v[120:123]
	v_mfma_f32_16x16x32_bf16 v[108:111], v[134:137], v[188:191], v[108:111]
	v_mfma_f32_16x16x32_bf16 v[104:107], v[148:151], v[188:191], v[104:107]
	v_mfma_f32_16x16x32_bf16 v[92:95], v[134:137], v[196:199], v[92:95]
	v_mfma_f32_16x16x32_bf16 v[88:91], v[148:151], v[196:199], v[88:91]
	v_mfma_f32_16x16x32_bf16 v[76:79], v[134:137], v[204:207], v[76:79]
	v_mfma_f32_16x16x32_bf16 v[72:75], v[148:151], v[204:207], v[72:75]
	v_mfma_f32_16x16x32_bf16 v[124:127], v[144:147], v[184:187], v[124:127]
	v_mfma_f32_16x16x32_bf16 v[120:123], v[158:161], v[184:187], v[120:123]
	v_mfma_f32_16x16x32_bf16 v[108:111], v[144:147], v[192:195], v[108:111]
	v_mfma_f32_16x16x32_bf16 v[104:107], v[158:161], v[192:195], v[104:107]
	v_mfma_f32_16x16x32_bf16 v[92:95], v[144:147], v[200:203], v[92:95]
	v_mfma_f32_16x16x32_bf16 v[88:91], v[158:161], v[200:203], v[88:91]
	v_mfma_f32_16x16x32_bf16 v[76:79], v[144:147], v[212:215], v[76:79]
	v_mfma_f32_16x16x32_bf16 v[72:75], v[158:161], v[212:215], v[72:75]
	v_mfma_f32_16x16x32_bf16 v[116:119], v[162:165], v[180:183], v[116:119]
	v_mfma_f32_16x16x32_bf16 v[112:115], v[172:175], v[180:183], v[112:115]
	v_mfma_f32_16x16x32_bf16 v[100:103], v[162:165], v[188:191], v[100:103]
	v_mfma_f32_16x16x32_bf16 v[96:99], v[172:175], v[188:191], v[96:99]
	v_mfma_f32_16x16x32_bf16 v[84:87], v[162:165], v[196:199], v[84:87]
	v_mfma_f32_16x16x32_bf16 v[80:83], v[172:175], v[196:199], v[80:83]
	v_mfma_f32_16x16x32_bf16 v[68:71], v[162:165], v[204:207], v[68:71]
	v_mfma_f32_16x16x32_bf16 v[64:67], v[172:175], v[204:207], v[64:67]
	v_mfma_f32_16x16x32_bf16 v[116:119], v[168:171], v[184:187], v[116:119]
	v_mfma_f32_16x16x32_bf16 v[112:115], v[176:179], v[184:187], v[112:115]
	v_mfma_f32_16x16x32_bf16 v[100:103], v[168:171], v[192:195], v[100:103]
	v_mfma_f32_16x16x32_bf16 v[96:99], v[176:179], v[192:195], v[96:99]
	v_mfma_f32_16x16x32_bf16 v[84:87], v[168:171], v[200:203], v[84:87]
	v_mfma_f32_16x16x32_bf16 v[80:83], v[176:179], v[200:203], v[80:83]
	v_mfma_f32_16x16x32_bf16 v[68:71], v[168:171], v[212:215], v[68:71]
	v_mfma_f32_16x16x32_bf16 v[64:67], v[176:179], v[212:215], v[64:67]
	s_barrier
; #define PG8_STAGE(bufoff, gbase, voff) do { _Pragma("unroll") for (int _i = 0; _i < 2; ++_i) \
;         __builtin_amdgcn_global_load_lds((const unsigned*)((const char*)(gbase) + (voff)[_i]), (PG8_LAS unsigned*)(lds + (bufoff) + ldsw + _i * 8192), 16, 0, 0); } while (0)
; #define PG8_LDA(dst, b, h) do { _Pragma("unroll") for (int m = 0; m < 4; ++m) _Pragma("unroll") for (int k = 0; k < 2; ++k) dst[m][k] = *(const PG8_LAS bf16x8*)(lds + PG8_SA(b, h) + aoff + m * 2048 + k * 1024); } while (0)
; #define PG8_MMA(ai, bj, At, Bt) do { __builtin_amdgcn_s_setprio(1); _Pragma("unroll") for (int m = 0; m < 4; ++m) _Pragma("unroll") for (int n = 0; n < 2; ++n) _Pragma("unroll") for (int k = 0; k < 2; ++k) \
;         acc[ai][bj][m][n] = __builtin_amdgcn_mfma_f32_16x16x32_bf16(Bt[n][k], At[m][k], acc[ai][bj][m][n], 0, 0, 0); __builtin_amdgcn_s_setprio(0); } while (0)
; #define PG8_WAIT_V(n) asm volatile("s_waitcnt vmcnt(" #n ")" ::: "memory")
; #define PG8_WAIT_L(n) asm volatile("s_waitcnt lgkmcnt(" #n ")" ::: "memory")
; #define PG8_BAR __builtin_amdgcn_s_barrier()
; #define PG8_SCHED __builtin_amdgcn_sched_barrier(0)
; template <class Epi, class Sched, bool ALIGN_EPI = false, bool SP2 = false>
; __device__ __forceinline__ void gemm_phase(PG8_LAS unsigned char* lds, const Gemm g, const Sched& S, const Epi& E) {
;     ...
;         for (int t = 0; t < nt; t += 2) {
;     ...
;             PG8_LDA(At, 1, 1); PG8_STAGE(PG8_SB(1, 0), b3, voffB); PG8_STAGE(PG8_SB(1, 1), b3 + hstep, voffB); PG8_STAGE(PG8_SA(1, 0), a3, voffA);
;             PG8_WAIT_V(8); PG8_WAIT_L(0); PG8_BAR; PG8_MMA(1, 0, At, B0); PG8_MMA(1, 1, At, B1); PG8_BAR; PG8_SCHED;
	s_add_i32 s2, s39, s10
	v_lshl_add_u64 v[138:139], v[138:139], 0, s[82:83]
	s_mov_b32 m0, s2
	ds_read_b128 v[180:183], v143 offset:49152
	ds_read_b128 v[184:187], v143 offset:50176
	ds_read_b128 v[188:191], v143 offset:51200
	ds_read_b128 v[192:195], v143 offset:52224
	ds_read_b128 v[196:199], v143 offset:53248
	ds_read_b128 v[200:203], v143 offset:54272
	ds_read_b128 v[204:207], v143 offset:55296
	ds_read_b128 v[212:215], v143 offset:56320
	global_load_lds_dwordx4 v[138:139], off
	v_lshl_add_u64 v[138:139], v[208:209], 0, s[82:83]
	s_add_i32 m0, s2, 0x2000
	s_add_i32 s2, s40, s10
	global_load_lds_dwordx4 v[138:139], off
	v_lshl_add_u64 v[138:139], v[216:217], 0, s[82:83]
	s_mov_b32 m0, s2
	s_nop 0
	global_load_lds_dwordx4 v[138:139], off
	v_lshl_add_u64 v[138:139], v[230:231], 0, s[82:83]
	s_add_i32 m0, s2, 0x2000
	s_nop 0
	global_load_lds_dwordx4 v[138:139], off
	v_lshl_add_u64 v[138:139], v[232:233], 0, s[82:83]
	s_mov_b32 m0, s23
	s_nop 0
	global_load_lds_dwordx4 v[138:139], off
	v_lshl_add_u64 v[138:139], v[234:235], 0, s[82:83]
	s_mov_b32 m0, s24
	s_nop 0
	global_load_lds_dwordx4 v[138:139], off
	s_waitcnt vmcnt(8)
	s_waitcnt lgkmcnt(0)
	s_barrier
	s_waitcnt lgkmcnt(0)
	v_mfma_f32_16x16x32_bf16 v[60:63], v[134:137], v[180:183], v[60:63]
	v_mfma_f32_16x16x32_bf16 v[56:59], v[148:151], v[180:183], v[56:59]
	v_mfma_f32_16x16x32_bf16 v[44:47], v[134:137], v[188:191], v[44:47]
	v_mfma_f32_16x16x32_bf16 v[40:43], v[148:151], v[188:191], v[40:43]
	v_mfma_f32_16x16x32_bf16 v[28:31], v[134:137], v[196:199], v[28:31]
	v_mfma_f32_16x16x32_bf16 v[24:27], v[148:151], v[196:199], v[24:27]
	v_mfma_f32_16x16x32_bf16 v[12:15], v[134:137], v[204:207], v[12:15]
	v_mfma_f32_16x16x32_bf16 v[8:11], v[148:151], v[204:207], v[8:11]
	v_mfma_f32_16x16x32_bf16 v[60:63], v[144:147], v[184:187], v[60:63]
	v_mfma_f32_16x16x32_bf16 v[56:59], v[158:161], v[184:187], v[56:59]
	v_mfma_f32_16x16x32_bf16 v[44:47], v[144:147], v[192:195], v[44:47]
	v_mfma_f32_16x16x32_bf16 v[40:43], v[158:161], v[192:195], v[40:43]
	v_mfma_f32_16x16x32_bf16 v[28:31], v[144:147], v[200:203], v[28:31]
	v_mfma_f32_16x16x32_bf16 v[24:27], v[158:161], v[200:203], v[24:27]
	v_mfma_f32_16x16x32_bf16 v[12:15], v[144:147], v[212:215], v[12:15]
	v_mfma_f32_16x16x32_bf16 v[8:11], v[158:161], v[212:215], v[8:11]
	v_mfma_f32_16x16x32_bf16 v[52:55], v[162:165], v[180:183], v[52:55]
	v_mfma_f32_16x16x32_bf16 v[48:51], v[172:175], v[180:183], v[48:51]
	v_mfma_f32_16x16x32_bf16 v[36:39], v[162:165], v[188:191], v[36:39]
	v_mfma_f32_16x16x32_bf16 v[32:35], v[172:175], v[188:191], v[32:35]
	v_mfma_f32_16x16x32_bf16 v[20:23], v[162:165], v[196:199], v[20:23]
	v_mfma_f32_16x16x32_bf16 v[16:19], v[172:175], v[196:199], v[16:19]
	v_mfma_f32_16x16x32_bf16 v[4:7], v[162:165], v[204:207], v[4:7]
	v_mfma_f32_16x16x32_bf16 v[0:3], v[172:175], v[204:207], v[0:3]
	v_mfma_f32_16x16x32_bf16 v[52:55], v[168:171], v[184:187], v[52:55]
	v_mfma_f32_16x16x32_bf16 v[48:51], v[176:179], v[184:187], v[48:51]
	v_mfma_f32_16x16x32_bf16 v[36:39], v[168:171], v[192:195], v[36:39]
	v_mfma_f32_16x16x32_bf16 v[32:35], v[176:179], v[192:195], v[32:35]
	v_mfma_f32_16x16x32_bf16 v[20:23], v[168:171], v[200:203], v[20:23]
	v_mfma_f32_16x16x32_bf16 v[16:19], v[176:179], v[200:203], v[16:19]
	v_mfma_f32_16x16x32_bf16 v[4:7], v[168:171], v[212:215], v[4:7]
	v_mfma_f32_16x16x32_bf16 v[0:3], v[176:179], v[212:215], v[0:3]
	s_barrier
	s_add_u32 s0, s0, 0x100
	s_addc_u32 s1, s1, 0
	s_add_u32 s36, s36, 0x100
	s_addc_u32 s37, s37, 0
	s_cmp_ge_i32 s38, s25
	s_mov_b32 s2, s38
	s_cbranch_scc0 .LBB0_158
	s_setprio 0

; template <class Epi, class Sched, bool ALIGN_EPI = false, bool SP2 = false>
; __device__ __forceinline__ void gemm_phase(PG8_LAS unsigned char* lds, const Gemm g, const Sched& S, const Epi& E) {
;     ...
;     f32x4 acc[2][2][4][2];
; #pragma unroll
;     for (int a = 0; a < 2; ++a)
; #pragma unroll
;         for (int b = 0; b < 2; ++b)
; #pragma unroll
;             for (int m = 0; m < 4; ++m)
; #pragma unroll
;                 for (int n = 0; n < 2; ++n) acc[a][b][m][n] = (f32x4){0.f, 0.f, 0.f, 0.f};
;     ...
;     for (;;) {
;         const bool has_next = S.next(ui + 1, nxt);
;         const char* nA = has_next ? (const char*)g.A + (size_t)nxt.pm * tstep : cA; const char* nB = has_next ? (const char*)g.Bt + (size_t)nxt.pn * tstep : cB;
;         for (int t = 0; t < nt; t += 2) {
.LBB0_192:
	v_mov_b32_e32 v123, 0
	s_andn2_b64 vcc, exec, s[18:19]
	v_mov_b32_e32 v122, v123
	v_mov_b32_e32 v121, v123
	v_mov_b32_e32 v120, v123
	v_mov_b32_e32 v127, v123
	v_mov_b32_e32 v126, v123
	v_mov_b32_e32 v125, v123
	v_mov_b32_e32 v124, v123
	v_mov_b32_e32 v111, v123
	v_mov_b32_e32 v110, v123
	v_mov_b32_e32 v109, v123
	v_mov_b32_e32 v108, v123
	v_mov_b32_e32 v107, v123
	v_mov_b32_e32 v106, v123
	v_mov_b32_e32 v105, v123
	v_mov_b32_e32 v104, v123
	v_mov_b32_e32 v95, v123
	v_mov_b32_e32 v94, v123
	v_mov_b32_e32 v93, v123
	v_mov_b32_e32 v92, v123
	v_mov_b32_e32 v91, v123
	v_mov_b32_e32 v90, v123
	v_mov_b32_e32 v89, v123
	v_mov_b32_e32 v88, v123
	v_mov_b32_e32 v79, v123
	v_mov_b32_e32 v78, v123
	v_mov_b32_e32 v77, v123
	v_mov_b32_e32 v76, v123
	v_mov_b32_e32 v75, v123
	v_mov_b32_e32 v74, v123
	v_mov_b32_e32 v73, v123
	v_mov_b32_e32 v72, v123
	v_mov_b32_e32 v119, v123
	v_mov_b32_e32 v118, v123
	v_mov_b32_e32 v117, v123
	v_mov_b32_e32 v116, v123
	v_mov_b32_e32 v115, v123
	v_mov_b32_e32 v114, v123
	v_mov_b32_e32 v113, v123
	v_mov_b32_e32 v112, v123
	v_mov_b32_e32 v103, v123
	v_mov_b32_e32 v102, v123
	v_mov_b32_e32 v101, v123
	v_mov_b32_e32 v100, v123
	v_mov_b32_e32 v99, v123
	v_mov_b32_e32 v98, v123
	v_mov_b32_e32 v97, v123
	v_mov_b32_e32 v96, v123
	v_mov_b32_e32 v87, v123
	v_mov_b32_e32 v86, v123
	v_mov_b32_e32 v85, v123
	v_mov_b32_e32 v84, v123
	v_mov_b32_e32 v83, v123
	v_mov_b32_e32 v82, v123
	v_mov_b32_e32 v81, v123
	v_mov_b32_e32 v80, v123
	v_mov_b32_e32 v71, v123
	v_mov_b32_e32 v70, v123
	v_mov_b32_e32 v69, v123
	v_mov_b32_e32 v68, v123
	v_mov_b32_e32 v67, v123
	v_mov_b32_e32 v66, v123
	v_mov_b32_e32 v65, v123
	v_mov_b32_e32 v64, v123
	v_mov_b32_e32 v63, v123
	v_mov_b32_e32 v62, v123
	v_mov_b32_e32 v61, v123
	v_mov_b32_e32 v60, v123
	v_mov_b32_e32 v59, v123
	v_mov_b32_e32 v58, v123
	v_mov_b32_e32 v57, v123
	v_mov_b32_e32 v56, v123
	v_mov_b32_e32 v47, v123
	v_mov_b32_e32 v46, v123
	v_mov_b32_e32 v45, v123
	v_mov_b32_e32 v44, v123
	v_mov_b32_e32 v43, v123
	v_mov_b32_e32 v42, v123
	v_mov_b32_e32 v41, v123
	v_mov_b32_e32 v40, v123
	v_mov_b32_e32 v31, v123
	v_mov_b32_e32 v30, v123
	v_mov_b32_e32 v29, v123
	v_mov_b32_e32 v28, v123
	v_mov_b32_e32 v27, v123
	v_mov_b32_e32 v26, v123
	v_mov_b32_e32 v25, v123
	v_mov_b32_e32 v24, v123
	v_mov_b32_e32 v15, v123
	v_mov_b32_e32 v14, v123
	v_mov_b32_e32 v13, v123
	v_mov_b32_e32 v12, v123
	v_mov_b32_e32 v11, v123
	v_mov_b32_e32 v10, v123
	v_mov_b32_e32 v9, v123
	v_mov_b32_e32 v8, v123
	v_mov_b32_e32 v55, v123
	v_mov_b32_e32 v54, v123
	v_mov_b32_e32 v53, v123
	v_mov_b32_e32 v52, v123
	v_mov_b32_e32 v51, v123
	v_mov_b32_e32 v50, v123
	v_mov_b32_e32 v49, v123
	v_mov_b32_e32 v48, v123
	v_mov_b32_e32 v39, v123
	v_mov_b32_e32 v38, v123
	v_mov_b32_e32 v37, v123
	v_mov_b32_e32 v36, v123
	v_mov_b32_e32 v35, v123
	v_mov_b32_e32 v34, v123
	v_mov_b32_e32 v33, v123
	v_mov_b32_e32 v32, v123
	v_mov_b32_e32 v23, v123
	v_mov_b32_e32 v22, v123
	v_mov_b32_e32 v21, v123
	v_mov_b32_e32 v20, v123
	v_mov_b32_e32 v19, v123
	v_mov_b32_e32 v18, v123
	v_mov_b32_e32 v17, v123
	v_mov_b32_e32 v16, v123
	v_mov_b32_e32 v7, v123
	v_mov_b32_e32 v6, v123
	v_mov_b32_e32 v5, v123
	v_mov_b32_e32 v4, v123
	v_mov_b32_e32 v3, v123
	v_mov_b32_e32 v2, v123
	v_mov_b32_e32 v1, v123
	v_mov_b32_e32 v0, v123
	s_cbranch_vccnz .LBB0_195
	s_add_u32 s6, s20, 0x80
	s_addc_u32 s7, s21, 0
	s_add_u32 s20, s8, 0x100
	v_mov_b32_e32 v0, 0
	s_addc_u32 s21, s9, 0
	s_mov_b32 s8, 0
	v_mov_b32_e32 v1, v0
	v_mov_b32_e32 v2, v0
	v_mov_b32_e32 v3, v0
	v_mov_b32_e32 v4, v0
	v_mov_b32_e32 v5, v0
	v_mov_b32_e32 v6, v0
	v_mov_b32_e32 v7, v0
	v_mov_b32_e32 v16, v0
	v_mov_b32_e32 v17, v0
	v_mov_b32_e32 v18, v0
	v_mov_b32_e32 v19, v0
	v_mov_b32_e32 v20, v0
	v_mov_b32_e32 v21, v0
	v_mov_b32_e32 v22, v0
	v_mov_b32_e32 v23, v0
	v_mov_b32_e32 v32, v0
	v_mov_b32_e32 v33, v0
	v_mov_b32_e32 v34, v0
	v_mov_b32_e32 v35, v0
	v_mov_b32_e32 v36, v0
	v_mov_b32_e32 v37, v0
	v_mov_b32_e32 v38, v0
	v_mov_b32_e32 v39, v0
	v_mov_b32_e32 v48, v0
	v_mov_b32_e32 v49, v0
	v_mov_b32_e32 v50, v0
	v_mov_b32_e32 v51, v0
	v_mov_b32_e32 v52, v0
	v_mov_b32_e32 v53, v0
	v_mov_b32_e32 v54, v0
	v_mov_b32_e32 v55, v0
	v_mov_b32_e32 v8, v0
	v_mov_b32_e32 v9, v0
	v_mov_b32_e32 v10, v0
	v_mov_b32_e32 v11, v0
	v_mov_b32_e32 v12, v0
	v_mov_b32_e32 v13, v0
	v_mov_b32_e32 v14, v0
	v_mov_b32_e32 v15, v0
	v_mov_b32_e32 v24, v0
	v_mov_b32_e32 v25, v0
	v_mov_b32_e32 v26, v0
	v_mov_b32_e32 v27, v0
	v_mov_b32_e32 v28, v0
	v_mov_b32_e32 v29, v0
	v_mov_b32_e32 v30, v0
	v_mov_b32_e32 v31, v0
	v_mov_b32_e32 v40, v0
	v_mov_b32_e32 v41, v0
	v_mov_b32_e32 v42, v0
	v_mov_b32_e32 v43, v0
	v_mov_b32_e32 v44, v0
	v_mov_b32_e32 v45, v0
	v_mov_b32_e32 v46, v0
	v_mov_b32_e32 v47, v0
	v_mov_b32_e32 v56, v0
	v_mov_b32_e32 v57, v0
	v_mov_b32_e32 v58, v0
	v_mov_b32_e32 v59, v0
	v_mov_b32_e32 v60, v0
	v_mov_b32_e32 v61, v0
	v_mov_b32_e32 v62, v0
	v_mov_b32_e32 v63, v0
	v_mov_b32_e32 v64, v0
	v_mov_b32_e32 v65, v0
	v_mov_b32_e32 v66, v0
	v_mov_b32_e32 v67, v0
	v_mov_b32_e32 v68, v0
	v_mov_b32_e32 v69, v0
	v_mov_b32_e32 v70, v0
	v_mov_b32_e32 v71, v0
	v_mov_b32_e32 v80, v0
	v_mov_b32_e32 v81, v0
	v_mov_b32_e32 v82, v0
	v_mov_b32_e32 v83, v0
	v_mov_b32_e32 v84, v0
	v_mov_b32_e32 v85, v0
	v_mov_b32_e32 v86, v0
	v_mov_b32_e32 v87, v0
	v_mov_b32_e32 v96, v0
	v_mov_b32_e32 v97, v0
	v_mov_b32_e32 v98, v0
	v_mov_b32_e32 v99, v0
	v_mov_b32_e32 v100, v0
	v_mov_b32_e32 v101, v0
	v_mov_b32_e32 v102, v0
	v_mov_b32_e32 v103, v0
	v_mov_b32_e32 v112, v0
	v_mov_b32_e32 v113, v0
	v_mov_b32_e32 v114, v0
	v_mov_b32_e32 v115, v0
	v_mov_b32_e32 v116, v0
	v_mov_b32_e32 v117, v0
	v_mov_b32_e32 v118, v0
	v_mov_b32_e32 v119, v0
	v_mov_b32_e32 v72, v0
	v_mov_b32_e32 v73, v0
	v_mov_b32_e32 v74, v0
	v_mov_b32_e32 v75, v0
	v_mov_b32_e32 v76, v0
	v_mov_b32_e32 v77, v0
	v_mov_b32_e32 v78, v0
	v_mov_b32_e32 v79, v0
	v_mov_b32_e32 v88, v0
	v_mov_b32_e32 v89, v0
	v_mov_b32_e32 v90, v0
	v_mov_b32_e32 v91, v0
	v_mov_b32_e32 v92, v0
	v_mov_b32_e32 v93, v0
	v_mov_b32_e32 v94, v0
	v_mov_b32_e32 v95, v0
	v_mov_b32_e32 v104, v0
	v_mov_b32_e32 v105, v0
	v_mov_b32_e32 v106, v0
	v_mov_b32_e32 v107, v0
	v_mov_b32_e32 v108, v0
	v_mov_b32_e32 v109, v0
	v_mov_b32_e32 v110, v0
	v_mov_b32_e32 v111, v0
	v_mov_b32_e32 v124, v0
	v_mov_b32_e32 v125, v0
	v_mov_b32_e32 v126, v0
	v_mov_b32_e32 v127, v0
	v_mov_b32_e32 v120, v0
	v_mov_b32_e32 v121, v0
	v_mov_b32_e32 v122, v0
	v_mov_b32_e32 v123, v0
	v_readfirstlane_b32 s100, v211
	s_cmp_ge_u32 s100, 0x100
	s_cbranch_scc0 .Lprio_skip10
	s_setprio 1
; #define PG8_STAGE(bufoff, gbase, voff) do { _Pragma("unroll") for (int _i = 0; _i < 2; ++_i) \
;         __builtin_amdgcn_global_load_lds((const unsigned*)((const char*)(gbase) + (voff)[_i]), (PG8_LAS unsigned*)(lds + (bufoff) + ldsw + _i * 8192), 16, 0, 0); } while (0)
; #define PG8_LDA(dst, b, h) do { _Pragma("unroll") for (int m = 0; m < 4; ++m) _Pragma("unroll") for (int k = 0; k < 2; ++k) dst[m][k] = *(const PG8_LAS bf16x8*)(lds + PG8_SA(b, h) + aoff + m * 2048 + k * 1024); } while (0)
; #define PG8_LDB(dst, b, h) do { _Pragma("unroll") for (int n = 0; n < 2; ++n) _Pragma("unroll") for (int k = 0; k < 2; ++k) dst[n][k] = *(const PG8_LAS bf16x8*)(lds + PG8_SB(b, h) + boff + n * 2048 + k * 1024); } while (0)
; #define PG8_MMA(ai, bj, At, Bt) do { __builtin_amdgcn_s_setprio(1); _Pragma("unroll") for (int m = 0; m < 4; ++m) _Pragma("unroll") for (int n = 0; n < 2; ++n) _Pragma("unroll") for (int k = 0; k < 2; ++k) \
;         acc[ai][bj][m][n] = __builtin_amdgcn_mfma_f32_16x16x32_bf16(Bt[n][k], At[m][k], acc[ai][bj][m][n], 0, 0, 0); __builtin_amdgcn_s_setprio(0); } while (0)
; #define PG8_WAIT_V(n) asm volatile("s_waitcnt vmcnt(" #n ")" ::: "memory")
; #define PG8_WAIT_L(n) asm volatile("s_waitcnt lgkmcnt(" #n ")" ::: "memory")
; #define PG8_BAR __builtin_amdgcn_s_barrier()
; #define PG8_SCHED __builtin_amdgcn_sched_barrier(0)
; template <class Epi, class Sched, bool ALIGN_EPI = false, bool SP2 = false>
; __device__ __forceinline__ void gemm_phase(PG8_LAS unsigned char* lds, const Gemm g, const Sched& S, const Epi& E) {
;     ...
;             PG8_LDB(B0, 0, 0); PG8_LDB(B1, 0, 1); PG8_SCHED; PG8_LDA(At, 0, 0); PG8_STAGE(PG8_SA(1, 1), a1 + hstep, voffA);
;             PG8_WAIT_V(8); PG8_WAIT_L(0); PG8_BAR; PG8_MMA(0, 0, At, B0); PG8_MMA(0, 1, At, B1); PG8_BAR; PG8_SCHED;
;             PG8_LDA(At, 0, 1); PG8_STAGE(PG8_SB(0, 0), b2, voffB); PG8_STAGE(PG8_SB(0, 1), b2 + hstep, voffB); PG8_STAGE(PG8_SA(0, 0), a2, voffA);
.Lprio_skip10:
.LBB0_194:
	s_add_i32 s42, s8, 2
	s_add_u32 s43, s6, 0x80
	s_addc_u32 s9, s7, 0
	s_add_i32 s46, 0, 0x10000
	s_cmp_eq_u32 s36, s8
	s_cselect_b32 s9, s1, s9
	s_cselect_b32 s8, s0, s43
	v_add_u32_e32 v150, s46, v139
	s_cselect_b32 s45, s3, s21
	s_cselect_b32 s44, s2, s20
	s_add_i32 s43, 0, 0x14000
	ds_read_b128 v[142:145], v150
	ds_read_b128 v[146:149], v150 offset:1024
	ds_read_b128 v[158:161], v150 offset:2048
	ds_read_b128 v[162:165], v150 offset:3072
	v_add_u32_e32 v150, s43, v139
	ds_read_b128 v[168:171], v150
	ds_read_b128 v[172:175], v150 offset:1024
	ds_read_b128 v[176:179], v150 offset:2048
	ds_read_b128 v[180:183], v150 offset:3072
	v_lshl_add_u64 v[150:151], s[6:7], 0, v[134:135]
	s_add_i32 m0, s25, 0xc000
	ds_read_b128 v[184:187], v141
	ds_read_b128 v[188:191], v141 offset:1024
	ds_read_b128 v[192:195], v141 offset:2048
	ds_read_b128 v[196:199], v141 offset:3072
	ds_read_b128 v[200:203], v141 offset:4096
	ds_read_b128 v[204:207], v141 offset:5120
	ds_read_b128 v[212:215], v141 offset:6144
	ds_read_b128 v[230:233], v141 offset:7168
	global_load_lds_dwordx4 v[150:151], off
	v_lshl_add_u64 v[150:151], s[6:7], 0, v[136:137]
	s_add_i32 m0, s25, 0xe000
	s_nop 0
	global_load_lds_dwordx4 v[150:151], off
	s_waitcnt vmcnt(8)
	s_waitcnt lgkmcnt(0)
	s_barrier
	s_waitcnt lgkmcnt(0)
	v_mfma_f32_16x16x32_bf16 v[120:123], v[142:145], v[184:187], v[120:123]
	v_mfma_f32_16x16x32_bf16 v[124:127], v[158:161], v[184:187], v[124:127]
	v_mfma_f32_16x16x32_bf16 v[108:111], v[142:145], v[192:195], v[108:111]
	v_mfma_f32_16x16x32_bf16 v[104:107], v[158:161], v[192:195], v[104:107]
	v_mfma_f32_16x16x32_bf16 v[92:95], v[142:145], v[200:203], v[92:95]
	v_mfma_f32_16x16x32_bf16 v[88:91], v[158:161], v[200:203], v[88:91]
	v_mfma_f32_16x16x32_bf16 v[76:79], v[142:145], v[212:215], v[76:79]
	v_mfma_f32_16x16x32_bf16 v[72:75], v[158:161], v[212:215], v[72:75]
	v_mfma_f32_16x16x32_bf16 v[120:123], v[146:149], v[188:191], v[120:123]
	v_mfma_f32_16x16x32_bf16 v[124:127], v[162:165], v[188:191], v[124:127]
	v_mfma_f32_16x16x32_bf16 v[108:111], v[146:149], v[196:199], v[108:111]
	v_mfma_f32_16x16x32_bf16 v[104:107], v[162:165], v[196:199], v[104:107]
	v_mfma_f32_16x16x32_bf16 v[92:95], v[146:149], v[204:207], v[92:95]
	v_mfma_f32_16x16x32_bf16 v[88:91], v[162:165], v[204:207], v[88:91]
	v_mfma_f32_16x16x32_bf16 v[76:79], v[146:149], v[230:233], v[76:79]
	v_mfma_f32_16x16x32_bf16 v[72:75], v[162:165], v[230:233], v[72:75]
	v_mfma_f32_16x16x32_bf16 v[116:119], v[168:171], v[184:187], v[116:119]
	v_mfma_f32_16x16x32_bf16 v[112:115], v[176:179], v[184:187], v[112:115]
	v_mfma_f32_16x16x32_bf16 v[100:103], v[168:171], v[192:195], v[100:103]
	v_mfma_f32_16x16x32_bf16 v[96:99], v[176:179], v[192:195], v[96:99]
	v_mfma_f32_16x16x32_bf16 v[84:87], v[168:171], v[200:203], v[84:87]
	v_mfma_f32_16x16x32_bf16 v[80:83], v[176:179], v[200:203], v[80:83]
	v_mfma_f32_16x16x32_bf16 v[68:71], v[168:171], v[212:215], v[68:71]
	v_mfma_f32_16x16x32_bf16 v[64:67], v[176:179], v[212:215], v[64:67]
	v_mfma_f32_16x16x32_bf16 v[116:119], v[172:175], v[188:191], v[116:119]
	v_mfma_f32_16x16x32_bf16 v[112:115], v[180:183], v[188:191], v[112:115]
	v_mfma_f32_16x16x32_bf16 v[100:103], v[172:175], v[196:199], v[100:103]
	v_mfma_f32_16x16x32_bf16 v[96:99], v[180:183], v[196:199], v[96:99]
	v_mfma_f32_16x16x32_bf16 v[84:87], v[172:175], v[204:207], v[84:87]
	v_mfma_f32_16x16x32_bf16 v[80:83], v[180:183], v[204:207], v[80:83]
	v_mfma_f32_16x16x32_bf16 v[68:71], v[172:175], v[230:233], v[68:71]
	v_mfma_f32_16x16x32_bf16 v[64:67], v[180:183], v[230:233], v[64:67]
	s_barrier
	s_add_i32 s46, s46, s24
	v_lshl_add_u64 v[150:151], s[44:45], 0, v[152:153]
	s_mov_b32 m0, s46
	ds_read_b128 v[184:187], v141 offset:16384
	ds_read_b128 v[188:191], v141 offset:17408
	ds_read_b128 v[192:195], v141 offset:18432
	ds_read_b128 v[196:199], v141 offset:19456
	ds_read_b128 v[200:203], v141 offset:20480
	ds_read_b128 v[204:207], v141 offset:21504
	ds_read_b128 v[212:215], v141 offset:22528
	ds_read_b128 v[230:233], v141 offset:23552
	global_load_lds_dwordx4 v[150:151], off
	s_add_i32 m0, s46, 0x2000
	v_lshl_add_u64 v[208:209], s[44:45], 0, v[128:129]
	s_add_u32 s44, s44, s12
	s_addc_u32 s45, s45, s13
	s_add_i32 s43, s43, s24
	global_load_lds_dwordx4 v[208:209], off
	v_lshl_add_u64 v[216:217], s[44:45], 0, v[152:153]
	s_mov_b32 m0, s43
	v_lshl_add_u64 v[234:235], s[44:45], 0, v[128:129]
	global_load_lds_dwordx4 v[216:217], off
	s_add_i32 m0, s43, 0x2000
	v_lshl_add_u64 v[236:237], s[8:9], 0, v[132:133]
	global_load_lds_dwordx4 v[234:235], off
	s_mov_b32 m0, s25
	v_lshl_add_u64 v[238:239], s[8:9], 0, v[130:131]
	global_load_lds_dwordx4 v[236:237], off
	s_mov_b32 m0, s28
	s_nop 0
	global_load_lds_dwordx4 v[238:239], off
	s_waitcnt vmcnt(8)
	s_waitcnt lgkmcnt(0)
	s_barrier
; #define PG8_STAGE(bufoff, gbase, voff) do { _Pragma("unroll") for (int _i = 0; _i < 2; ++_i) \
;         __builtin_amdgcn_global_load_lds((const unsigned*)((const char*)(gbase) + (voff)[_i]), (PG8_LAS unsigned*)(lds + (bufoff) + ldsw + _i * 8192), 16, 0, 0); } while (0)
; #define PG8_LDA(dst, b, h) do { _Pragma("unroll") for (int m = 0; m < 4; ++m) _Pragma("unroll") for (int k = 0; k < 2; ++k) dst[m][k] = *(const PG8_LAS bf16x8*)(lds + PG8_SA(b, h) + aoff + m * 2048 + k * 1024); } while (0)
; #define PG8_LDB(dst, b, h) do { _Pragma("unroll") for (int n = 0; n < 2; ++n) _Pragma("unroll") for (int k = 0; k < 2; ++k) dst[n][k] = *(const PG8_LAS bf16x8*)(lds + PG8_SB(b, h) + boff + n * 2048 + k * 1024); } while (0)
; #define PG8_MMA(ai, bj, At, Bt) do { __builtin_amdgcn_s_setprio(1); _Pragma("unroll") for (int m = 0; m < 4; ++m) _Pragma("unroll") for (int n = 0; n < 2; ++n) _Pragma("unroll") for (int k = 0; k < 2; ++k) \
;         acc[ai][bj][m][n] = __builtin_amdgcn_mfma_f32_16x16x32_bf16(Bt[n][k], At[m][k], acc[ai][bj][m][n], 0, 0, 0); __builtin_amdgcn_s_setprio(0); } while (0)
; #define PG8_WAIT_V(n) asm volatile("s_waitcnt vmcnt(" #n ")" ::: "memory")
; #define PG8_WAIT_L(n) asm volatile("s_waitcnt lgkmcnt(" #n ")" ::: "memory")
; #define PG8_BAR __builtin_amdgcn_s_barrier()
; #define PG8_SCHED __builtin_amdgcn_sched_barrier(0)
; template <class Epi, class Sched, bool ALIGN_EPI = false, bool SP2 = false>
; __device__ __forceinline__ void gemm_phase(PG8_LAS unsigned char* lds, const Gemm g, const Sched& S, const Epi& E) {
;     ...
;             PG8_WAIT_V(8); PG8_WAIT_L(0); PG8_BAR; PG8_MMA(1, 0, At, B0); PG8_MMA(1, 1, At, B1); PG8_BAR; PG8_SCHED;
;             PG8_LDB(B0, 1, 0); PG8_LDB(B1, 1, 1); PG8_SCHED; PG8_LDA(At, 1, 0); PG8_STAGE(PG8_SA(0, 1), a2 + hstep, voffA);
;             PG8_WAIT_V(8); PG8_WAIT_L(0); PG8_BAR; PG8_MMA(0, 0, At, B0); PG8_MMA(0, 1, At, B1); PG8_BAR; PG8_SCHED;
	s_waitcnt lgkmcnt(0)
	v_mfma_f32_16x16x32_bf16 v[60:63], v[142:145], v[184:187], v[60:63]
	v_mfma_f32_16x16x32_bf16 v[56:59], v[158:161], v[184:187], v[56:59]
	v_mfma_f32_16x16x32_bf16 v[44:47], v[142:145], v[192:195], v[44:47]
	v_mfma_f32_16x16x32_bf16 v[40:43], v[158:161], v[192:195], v[40:43]
	v_mfma_f32_16x16x32_bf16 v[28:31], v[142:145], v[200:203], v[28:31]
	v_mfma_f32_16x16x32_bf16 v[24:27], v[158:161], v[200:203], v[24:27]
	v_mfma_f32_16x16x32_bf16 v[12:15], v[142:145], v[212:215], v[12:15]
	v_mfma_f32_16x16x32_bf16 v[8:11], v[158:161], v[212:215], v[8:11]
	v_mfma_f32_16x16x32_bf16 v[60:63], v[146:149], v[188:191], v[60:63]
	v_mfma_f32_16x16x32_bf16 v[56:59], v[162:165], v[188:191], v[56:59]
	v_mfma_f32_16x16x32_bf16 v[44:47], v[146:149], v[196:199], v[44:47]
	v_mfma_f32_16x16x32_bf16 v[40:43], v[162:165], v[196:199], v[40:43]
	v_mfma_f32_16x16x32_bf16 v[28:31], v[146:149], v[204:207], v[28:31]
	v_mfma_f32_16x16x32_bf16 v[24:27], v[162:165], v[204:207], v[24:27]
	v_mfma_f32_16x16x32_bf16 v[12:15], v[146:149], v[230:233], v[12:15]
	v_mfma_f32_16x16x32_bf16 v[8:11], v[162:165], v[230:233], v[8:11]
	v_mfma_f32_16x16x32_bf16 v[52:55], v[168:171], v[184:187], v[52:55]
	v_mfma_f32_16x16x32_bf16 v[48:51], v[176:179], v[184:187], v[48:51]
	v_mfma_f32_16x16x32_bf16 v[36:39], v[168:171], v[192:195], v[36:39]
	v_mfma_f32_16x16x32_bf16 v[32:35], v[176:179], v[192:195], v[32:35]
	v_mfma_f32_16x16x32_bf16 v[20:23], v[168:171], v[200:203], v[20:23]
	v_mfma_f32_16x16x32_bf16 v[16:19], v[176:179], v[200:203], v[16:19]
	v_mfma_f32_16x16x32_bf16 v[4:7], v[168:171], v[212:215], v[4:7]
	v_mfma_f32_16x16x32_bf16 v[0:3], v[176:179], v[212:215], v[0:3]
	v_mfma_f32_16x16x32_bf16 v[52:55], v[172:175], v[188:191], v[52:55]
	v_mfma_f32_16x16x32_bf16 v[48:51], v[180:183], v[188:191], v[48:51]
	v_mfma_f32_16x16x32_bf16 v[36:39], v[172:175], v[196:199], v[36:39]
	v_mfma_f32_16x16x32_bf16 v[32:35], v[180:183], v[196:199], v[32:35]
	v_mfma_f32_16x16x32_bf16 v[20:23], v[172:175], v[204:207], v[20:23]
	v_mfma_f32_16x16x32_bf16 v[16:19], v[180:183], v[204:207], v[16:19]
	v_mfma_f32_16x16x32_bf16 v[4:7], v[172:175], v[230:233], v[4:7]
	v_mfma_f32_16x16x32_bf16 v[0:3], v[180:183], v[230:233], v[0:3]
	s_barrier
	s_add_i32 s43, 0, 0x18000
	s_add_i32 s44, 0, 0x1c000
	v_add_u32_e32 v162, s43, v139
	v_add_u32_e32 v167, s44, v139
	ds_read_b128 v[142:145], v162
	ds_read_b128 v[146:149], v162 offset:1024
	ds_read_b128 v[158:161], v162 offset:2048
	ds_read_b128 v[162:165], v162 offset:3072
	ds_read_b128 v[168:171], v167
	ds_read_b128 v[172:175], v167 offset:1024
	ds_read_b128 v[176:179], v167 offset:2048
	ds_read_b128 v[180:183], v167 offset:3072
	s_add_u32 s8, s8, s12
	s_addc_u32 s9, s9, s13
	s_mov_b32 m0, s29
	v_lshl_add_u64 v[240:241], s[8:9], 0, v[132:133]
	ds_read_b128 v[184:187], v141 offset:32768
	ds_read_b128 v[188:191], v141 offset:33792
	ds_read_b128 v[192:195], v141 offset:34816
	ds_read_b128 v[196:199], v141 offset:35840
	ds_read_b128 v[200:203], v141 offset:36864
	ds_read_b128 v[204:207], v141 offset:37888
	ds_read_b128 v[212:215], v141 offset:38912
	ds_read_b128 v[230:233], v141 offset:39936
	global_load_lds_dwordx4 v[240:241], off
	v_lshl_add_u64 v[240:241], s[8:9], 0, v[130:131]
	s_mov_b32 m0, s30
	s_nop 0
	global_load_lds_dwordx4 v[240:241], off
	s_waitcnt vmcnt(8)
	s_waitcnt lgkmcnt(0)
	s_barrier
	s_waitcnt lgkmcnt(0)
	v_mfma_f32_16x16x32_bf16 v[120:123], v[142:145], v[184:187], v[120:123]
	v_mfma_f32_16x16x32_bf16 v[124:127], v[158:161], v[184:187], v[124:127]
	v_mfma_f32_16x16x32_bf16 v[108:111], v[142:145], v[192:195], v[108:111]
	v_mfma_f32_16x16x32_bf16 v[104:107], v[158:161], v[192:195], v[104:107]
	v_mfma_f32_16x16x32_bf16 v[92:95], v[142:145], v[200:203], v[92:95]
	v_mfma_f32_16x16x32_bf16 v[88:91], v[158:161], v[200:203], v[88:91]
	v_mfma_f32_16x16x32_bf16 v[76:79], v[142:145], v[212:215], v[76:79]
	v_mfma_f32_16x16x32_bf16 v[72:75], v[158:161], v[212:215], v[72:75]
	v_mfma_f32_16x16x32_bf16 v[120:123], v[146:149], v[188:191], v[120:123]
	v_mfma_f32_16x16x32_bf16 v[124:127], v[162:165], v[188:191], v[124:127]
	v_mfma_f32_16x16x32_bf16 v[108:111], v[146:149], v[196:199], v[108:111]
	v_mfma_f32_16x16x32_bf16 v[104:107], v[162:165], v[196:199], v[104:107]
	v_mfma_f32_16x16x32_bf16 v[92:95], v[146:149], v[204:207], v[92:95]
	v_mfma_f32_16x16x32_bf16 v[88:91], v[162:165], v[204:207], v[88:91]
	v_mfma_f32_16x16x32_bf16 v[76:79], v[146:149], v[230:233], v[76:79]
	v_mfma_f32_16x16x32_bf16 v[72:75], v[162:165], v[230:233], v[72:75]
	v_mfma_f32_16x16x32_bf16 v[116:119], v[168:171], v[184:187], v[116:119]
	v_mfma_f32_16x16x32_bf16 v[112:115], v[176:179], v[184:187], v[112:115]
	v_mfma_f32_16x16x32_bf16 v[100:103], v[168:171], v[192:195], v[100:103]
	v_mfma_f32_16x16x32_bf16 v[96:99], v[176:179], v[192:195], v[96:99]
	v_mfma_f32_16x16x32_bf16 v[84:87], v[168:171], v[200:203], v[84:87]
	v_mfma_f32_16x16x32_bf16 v[80:83], v[176:179], v[200:203], v[80:83]
	v_mfma_f32_16x16x32_bf16 v[68:71], v[168:171], v[212:215], v[68:71]
	v_mfma_f32_16x16x32_bf16 v[64:67], v[176:179], v[212:215], v[64:67]
	v_mfma_f32_16x16x32_bf16 v[116:119], v[172:175], v[188:191], v[116:119]
	v_mfma_f32_16x16x32_bf16 v[112:115], v[180:183], v[188:191], v[112:115]
	v_mfma_f32_16x16x32_bf16 v[100:103], v[172:175], v[196:199], v[100:103]
	v_mfma_f32_16x16x32_bf16 v[96:99], v[180:183], v[196:199], v[96:99]
	v_mfma_f32_16x16x32_bf16 v[84:87], v[172:175], v[204:207], v[84:87]
	v_mfma_f32_16x16x32_bf16 v[80:83], v[180:183], v[204:207], v[80:83]
	v_mfma_f32_16x16x32_bf16 v[68:71], v[172:175], v[230:233], v[68:71]
	v_mfma_f32_16x16x32_bf16 v[64:67], v[180:183], v[230:233], v[64:67]
	s_barrier
; #define PG8_STAGE(bufoff, gbase, voff) do { _Pragma("unroll") for (int _i = 0; _i < 2; ++_i) \
;         __builtin_amdgcn_global_load_lds((const unsigned*)((const char*)(gbase) + (voff)[_i]), (PG8_LAS unsigned*)(lds + (bufoff) + ldsw + _i * 8192), 16, 0, 0); } while (0)
; #define PG8_LDA(dst, b, h) do { _Pragma("unroll") for (int m = 0; m < 4; ++m) _Pragma("unroll") for (int k = 0; k < 2; ++k) dst[m][k] = *(const PG8_LAS bf16x8*)(lds + PG8_SA(b, h) + aoff + m * 2048 + k * 1024); } while (0)
; #define PG8_MMA(ai, bj, At, Bt) do { __builtin_amdgcn_s_setprio(1); _Pragma("unroll") for (int m = 0; m < 4; ++m) _Pragma("unroll") for (int n = 0; n < 2; ++n) _Pragma("unroll") for (int k = 0; k < 2; ++k) \
;         acc[ai][bj][m][n] = __builtin_amdgcn_mfma_f32_16x16x32_bf16(Bt[n][k], At[m][k], acc[ai][bj][m][n], 0, 0, 0); __builtin_amdgcn_s_setprio(0); } while (0)
; #define PG8_WAIT_V(n) asm volatile("s_waitcnt vmcnt(" #n ")" ::: "memory")
; #define PG8_WAIT_L(n) asm volatile("s_waitcnt lgkmcnt(" #n ")" ::: "memory")
; #define PG8_BAR __builtin_amdgcn_s_barrier()
; #define PG8_SCHED __builtin_amdgcn_sched_barrier(0)
; template <class Epi, class Sched, bool ALIGN_EPI = false, bool SP2 = false>
; __device__ __forceinline__ void gemm_phase(PG8_LAS unsigned char* lds, const Gemm g, const Sched& S, const Epi& E) {
;     ...
;         for (int t = 0; t < nt; t += 2) {
;     ...
;             PG8_LDA(At, 1, 1); PG8_STAGE(PG8_SB(1, 0), b3, voffB); PG8_STAGE(PG8_SB(1, 1), b3 + hstep, voffB); PG8_STAGE(PG8_SA(1, 0), a3, voffA);
;             PG8_WAIT_V(8); PG8_WAIT_L(0); PG8_BAR; PG8_MMA(1, 0, At, B0); PG8_MMA(1, 1, At, B1); PG8_BAR; PG8_SCHED;
	s_add_i32 s8, s43, s24
	v_lshl_add_u64 v[150:151], v[150:151], 0, s[82:83]
	s_mov_b32 m0, s8
	ds_read_b128 v[184:187], v141 offset:49152
	ds_read_b128 v[188:191], v141 offset:50176
	ds_read_b128 v[192:195], v141 offset:51200
	ds_read_b128 v[196:199], v141 offset:52224
	ds_read_b128 v[200:203], v141 offset:53248
	ds_read_b128 v[204:207], v141 offset:54272
	ds_read_b128 v[212:215], v141 offset:55296
	ds_read_b128 v[230:233], v141 offset:56320
	global_load_lds_dwordx4 v[150:151], off
	v_lshl_add_u64 v[150:151], v[208:209], 0, s[82:83]
	s_add_i32 m0, s8, 0x2000
	s_add_i32 s8, s44, s24
	global_load_lds_dwordx4 v[150:151], off
	v_lshl_add_u64 v[150:151], v[216:217], 0, s[82:83]
	s_mov_b32 m0, s8
	s_nop 0
	global_load_lds_dwordx4 v[150:151], off
	v_lshl_add_u64 v[150:151], v[234:235], 0, s[82:83]
	s_add_i32 m0, s8, 0x2000
	s_nop 0
	global_load_lds_dwordx4 v[150:151], off
	v_lshl_add_u64 v[150:151], v[236:237], 0, s[82:83]
	s_mov_b32 m0, s31
	s_nop 0
	global_load_lds_dwordx4 v[150:151], off
	v_lshl_add_u64 v[150:151], v[238:239], 0, s[82:83]
	s_mov_b32 m0, s34
	s_nop 0
	global_load_lds_dwordx4 v[150:151], off
	s_waitcnt vmcnt(8)
	s_waitcnt lgkmcnt(0)
	s_barrier
	s_waitcnt lgkmcnt(0)
	v_mfma_f32_16x16x32_bf16 v[60:63], v[142:145], v[184:187], v[60:63]
	v_mfma_f32_16x16x32_bf16 v[56:59], v[158:161], v[184:187], v[56:59]
	v_mfma_f32_16x16x32_bf16 v[44:47], v[142:145], v[192:195], v[44:47]
	v_mfma_f32_16x16x32_bf16 v[40:43], v[158:161], v[192:195], v[40:43]
	v_mfma_f32_16x16x32_bf16 v[28:31], v[142:145], v[200:203], v[28:31]
	v_mfma_f32_16x16x32_bf16 v[24:27], v[158:161], v[200:203], v[24:27]
	v_mfma_f32_16x16x32_bf16 v[12:15], v[142:145], v[212:215], v[12:15]
	v_mfma_f32_16x16x32_bf16 v[8:11], v[158:161], v[212:215], v[8:11]
	v_mfma_f32_16x16x32_bf16 v[60:63], v[146:149], v[188:191], v[60:63]
	v_mfma_f32_16x16x32_bf16 v[56:59], v[162:165], v[188:191], v[56:59]
	v_mfma_f32_16x16x32_bf16 v[44:47], v[146:149], v[196:199], v[44:47]
	v_mfma_f32_16x16x32_bf16 v[40:43], v[162:165], v[196:199], v[40:43]
	v_mfma_f32_16x16x32_bf16 v[28:31], v[146:149], v[204:207], v[28:31]
	v_mfma_f32_16x16x32_bf16 v[24:27], v[162:165], v[204:207], v[24:27]
	v_mfma_f32_16x16x32_bf16 v[12:15], v[146:149], v[230:233], v[12:15]
	v_mfma_f32_16x16x32_bf16 v[8:11], v[162:165], v[230:233], v[8:11]
	v_mfma_f32_16x16x32_bf16 v[52:55], v[168:171], v[184:187], v[52:55]
	v_mfma_f32_16x16x32_bf16 v[48:51], v[176:179], v[184:187], v[48:51]
	v_mfma_f32_16x16x32_bf16 v[36:39], v[168:171], v[192:195], v[36:39]
	v_mfma_f32_16x16x32_bf16 v[32:35], v[176:179], v[192:195], v[32:35]
	v_mfma_f32_16x16x32_bf16 v[20:23], v[168:171], v[200:203], v[20:23]
	v_mfma_f32_16x16x32_bf16 v[16:19], v[176:179], v[200:203], v[16:19]
	v_mfma_f32_16x16x32_bf16 v[4:7], v[168:171], v[212:215], v[4:7]
	v_mfma_f32_16x16x32_bf16 v[0:3], v[176:179], v[212:215], v[0:3]
	v_mfma_f32_16x16x32_bf16 v[52:55], v[172:175], v[188:191], v[52:55]
	v_mfma_f32_16x16x32_bf16 v[48:51], v[180:183], v[188:191], v[48:51]
	v_mfma_f32_16x16x32_bf16 v[36:39], v[172:175], v[196:199], v[36:39]
	v_mfma_f32_16x16x32_bf16 v[32:35], v[180:183], v[196:199], v[32:35]
	v_mfma_f32_16x16x32_bf16 v[20:23], v[172:175], v[204:207], v[20:23]
	v_mfma_f32_16x16x32_bf16 v[16:19], v[180:183], v[204:207], v[16:19]
	v_mfma_f32_16x16x32_bf16 v[4:7], v[172:175], v[230:233], v[4:7]
	v_mfma_f32_16x16x32_bf16 v[0:3], v[180:183], v[230:233], v[0:3]
	s_barrier
	s_add_u32 s6, s6, 0x100
	s_addc_u32 s7, s7, 0
	s_add_u32 s20, s20, 0x100
	s_addc_u32 s21, s21, 0
	s_cmp_ge_i32 s42, s35
	s_mov_b32 s8, s42
	s_cbranch_scc0 .LBB0_194
	s_setprio 0

; template <class Epi, class Sched, bool ALIGN_EPI = false, bool SP2 = false>
; __device__ __forceinline__ void gemm_phase(PG8_LAS unsigned char* lds, const Gemm g, const Sched& S, const Epi& E) {
;     ...
;     f32x4 acc[2][2][4][2];
; #pragma unroll
;     for (int a = 0; a < 2; ++a)
; #pragma unroll
;         for (int b = 0; b < 2; ++b)
; #pragma unroll
;             for (int m = 0; m < 4; ++m)
; #pragma unroll
;                 for (int n = 0; n < 2; ++n) acc[a][b][m][n] = (f32x4){0.f, 0.f, 0.f, 0.f};
;     ...
;     for (;;) {
;         const bool has_next = S.next(ui + 1, nxt);
;         const char* nA = has_next ? (const char*)g.A + (size_t)nxt.pm * tstep : cA; const char* nB = has_next ? (const char*)g.Bt + (size_t)nxt.pn * tstep : cB;
;         for (int t = 0; t < nt; t += 2) {
.LBB0_361:
	v_mov_b32_e32 v127, 0
	s_andn2_b64 vcc, exec, s[46:47]
	v_mov_b32_e32 v126, v127
	v_mov_b32_e32 v125, v127
	v_mov_b32_e32 v124, v127
	v_mov_b32_e32 v123, v127
	v_mov_b32_e32 v122, v127
	v_mov_b32_e32 v121, v127
	v_mov_b32_e32 v120, v127
	v_mov_b32_e32 v119, v127
	v_mov_b32_e32 v118, v127
	v_mov_b32_e32 v117, v127
	v_mov_b32_e32 v116, v127
	v_mov_b32_e32 v115, v127
	v_mov_b32_e32 v114, v127
	v_mov_b32_e32 v113, v127
	v_mov_b32_e32 v112, v127
	v_mov_b32_e32 v111, v127
	v_mov_b32_e32 v110, v127
	v_mov_b32_e32 v109, v127
	v_mov_b32_e32 v108, v127
	s_waitcnt vmcnt(0)
	v_mov_b32_e32 v107, v127
	v_mov_b32_e32 v106, v127
	v_mov_b32_e32 v105, v127
	v_mov_b32_e32 v104, v127
	v_mov_b32_e32 v103, v127
	v_mov_b32_e32 v102, v127
	v_mov_b32_e32 v101, v127
	v_mov_b32_e32 v100, v127
	v_mov_b32_e32 v99, v127
	v_mov_b32_e32 v98, v127
	v_mov_b32_e32 v97, v127
	v_mov_b32_e32 v96, v127
	v_mov_b32_e32 v63, v127
	v_mov_b32_e32 v62, v127
	v_mov_b32_e32 v61, v127
	v_mov_b32_e32 v60, v127
	v_mov_b32_e32 v59, v127
	v_mov_b32_e32 v58, v127
	v_mov_b32_e32 v57, v127
	v_mov_b32_e32 v56, v127
	v_mov_b32_e32 v55, v127
	v_mov_b32_e32 v54, v127
	v_mov_b32_e32 v53, v127
	v_mov_b32_e32 v52, v127
	v_mov_b32_e32 v51, v127
	v_mov_b32_e32 v50, v127
	v_mov_b32_e32 v49, v127
	v_mov_b32_e32 v48, v127
	v_mov_b32_e32 v47, v127
	v_mov_b32_e32 v46, v127
	v_mov_b32_e32 v45, v127
	v_mov_b32_e32 v44, v127
	v_mov_b32_e32 v43, v127
	v_mov_b32_e32 v42, v127
	v_mov_b32_e32 v41, v127
	v_mov_b32_e32 v40, v127
	v_mov_b32_e32 v39, v127
	v_mov_b32_e32 v38, v127
	v_mov_b32_e32 v37, v127
	v_mov_b32_e32 v36, v127
	v_mov_b32_e32 v35, v127
	v_mov_b32_e32 v34, v127
	v_mov_b32_e32 v33, v127
	v_mov_b32_e32 v32, v127
	v_mov_b32_e32 v95, v127
	v_mov_b32_e32 v94, v127
	v_mov_b32_e32 v93, v127
	v_mov_b32_e32 v92, v127
	v_mov_b32_e32 v91, v127
	v_mov_b32_e32 v90, v127
	v_mov_b32_e32 v89, v127
	v_mov_b32_e32 v88, v127
	v_mov_b32_e32 v87, v127
	v_mov_b32_e32 v86, v127
	v_mov_b32_e32 v85, v127
	v_mov_b32_e32 v84, v127
	v_mov_b32_e32 v83, v127
	v_mov_b32_e32 v82, v127
	v_mov_b32_e32 v81, v127
	v_mov_b32_e32 v80, v127
	v_mov_b32_e32 v79, v127
	v_mov_b32_e32 v78, v127
	v_mov_b32_e32 v77, v127
	v_mov_b32_e32 v76, v127
	v_mov_b32_e32 v75, v127
	v_mov_b32_e32 v74, v127
	v_mov_b32_e32 v73, v127
	v_mov_b32_e32 v72, v127
	v_mov_b32_e32 v71, v127
	v_mov_b32_e32 v70, v127
	v_mov_b32_e32 v69, v127
	v_mov_b32_e32 v68, v127
	v_mov_b32_e32 v67, v127
	v_mov_b32_e32 v66, v127
	v_mov_b32_e32 v65, v127
	v_mov_b32_e32 v64, v127
	v_mov_b32_e32 v31, v127
	v_mov_b32_e32 v30, v127
	v_mov_b32_e32 v29, v127
	v_mov_b32_e32 v28, v127
	v_mov_b32_e32 v27, v127
	v_mov_b32_e32 v26, v127
	v_mov_b32_e32 v25, v127
	v_mov_b32_e32 v24, v127
	v_mov_b32_e32 v23, v127
	v_mov_b32_e32 v22, v127
	v_mov_b32_e32 v21, v127
	v_mov_b32_e32 v20, v127
	v_mov_b32_e32 v19, v127
	v_mov_b32_e32 v18, v127
	v_mov_b32_e32 v17, v127
	v_mov_b32_e32 v16, v127
	v_mov_b32_e32 v15, v127
	v_mov_b32_e32 v14, v127
	v_mov_b32_e32 v13, v127
	v_mov_b32_e32 v12, v127
	v_mov_b32_e32 v11, v127
	v_mov_b32_e32 v10, v127
	v_mov_b32_e32 v9, v127
	v_mov_b32_e32 v8, v127
	v_mov_b32_e32 v3, v127
	v_mov_b32_e32 v2, v127
	v_mov_b32_e32 v1, v127
	v_mov_b32_e32 v0, v127
	v_mov_b32_e32 v7, v127
	v_mov_b32_e32 v6, v127
	v_mov_b32_e32 v5, v127
	v_mov_b32_e32 v4, v127
	s_cbranch_vccnz .LBB0_364
	s_add_u32 s0, s0, 0x80
	s_addc_u32 s1, s1, 0
	s_add_u32 s40, s2, 0x100
	v_mov_b32_e32 v4, 0
	s_addc_u32 s41, s3, 0
	s_mov_b32 s2, 0
	v_mov_b32_e32 v5, v4
	v_mov_b32_e32 v6, v4
	v_mov_b32_e32 v7, v4
	v_mov_b32_e32 v0, v4
	v_mov_b32_e32 v1, v4
	v_mov_b32_e32 v2, v4
	v_mov_b32_e32 v3, v4
	v_mov_b32_e32 v8, v4
	v_mov_b32_e32 v9, v4
	v_mov_b32_e32 v10, v4
	v_mov_b32_e32 v11, v4
	v_mov_b32_e32 v12, v4
	v_mov_b32_e32 v13, v4
	v_mov_b32_e32 v14, v4
	v_mov_b32_e32 v15, v4
	v_mov_b32_e32 v16, v4
	v_mov_b32_e32 v17, v4
	v_mov_b32_e32 v18, v4
	v_mov_b32_e32 v19, v4
	v_mov_b32_e32 v20, v4
	v_mov_b32_e32 v21, v4
	v_mov_b32_e32 v22, v4
	v_mov_b32_e32 v23, v4
	v_mov_b32_e32 v24, v4
	v_mov_b32_e32 v25, v4
	v_mov_b32_e32 v26, v4
	v_mov_b32_e32 v27, v4
	v_mov_b32_e32 v28, v4
	v_mov_b32_e32 v29, v4
	v_mov_b32_e32 v30, v4
	v_mov_b32_e32 v31, v4
	v_mov_b32_e32 v64, v4
	v_mov_b32_e32 v65, v4
	v_mov_b32_e32 v66, v4
	v_mov_b32_e32 v67, v4
	v_mov_b32_e32 v68, v4
	v_mov_b32_e32 v69, v4
	v_mov_b32_e32 v70, v4
	v_mov_b32_e32 v71, v4
	v_mov_b32_e32 v72, v4
	v_mov_b32_e32 v73, v4
	v_mov_b32_e32 v74, v4
	v_mov_b32_e32 v75, v4
	v_mov_b32_e32 v76, v4
	v_mov_b32_e32 v77, v4
	v_mov_b32_e32 v78, v4
	v_mov_b32_e32 v79, v4
	v_mov_b32_e32 v80, v4
	v_mov_b32_e32 v81, v4
	v_mov_b32_e32 v82, v4
	v_mov_b32_e32 v83, v4
	v_mov_b32_e32 v84, v4
	v_mov_b32_e32 v85, v4
	v_mov_b32_e32 v86, v4
	v_mov_b32_e32 v87, v4
	v_mov_b32_e32 v88, v4
	v_mov_b32_e32 v89, v4
	v_mov_b32_e32 v90, v4
	v_mov_b32_e32 v91, v4
	v_mov_b32_e32 v92, v4
	v_mov_b32_e32 v93, v4
	v_mov_b32_e32 v94, v4
	v_mov_b32_e32 v95, v4
	v_mov_b32_e32 v32, v4
	v_mov_b32_e32 v33, v4
	v_mov_b32_e32 v34, v4
	v_mov_b32_e32 v35, v4
	v_mov_b32_e32 v36, v4
	v_mov_b32_e32 v37, v4
	v_mov_b32_e32 v38, v4
	v_mov_b32_e32 v39, v4
	v_mov_b32_e32 v40, v4
	v_mov_b32_e32 v41, v4
	v_mov_b32_e32 v42, v4
	v_mov_b32_e32 v43, v4
	v_mov_b32_e32 v44, v4
	v_mov_b32_e32 v45, v4
	v_mov_b32_e32 v46, v4
	v_mov_b32_e32 v47, v4
	v_mov_b32_e32 v48, v4
	v_mov_b32_e32 v49, v4
	v_mov_b32_e32 v50, v4
	v_mov_b32_e32 v51, v4
	v_mov_b32_e32 v52, v4
	v_mov_b32_e32 v53, v4
	v_mov_b32_e32 v54, v4
	v_mov_b32_e32 v55, v4
	v_mov_b32_e32 v56, v4
	v_mov_b32_e32 v57, v4
	v_mov_b32_e32 v58, v4
	v_mov_b32_e32 v59, v4
	v_mov_b32_e32 v60, v4
	v_mov_b32_e32 v61, v4
	v_mov_b32_e32 v62, v4
	v_mov_b32_e32 v63, v4
	v_mov_b32_e32 v96, v4
	v_mov_b32_e32 v97, v4
	v_mov_b32_e32 v98, v4
	v_mov_b32_e32 v99, v4
	v_mov_b32_e32 v100, v4
	v_mov_b32_e32 v101, v4
	v_mov_b32_e32 v102, v4
	v_mov_b32_e32 v103, v4
	v_mov_b32_e32 v104, v4
	v_mov_b32_e32 v105, v4
	v_mov_b32_e32 v106, v4
	v_mov_b32_e32 v107, v4
	v_mov_b32_e32 v108, v4
	v_mov_b32_e32 v109, v4
	v_mov_b32_e32 v110, v4
	v_mov_b32_e32 v111, v4
	v_mov_b32_e32 v112, v4
	v_mov_b32_e32 v113, v4
	v_mov_b32_e32 v114, v4
	v_mov_b32_e32 v115, v4
	v_mov_b32_e32 v116, v4
	v_mov_b32_e32 v117, v4
	v_mov_b32_e32 v118, v4
	v_mov_b32_e32 v119, v4
	v_mov_b32_e32 v120, v4
	v_mov_b32_e32 v121, v4
	v_mov_b32_e32 v122, v4
	v_mov_b32_e32 v123, v4
	v_mov_b32_e32 v124, v4
	v_mov_b32_e32 v125, v4
	v_mov_b32_e32 v126, v4
	v_mov_b32_e32 v127, v4
	v_readfirstlane_b32 s100, v211
	s_cmp_ge_u32 s100, 0x100
	s_cbranch_scc0 .Lprio_skip9
	s_setprio 1
; #define PG8_STAGE(bufoff, gbase, voff) do { _Pragma("unroll") for (int _i = 0; _i < 2; ++_i) \
;         __builtin_amdgcn_global_load_lds((const unsigned*)((const char*)(gbase) + (voff)[_i]), (PG8_LAS unsigned*)(lds + (bufoff) + ldsw + _i * 8192), 16, 0, 0); } while (0)
; #define PG8_LDA(dst, b, h) do { _Pragma("unroll") for (int m = 0; m < 4; ++m) _Pragma("unroll") for (int k = 0; k < 2; ++k) dst[m][k] = *(const PG8_LAS bf16x8*)(lds + PG8_SA(b, h) + aoff + m * 2048 + k * 1024); } while (0)
; #define PG8_LDB(dst, b, h) do { _Pragma("unroll") for (int n = 0; n < 2; ++n) _Pragma("unroll") for (int k = 0; k < 2; ++k) dst[n][k] = *(const PG8_LAS bf16x8*)(lds + PG8_SB(b, h) + boff + n * 2048 + k * 1024); } while (0)
; #define PG8_MMA(ai, bj, At, Bt) do { __builtin_amdgcn_s_setprio(1); _Pragma("unroll") for (int m = 0; m < 4; ++m) _Pragma("unroll") for (int n = 0; n < 2; ++n) _Pragma("unroll") for (int k = 0; k < 2; ++k) \
;         acc[ai][bj][m][n] = __builtin_amdgcn_mfma_f32_16x16x32_bf16(Bt[n][k], At[m][k], acc[ai][bj][m][n], 0, 0, 0); __builtin_amdgcn_s_setprio(0); } while (0)
; #define PG8_WAIT_V(n) asm volatile("s_waitcnt vmcnt(" #n ")" ::: "memory")
; #define PG8_WAIT_L(n) asm volatile("s_waitcnt lgkmcnt(" #n ")" ::: "memory")
; #define PG8_BAR __builtin_amdgcn_s_barrier()
; #define PG8_SCHED __builtin_amdgcn_sched_barrier(0)
; template <class Epi, class Sched, bool ALIGN_EPI = false, bool SP2 = false>
; __device__ __forceinline__ void gemm_phase(PG8_LAS unsigned char* lds, const Gemm g, const Sched& S, const Epi& E) {
;     ...
;             PG8_LDB(B0, 0, 0); PG8_LDB(B1, 0, 1); PG8_SCHED; PG8_LDA(At, 0, 0); PG8_STAGE(PG8_SA(1, 1), a1 + hstep, voffA);
;             PG8_WAIT_V(8); PG8_WAIT_L(0); PG8_BAR; PG8_MMA(0, 0, At, B0); PG8_MMA(0, 1, At, B1); PG8_BAR; PG8_SCHED;
;             PG8_LDA(At, 0, 1); PG8_STAGE(PG8_SB(0, 0), b2, voffB); PG8_STAGE(PG8_SB(0, 1), b2 + hstep, voffB); PG8_STAGE(PG8_SA(0, 0), a2, voffA);
.Lprio_skip9:
.LBB0_363:
	s_add_i32 s42, s2, 2
	s_add_u32 s43, s0, 0x80
	s_addc_u32 s3, s1, 0
	s_add_i32 s48, 0, 0x10000
	s_cmp_eq_u32 s34, s2
	s_cselect_b32 s3, s7, s3
	s_cselect_b32 s2, s6, s43
	s_cselect_b32 s45, s53, s41
	s_cselect_b32 s44, s52, s40
	s_add_i32 s43, 0, 0x14000
	v_add_u32_e32 v140, s48, v202
	v_add_u32_e32 v158, s43, v202
	ds_read_b128 v[128:131], v140
	ds_read_b128 v[132:135], v140 offset:1024
	ds_read_b128 v[136:139], v140 offset:2048
	ds_read_b128 v[140:143], v140 offset:3072
	ds_read_b128 v[144:147], v158
	ds_read_b128 v[148:151], v158 offset:1024
	ds_read_b128 v[178:181], v158 offset:2048
	ds_read_b128 v[182:185], v158 offset:3072
	v_lshl_add_u64 v[158:159], s[0:1], 0, v[174:175]
	s_add_i32 m0, s23, 0xc000
	ds_read_b128 v[186:189], v204
	ds_read_b128 v[190:193], v204 offset:1024
	ds_read_b128 v[194:197], v204 offset:2048
	ds_read_b128 v[198:201], v204 offset:3072
	ds_read_b128 v[206:209], v204 offset:4096
	ds_read_b128 v[212:215], v204 offset:5120
	ds_read_b128 v[230:233], v204 offset:6144
	ds_read_b128 v[234:237], v204 offset:7168
	global_load_lds_dwordx4 v[158:159], off
	v_lshl_add_u64 v[158:159], s[0:1], 0, v[176:177]
	s_add_i32 m0, s23, 0xe000
	s_nop 0
	global_load_lds_dwordx4 v[158:159], off
	s_waitcnt vmcnt(8)
	s_waitcnt lgkmcnt(0)
	s_barrier
	s_waitcnt lgkmcnt(0)
	v_mfma_f32_16x16x32_bf16 v[124:127], v[128:131], v[186:189], v[124:127]
	v_mfma_f32_16x16x32_bf16 v[120:123], v[136:139], v[186:189], v[120:123]
	v_mfma_f32_16x16x32_bf16 v[116:119], v[128:131], v[194:197], v[116:119]
	v_mfma_f32_16x16x32_bf16 v[112:115], v[136:139], v[194:197], v[112:115]
	v_mfma_f32_16x16x32_bf16 v[108:111], v[128:131], v[206:209], v[108:111]
	v_mfma_f32_16x16x32_bf16 v[104:107], v[136:139], v[206:209], v[104:107]
	v_mfma_f32_16x16x32_bf16 v[100:103], v[128:131], v[230:233], v[100:103]
	v_mfma_f32_16x16x32_bf16 v[96:99], v[136:139], v[230:233], v[96:99]
	v_mfma_f32_16x16x32_bf16 v[124:127], v[132:135], v[190:193], v[124:127]
	v_mfma_f32_16x16x32_bf16 v[120:123], v[140:143], v[190:193], v[120:123]
	v_mfma_f32_16x16x32_bf16 v[116:119], v[132:135], v[198:201], v[116:119]
	v_mfma_f32_16x16x32_bf16 v[112:115], v[140:143], v[198:201], v[112:115]
	v_mfma_f32_16x16x32_bf16 v[108:111], v[132:135], v[212:215], v[108:111]
	v_mfma_f32_16x16x32_bf16 v[104:107], v[140:143], v[212:215], v[104:107]
	v_mfma_f32_16x16x32_bf16 v[100:103], v[132:135], v[234:237], v[100:103]
	v_mfma_f32_16x16x32_bf16 v[96:99], v[140:143], v[234:237], v[96:99]
	v_mfma_f32_16x16x32_bf16 v[60:63], v[144:147], v[186:189], v[60:63]
	v_mfma_f32_16x16x32_bf16 v[56:59], v[178:181], v[186:189], v[56:59]
	v_mfma_f32_16x16x32_bf16 v[52:55], v[144:147], v[194:197], v[52:55]
	v_mfma_f32_16x16x32_bf16 v[48:51], v[178:181], v[194:197], v[48:51]
	v_mfma_f32_16x16x32_bf16 v[44:47], v[144:147], v[206:209], v[44:47]
	v_mfma_f32_16x16x32_bf16 v[40:43], v[178:181], v[206:209], v[40:43]
	v_mfma_f32_16x16x32_bf16 v[36:39], v[144:147], v[230:233], v[36:39]
	v_mfma_f32_16x16x32_bf16 v[32:35], v[178:181], v[230:233], v[32:35]
	v_mfma_f32_16x16x32_bf16 v[60:63], v[148:151], v[190:193], v[60:63]
	v_mfma_f32_16x16x32_bf16 v[56:59], v[182:185], v[190:193], v[56:59]
	v_mfma_f32_16x16x32_bf16 v[52:55], v[148:151], v[198:201], v[52:55]
	v_mfma_f32_16x16x32_bf16 v[48:51], v[182:185], v[198:201], v[48:51]
	v_mfma_f32_16x16x32_bf16 v[44:47], v[148:151], v[212:215], v[44:47]
	v_mfma_f32_16x16x32_bf16 v[40:43], v[182:185], v[212:215], v[40:43]
	v_mfma_f32_16x16x32_bf16 v[36:39], v[148:151], v[234:237], v[36:39]
	v_mfma_f32_16x16x32_bf16 v[32:35], v[182:185], v[234:237], v[32:35]
	s_barrier
	s_add_i32 s48, s48, s22
	v_lshl_add_u64 v[158:159], s[44:45], 0, v[152:153]
	s_mov_b32 m0, s48
	ds_read_b128 v[186:189], v204 offset:16384
	ds_read_b128 v[190:193], v204 offset:17408
	ds_read_b128 v[194:197], v204 offset:18432
	ds_read_b128 v[198:201], v204 offset:19456
	ds_read_b128 v[206:209], v204 offset:20480
	ds_read_b128 v[212:215], v204 offset:21504
	ds_read_b128 v[230:233], v204 offset:22528
	ds_read_b128 v[234:237], v204 offset:23552
	global_load_lds_dwordx4 v[158:159], off
	s_add_i32 m0, s48, 0x2000
	v_lshl_add_u64 v[160:161], s[44:45], 0, v[168:169]
	s_add_u32 s44, s44, s8
	s_addc_u32 s45, s45, s9
	s_add_i32 s43, s43, s22
	global_load_lds_dwordx4 v[160:161], off
	v_lshl_add_u64 v[162:163], s[44:45], 0, v[152:153]
	s_mov_b32 m0, s43
	v_lshl_add_u64 v[164:165], s[44:45], 0, v[168:169]
	global_load_lds_dwordx4 v[162:163], off
	s_add_i32 m0, s43, 0x2000
	v_lshl_add_u64 v[216:217], s[2:3], 0, v[172:173]
	global_load_lds_dwordx4 v[164:165], off
	s_mov_b32 m0, s23
	v_lshl_add_u64 v[238:239], s[2:3], 0, v[170:171]
	global_load_lds_dwordx4 v[216:217], off
	s_mov_b32 m0, s24
	s_nop 0
	global_load_lds_dwordx4 v[238:239], off
	s_waitcnt vmcnt(8)
	s_waitcnt lgkmcnt(0)
	s_barrier
; #define PG8_STAGE(bufoff, gbase, voff) do { _Pragma("unroll") for (int _i = 0; _i < 2; ++_i) \
;         __builtin_amdgcn_global_load_lds((const unsigned*)((const char*)(gbase) + (voff)[_i]), (PG8_LAS unsigned*)(lds + (bufoff) + ldsw + _i * 8192), 16, 0, 0); } while (0)
; #define PG8_LDA(dst, b, h) do { _Pragma("unroll") for (int m = 0; m < 4; ++m) _Pragma("unroll") for (int k = 0; k < 2; ++k) dst[m][k] = *(const PG8_LAS bf16x8*)(lds + PG8_SA(b, h) + aoff + m * 2048 + k * 1024); } while (0)
; #define PG8_LDB(dst, b, h) do { _Pragma("unroll") for (int n = 0; n < 2; ++n) _Pragma("unroll") for (int k = 0; k < 2; ++k) dst[n][k] = *(const PG8_LAS bf16x8*)(lds + PG8_SB(b, h) + boff + n * 2048 + k * 1024); } while (0)
; #define PG8_MMA(ai, bj, At, Bt) do { __builtin_amdgcn_s_setprio(1); _Pragma("unroll") for (int m = 0; m < 4; ++m) _Pragma("unroll") for (int n = 0; n < 2; ++n) _Pragma("unroll") for (int k = 0; k < 2; ++k) \
;         acc[ai][bj][m][n] = __builtin_amdgcn_mfma_f32_16x16x32_bf16(Bt[n][k], At[m][k], acc[ai][bj][m][n], 0, 0, 0); __builtin_amdgcn_s_setprio(0); } while (0)
; #define PG8_WAIT_V(n) asm volatile("s_waitcnt vmcnt(" #n ")" ::: "memory")
; #define PG8_WAIT_L(n) asm volatile("s_waitcnt lgkmcnt(" #n ")" ::: "memory")
; #define PG8_BAR __builtin_amdgcn_s_barrier()
; #define PG8_SCHED __builtin_amdgcn_sched_barrier(0)
; template <class Epi, class Sched, bool ALIGN_EPI = false, bool SP2 = false>
; __device__ __forceinline__ void gemm_phase(PG8_LAS unsigned char* lds, const Gemm g, const Sched& S, const Epi& E) {
;     ...
;             PG8_WAIT_V(8); PG8_WAIT_L(0); PG8_BAR; PG8_MMA(1, 0, At, B0); PG8_MMA(1, 1, At, B1); PG8_BAR; PG8_SCHED;
;             PG8_LDB(B0, 1, 0); PG8_LDB(B1, 1, 1); PG8_SCHED; PG8_LDA(At, 1, 0); PG8_STAGE(PG8_SA(0, 1), a2 + hstep, voffA);
;             PG8_WAIT_V(8); PG8_WAIT_L(0); PG8_BAR; PG8_MMA(0, 0, At, B0); PG8_MMA(0, 1, At, B1); PG8_BAR; PG8_SCHED;
	s_waitcnt lgkmcnt(0)
	v_mfma_f32_16x16x32_bf16 v[92:95], v[128:131], v[186:189], v[92:95]
	v_mfma_f32_16x16x32_bf16 v[88:91], v[136:139], v[186:189], v[88:91]
	v_mfma_f32_16x16x32_bf16 v[84:87], v[128:131], v[194:197], v[84:87]
	v_mfma_f32_16x16x32_bf16 v[80:83], v[136:139], v[194:197], v[80:83]
	v_mfma_f32_16x16x32_bf16 v[76:79], v[128:131], v[206:209], v[76:79]
	v_mfma_f32_16x16x32_bf16 v[72:75], v[136:139], v[206:209], v[72:75]
	v_mfma_f32_16x16x32_bf16 v[68:71], v[128:131], v[230:233], v[68:71]
	v_mfma_f32_16x16x32_bf16 v[64:67], v[136:139], v[230:233], v[64:67]
	v_mfma_f32_16x16x32_bf16 v[92:95], v[132:135], v[190:193], v[92:95]
	v_mfma_f32_16x16x32_bf16 v[88:91], v[140:143], v[190:193], v[88:91]
	v_mfma_f32_16x16x32_bf16 v[84:87], v[132:135], v[198:201], v[84:87]
	v_mfma_f32_16x16x32_bf16 v[80:83], v[140:143], v[198:201], v[80:83]
	v_mfma_f32_16x16x32_bf16 v[76:79], v[132:135], v[212:215], v[76:79]
	v_mfma_f32_16x16x32_bf16 v[72:75], v[140:143], v[212:215], v[72:75]
	v_mfma_f32_16x16x32_bf16 v[68:71], v[132:135], v[234:237], v[68:71]
	v_mfma_f32_16x16x32_bf16 v[64:67], v[140:143], v[234:237], v[64:67]
	v_mfma_f32_16x16x32_bf16 v[28:31], v[144:147], v[186:189], v[28:31]
	v_mfma_f32_16x16x32_bf16 v[24:27], v[178:181], v[186:189], v[24:27]
	v_mfma_f32_16x16x32_bf16 v[20:23], v[144:147], v[194:197], v[20:23]
	v_mfma_f32_16x16x32_bf16 v[16:19], v[178:181], v[194:197], v[16:19]
	v_mfma_f32_16x16x32_bf16 v[12:15], v[144:147], v[206:209], v[12:15]
	v_mfma_f32_16x16x32_bf16 v[8:11], v[178:181], v[206:209], v[8:11]
	v_mfma_f32_16x16x32_bf16 v[0:3], v[144:147], v[230:233], v[0:3]
	v_mfma_f32_16x16x32_bf16 v[4:7], v[178:181], v[230:233], v[4:7]
	v_mfma_f32_16x16x32_bf16 v[28:31], v[148:151], v[190:193], v[28:31]
	v_mfma_f32_16x16x32_bf16 v[24:27], v[182:185], v[190:193], v[24:27]
	v_mfma_f32_16x16x32_bf16 v[20:23], v[148:151], v[198:201], v[20:23]
	v_mfma_f32_16x16x32_bf16 v[16:19], v[182:185], v[198:201], v[16:19]
	v_mfma_f32_16x16x32_bf16 v[12:15], v[148:151], v[212:215], v[12:15]
	v_mfma_f32_16x16x32_bf16 v[8:11], v[182:185], v[212:215], v[8:11]
	v_mfma_f32_16x16x32_bf16 v[0:3], v[148:151], v[234:237], v[0:3]
	v_mfma_f32_16x16x32_bf16 v[4:7], v[182:185], v[234:237], v[4:7]
	s_barrier
	s_add_i32 s43, 0, 0x18000
	s_add_i32 s44, 0, 0x1c000
	v_add_u32_e32 v140, s43, v202
	v_add_u32_e32 v182, s44, v202
	ds_read_b128 v[128:131], v140
	ds_read_b128 v[132:135], v140 offset:1024
	ds_read_b128 v[136:139], v140 offset:2048
	ds_read_b128 v[140:143], v140 offset:3072
	ds_read_b128 v[144:147], v182
	ds_read_b128 v[148:151], v182 offset:1024
	ds_read_b128 v[178:181], v182 offset:2048
	ds_read_b128 v[182:185], v182 offset:3072
	s_add_u32 s2, s2, s8
	s_addc_u32 s3, s3, s9
	s_mov_b32 m0, s25
	v_lshl_add_u64 v[240:241], s[2:3], 0, v[172:173]
	ds_read_b128 v[186:189], v204 offset:32768
	ds_read_b128 v[190:193], v204 offset:33792
	ds_read_b128 v[194:197], v204 offset:34816
	ds_read_b128 v[198:201], v204 offset:35840
	ds_read_b128 v[206:209], v204 offset:36864
	ds_read_b128 v[212:215], v204 offset:37888
	ds_read_b128 v[230:233], v204 offset:38912
	ds_read_b128 v[234:237], v204 offset:39936
	global_load_lds_dwordx4 v[240:241], off
	v_lshl_add_u64 v[240:241], s[2:3], 0, v[170:171]
	s_mov_b32 m0, s28
	s_nop 0
	global_load_lds_dwordx4 v[240:241], off
	s_waitcnt vmcnt(8)
	s_waitcnt lgkmcnt(0)
	s_barrier
	s_waitcnt lgkmcnt(0)
	v_mfma_f32_16x16x32_bf16 v[124:127], v[128:131], v[186:189], v[124:127]
	v_mfma_f32_16x16x32_bf16 v[120:123], v[136:139], v[186:189], v[120:123]
	v_mfma_f32_16x16x32_bf16 v[116:119], v[128:131], v[194:197], v[116:119]
	v_mfma_f32_16x16x32_bf16 v[112:115], v[136:139], v[194:197], v[112:115]
	v_mfma_f32_16x16x32_bf16 v[108:111], v[128:131], v[206:209], v[108:111]
	v_mfma_f32_16x16x32_bf16 v[104:107], v[136:139], v[206:209], v[104:107]
	v_mfma_f32_16x16x32_bf16 v[100:103], v[128:131], v[230:233], v[100:103]
	v_mfma_f32_16x16x32_bf16 v[96:99], v[136:139], v[230:233], v[96:99]
	v_mfma_f32_16x16x32_bf16 v[124:127], v[132:135], v[190:193], v[124:127]
	v_mfma_f32_16x16x32_bf16 v[120:123], v[140:143], v[190:193], v[120:123]
	v_mfma_f32_16x16x32_bf16 v[116:119], v[132:135], v[198:201], v[116:119]
	v_mfma_f32_16x16x32_bf16 v[112:115], v[140:143], v[198:201], v[112:115]
	v_mfma_f32_16x16x32_bf16 v[108:111], v[132:135], v[212:215], v[108:111]
	v_mfma_f32_16x16x32_bf16 v[104:107], v[140:143], v[212:215], v[104:107]
	v_mfma_f32_16x16x32_bf16 v[100:103], v[132:135], v[234:237], v[100:103]
	v_mfma_f32_16x16x32_bf16 v[96:99], v[140:143], v[234:237], v[96:99]
	v_mfma_f32_16x16x32_bf16 v[60:63], v[144:147], v[186:189], v[60:63]
	v_mfma_f32_16x16x32_bf16 v[56:59], v[178:181], v[186:189], v[56:59]
	v_mfma_f32_16x16x32_bf16 v[52:55], v[144:147], v[194:197], v[52:55]
	v_mfma_f32_16x16x32_bf16 v[48:51], v[178:181], v[194:197], v[48:51]
	v_mfma_f32_16x16x32_bf16 v[44:47], v[144:147], v[206:209], v[44:47]
	v_mfma_f32_16x16x32_bf16 v[40:43], v[178:181], v[206:209], v[40:43]
	v_mfma_f32_16x16x32_bf16 v[36:39], v[144:147], v[230:233], v[36:39]
	v_mfma_f32_16x16x32_bf16 v[32:35], v[178:181], v[230:233], v[32:35]
	v_mfma_f32_16x16x32_bf16 v[60:63], v[148:151], v[190:193], v[60:63]
	v_mfma_f32_16x16x32_bf16 v[56:59], v[182:185], v[190:193], v[56:59]
	v_mfma_f32_16x16x32_bf16 v[52:55], v[148:151], v[198:201], v[52:55]
	v_mfma_f32_16x16x32_bf16 v[48:51], v[182:185], v[198:201], v[48:51]
	v_mfma_f32_16x16x32_bf16 v[44:47], v[148:151], v[212:215], v[44:47]
	v_mfma_f32_16x16x32_bf16 v[40:43], v[182:185], v[212:215], v[40:43]
	v_mfma_f32_16x16x32_bf16 v[36:39], v[148:151], v[234:237], v[36:39]
	v_mfma_f32_16x16x32_bf16 v[32:35], v[182:185], v[234:237], v[32:35]
	s_barrier
; #define PG8_STAGE(bufoff, gbase, voff) do { _Pragma("unroll") for (int _i = 0; _i < 2; ++_i) \
;         __builtin_amdgcn_global_load_lds((const unsigned*)((const char*)(gbase) + (voff)[_i]), (PG8_LAS unsigned*)(lds + (bufoff) + ldsw + _i * 8192), 16, 0, 0); } while (0)
; #define PG8_LDA(dst, b, h) do { _Pragma("unroll") for (int m = 0; m < 4; ++m) _Pragma("unroll") for (int k = 0; k < 2; ++k) dst[m][k] = *(const PG8_LAS bf16x8*)(lds + PG8_SA(b, h) + aoff + m * 2048 + k * 1024); } while (0)
; #define PG8_MMA(ai, bj, At, Bt) do { __builtin_amdgcn_s_setprio(1); _Pragma("unroll") for (int m = 0; m < 4; ++m) _Pragma("unroll") for (int n = 0; n < 2; ++n) _Pragma("unroll") for (int k = 0; k < 2; ++k) \
;         acc[ai][bj][m][n] = __builtin_amdgcn_mfma_f32_16x16x32_bf16(Bt[n][k], At[m][k], acc[ai][bj][m][n], 0, 0, 0); __builtin_amdgcn_s_setprio(0); } while (0)
; #define PG8_WAIT_V(n) asm volatile("s_waitcnt vmcnt(" #n ")" ::: "memory")
; #define PG8_WAIT_L(n) asm volatile("s_waitcnt lgkmcnt(" #n ")" ::: "memory")
; #define PG8_BAR __builtin_amdgcn_s_barrier()
; #define PG8_SCHED __builtin_amdgcn_sched_barrier(0)
; template <class Epi, class Sched, bool ALIGN_EPI = false, bool SP2 = false>
; __device__ __forceinline__ void gemm_phase(PG8_LAS unsigned char* lds, const Gemm g, const Sched& S, const Epi& E) {
;     ...
;         for (int t = 0; t < nt; t += 2) {
;     ...
;             PG8_LDA(At, 1, 1); PG8_STAGE(PG8_SB(1, 0), b3, voffB); PG8_STAGE(PG8_SB(1, 1), b3 + hstep, voffB); PG8_STAGE(PG8_SA(1, 0), a3, voffA);
;             PG8_WAIT_V(8); PG8_WAIT_L(0); PG8_BAR; PG8_MMA(1, 0, At, B0); PG8_MMA(1, 1, At, B1); PG8_BAR; PG8_SCHED;
	s_add_i32 s2, s43, s22
	v_lshl_add_u64 v[158:159], v[158:159], 0, s[82:83]
	s_mov_b32 m0, s2
	ds_read_b128 v[186:189], v204 offset:49152
	ds_read_b128 v[190:193], v204 offset:50176
	ds_read_b128 v[194:197], v204 offset:51200
	ds_read_b128 v[198:201], v204 offset:52224
	ds_read_b128 v[206:209], v204 offset:53248
	ds_read_b128 v[212:215], v204 offset:54272
	ds_read_b128 v[230:233], v204 offset:55296
	ds_read_b128 v[234:237], v204 offset:56320
	global_load_lds_dwordx4 v[158:159], off
	v_lshl_add_u64 v[158:159], v[160:161], 0, s[82:83]
	s_add_i32 m0, s2, 0x2000
	s_add_i32 s2, s44, s22
	global_load_lds_dwordx4 v[158:159], off
	v_lshl_add_u64 v[158:159], v[162:163], 0, s[82:83]
	s_mov_b32 m0, s2
	s_nop 0
	global_load_lds_dwordx4 v[158:159], off
	v_lshl_add_u64 v[158:159], v[164:165], 0, s[82:83]
	s_add_i32 m0, s2, 0x2000
	s_nop 0
	global_load_lds_dwordx4 v[158:159], off
	v_lshl_add_u64 v[158:159], v[216:217], 0, s[82:83]
	s_mov_b32 m0, s29
	s_nop 0
	global_load_lds_dwordx4 v[158:159], off
	v_lshl_add_u64 v[158:159], v[238:239], 0, s[82:83]
	s_mov_b32 m0, s30
	s_nop 0
	global_load_lds_dwordx4 v[158:159], off
	s_waitcnt vmcnt(8)
	s_waitcnt lgkmcnt(0)
	s_barrier
	s_waitcnt lgkmcnt(0)
	v_mfma_f32_16x16x32_bf16 v[92:95], v[128:131], v[186:189], v[92:95]
	v_mfma_f32_16x16x32_bf16 v[88:91], v[136:139], v[186:189], v[88:91]
	v_mfma_f32_16x16x32_bf16 v[84:87], v[128:131], v[194:197], v[84:87]
	v_mfma_f32_16x16x32_bf16 v[80:83], v[136:139], v[194:197], v[80:83]
	v_mfma_f32_16x16x32_bf16 v[76:79], v[128:131], v[206:209], v[76:79]
	v_mfma_f32_16x16x32_bf16 v[72:75], v[136:139], v[206:209], v[72:75]
	v_mfma_f32_16x16x32_bf16 v[68:71], v[128:131], v[230:233], v[68:71]
	v_mfma_f32_16x16x32_bf16 v[64:67], v[136:139], v[230:233], v[64:67]
	v_mfma_f32_16x16x32_bf16 v[92:95], v[132:135], v[190:193], v[92:95]
	v_mfma_f32_16x16x32_bf16 v[88:91], v[140:143], v[190:193], v[88:91]
	v_mfma_f32_16x16x32_bf16 v[84:87], v[132:135], v[198:201], v[84:87]
	v_mfma_f32_16x16x32_bf16 v[80:83], v[140:143], v[198:201], v[80:83]
	v_mfma_f32_16x16x32_bf16 v[76:79], v[132:135], v[212:215], v[76:79]
	v_mfma_f32_16x16x32_bf16 v[72:75], v[140:143], v[212:215], v[72:75]
	v_mfma_f32_16x16x32_bf16 v[68:71], v[132:135], v[234:237], v[68:71]
	v_mfma_f32_16x16x32_bf16 v[64:67], v[140:143], v[234:237], v[64:67]
	v_mfma_f32_16x16x32_bf16 v[28:31], v[144:147], v[186:189], v[28:31]
	v_mfma_f32_16x16x32_bf16 v[24:27], v[178:181], v[186:189], v[24:27]
	v_mfma_f32_16x16x32_bf16 v[20:23], v[144:147], v[194:197], v[20:23]
	v_mfma_f32_16x16x32_bf16 v[16:19], v[178:181], v[194:197], v[16:19]
	v_mfma_f32_16x16x32_bf16 v[12:15], v[144:147], v[206:209], v[12:15]
	v_mfma_f32_16x16x32_bf16 v[8:11], v[178:181], v[206:209], v[8:11]
	v_mfma_f32_16x16x32_bf16 v[0:3], v[144:147], v[230:233], v[0:3]
	v_mfma_f32_16x16x32_bf16 v[4:7], v[178:181], v[230:233], v[4:7]
	v_mfma_f32_16x16x32_bf16 v[28:31], v[148:151], v[190:193], v[28:31]
	v_mfma_f32_16x16x32_bf16 v[24:27], v[182:185], v[190:193], v[24:27]
	v_mfma_f32_16x16x32_bf16 v[20:23], v[148:151], v[198:201], v[20:23]
	v_mfma_f32_16x16x32_bf16 v[16:19], v[182:185], v[198:201], v[16:19]
	v_mfma_f32_16x16x32_bf16 v[12:15], v[148:151], v[212:215], v[12:15]
	v_mfma_f32_16x16x32_bf16 v[8:11], v[182:185], v[212:215], v[8:11]
	v_mfma_f32_16x16x32_bf16 v[0:3], v[148:151], v[234:237], v[0:3]
	v_mfma_f32_16x16x32_bf16 v[4:7], v[182:185], v[234:237], v[4:7]
	s_barrier
	s_add_u32 s0, s0, 0x100
	s_addc_u32 s1, s1, 0
	s_add_u32 s40, s40, 0x100
	s_addc_u32 s41, s41, 0
	s_cmp_ge_i32 s42, s31
	s_mov_b32 s2, s42
	s_cbranch_scc0 .LBB0_363
	s_setprio 0

; template <class Epi, class Sched, bool ALIGN_EPI = false, bool SP2 = false>
; __device__ __forceinline__ void gemm_phase(PG8_LAS unsigned char* lds, const Gemm g, const Sched& S, const Epi& E) {
;     ...
;     f32x4 acc[2][2][4][2];
; #pragma unroll
;     for (int a = 0; a < 2; ++a)
; #pragma unroll
;         for (int b = 0; b < 2; ++b)
; #pragma unroll
;             for (int m = 0; m < 4; ++m)
; #pragma unroll
;                 for (int n = 0; n < 2; ++n) acc[a][b][m][n] = (f32x4){0.f, 0.f, 0.f, 0.f};
;     ...
;     for (;;) {
;         const bool has_next = S.next(ui + 1, nxt);
;         const char* nA = has_next ? (const char*)g.A + (size_t)nxt.pm * tstep : cA; const char* nB = has_next ? (const char*)g.Bt + (size_t)nxt.pn * tstep : cB;
;         for (int t = 0; t < nt; t += 2) {
.LBB0_390:
	v_mov_b32_e32 v123, 0
	s_andn2_b64 vcc, exec, s[50:51]
	v_mov_b32_e32 v122, v123
	v_mov_b32_e32 v121, v123
	v_mov_b32_e32 v120, v123
	v_mov_b32_e32 v127, v123
	v_mov_b32_e32 v126, v123
	v_mov_b32_e32 v125, v123
	v_mov_b32_e32 v124, v123
	v_mov_b32_e32 v119, v123
	v_mov_b32_e32 v118, v123
	v_mov_b32_e32 v117, v123
	v_mov_b32_e32 v116, v123
	v_mov_b32_e32 v115, v123
	v_mov_b32_e32 v114, v123
	v_mov_b32_e32 v113, v123
	v_mov_b32_e32 v112, v123
	v_mov_b32_e32 v111, v123
	v_mov_b32_e32 v110, v123
	v_mov_b32_e32 v109, v123
	v_mov_b32_e32 v108, v123
	s_waitcnt vmcnt(0)
	v_mov_b32_e32 v107, v123
	v_mov_b32_e32 v106, v123
	v_mov_b32_e32 v105, v123
	v_mov_b32_e32 v104, v123
	v_mov_b32_e32 v103, v123
	v_mov_b32_e32 v102, v123
	v_mov_b32_e32 v101, v123
	v_mov_b32_e32 v100, v123
	v_mov_b32_e32 v99, v123
	v_mov_b32_e32 v98, v123
	v_mov_b32_e32 v97, v123
	v_mov_b32_e32 v96, v123
	v_mov_b32_e32 v63, v123
	v_mov_b32_e32 v62, v123
	v_mov_b32_e32 v61, v123
	v_mov_b32_e32 v60, v123
	v_mov_b32_e32 v59, v123
	v_mov_b32_e32 v58, v123
	v_mov_b32_e32 v57, v123
	v_mov_b32_e32 v56, v123
	v_mov_b32_e32 v55, v123
	v_mov_b32_e32 v54, v123
	v_mov_b32_e32 v53, v123
	v_mov_b32_e32 v52, v123
	v_mov_b32_e32 v51, v123
	v_mov_b32_e32 v50, v123
	v_mov_b32_e32 v49, v123
	v_mov_b32_e32 v48, v123
	v_mov_b32_e32 v47, v123
	v_mov_b32_e32 v46, v123
	v_mov_b32_e32 v45, v123
	v_mov_b32_e32 v44, v123
	v_mov_b32_e32 v43, v123
	v_mov_b32_e32 v42, v123
	v_mov_b32_e32 v41, v123
	v_mov_b32_e32 v40, v123
	v_mov_b32_e32 v39, v123
	v_mov_b32_e32 v38, v123
	v_mov_b32_e32 v37, v123
	v_mov_b32_e32 v36, v123
	v_mov_b32_e32 v35, v123
	v_mov_b32_e32 v34, v123
	v_mov_b32_e32 v33, v123
	v_mov_b32_e32 v32, v123
	v_mov_b32_e32 v95, v123
	v_mov_b32_e32 v94, v123
	v_mov_b32_e32 v93, v123
	v_mov_b32_e32 v92, v123
	v_mov_b32_e32 v91, v123
	v_mov_b32_e32 v90, v123
	v_mov_b32_e32 v89, v123
	v_mov_b32_e32 v88, v123
	v_mov_b32_e32 v87, v123
	v_mov_b32_e32 v86, v123
	v_mov_b32_e32 v85, v123
	v_mov_b32_e32 v84, v123
	v_mov_b32_e32 v83, v123
	v_mov_b32_e32 v82, v123
	v_mov_b32_e32 v81, v123
	v_mov_b32_e32 v80, v123
	v_mov_b32_e32 v79, v123
	v_mov_b32_e32 v78, v123
	v_mov_b32_e32 v77, v123
	v_mov_b32_e32 v76, v123
	v_mov_b32_e32 v75, v123
	v_mov_b32_e32 v74, v123
	v_mov_b32_e32 v73, v123
	v_mov_b32_e32 v72, v123
	v_mov_b32_e32 v71, v123
	v_mov_b32_e32 v70, v123
	v_mov_b32_e32 v69, v123
	v_mov_b32_e32 v68, v123
	v_mov_b32_e32 v67, v123
	v_mov_b32_e32 v66, v123
	v_mov_b32_e32 v65, v123
	v_mov_b32_e32 v64, v123
	v_mov_b32_e32 v31, v123
	v_mov_b32_e32 v30, v123
	v_mov_b32_e32 v29, v123
	v_mov_b32_e32 v28, v123
	v_mov_b32_e32 v27, v123
	v_mov_b32_e32 v26, v123
	v_mov_b32_e32 v25, v123
	v_mov_b32_e32 v24, v123
	v_mov_b32_e32 v23, v123
	v_mov_b32_e32 v22, v123
	v_mov_b32_e32 v21, v123
	v_mov_b32_e32 v20, v123
	v_mov_b32_e32 v19, v123
	v_mov_b32_e32 v18, v123
	v_mov_b32_e32 v17, v123
	v_mov_b32_e32 v16, v123
	v_mov_b32_e32 v15, v123
	v_mov_b32_e32 v14, v123
	v_mov_b32_e32 v13, v123
	v_mov_b32_e32 v12, v123
	v_mov_b32_e32 v11, v123
	v_mov_b32_e32 v10, v123
	v_mov_b32_e32 v9, v123
	v_mov_b32_e32 v8, v123
	v_mov_b32_e32 v7, v123
	v_mov_b32_e32 v6, v123
	v_mov_b32_e32 v5, v123
	v_mov_b32_e32 v4, v123
	v_mov_b32_e32 v3, v123
	v_mov_b32_e32 v2, v123
	v_mov_b32_e32 v1, v123
	v_mov_b32_e32 v0, v123
	s_cbranch_vccnz .LBB0_393
	s_add_u32 s0, s0, 0x80
	s_addc_u32 s1, s1, 0
	s_add_u32 s40, s2, 0x100
	v_mov_b32_e32 v0, 0
	s_addc_u32 s41, s3, 0
	s_mov_b32 s2, 0
	v_mov_b32_e32 v1, v0
	v_mov_b32_e32 v2, v0
	v_mov_b32_e32 v3, v0
	v_mov_b32_e32 v4, v0
	v_mov_b32_e32 v5, v0
	v_mov_b32_e32 v6, v0
	v_mov_b32_e32 v7, v0
	v_mov_b32_e32 v8, v0
	v_mov_b32_e32 v9, v0
	v_mov_b32_e32 v10, v0
	v_mov_b32_e32 v11, v0
	v_mov_b32_e32 v12, v0
	v_mov_b32_e32 v13, v0
	v_mov_b32_e32 v14, v0
	v_mov_b32_e32 v15, v0
	v_mov_b32_e32 v16, v0
	v_mov_b32_e32 v17, v0
	v_mov_b32_e32 v18, v0
	v_mov_b32_e32 v19, v0
	v_mov_b32_e32 v20, v0
	v_mov_b32_e32 v21, v0
	v_mov_b32_e32 v22, v0
	v_mov_b32_e32 v23, v0
	v_mov_b32_e32 v24, v0
	v_mov_b32_e32 v25, v0
	v_mov_b32_e32 v26, v0
	v_mov_b32_e32 v27, v0
	v_mov_b32_e32 v28, v0
	v_mov_b32_e32 v29, v0
	v_mov_b32_e32 v30, v0
	v_mov_b32_e32 v31, v0
	v_mov_b32_e32 v64, v0
	v_mov_b32_e32 v65, v0
	v_mov_b32_e32 v66, v0
	v_mov_b32_e32 v67, v0
	v_mov_b32_e32 v68, v0
	v_mov_b32_e32 v69, v0
	v_mov_b32_e32 v70, v0
	v_mov_b32_e32 v71, v0
	v_mov_b32_e32 v72, v0
	v_mov_b32_e32 v73, v0
	v_mov_b32_e32 v74, v0
	v_mov_b32_e32 v75, v0
	v_mov_b32_e32 v76, v0
	v_mov_b32_e32 v77, v0
	v_mov_b32_e32 v78, v0
	v_mov_b32_e32 v79, v0
	v_mov_b32_e32 v80, v0
	v_mov_b32_e32 v81, v0
	v_mov_b32_e32 v82, v0
	v_mov_b32_e32 v83, v0
	v_mov_b32_e32 v84, v0
	v_mov_b32_e32 v85, v0
	v_mov_b32_e32 v86, v0
	v_mov_b32_e32 v87, v0
	v_mov_b32_e32 v88, v0
	v_mov_b32_e32 v89, v0
	v_mov_b32_e32 v90, v0
	v_mov_b32_e32 v91, v0
	v_mov_b32_e32 v92, v0
	v_mov_b32_e32 v93, v0
	v_mov_b32_e32 v94, v0
	v_mov_b32_e32 v95, v0
	v_mov_b32_e32 v32, v0
	v_mov_b32_e32 v33, v0
	v_mov_b32_e32 v34, v0
	v_mov_b32_e32 v35, v0
	v_mov_b32_e32 v36, v0
	v_mov_b32_e32 v37, v0
	v_mov_b32_e32 v38, v0
	v_mov_b32_e32 v39, v0
	v_mov_b32_e32 v40, v0
	v_mov_b32_e32 v41, v0
	v_mov_b32_e32 v42, v0
	v_mov_b32_e32 v43, v0
	v_mov_b32_e32 v44, v0
	v_mov_b32_e32 v45, v0
	v_mov_b32_e32 v46, v0
	v_mov_b32_e32 v47, v0
	v_mov_b32_e32 v48, v0
	v_mov_b32_e32 v49, v0
	v_mov_b32_e32 v50, v0
	v_mov_b32_e32 v51, v0
	v_mov_b32_e32 v52, v0
	v_mov_b32_e32 v53, v0
	v_mov_b32_e32 v54, v0
	v_mov_b32_e32 v55, v0
	v_mov_b32_e32 v56, v0
	v_mov_b32_e32 v57, v0
	v_mov_b32_e32 v58, v0
	v_mov_b32_e32 v59, v0
	v_mov_b32_e32 v60, v0
	v_mov_b32_e32 v61, v0
	v_mov_b32_e32 v62, v0
	v_mov_b32_e32 v63, v0
	v_mov_b32_e32 v96, v0
	v_mov_b32_e32 v97, v0
	v_mov_b32_e32 v98, v0
	v_mov_b32_e32 v99, v0
	v_mov_b32_e32 v100, v0
	v_mov_b32_e32 v101, v0
	v_mov_b32_e32 v102, v0
	v_mov_b32_e32 v103, v0
	v_mov_b32_e32 v104, v0
	v_mov_b32_e32 v105, v0
	v_mov_b32_e32 v106, v0
	v_mov_b32_e32 v107, v0
	v_mov_b32_e32 v108, v0
	v_mov_b32_e32 v109, v0
	v_mov_b32_e32 v110, v0
	v_mov_b32_e32 v111, v0
	v_mov_b32_e32 v112, v0
	v_mov_b32_e32 v113, v0
	v_mov_b32_e32 v114, v0
	v_mov_b32_e32 v115, v0
	v_mov_b32_e32 v116, v0
	v_mov_b32_e32 v117, v0
	v_mov_b32_e32 v118, v0
	v_mov_b32_e32 v119, v0
	v_mov_b32_e32 v124, v0
	v_mov_b32_e32 v125, v0
	v_mov_b32_e32 v126, v0
	v_mov_b32_e32 v127, v0
	v_mov_b32_e32 v120, v0
	v_mov_b32_e32 v121, v0
	v_mov_b32_e32 v122, v0
	v_mov_b32_e32 v123, v0
	v_readfirstlane_b32 s100, v211
	s_cmp_ge_u32 s100, 0x100
	s_cbranch_scc0 .Lprio_skip8
	s_setprio 1
; #define PG8_STAGE(bufoff, gbase, voff) do { _Pragma("unroll") for (int _i = 0; _i < 2; ++_i) \
;         __builtin_amdgcn_global_load_lds((const unsigned*)((const char*)(gbase) + (voff)[_i]), (PG8_LAS unsigned*)(lds + (bufoff) + ldsw + _i * 8192), 16, 0, 0); } while (0)
; #define PG8_LDA(dst, b, h) do { _Pragma("unroll") for (int m = 0; m < 4; ++m) _Pragma("unroll") for (int k = 0; k < 2; ++k) dst[m][k] = *(const PG8_LAS bf16x8*)(lds + PG8_SA(b, h) + aoff + m * 2048 + k * 1024); } while (0)
; #define PG8_LDB(dst, b, h) do { _Pragma("unroll") for (int n = 0; n < 2; ++n) _Pragma("unroll") for (int k = 0; k < 2; ++k) dst[n][k] = *(const PG8_LAS bf16x8*)(lds + PG8_SB(b, h) + boff + n * 2048 + k * 1024); } while (0)
; #define PG8_MMA(ai, bj, At, Bt) do { __builtin_amdgcn_s_setprio(1); _Pragma("unroll") for (int m = 0; m < 4; ++m) _Pragma("unroll") for (int n = 0; n < 2; ++n) _Pragma("unroll") for (int k = 0; k < 2; ++k) \
;         acc[ai][bj][m][n] = __builtin_amdgcn_mfma_f32_16x16x32_bf16(Bt[n][k], At[m][k], acc[ai][bj][m][n], 0, 0, 0); __builtin_amdgcn_s_setprio(0); } while (0)
; #define PG8_WAIT_V(n) asm volatile("s_waitcnt vmcnt(" #n ")" ::: "memory")
; #define PG8_WAIT_L(n) asm volatile("s_waitcnt lgkmcnt(" #n ")" ::: "memory")
; #define PG8_BAR __builtin_amdgcn_s_barrier()
; #define PG8_SCHED __builtin_amdgcn_sched_barrier(0)
; template <class Epi, class Sched, bool ALIGN_EPI = false, bool SP2 = false>
; __device__ __forceinline__ void gemm_phase(PG8_LAS unsigned char* lds, const Gemm g, const Sched& S, const Epi& E) {
;     ...
;             PG8_LDB(B0, 0, 0); PG8_LDB(B1, 0, 1); PG8_SCHED; PG8_LDA(At, 0, 0); PG8_STAGE(PG8_SA(1, 1), a1 + hstep, voffA);
;             PG8_WAIT_V(8); PG8_WAIT_L(0); PG8_BAR; PG8_MMA(0, 0, At, B0); PG8_MMA(0, 1, At, B1); PG8_BAR; PG8_SCHED;
;             PG8_LDA(At, 0, 1); PG8_STAGE(PG8_SB(0, 0), b2, voffB); PG8_STAGE(PG8_SB(0, 1), b2 + hstep, voffB); PG8_STAGE(PG8_SA(0, 0), a2, voffA);
.Lprio_skip8:
.LBB0_392:
	s_add_i32 s42, s2, 2
	s_add_u32 s43, s0, 0x80
	s_addc_u32 s3, s1, 0
	s_add_i32 s48, 0, 0x10000
	s_cmp_eq_u32 s34, s2
	s_cselect_b32 s3, s7, s3
	s_cselect_b32 s2, s6, s43
	s_cselect_b32 s45, s71, s41
	s_cselect_b32 s44, s70, s40
	s_add_i32 s43, 0, 0x14000
	v_add_u32_e32 v140, s48, v193
	v_add_u32_e32 v152, s43, v193
	ds_read_b128 v[128:131], v140
	ds_read_b128 v[132:135], v140 offset:1024
	ds_read_b128 v[136:139], v140 offset:2048
	ds_read_b128 v[140:143], v140 offset:3072
	ds_read_b128 v[172:175], v152
	ds_read_b128 v[176:179], v152 offset:1024
	ds_read_b128 v[180:183], v152 offset:2048
	ds_read_b128 v[184:187], v152 offset:3072
	v_lshl_add_u64 v[158:159], s[0:1], 0, v[168:169]
	s_add_i32 m0, s23, 0xc000
	ds_read_b128 v[188:191], v195
	ds_read_b128 v[196:199], v195 offset:1024
	ds_read_b128 v[200:203], v195 offset:2048
	ds_read_b128 v[204:207], v195 offset:3072
	ds_read_b128 v[212:215], v195 offset:4096
	ds_read_b128 v[230:233], v195 offset:5120
	ds_read_b128 v[234:237], v195 offset:6144
	ds_read_b128 v[238:241], v195 offset:7168
	global_load_lds_dwordx4 v[158:159], off
	v_lshl_add_u64 v[158:159], s[0:1], 0, v[170:171]
	s_add_i32 m0, s23, 0xe000
	s_nop 0
	global_load_lds_dwordx4 v[158:159], off
	s_waitcnt vmcnt(8)
	s_waitcnt lgkmcnt(0)
	s_barrier
	s_waitcnt lgkmcnt(0)
	v_mfma_f32_16x16x32_bf16 v[120:123], v[128:131], v[188:191], v[120:123]
	v_mfma_f32_16x16x32_bf16 v[124:127], v[136:139], v[188:191], v[124:127]
	v_mfma_f32_16x16x32_bf16 v[116:119], v[128:131], v[200:203], v[116:119]
	v_mfma_f32_16x16x32_bf16 v[112:115], v[136:139], v[200:203], v[112:115]
	v_mfma_f32_16x16x32_bf16 v[108:111], v[128:131], v[212:215], v[108:111]
	v_mfma_f32_16x16x32_bf16 v[104:107], v[136:139], v[212:215], v[104:107]
	v_mfma_f32_16x16x32_bf16 v[100:103], v[128:131], v[234:237], v[100:103]
	v_mfma_f32_16x16x32_bf16 v[96:99], v[136:139], v[234:237], v[96:99]
	v_mfma_f32_16x16x32_bf16 v[120:123], v[132:135], v[196:199], v[120:123]
	v_mfma_f32_16x16x32_bf16 v[124:127], v[140:143], v[196:199], v[124:127]
	v_mfma_f32_16x16x32_bf16 v[116:119], v[132:135], v[204:207], v[116:119]
	v_mfma_f32_16x16x32_bf16 v[112:115], v[140:143], v[204:207], v[112:115]
	v_mfma_f32_16x16x32_bf16 v[108:111], v[132:135], v[230:233], v[108:111]
	v_mfma_f32_16x16x32_bf16 v[104:107], v[140:143], v[230:233], v[104:107]
	v_mfma_f32_16x16x32_bf16 v[100:103], v[132:135], v[238:241], v[100:103]
	v_mfma_f32_16x16x32_bf16 v[96:99], v[140:143], v[238:241], v[96:99]
	v_mfma_f32_16x16x32_bf16 v[60:63], v[172:175], v[188:191], v[60:63]
	v_mfma_f32_16x16x32_bf16 v[56:59], v[180:183], v[188:191], v[56:59]
	v_mfma_f32_16x16x32_bf16 v[52:55], v[172:175], v[200:203], v[52:55]
	v_mfma_f32_16x16x32_bf16 v[48:51], v[180:183], v[200:203], v[48:51]
	v_mfma_f32_16x16x32_bf16 v[44:47], v[172:175], v[212:215], v[44:47]
	v_mfma_f32_16x16x32_bf16 v[40:43], v[180:183], v[212:215], v[40:43]
	v_mfma_f32_16x16x32_bf16 v[36:39], v[172:175], v[234:237], v[36:39]
	v_mfma_f32_16x16x32_bf16 v[32:35], v[180:183], v[234:237], v[32:35]
	v_mfma_f32_16x16x32_bf16 v[60:63], v[176:179], v[196:199], v[60:63]
	v_mfma_f32_16x16x32_bf16 v[56:59], v[184:187], v[196:199], v[56:59]
	v_mfma_f32_16x16x32_bf16 v[52:55], v[176:179], v[204:207], v[52:55]
	v_mfma_f32_16x16x32_bf16 v[48:51], v[184:187], v[204:207], v[48:51]
	v_mfma_f32_16x16x32_bf16 v[44:47], v[176:179], v[230:233], v[44:47]
	v_mfma_f32_16x16x32_bf16 v[40:43], v[184:187], v[230:233], v[40:43]
	v_mfma_f32_16x16x32_bf16 v[36:39], v[176:179], v[238:241], v[36:39]
	v_mfma_f32_16x16x32_bf16 v[32:35], v[184:187], v[238:241], v[32:35]
	s_barrier
	s_add_i32 s48, s48, s22
	v_lshl_add_u64 v[158:159], s[44:45], 0, v[148:149]
	s_mov_b32 m0, s48
	ds_read_b128 v[188:191], v195 offset:16384
	ds_read_b128 v[196:199], v195 offset:17408
	ds_read_b128 v[200:203], v195 offset:18432
	ds_read_b128 v[204:207], v195 offset:19456
	ds_read_b128 v[212:215], v195 offset:20480
	ds_read_b128 v[230:233], v195 offset:21504
	ds_read_b128 v[234:237], v195 offset:22528
	ds_read_b128 v[238:241], v195 offset:23552
	global_load_lds_dwordx4 v[158:159], off
	s_add_i32 m0, s48, 0x2000
	v_lshl_add_u64 v[160:161], s[44:45], 0, v[144:145]
	s_add_u32 s44, s44, s8
	s_addc_u32 s45, s45, s9
	s_add_i32 s43, s43, s22
	global_load_lds_dwordx4 v[160:161], off
	v_lshl_add_u64 v[162:163], s[44:45], 0, v[148:149]
	s_mov_b32 m0, s43
	v_lshl_add_u64 v[164:165], s[44:45], 0, v[144:145]
	global_load_lds_dwordx4 v[162:163], off
	s_add_i32 m0, s43, 0x2000
	v_lshl_add_u64 v[208:209], s[2:3], 0, v[150:151]
	global_load_lds_dwordx4 v[164:165], off
	s_mov_b32 m0, s23
	v_lshl_add_u64 v[216:217], s[2:3], 0, v[146:147]
	global_load_lds_dwordx4 v[208:209], off
	s_mov_b32 m0, s24
	s_nop 0
	global_load_lds_dwordx4 v[216:217], off
	s_waitcnt vmcnt(8)
	s_waitcnt lgkmcnt(0)
	s_barrier
; #define PG8_STAGE(bufoff, gbase, voff) do { _Pragma("unroll") for (int _i = 0; _i < 2; ++_i) \
;         __builtin_amdgcn_global_load_lds((const unsigned*)((const char*)(gbase) + (voff)[_i]), (PG8_LAS unsigned*)(lds + (bufoff) + ldsw + _i * 8192), 16, 0, 0); } while (0)
; #define PG8_LDA(dst, b, h) do { _Pragma("unroll") for (int m = 0; m < 4; ++m) _Pragma("unroll") for (int k = 0; k < 2; ++k) dst[m][k] = *(const PG8_LAS bf16x8*)(lds + PG8_SA(b, h) + aoff + m * 2048 + k * 1024); } while (0)
; #define PG8_LDB(dst, b, h) do { _Pragma("unroll") for (int n = 0; n < 2; ++n) _Pragma("unroll") for (int k = 0; k < 2; ++k) dst[n][k] = *(const PG8_LAS bf16x8*)(lds + PG8_SB(b, h) + boff + n * 2048 + k * 1024); } while (0)
; #define PG8_MMA(ai, bj, At, Bt) do { __builtin_amdgcn_s_setprio(1); _Pragma("unroll") for (int m = 0; m < 4; ++m) _Pragma("unroll") for (int n = 0; n < 2; ++n) _Pragma("unroll") for (int k = 0; k < 2; ++k) \
;         acc[ai][bj][m][n] = __builtin_amdgcn_mfma_f32_16x16x32_bf16(Bt[n][k], At[m][k], acc[ai][bj][m][n], 0, 0, 0); __builtin_amdgcn_s_setprio(0); } while (0)
; #define PG8_WAIT_V(n) asm volatile("s_waitcnt vmcnt(" #n ")" ::: "memory")
; #define PG8_WAIT_L(n) asm volatile("s_waitcnt lgkmcnt(" #n ")" ::: "memory")
; #define PG8_BAR __builtin_amdgcn_s_barrier()
; #define PG8_SCHED __builtin_amdgcn_sched_barrier(0)
; template <class Epi, class Sched, bool ALIGN_EPI = false, bool SP2 = false>
; __device__ __forceinline__ void gemm_phase(PG8_LAS unsigned char* lds, const Gemm g, const Sched& S, const Epi& E) {
;     ...
;             PG8_WAIT_V(8); PG8_WAIT_L(0); PG8_BAR; PG8_MMA(1, 0, At, B0); PG8_MMA(1, 1, At, B1); PG8_BAR; PG8_SCHED;
;             PG8_LDB(B0, 1, 0); PG8_LDB(B1, 1, 1); PG8_SCHED; PG8_LDA(At, 1, 0); PG8_STAGE(PG8_SA(0, 1), a2 + hstep, voffA);
;             PG8_WAIT_V(8); PG8_WAIT_L(0); PG8_BAR; PG8_MMA(0, 0, At, B0); PG8_MMA(0, 1, At, B1); PG8_BAR; PG8_SCHED;
	s_waitcnt lgkmcnt(0)
	v_mfma_f32_16x16x32_bf16 v[92:95], v[128:131], v[188:191], v[92:95]
	v_mfma_f32_16x16x32_bf16 v[88:91], v[136:139], v[188:191], v[88:91]
	v_mfma_f32_16x16x32_bf16 v[84:87], v[128:131], v[200:203], v[84:87]
	v_mfma_f32_16x16x32_bf16 v[80:83], v[136:139], v[200:203], v[80:83]
	v_mfma_f32_16x16x32_bf16 v[76:79], v[128:131], v[212:215], v[76:79]
	v_mfma_f32_16x16x32_bf16 v[72:75], v[136:139], v[212:215], v[72:75]
	v_mfma_f32_16x16x32_bf16 v[68:71], v[128:131], v[234:237], v[68:71]
	v_mfma_f32_16x16x32_bf16 v[64:67], v[136:139], v[234:237], v[64:67]
	v_mfma_f32_16x16x32_bf16 v[92:95], v[132:135], v[196:199], v[92:95]
	v_mfma_f32_16x16x32_bf16 v[88:91], v[140:143], v[196:199], v[88:91]
	v_mfma_f32_16x16x32_bf16 v[84:87], v[132:135], v[204:207], v[84:87]
	v_mfma_f32_16x16x32_bf16 v[80:83], v[140:143], v[204:207], v[80:83]
	v_mfma_f32_16x16x32_bf16 v[76:79], v[132:135], v[230:233], v[76:79]
	v_mfma_f32_16x16x32_bf16 v[72:75], v[140:143], v[230:233], v[72:75]
	v_mfma_f32_16x16x32_bf16 v[68:71], v[132:135], v[238:241], v[68:71]
	v_mfma_f32_16x16x32_bf16 v[64:67], v[140:143], v[238:241], v[64:67]
	v_mfma_f32_16x16x32_bf16 v[28:31], v[172:175], v[188:191], v[28:31]
	v_mfma_f32_16x16x32_bf16 v[24:27], v[180:183], v[188:191], v[24:27]
	v_mfma_f32_16x16x32_bf16 v[20:23], v[172:175], v[200:203], v[20:23]
	v_mfma_f32_16x16x32_bf16 v[16:19], v[180:183], v[200:203], v[16:19]
	v_mfma_f32_16x16x32_bf16 v[12:15], v[172:175], v[212:215], v[12:15]
	v_mfma_f32_16x16x32_bf16 v[8:11], v[180:183], v[212:215], v[8:11]
	v_mfma_f32_16x16x32_bf16 v[4:7], v[172:175], v[234:237], v[4:7]
	v_mfma_f32_16x16x32_bf16 v[0:3], v[180:183], v[234:237], v[0:3]
	v_mfma_f32_16x16x32_bf16 v[28:31], v[176:179], v[196:199], v[28:31]
	v_mfma_f32_16x16x32_bf16 v[24:27], v[184:187], v[196:199], v[24:27]
	v_mfma_f32_16x16x32_bf16 v[20:23], v[176:179], v[204:207], v[20:23]
	v_mfma_f32_16x16x32_bf16 v[16:19], v[184:187], v[204:207], v[16:19]
	v_mfma_f32_16x16x32_bf16 v[12:15], v[176:179], v[230:233], v[12:15]
	v_mfma_f32_16x16x32_bf16 v[8:11], v[184:187], v[230:233], v[8:11]
	v_mfma_f32_16x16x32_bf16 v[4:7], v[176:179], v[238:241], v[4:7]
	v_mfma_f32_16x16x32_bf16 v[0:3], v[184:187], v[238:241], v[0:3]
	s_barrier
	s_add_i32 s43, 0, 0x18000
	s_add_i32 s44, 0, 0x1c000
	v_add_u32_e32 v140, s43, v193
	v_add_u32_e32 v152, s44, v193
	ds_read_b128 v[128:131], v140
	ds_read_b128 v[132:135], v140 offset:1024
	ds_read_b128 v[136:139], v140 offset:2048
	ds_read_b128 v[140:143], v140 offset:3072
	ds_read_b128 v[172:175], v152
	ds_read_b128 v[176:179], v152 offset:1024
	ds_read_b128 v[180:183], v152 offset:2048
	ds_read_b128 v[184:187], v152 offset:3072
	s_add_u32 s2, s2, s8
	s_addc_u32 s3, s3, s9
	s_mov_b32 m0, s25
	v_lshl_add_u64 v[242:243], s[2:3], 0, v[150:151]
	ds_read_b128 v[188:191], v195 offset:32768
	ds_read_b128 v[196:199], v195 offset:33792
	ds_read_b128 v[200:203], v195 offset:34816
	ds_read_b128 v[204:207], v195 offset:35840
	ds_read_b128 v[212:215], v195 offset:36864
	ds_read_b128 v[230:233], v195 offset:37888
	ds_read_b128 v[234:237], v195 offset:38912
	ds_read_b128 v[238:241], v195 offset:39936
	global_load_lds_dwordx4 v[242:243], off
	v_lshl_add_u64 v[242:243], s[2:3], 0, v[146:147]
	s_mov_b32 m0, s28
	s_nop 0
	global_load_lds_dwordx4 v[242:243], off
	s_waitcnt vmcnt(8)
	s_waitcnt lgkmcnt(0)
	s_barrier
	s_waitcnt lgkmcnt(0)
	v_mfma_f32_16x16x32_bf16 v[120:123], v[128:131], v[188:191], v[120:123]
	v_mfma_f32_16x16x32_bf16 v[124:127], v[136:139], v[188:191], v[124:127]
	v_mfma_f32_16x16x32_bf16 v[116:119], v[128:131], v[200:203], v[116:119]
	v_mfma_f32_16x16x32_bf16 v[112:115], v[136:139], v[200:203], v[112:115]
	v_mfma_f32_16x16x32_bf16 v[108:111], v[128:131], v[212:215], v[108:111]
	v_mfma_f32_16x16x32_bf16 v[104:107], v[136:139], v[212:215], v[104:107]
	v_mfma_f32_16x16x32_bf16 v[100:103], v[128:131], v[234:237], v[100:103]
	v_mfma_f32_16x16x32_bf16 v[96:99], v[136:139], v[234:237], v[96:99]
	v_mfma_f32_16x16x32_bf16 v[120:123], v[132:135], v[196:199], v[120:123]
	v_mfma_f32_16x16x32_bf16 v[124:127], v[140:143], v[196:199], v[124:127]
	v_mfma_f32_16x16x32_bf16 v[116:119], v[132:135], v[204:207], v[116:119]
	v_mfma_f32_16x16x32_bf16 v[112:115], v[140:143], v[204:207], v[112:115]
	v_mfma_f32_16x16x32_bf16 v[108:111], v[132:135], v[230:233], v[108:111]
	v_mfma_f32_16x16x32_bf16 v[104:107], v[140:143], v[230:233], v[104:107]
	v_mfma_f32_16x16x32_bf16 v[100:103], v[132:135], v[238:241], v[100:103]
	v_mfma_f32_16x16x32_bf16 v[96:99], v[140:143], v[238:241], v[96:99]
	v_mfma_f32_16x16x32_bf16 v[60:63], v[172:175], v[188:191], v[60:63]
	v_mfma_f32_16x16x32_bf16 v[56:59], v[180:183], v[188:191], v[56:59]
	v_mfma_f32_16x16x32_bf16 v[52:55], v[172:175], v[200:203], v[52:55]
	v_mfma_f32_16x16x32_bf16 v[48:51], v[180:183], v[200:203], v[48:51]
	v_mfma_f32_16x16x32_bf16 v[44:47], v[172:175], v[212:215], v[44:47]
	v_mfma_f32_16x16x32_bf16 v[40:43], v[180:183], v[212:215], v[40:43]
	v_mfma_f32_16x16x32_bf16 v[36:39], v[172:175], v[234:237], v[36:39]
	v_mfma_f32_16x16x32_bf16 v[32:35], v[180:183], v[234:237], v[32:35]
	v_mfma_f32_16x16x32_bf16 v[60:63], v[176:179], v[196:199], v[60:63]
	v_mfma_f32_16x16x32_bf16 v[56:59], v[184:187], v[196:199], v[56:59]
	v_mfma_f32_16x16x32_bf16 v[52:55], v[176:179], v[204:207], v[52:55]
	v_mfma_f32_16x16x32_bf16 v[48:51], v[184:187], v[204:207], v[48:51]
	v_mfma_f32_16x16x32_bf16 v[44:47], v[176:179], v[230:233], v[44:47]
	v_mfma_f32_16x16x32_bf16 v[40:43], v[184:187], v[230:233], v[40:43]
	v_mfma_f32_16x16x32_bf16 v[36:39], v[176:179], v[238:241], v[36:39]
	v_mfma_f32_16x16x32_bf16 v[32:35], v[184:187], v[238:241], v[32:35]
	s_barrier
; #define PG8_STAGE(bufoff, gbase, voff) do { _Pragma("unroll") for (int _i = 0; _i < 2; ++_i) \
;         __builtin_amdgcn_global_load_lds((const unsigned*)((const char*)(gbase) + (voff)[_i]), (PG8_LAS unsigned*)(lds + (bufoff) + ldsw + _i * 8192), 16, 0, 0); } while (0)
; #define PG8_LDA(dst, b, h) do { _Pragma("unroll") for (int m = 0; m < 4; ++m) _Pragma("unroll") for (int k = 0; k < 2; ++k) dst[m][k] = *(const PG8_LAS bf16x8*)(lds + PG8_SA(b, h) + aoff + m * 2048 + k * 1024); } while (0)
; #define PG8_MMA(ai, bj, At, Bt) do { __builtin_amdgcn_s_setprio(1); _Pragma("unroll") for (int m = 0; m < 4; ++m) _Pragma("unroll") for (int n = 0; n < 2; ++n) _Pragma("unroll") for (int k = 0; k < 2; ++k) \
;         acc[ai][bj][m][n] = __builtin_amdgcn_mfma_f32_16x16x32_bf16(Bt[n][k], At[m][k], acc[ai][bj][m][n], 0, 0, 0); __builtin_amdgcn_s_setprio(0); } while (0)
; #define PG8_WAIT_V(n) asm volatile("s_waitcnt vmcnt(" #n ")" ::: "memory")
; #define PG8_WAIT_L(n) asm volatile("s_waitcnt lgkmcnt(" #n ")" ::: "memory")
; #define PG8_BAR __builtin_amdgcn_s_barrier()
; #define PG8_SCHED __builtin_amdgcn_sched_barrier(0)
; template <class Epi, class Sched, bool ALIGN_EPI = false, bool SP2 = false>
; __device__ __forceinline__ void gemm_phase(PG8_LAS unsigned char* lds, const Gemm g, const Sched& S, const Epi& E) {
;     ...
;         for (int t = 0; t < nt; t += 2) {
;             const bool last = (t == nt - 2);
;     ...
;             PG8_LDA(At, 1, 1); PG8_STAGE(PG8_SB(1, 0), b3, voffB); PG8_STAGE(PG8_SB(1, 1), b3 + hstep, voffB); PG8_STAGE(PG8_SA(1, 0), a3, voffA);
;             PG8_WAIT_V(8); PG8_WAIT_L(0); PG8_BAR; PG8_MMA(1, 0, At, B0); PG8_MMA(1, 1, At, B1); PG8_BAR; PG8_SCHED;
	s_add_i32 s2, s43, s22
	v_lshl_add_u64 v[158:159], v[158:159], 0, s[82:83]
	s_mov_b32 m0, s2
	ds_read_b128 v[188:191], v195 offset:49152
	ds_read_b128 v[196:199], v195 offset:50176
	ds_read_b128 v[200:203], v195 offset:51200
	ds_read_b128 v[204:207], v195 offset:52224
	ds_read_b128 v[212:215], v195 offset:53248
	ds_read_b128 v[230:233], v195 offset:54272
	ds_read_b128 v[234:237], v195 offset:55296
	ds_read_b128 v[238:241], v195 offset:56320
	global_load_lds_dwordx4 v[158:159], off
	v_lshl_add_u64 v[158:159], v[160:161], 0, s[82:83]
	s_add_i32 m0, s2, 0x2000
	s_add_i32 s2, s44, s22
	global_load_lds_dwordx4 v[158:159], off
	v_lshl_add_u64 v[158:159], v[162:163], 0, s[82:83]
	s_mov_b32 m0, s2
	s_nop 0
	global_load_lds_dwordx4 v[158:159], off
	v_lshl_add_u64 v[158:159], v[164:165], 0, s[82:83]
	s_add_i32 m0, s2, 0x2000
	s_nop 0
	global_load_lds_dwordx4 v[158:159], off
	v_lshl_add_u64 v[158:159], v[208:209], 0, s[82:83]
	s_mov_b32 m0, s29
	s_nop 0
	global_load_lds_dwordx4 v[158:159], off
	v_lshl_add_u64 v[158:159], v[216:217], 0, s[82:83]
	s_mov_b32 m0, s30
	s_nop 0
	global_load_lds_dwordx4 v[158:159], off
	s_waitcnt vmcnt(8)
	s_waitcnt lgkmcnt(0)
	s_barrier
	s_waitcnt lgkmcnt(0)
	v_mfma_f32_16x16x32_bf16 v[92:95], v[128:131], v[188:191], v[92:95]
	v_mfma_f32_16x16x32_bf16 v[88:91], v[136:139], v[188:191], v[88:91]
	v_mfma_f32_16x16x32_bf16 v[84:87], v[128:131], v[200:203], v[84:87]
	v_mfma_f32_16x16x32_bf16 v[80:83], v[136:139], v[200:203], v[80:83]
	v_mfma_f32_16x16x32_bf16 v[76:79], v[128:131], v[212:215], v[76:79]
	v_mfma_f32_16x16x32_bf16 v[72:75], v[136:139], v[212:215], v[72:75]
	v_mfma_f32_16x16x32_bf16 v[68:71], v[128:131], v[234:237], v[68:71]
	v_mfma_f32_16x16x32_bf16 v[64:67], v[136:139], v[234:237], v[64:67]
	v_mfma_f32_16x16x32_bf16 v[92:95], v[132:135], v[196:199], v[92:95]
	v_mfma_f32_16x16x32_bf16 v[88:91], v[140:143], v[196:199], v[88:91]
	v_mfma_f32_16x16x32_bf16 v[84:87], v[132:135], v[204:207], v[84:87]
	v_mfma_f32_16x16x32_bf16 v[80:83], v[140:143], v[204:207], v[80:83]
	v_mfma_f32_16x16x32_bf16 v[76:79], v[132:135], v[230:233], v[76:79]
	v_mfma_f32_16x16x32_bf16 v[72:75], v[140:143], v[230:233], v[72:75]
	v_mfma_f32_16x16x32_bf16 v[68:71], v[132:135], v[238:241], v[68:71]
	v_mfma_f32_16x16x32_bf16 v[64:67], v[140:143], v[238:241], v[64:67]
	v_mfma_f32_16x16x32_bf16 v[28:31], v[172:175], v[188:191], v[28:31]
	v_mfma_f32_16x16x32_bf16 v[24:27], v[180:183], v[188:191], v[24:27]
	v_mfma_f32_16x16x32_bf16 v[20:23], v[172:175], v[200:203], v[20:23]
	v_mfma_f32_16x16x32_bf16 v[16:19], v[180:183], v[200:203], v[16:19]
	v_mfma_f32_16x16x32_bf16 v[12:15], v[172:175], v[212:215], v[12:15]
	v_mfma_f32_16x16x32_bf16 v[8:11], v[180:183], v[212:215], v[8:11]
	v_mfma_f32_16x16x32_bf16 v[4:7], v[172:175], v[234:237], v[4:7]
	v_mfma_f32_16x16x32_bf16 v[0:3], v[180:183], v[234:237], v[0:3]
	v_mfma_f32_16x16x32_bf16 v[28:31], v[176:179], v[196:199], v[28:31]
	v_mfma_f32_16x16x32_bf16 v[24:27], v[184:187], v[196:199], v[24:27]
	v_mfma_f32_16x16x32_bf16 v[20:23], v[176:179], v[204:207], v[20:23]
	v_mfma_f32_16x16x32_bf16 v[16:19], v[184:187], v[204:207], v[16:19]
	v_mfma_f32_16x16x32_bf16 v[12:15], v[176:179], v[230:233], v[12:15]
	v_mfma_f32_16x16x32_bf16 v[8:11], v[184:187], v[230:233], v[8:11]
	v_mfma_f32_16x16x32_bf16 v[4:7], v[176:179], v[238:241], v[4:7]
	v_mfma_f32_16x16x32_bf16 v[0:3], v[184:187], v[238:241], v[0:3]
	s_barrier
	s_add_u32 s0, s0, 0x100
	s_addc_u32 s1, s1, 0
	s_add_u32 s40, s40, 0x100
	s_addc_u32 s41, s41, 0
	s_cmp_ge_i32 s42, s31
	s_mov_b32 s2, s42
	s_cbranch_scc0 .LBB0_392
	s_setprio 0

; template <class Epi, class Sched, bool ALIGN_EPI = false, bool SP2 = false>
; __device__ __forceinline__ void gemm_phase(PG8_LAS unsigned char* lds, const Gemm g, const Sched& S, const Epi& E) {
;     ...
;         for (int t = 0; t < nt; t += 2) {
;             const bool last = (t == nt - 2);
;     ...
; #pragma unroll
;         for (int a = 0; a < 2; ++a)
; #pragma unroll
;             for (int b = 0; b < 2; ++b)
; #pragma unroll
;                 for (int m = 0; m < 4; ++m)
; #pragma unroll
;                     for (int n = 0; n < 2; ++n) acc[a][b][m][n] = (f32x4){0.f, 0.f, 0.f, 0.f};
;         cur = nxt; cA = nA; cB = nB; ++ui;
.LBB0_419:
	v_mov_b32_e32 v123, 0
	s_andn2_b64 vcc, exec, s[26:27]
	v_mov_b32_e32 v122, v123
	v_mov_b32_e32 v121, v123
	v_mov_b32_e32 v120, v123
	v_mov_b32_e32 v127, v123
	v_mov_b32_e32 v126, v123
	v_mov_b32_e32 v125, v123
	v_mov_b32_e32 v124, v123
	v_mov_b32_e32 v119, v123
	v_mov_b32_e32 v118, v123
	v_mov_b32_e32 v117, v123
	v_mov_b32_e32 v116, v123
	v_mov_b32_e32 v115, v123
	v_mov_b32_e32 v114, v123
	v_mov_b32_e32 v113, v123
	v_mov_b32_e32 v112, v123
	v_mov_b32_e32 v111, v123
	v_mov_b32_e32 v110, v123
	v_mov_b32_e32 v109, v123
	v_mov_b32_e32 v108, v123
	s_waitcnt vmcnt(0)
	v_mov_b32_e32 v107, v123
	v_mov_b32_e32 v106, v123
	v_mov_b32_e32 v105, v123
	v_mov_b32_e32 v104, v123
	v_mov_b32_e32 v103, v123
	v_mov_b32_e32 v102, v123
	v_mov_b32_e32 v101, v123
	v_mov_b32_e32 v100, v123
	v_mov_b32_e32 v99, v123
	v_mov_b32_e32 v98, v123
	v_mov_b32_e32 v97, v123
	v_mov_b32_e32 v96, v123
	v_mov_b32_e32 v63, v123
	v_mov_b32_e32 v62, v123
	v_mov_b32_e32 v61, v123
	v_mov_b32_e32 v60, v123
	v_mov_b32_e32 v59, v123
	v_mov_b32_e32 v58, v123
	v_mov_b32_e32 v57, v123
	v_mov_b32_e32 v56, v123
	v_mov_b32_e32 v55, v123
	v_mov_b32_e32 v54, v123
	v_mov_b32_e32 v53, v123
	v_mov_b32_e32 v52, v123
	v_mov_b32_e32 v51, v123
	v_mov_b32_e32 v50, v123
	v_mov_b32_e32 v49, v123
	v_mov_b32_e32 v48, v123
	v_mov_b32_e32 v47, v123
	v_mov_b32_e32 v46, v123
	v_mov_b32_e32 v45, v123
	v_mov_b32_e32 v44, v123
	v_mov_b32_e32 v43, v123
	v_mov_b32_e32 v42, v123
	v_mov_b32_e32 v41, v123
	v_mov_b32_e32 v40, v123
	v_mov_b32_e32 v39, v123
	v_mov_b32_e32 v38, v123
	v_mov_b32_e32 v37, v123
	v_mov_b32_e32 v36, v123
	v_mov_b32_e32 v35, v123
	v_mov_b32_e32 v34, v123
	v_mov_b32_e32 v33, v123
	v_mov_b32_e32 v32, v123
	v_mov_b32_e32 v95, v123
	v_mov_b32_e32 v94, v123
	v_mov_b32_e32 v93, v123
	v_mov_b32_e32 v92, v123
	v_mov_b32_e32 v91, v123
	v_mov_b32_e32 v90, v123
	v_mov_b32_e32 v89, v123
	v_mov_b32_e32 v88, v123
	v_mov_b32_e32 v87, v123
	v_mov_b32_e32 v86, v123
	v_mov_b32_e32 v85, v123
	v_mov_b32_e32 v84, v123
	v_mov_b32_e32 v83, v123
	v_mov_b32_e32 v82, v123
	v_mov_b32_e32 v81, v123
	v_mov_b32_e32 v80, v123
	v_mov_b32_e32 v79, v123
	v_mov_b32_e32 v78, v123
	v_mov_b32_e32 v77, v123
	v_mov_b32_e32 v76, v123
	v_mov_b32_e32 v75, v123
	v_mov_b32_e32 v74, v123
	v_mov_b32_e32 v73, v123
	v_mov_b32_e32 v72, v123
	v_mov_b32_e32 v71, v123
	v_mov_b32_e32 v70, v123
	v_mov_b32_e32 v69, v123
	v_mov_b32_e32 v68, v123
	v_mov_b32_e32 v67, v123
	v_mov_b32_e32 v66, v123
	v_mov_b32_e32 v65, v123
	v_mov_b32_e32 v64, v123
	v_mov_b32_e32 v31, v123
	v_mov_b32_e32 v30, v123
	v_mov_b32_e32 v29, v123
	v_mov_b32_e32 v28, v123
	v_mov_b32_e32 v27, v123
	v_mov_b32_e32 v26, v123
	v_mov_b32_e32 v25, v123
	v_mov_b32_e32 v24, v123
	v_mov_b32_e32 v23, v123
	v_mov_b32_e32 v22, v123
	v_mov_b32_e32 v21, v123
	v_mov_b32_e32 v20, v123
	v_mov_b32_e32 v19, v123
	v_mov_b32_e32 v18, v123
	v_mov_b32_e32 v17, v123
	v_mov_b32_e32 v16, v123
	v_mov_b32_e32 v15, v123
	v_mov_b32_e32 v14, v123
	v_mov_b32_e32 v13, v123
	v_mov_b32_e32 v12, v123
	v_mov_b32_e32 v11, v123
	v_mov_b32_e32 v10, v123
	v_mov_b32_e32 v9, v123
	v_mov_b32_e32 v8, v123
	v_mov_b32_e32 v7, v123
	v_mov_b32_e32 v6, v123
	v_mov_b32_e32 v5, v123
	v_mov_b32_e32 v4, v123
	v_mov_b32_e32 v3, v123
	v_mov_b32_e32 v2, v123
	v_mov_b32_e32 v1, v123
	v_mov_b32_e32 v0, v123
	s_cbranch_vccnz .LBB0_422
	s_add_u32 s0, s0, 0x80
	s_addc_u32 s1, s1, 0
	s_add_u32 s40, s2, 0x100
	v_mov_b32_e32 v0, 0
	s_addc_u32 s41, s3, 0
	s_mov_b32 s2, 0
	v_mov_b32_e32 v1, v0
	v_mov_b32_e32 v2, v0
	v_mov_b32_e32 v3, v0
	v_mov_b32_e32 v4, v0
	v_mov_b32_e32 v5, v0
	v_mov_b32_e32 v6, v0
	v_mov_b32_e32 v7, v0
	v_mov_b32_e32 v8, v0
	v_mov_b32_e32 v9, v0
	v_mov_b32_e32 v10, v0
	v_mov_b32_e32 v11, v0
	v_mov_b32_e32 v12, v0
	v_mov_b32_e32 v13, v0
	v_mov_b32_e32 v14, v0
	v_mov_b32_e32 v15, v0
	v_mov_b32_e32 v16, v0
	v_mov_b32_e32 v17, v0
	v_mov_b32_e32 v18, v0
	v_mov_b32_e32 v19, v0
	v_mov_b32_e32 v20, v0
	v_mov_b32_e32 v21, v0
	v_mov_b32_e32 v22, v0
	v_mov_b32_e32 v23, v0
	v_mov_b32_e32 v24, v0
	v_mov_b32_e32 v25, v0
	v_mov_b32_e32 v26, v0
	v_mov_b32_e32 v27, v0
	v_mov_b32_e32 v28, v0
	v_mov_b32_e32 v29, v0
	v_mov_b32_e32 v30, v0
	v_mov_b32_e32 v31, v0
	v_mov_b32_e32 v64, v0
	v_mov_b32_e32 v65, v0
	v_mov_b32_e32 v66, v0
	v_mov_b32_e32 v67, v0
	v_mov_b32_e32 v68, v0
	v_mov_b32_e32 v69, v0
	v_mov_b32_e32 v70, v0
	v_mov_b32_e32 v71, v0
	v_mov_b32_e32 v72, v0
	v_mov_b32_e32 v73, v0
	v_mov_b32_e32 v74, v0
	v_mov_b32_e32 v75, v0
	v_mov_b32_e32 v76, v0
	v_mov_b32_e32 v77, v0
	v_mov_b32_e32 v78, v0
	v_mov_b32_e32 v79, v0
	v_mov_b32_e32 v80, v0
	v_mov_b32_e32 v81, v0
	v_mov_b32_e32 v82, v0
	v_mov_b32_e32 v83, v0
	v_mov_b32_e32 v84, v0
	v_mov_b32_e32 v85, v0
	v_mov_b32_e32 v86, v0
	v_mov_b32_e32 v87, v0
	v_mov_b32_e32 v88, v0
	v_mov_b32_e32 v89, v0
	v_mov_b32_e32 v90, v0
	v_mov_b32_e32 v91, v0
	v_mov_b32_e32 v92, v0
	v_mov_b32_e32 v93, v0
	v_mov_b32_e32 v94, v0
	v_mov_b32_e32 v95, v0
	v_mov_b32_e32 v32, v0
	v_mov_b32_e32 v33, v0
	v_mov_b32_e32 v34, v0
	v_mov_b32_e32 v35, v0
	v_mov_b32_e32 v36, v0
	v_mov_b32_e32 v37, v0
	v_mov_b32_e32 v38, v0
	v_mov_b32_e32 v39, v0
	v_mov_b32_e32 v40, v0
	v_mov_b32_e32 v41, v0
	v_mov_b32_e32 v42, v0
	v_mov_b32_e32 v43, v0
	v_mov_b32_e32 v44, v0
	v_mov_b32_e32 v45, v0
	v_mov_b32_e32 v46, v0
	v_mov_b32_e32 v47, v0
	v_mov_b32_e32 v48, v0
	v_mov_b32_e32 v49, v0
	v_mov_b32_e32 v50, v0
	v_mov_b32_e32 v51, v0
	v_mov_b32_e32 v52, v0
	v_mov_b32_e32 v53, v0
	v_mov_b32_e32 v54, v0
	v_mov_b32_e32 v55, v0
	v_mov_b32_e32 v56, v0
	v_mov_b32_e32 v57, v0
	v_mov_b32_e32 v58, v0
	v_mov_b32_e32 v59, v0
	v_mov_b32_e32 v60, v0
	v_mov_b32_e32 v61, v0
	v_mov_b32_e32 v62, v0
	v_mov_b32_e32 v63, v0
	v_mov_b32_e32 v96, v0
	v_mov_b32_e32 v97, v0
	v_mov_b32_e32 v98, v0
	v_mov_b32_e32 v99, v0
	v_mov_b32_e32 v100, v0
	v_mov_b32_e32 v101, v0
	v_mov_b32_e32 v102, v0
	v_mov_b32_e32 v103, v0
	v_mov_b32_e32 v104, v0
	v_mov_b32_e32 v105, v0
	v_mov_b32_e32 v106, v0
	v_mov_b32_e32 v107, v0
	v_mov_b32_e32 v108, v0
	v_mov_b32_e32 v109, v0
	v_mov_b32_e32 v110, v0
	v_mov_b32_e32 v111, v0
	v_mov_b32_e32 v112, v0
	v_mov_b32_e32 v113, v0
	v_mov_b32_e32 v114, v0
	v_mov_b32_e32 v115, v0
	v_mov_b32_e32 v116, v0
	v_mov_b32_e32 v117, v0
	v_mov_b32_e32 v118, v0
	v_mov_b32_e32 v119, v0
	v_mov_b32_e32 v124, v0
	v_mov_b32_e32 v125, v0
	v_mov_b32_e32 v126, v0
	v_mov_b32_e32 v127, v0
	v_mov_b32_e32 v120, v0
	v_mov_b32_e32 v121, v0
	v_mov_b32_e32 v122, v0
	v_mov_b32_e32 v123, v0
	v_readfirstlane_b32 s100, v211
	s_cmp_ge_u32 s100, 0x100
	s_cbranch_scc0 .Lprio_skip7
	s_setprio 1
; #define PG8_STAGE(bufoff, gbase, voff) do { _Pragma("unroll") for (int _i = 0; _i < 2; ++_i) \
;         __builtin_amdgcn_global_load_lds((const unsigned*)((const char*)(gbase) + (voff)[_i]), (PG8_LAS unsigned*)(lds + (bufoff) + ldsw + _i * 8192), 16, 0, 0); } while (0)
; #define PG8_LDA(dst, b, h) do { _Pragma("unroll") for (int m = 0; m < 4; ++m) _Pragma("unroll") for (int k = 0; k < 2; ++k) dst[m][k] = *(const PG8_LAS bf16x8*)(lds + PG8_SA(b, h) + aoff + m * 2048 + k * 1024); } while (0)
; #define PG8_LDB(dst, b, h) do { _Pragma("unroll") for (int n = 0; n < 2; ++n) _Pragma("unroll") for (int k = 0; k < 2; ++k) dst[n][k] = *(const PG8_LAS bf16x8*)(lds + PG8_SB(b, h) + boff + n * 2048 + k * 1024); } while (0)
; #define PG8_MMA(ai, bj, At, Bt) do { __builtin_amdgcn_s_setprio(1); _Pragma("unroll") for (int m = 0; m < 4; ++m) _Pragma("unroll") for (int n = 0; n < 2; ++n) _Pragma("unroll") for (int k = 0; k < 2; ++k) \
;         acc[ai][bj][m][n] = __builtin_amdgcn_mfma_f32_16x16x32_bf16(Bt[n][k], At[m][k], acc[ai][bj][m][n], 0, 0, 0); __builtin_amdgcn_s_setprio(0); } while (0)
; #define PG8_WAIT_V(n) asm volatile("s_waitcnt vmcnt(" #n ")" ::: "memory")
; #define PG8_WAIT_L(n) asm volatile("s_waitcnt lgkmcnt(" #n ")" ::: "memory")
; template <class Epi, class Sched, bool ALIGN_EPI = false, bool SP2 = false>
; __device__ __forceinline__ void gemm_phase(PG8_LAS unsigned char* lds, const Gemm g, const Sched& S, const Epi& E) {
;     ...
;             const bool last = (t == nt - 2);
;             const char* a1 = cA + (size_t)(t + 1) * kstep;
;             const char* a2 = last ? nA : cA + (size_t)(t + 2) * kstep; const char* b2 = last ? nB : cB + (size_t)(t + 2) * kstep;
;             const char* a3 = a2 + kstep; const char* b3 = b2 + kstep;
;             if (last && has_next) S.a_ready(nxt);
;             if constexpr (SP2) {
;             PG8_LDB(B0, 0, 0); PG8_LDB(B1, 0, 1); PG8_SCHED; PG8_LDA(At, 0, 0); PG8_STAGE(PG8_SA(1, 1), a1 + hstep, voffA);
;             PG8_WAIT_V(8); PG8_WAIT_L(0); PG8_BAR; PG8_MMA(0, 0, At, B0); PG8_MMA(0, 1, At, B1); PG8_BAR; PG8_SCHED;
;             PG8_LDA(At, 0, 1); PG8_STAGE(PG8_SB(0, 0), b2, voffB); PG8_STAGE(PG8_SB(0, 1), b2 + hstep, voffB); PG8_STAGE(PG8_SA(0, 0), a2, voffA);
;             PG8_WAIT_V(8); PG8_WAIT_L(0); PG8_BAR; PG8_MMA(1, 0, At, B0); PG8_MMA(1, 1, At, B1); PG8_BAR; PG8_SCHED;
.Lprio_skip7:
.LBB0_421:
	s_add_i32 s42, s2, 2
	s_add_u32 s43, s0, 0x80
	s_addc_u32 s3, s1, 0
	s_add_i32 s48, 0, 0x10000
	s_cmp_eq_u32 s34, s2
	s_cselect_b32 s3, s7, s3
	s_cselect_b32 s2, s6, s43
	v_add_u32_e32 v158, s48, v151
	s_cselect_b32 s45, s51, s41
	s_cselect_b32 s44, s50, s40
	s_add_i32 s43, 0, 0x14000
	ds_read_b128 v[128:131], v158
	ds_read_b128 v[132:135], v158 offset:1024
	ds_read_b128 v[146:149], v158 offset:2048
	ds_read_b128 v[170:173], v158 offset:3072
	v_add_u32_e32 v158, s43, v151
	ds_read_b128 v[174:177], v158
	ds_read_b128 v[178:181], v158 offset:1024
	ds_read_b128 v[182:185], v158 offset:2048
	ds_read_b128 v[186:189], v158 offset:3072
	v_lshl_add_u64 v[158:159], s[0:1], 0, v[142:143]
	s_add_i32 m0, s23, 0xc000
	ds_read_b128 v[190:193], v168
	ds_read_b128 v[194:197], v168 offset:1024
	ds_read_b128 v[198:201], v168 offset:2048
	ds_read_b128 v[202:205], v168 offset:3072
	ds_read_b128 v[206:209], v168 offset:4096
	ds_read_b128 v[212:215], v168 offset:5120
	ds_read_b128 v[230:233], v168 offset:6144
	ds_read_b128 v[234:237], v168 offset:7168
	global_load_lds_dwordx4 v[158:159], off
	v_lshl_add_u64 v[158:159], s[0:1], 0, v[144:145]
	s_add_i32 m0, s23, 0xe000
	s_nop 0
	global_load_lds_dwordx4 v[158:159], off
	s_waitcnt vmcnt(8)
	s_waitcnt lgkmcnt(0)
	s_barrier
	s_waitcnt lgkmcnt(0)
	v_mfma_f32_16x16x32_bf16 v[120:123], v[128:131], v[190:193], v[120:123]
	v_mfma_f32_16x16x32_bf16 v[124:127], v[146:149], v[190:193], v[124:127]
	v_mfma_f32_16x16x32_bf16 v[116:119], v[128:131], v[198:201], v[116:119]
	v_mfma_f32_16x16x32_bf16 v[112:115], v[146:149], v[198:201], v[112:115]
	v_mfma_f32_16x16x32_bf16 v[108:111], v[128:131], v[206:209], v[108:111]
	v_mfma_f32_16x16x32_bf16 v[104:107], v[146:149], v[206:209], v[104:107]
	v_mfma_f32_16x16x32_bf16 v[100:103], v[128:131], v[230:233], v[100:103]
	v_mfma_f32_16x16x32_bf16 v[96:99], v[146:149], v[230:233], v[96:99]
	v_mfma_f32_16x16x32_bf16 v[120:123], v[132:135], v[194:197], v[120:123]
	v_mfma_f32_16x16x32_bf16 v[124:127], v[170:173], v[194:197], v[124:127]
	v_mfma_f32_16x16x32_bf16 v[116:119], v[132:135], v[202:205], v[116:119]
	v_mfma_f32_16x16x32_bf16 v[112:115], v[170:173], v[202:205], v[112:115]
	v_mfma_f32_16x16x32_bf16 v[108:111], v[132:135], v[212:215], v[108:111]
	v_mfma_f32_16x16x32_bf16 v[104:107], v[170:173], v[212:215], v[104:107]
	v_mfma_f32_16x16x32_bf16 v[100:103], v[132:135], v[234:237], v[100:103]
	v_mfma_f32_16x16x32_bf16 v[96:99], v[170:173], v[234:237], v[96:99]
	v_mfma_f32_16x16x32_bf16 v[60:63], v[174:177], v[190:193], v[60:63]
	v_mfma_f32_16x16x32_bf16 v[56:59], v[182:185], v[190:193], v[56:59]
	v_mfma_f32_16x16x32_bf16 v[52:55], v[174:177], v[198:201], v[52:55]
	v_mfma_f32_16x16x32_bf16 v[48:51], v[182:185], v[198:201], v[48:51]
	v_mfma_f32_16x16x32_bf16 v[44:47], v[174:177], v[206:209], v[44:47]
	v_mfma_f32_16x16x32_bf16 v[40:43], v[182:185], v[206:209], v[40:43]
	v_mfma_f32_16x16x32_bf16 v[36:39], v[174:177], v[230:233], v[36:39]
	v_mfma_f32_16x16x32_bf16 v[32:35], v[182:185], v[230:233], v[32:35]
	v_mfma_f32_16x16x32_bf16 v[60:63], v[178:181], v[194:197], v[60:63]
	v_mfma_f32_16x16x32_bf16 v[56:59], v[186:189], v[194:197], v[56:59]
	v_mfma_f32_16x16x32_bf16 v[52:55], v[178:181], v[202:205], v[52:55]
	v_mfma_f32_16x16x32_bf16 v[48:51], v[186:189], v[202:205], v[48:51]
	v_mfma_f32_16x16x32_bf16 v[44:47], v[178:181], v[212:215], v[44:47]
	v_mfma_f32_16x16x32_bf16 v[40:43], v[186:189], v[212:215], v[40:43]
	v_mfma_f32_16x16x32_bf16 v[36:39], v[178:181], v[234:237], v[36:39]
	v_mfma_f32_16x16x32_bf16 v[32:35], v[186:189], v[234:237], v[32:35]
	s_barrier
	s_add_i32 s48, s48, s22
	v_lshl_add_u64 v[158:159], s[44:45], 0, v[152:153]
	s_mov_b32 m0, s48
	ds_read_b128 v[190:193], v168 offset:16384
	ds_read_b128 v[194:197], v168 offset:17408
	ds_read_b128 v[198:201], v168 offset:18432
	ds_read_b128 v[202:205], v168 offset:19456
	ds_read_b128 v[206:209], v168 offset:20480
	ds_read_b128 v[212:215], v168 offset:21504
	ds_read_b128 v[230:233], v168 offset:22528
	ds_read_b128 v[234:237], v168 offset:23552
	global_load_lds_dwordx4 v[158:159], off
	s_add_i32 m0, s48, 0x2000
	v_lshl_add_u64 v[160:161], s[44:45], 0, v[136:137]
	s_add_u32 s44, s44, s8
	s_addc_u32 s45, s45, s9
	s_add_i32 s43, s43, s22
	global_load_lds_dwordx4 v[160:161], off
	v_lshl_add_u64 v[162:163], s[44:45], 0, v[152:153]
	s_mov_b32 m0, s43
	v_lshl_add_u64 v[164:165], s[44:45], 0, v[136:137]
	global_load_lds_dwordx4 v[162:163], off
	s_add_i32 m0, s43, 0x2000
	v_lshl_add_u64 v[216:217], s[2:3], 0, v[140:141]
	global_load_lds_dwordx4 v[164:165], off
	s_mov_b32 m0, s23
	v_lshl_add_u64 v[238:239], s[2:3], 0, v[138:139]
	global_load_lds_dwordx4 v[216:217], off
	s_mov_b32 m0, s24
	s_nop 0
	global_load_lds_dwordx4 v[238:239], off
	s_waitcnt vmcnt(8)
	s_waitcnt lgkmcnt(0)
	s_barrier
; #define PG8_STAGE(bufoff, gbase, voff) do { _Pragma("unroll") for (int _i = 0; _i < 2; ++_i) \
;         __builtin_amdgcn_global_load_lds((const unsigned*)((const char*)(gbase) + (voff)[_i]), (PG8_LAS unsigned*)(lds + (bufoff) + ldsw + _i * 8192), 16, 0, 0); } while (0)
; #define PG8_LDA(dst, b, h) do { _Pragma("unroll") for (int m = 0; m < 4; ++m) _Pragma("unroll") for (int k = 0; k < 2; ++k) dst[m][k] = *(const PG8_LAS bf16x8*)(lds + PG8_SA(b, h) + aoff + m * 2048 + k * 1024); } while (0)
; #define PG8_LDB(dst, b, h) do { _Pragma("unroll") for (int n = 0; n < 2; ++n) _Pragma("unroll") for (int k = 0; k < 2; ++k) dst[n][k] = *(const PG8_LAS bf16x8*)(lds + PG8_SB(b, h) + boff + n * 2048 + k * 1024); } while (0)
; #define PG8_MMA(ai, bj, At, Bt) do { __builtin_amdgcn_s_setprio(1); _Pragma("unroll") for (int m = 0; m < 4; ++m) _Pragma("unroll") for (int n = 0; n < 2; ++n) _Pragma("unroll") for (int k = 0; k < 2; ++k) \
;         acc[ai][bj][m][n] = __builtin_amdgcn_mfma_f32_16x16x32_bf16(Bt[n][k], At[m][k], acc[ai][bj][m][n], 0, 0, 0); __builtin_amdgcn_s_setprio(0); } while (0)
; #define PG8_WAIT_V(n) asm volatile("s_waitcnt vmcnt(" #n ")" ::: "memory")
; #define PG8_WAIT_L(n) asm volatile("s_waitcnt lgkmcnt(" #n ")" ::: "memory")
; #define PG8_BAR __builtin_amdgcn_s_barrier()
; #define PG8_SCHED __builtin_amdgcn_sched_barrier(0)
; template <class Epi, class Sched, bool ALIGN_EPI = false, bool SP2 = false>
; __device__ __forceinline__ void gemm_phase(PG8_LAS unsigned char* lds, const Gemm g, const Sched& S, const Epi& E) {
;     ...
;             PG8_WAIT_V(8); PG8_WAIT_L(0); PG8_BAR; PG8_MMA(1, 0, At, B0); PG8_MMA(1, 1, At, B1); PG8_BAR; PG8_SCHED;
;             PG8_LDB(B0, 1, 0); PG8_LDB(B1, 1, 1); PG8_SCHED; PG8_LDA(At, 1, 0); PG8_STAGE(PG8_SA(0, 1), a2 + hstep, voffA);
;             PG8_WAIT_V(8); PG8_WAIT_L(0); PG8_BAR; PG8_MMA(0, 0, At, B0); PG8_MMA(0, 1, At, B1); PG8_BAR; PG8_SCHED;
	s_waitcnt lgkmcnt(0)
	v_mfma_f32_16x16x32_bf16 v[92:95], v[128:131], v[190:193], v[92:95]
	v_mfma_f32_16x16x32_bf16 v[88:91], v[146:149], v[190:193], v[88:91]
	v_mfma_f32_16x16x32_bf16 v[84:87], v[128:131], v[198:201], v[84:87]
	v_mfma_f32_16x16x32_bf16 v[80:83], v[146:149], v[198:201], v[80:83]
	v_mfma_f32_16x16x32_bf16 v[76:79], v[128:131], v[206:209], v[76:79]
	v_mfma_f32_16x16x32_bf16 v[72:75], v[146:149], v[206:209], v[72:75]
	v_mfma_f32_16x16x32_bf16 v[68:71], v[128:131], v[230:233], v[68:71]
	v_mfma_f32_16x16x32_bf16 v[64:67], v[146:149], v[230:233], v[64:67]
	v_mfma_f32_16x16x32_bf16 v[92:95], v[132:135], v[194:197], v[92:95]
	v_mfma_f32_16x16x32_bf16 v[88:91], v[170:173], v[194:197], v[88:91]
	v_mfma_f32_16x16x32_bf16 v[84:87], v[132:135], v[202:205], v[84:87]
	v_mfma_f32_16x16x32_bf16 v[80:83], v[170:173], v[202:205], v[80:83]
	v_mfma_f32_16x16x32_bf16 v[76:79], v[132:135], v[212:215], v[76:79]
	v_mfma_f32_16x16x32_bf16 v[72:75], v[170:173], v[212:215], v[72:75]
	v_mfma_f32_16x16x32_bf16 v[68:71], v[132:135], v[234:237], v[68:71]
	v_mfma_f32_16x16x32_bf16 v[64:67], v[170:173], v[234:237], v[64:67]
	v_mfma_f32_16x16x32_bf16 v[28:31], v[174:177], v[190:193], v[28:31]
	v_mfma_f32_16x16x32_bf16 v[24:27], v[182:185], v[190:193], v[24:27]
	v_mfma_f32_16x16x32_bf16 v[20:23], v[174:177], v[198:201], v[20:23]
	v_mfma_f32_16x16x32_bf16 v[16:19], v[182:185], v[198:201], v[16:19]
	v_mfma_f32_16x16x32_bf16 v[12:15], v[174:177], v[206:209], v[12:15]
	v_mfma_f32_16x16x32_bf16 v[8:11], v[182:185], v[206:209], v[8:11]
	v_mfma_f32_16x16x32_bf16 v[4:7], v[174:177], v[230:233], v[4:7]
	v_mfma_f32_16x16x32_bf16 v[0:3], v[182:185], v[230:233], v[0:3]
	v_mfma_f32_16x16x32_bf16 v[28:31], v[178:181], v[194:197], v[28:31]
	v_mfma_f32_16x16x32_bf16 v[24:27], v[186:189], v[194:197], v[24:27]
	v_mfma_f32_16x16x32_bf16 v[20:23], v[178:181], v[202:205], v[20:23]
	v_mfma_f32_16x16x32_bf16 v[16:19], v[186:189], v[202:205], v[16:19]
	v_mfma_f32_16x16x32_bf16 v[12:15], v[178:181], v[212:215], v[12:15]
	v_mfma_f32_16x16x32_bf16 v[8:11], v[186:189], v[212:215], v[8:11]
	v_mfma_f32_16x16x32_bf16 v[4:7], v[178:181], v[234:237], v[4:7]
	v_mfma_f32_16x16x32_bf16 v[0:3], v[186:189], v[234:237], v[0:3]
	s_barrier
	s_add_i32 s43, 0, 0x18000
	v_add_u32_e32 v169, s43, v151
	s_add_i32 s44, 0, 0x1c000
	ds_read_b128 v[128:131], v169
	ds_read_b128 v[132:135], v169 offset:1024
	ds_read_b128 v[146:149], v169 offset:2048
	ds_read_b128 v[170:173], v169 offset:3072
	v_add_u32_e32 v169, s44, v151
	ds_read_b128 v[174:177], v169
	ds_read_b128 v[178:181], v169 offset:1024
	ds_read_b128 v[182:185], v169 offset:2048
	ds_read_b128 v[186:189], v169 offset:3072
	s_add_u32 s2, s2, s8
	s_addc_u32 s3, s3, s9
	s_mov_b32 m0, s25
	v_lshl_add_u64 v[240:241], s[2:3], 0, v[140:141]
	ds_read_b128 v[190:193], v168 offset:32768
	ds_read_b128 v[194:197], v168 offset:33792
	ds_read_b128 v[198:201], v168 offset:34816
	ds_read_b128 v[202:205], v168 offset:35840
	ds_read_b128 v[206:209], v168 offset:36864
	ds_read_b128 v[212:215], v168 offset:37888
	ds_read_b128 v[230:233], v168 offset:38912
	ds_read_b128 v[234:237], v168 offset:39936
	global_load_lds_dwordx4 v[240:241], off
	v_lshl_add_u64 v[240:241], s[2:3], 0, v[138:139]
	s_mov_b32 m0, s28
	s_nop 0
	global_load_lds_dwordx4 v[240:241], off
	s_waitcnt vmcnt(8)
	s_waitcnt lgkmcnt(0)
	s_barrier
	s_waitcnt lgkmcnt(0)
	v_mfma_f32_16x16x32_bf16 v[120:123], v[128:131], v[190:193], v[120:123]
	v_mfma_f32_16x16x32_bf16 v[124:127], v[146:149], v[190:193], v[124:127]
	v_mfma_f32_16x16x32_bf16 v[116:119], v[128:131], v[198:201], v[116:119]
	v_mfma_f32_16x16x32_bf16 v[112:115], v[146:149], v[198:201], v[112:115]
	v_mfma_f32_16x16x32_bf16 v[108:111], v[128:131], v[206:209], v[108:111]
	v_mfma_f32_16x16x32_bf16 v[104:107], v[146:149], v[206:209], v[104:107]
	v_mfma_f32_16x16x32_bf16 v[100:103], v[128:131], v[230:233], v[100:103]
	v_mfma_f32_16x16x32_bf16 v[96:99], v[146:149], v[230:233], v[96:99]
	v_mfma_f32_16x16x32_bf16 v[120:123], v[132:135], v[194:197], v[120:123]
	v_mfma_f32_16x16x32_bf16 v[124:127], v[170:173], v[194:197], v[124:127]
	v_mfma_f32_16x16x32_bf16 v[116:119], v[132:135], v[202:205], v[116:119]
	v_mfma_f32_16x16x32_bf16 v[112:115], v[170:173], v[202:205], v[112:115]
	v_mfma_f32_16x16x32_bf16 v[108:111], v[132:135], v[212:215], v[108:111]
	v_mfma_f32_16x16x32_bf16 v[104:107], v[170:173], v[212:215], v[104:107]
	v_mfma_f32_16x16x32_bf16 v[100:103], v[132:135], v[234:237], v[100:103]
	v_mfma_f32_16x16x32_bf16 v[96:99], v[170:173], v[234:237], v[96:99]
	v_mfma_f32_16x16x32_bf16 v[60:63], v[174:177], v[190:193], v[60:63]
	v_mfma_f32_16x16x32_bf16 v[56:59], v[182:185], v[190:193], v[56:59]
	v_mfma_f32_16x16x32_bf16 v[52:55], v[174:177], v[198:201], v[52:55]
	v_mfma_f32_16x16x32_bf16 v[48:51], v[182:185], v[198:201], v[48:51]
	v_mfma_f32_16x16x32_bf16 v[44:47], v[174:177], v[206:209], v[44:47]
	v_mfma_f32_16x16x32_bf16 v[40:43], v[182:185], v[206:209], v[40:43]
	v_mfma_f32_16x16x32_bf16 v[36:39], v[174:177], v[230:233], v[36:39]
	v_mfma_f32_16x16x32_bf16 v[32:35], v[182:185], v[230:233], v[32:35]
	v_mfma_f32_16x16x32_bf16 v[60:63], v[178:181], v[194:197], v[60:63]
	v_mfma_f32_16x16x32_bf16 v[56:59], v[186:189], v[194:197], v[56:59]
	v_mfma_f32_16x16x32_bf16 v[52:55], v[178:181], v[202:205], v[52:55]
	v_mfma_f32_16x16x32_bf16 v[48:51], v[186:189], v[202:205], v[48:51]
	v_mfma_f32_16x16x32_bf16 v[44:47], v[178:181], v[212:215], v[44:47]
	v_mfma_f32_16x16x32_bf16 v[40:43], v[186:189], v[212:215], v[40:43]
	v_mfma_f32_16x16x32_bf16 v[36:39], v[178:181], v[234:237], v[36:39]
	v_mfma_f32_16x16x32_bf16 v[32:35], v[186:189], v[234:237], v[32:35]
	s_barrier
; #define PG8_STAGE(bufoff, gbase, voff) do { _Pragma("unroll") for (int _i = 0; _i < 2; ++_i) \
;         __builtin_amdgcn_global_load_lds((const unsigned*)((const char*)(gbase) + (voff)[_i]), (PG8_LAS unsigned*)(lds + (bufoff) + ldsw + _i * 8192), 16, 0, 0); } while (0)
; #define PG8_LDA(dst, b, h) do { _Pragma("unroll") for (int m = 0; m < 4; ++m) _Pragma("unroll") for (int k = 0; k < 2; ++k) dst[m][k] = *(const PG8_LAS bf16x8*)(lds + PG8_SA(b, h) + aoff + m * 2048 + k * 1024); } while (0)
; #define PG8_MMA(ai, bj, At, Bt) do { __builtin_amdgcn_s_setprio(1); _Pragma("unroll") for (int m = 0; m < 4; ++m) _Pragma("unroll") for (int n = 0; n < 2; ++n) _Pragma("unroll") for (int k = 0; k < 2; ++k) \
;         acc[ai][bj][m][n] = __builtin_amdgcn_mfma_f32_16x16x32_bf16(Bt[n][k], At[m][k], acc[ai][bj][m][n], 0, 0, 0); __builtin_amdgcn_s_setprio(0); } while (0)
; #define PG8_WAIT_V(n) asm volatile("s_waitcnt vmcnt(" #n ")" ::: "memory")
; #define PG8_WAIT_L(n) asm volatile("s_waitcnt lgkmcnt(" #n ")" ::: "memory")
; #define PG8_BAR __builtin_amdgcn_s_barrier()
; #define PG8_SCHED __builtin_amdgcn_sched_barrier(0)
; template <class Epi, class Sched, bool ALIGN_EPI = false, bool SP2 = false>
; __device__ __forceinline__ void gemm_phase(PG8_LAS unsigned char* lds, const Gemm g, const Sched& S, const Epi& E) {
;     ...
;         for (int t = 0; t < nt; t += 2) {
;             const bool last = (t == nt - 2);
;     ...
;             PG8_LDA(At, 1, 1); PG8_STAGE(PG8_SB(1, 0), b3, voffB); PG8_STAGE(PG8_SB(1, 1), b3 + hstep, voffB); PG8_STAGE(PG8_SA(1, 0), a3, voffA);
;             PG8_WAIT_V(8); PG8_WAIT_L(0); PG8_BAR; PG8_MMA(1, 0, At, B0); PG8_MMA(1, 1, At, B1); PG8_BAR; PG8_SCHED;
	s_add_i32 s2, s43, s22
	v_lshl_add_u64 v[158:159], v[158:159], 0, s[82:83]
	s_mov_b32 m0, s2
	ds_read_b128 v[190:193], v168 offset:49152
	ds_read_b128 v[194:197], v168 offset:50176
	ds_read_b128 v[198:201], v168 offset:51200
	ds_read_b128 v[202:205], v168 offset:52224
	ds_read_b128 v[206:209], v168 offset:53248
	ds_read_b128 v[212:215], v168 offset:54272
	ds_read_b128 v[230:233], v168 offset:55296
	ds_read_b128 v[234:237], v168 offset:56320
	global_load_lds_dwordx4 v[158:159], off
	v_lshl_add_u64 v[158:159], v[160:161], 0, s[82:83]
	s_add_i32 m0, s2, 0x2000
	s_add_i32 s2, s44, s22
	global_load_lds_dwordx4 v[158:159], off
	v_lshl_add_u64 v[158:159], v[162:163], 0, s[82:83]
	s_mov_b32 m0, s2
	s_nop 0
	global_load_lds_dwordx4 v[158:159], off
	v_lshl_add_u64 v[158:159], v[164:165], 0, s[82:83]
	s_add_i32 m0, s2, 0x2000
	s_nop 0
	global_load_lds_dwordx4 v[158:159], off
	v_lshl_add_u64 v[158:159], v[216:217], 0, s[82:83]
	s_mov_b32 m0, s29
	s_nop 0
	global_load_lds_dwordx4 v[158:159], off
	v_lshl_add_u64 v[158:159], v[238:239], 0, s[82:83]
	s_mov_b32 m0, s30
	s_nop 0
	global_load_lds_dwordx4 v[158:159], off
	s_waitcnt vmcnt(8)
	s_waitcnt lgkmcnt(0)
	s_barrier
	s_waitcnt lgkmcnt(0)
	v_mfma_f32_16x16x32_bf16 v[92:95], v[128:131], v[190:193], v[92:95]
	v_mfma_f32_16x16x32_bf16 v[88:91], v[146:149], v[190:193], v[88:91]
	v_mfma_f32_16x16x32_bf16 v[84:87], v[128:131], v[198:201], v[84:87]
	v_mfma_f32_16x16x32_bf16 v[80:83], v[146:149], v[198:201], v[80:83]
	v_mfma_f32_16x16x32_bf16 v[76:79], v[128:131], v[206:209], v[76:79]
	v_mfma_f32_16x16x32_bf16 v[72:75], v[146:149], v[206:209], v[72:75]
	v_mfma_f32_16x16x32_bf16 v[68:71], v[128:131], v[230:233], v[68:71]
	v_mfma_f32_16x16x32_bf16 v[64:67], v[146:149], v[230:233], v[64:67]
	v_mfma_f32_16x16x32_bf16 v[92:95], v[132:135], v[194:197], v[92:95]
	v_mfma_f32_16x16x32_bf16 v[88:91], v[170:173], v[194:197], v[88:91]
	v_mfma_f32_16x16x32_bf16 v[84:87], v[132:135], v[202:205], v[84:87]
	v_mfma_f32_16x16x32_bf16 v[80:83], v[170:173], v[202:205], v[80:83]
	v_mfma_f32_16x16x32_bf16 v[76:79], v[132:135], v[212:215], v[76:79]
	v_mfma_f32_16x16x32_bf16 v[72:75], v[170:173], v[212:215], v[72:75]
	v_mfma_f32_16x16x32_bf16 v[68:71], v[132:135], v[234:237], v[68:71]
	v_mfma_f32_16x16x32_bf16 v[64:67], v[170:173], v[234:237], v[64:67]
	v_mfma_f32_16x16x32_bf16 v[28:31], v[174:177], v[190:193], v[28:31]
	v_mfma_f32_16x16x32_bf16 v[24:27], v[182:185], v[190:193], v[24:27]
	v_mfma_f32_16x16x32_bf16 v[20:23], v[174:177], v[198:201], v[20:23]
	v_mfma_f32_16x16x32_bf16 v[16:19], v[182:185], v[198:201], v[16:19]
	v_mfma_f32_16x16x32_bf16 v[12:15], v[174:177], v[206:209], v[12:15]
	v_mfma_f32_16x16x32_bf16 v[8:11], v[182:185], v[206:209], v[8:11]
	v_mfma_f32_16x16x32_bf16 v[4:7], v[174:177], v[230:233], v[4:7]
	v_mfma_f32_16x16x32_bf16 v[0:3], v[182:185], v[230:233], v[0:3]
	v_mfma_f32_16x16x32_bf16 v[28:31], v[178:181], v[194:197], v[28:31]
	v_mfma_f32_16x16x32_bf16 v[24:27], v[186:189], v[194:197], v[24:27]
	v_mfma_f32_16x16x32_bf16 v[20:23], v[178:181], v[202:205], v[20:23]
	v_mfma_f32_16x16x32_bf16 v[16:19], v[186:189], v[202:205], v[16:19]
	v_mfma_f32_16x16x32_bf16 v[12:15], v[178:181], v[212:215], v[12:15]
	v_mfma_f32_16x16x32_bf16 v[8:11], v[186:189], v[212:215], v[8:11]
	v_mfma_f32_16x16x32_bf16 v[4:7], v[178:181], v[234:237], v[4:7]
	v_mfma_f32_16x16x32_bf16 v[0:3], v[186:189], v[234:237], v[0:3]
	s_barrier
	s_add_u32 s0, s0, 0x100
	s_addc_u32 s1, s1, 0
	s_add_u32 s40, s40, 0x100
	s_addc_u32 s41, s41, 0
	s_cmp_ge_i32 s42, s31
	s_mov_b32 s2, s42
	s_cbranch_scc0 .LBB0_421
	s_setprio 0

; template <class Epi, class Sched, bool ALIGN_EPI = false, bool SP2 = false>
; __device__ __forceinline__ void gemm_phase(PG8_LAS unsigned char* lds, const Gemm g, const Sched& S, const Epi& E) {
;     ...
;         for (int t = 0; t < nt; t += 2) {
;             const bool last = (t == nt - 2);
;     ...
; #pragma unroll
;         for (int a = 0; a < 2; ++a)
; #pragma unroll
;             for (int b = 0; b < 2; ++b)
; #pragma unroll
;                 for (int m = 0; m < 4; ++m)
; #pragma unroll
;                     for (int n = 0; n < 2; ++n) acc[a][b][m][n] = (f32x4){0.f, 0.f, 0.f, 0.f};
;         cur = nxt; cA = nA; cB = nB; ++ui;
.LBB0_442:
	v_mov_b32_e32 v131, 0
	s_andn2_b64 vcc, exec, s[70:71]
	v_mov_b32_e32 v130, v131
	s_waitcnt vmcnt(0)
	v_mov_b32_e32 v129, v131
	v_mov_b32_e32 v128, v131
	v_mov_b32_e32 v135, v131
	v_mov_b32_e32 v134, v131
	v_mov_b32_e32 v133, v131
	v_mov_b32_e32 v132, v131
	v_mov_b32_e32 v127, v131
	v_mov_b32_e32 v126, v131
	v_mov_b32_e32 v125, v131
	v_mov_b32_e32 v124, v131
	v_mov_b32_e32 v123, v131
	v_mov_b32_e32 v122, v131
	v_mov_b32_e32 v121, v131
	v_mov_b32_e32 v120, v131
	v_mov_b32_e32 v119, v131
	v_mov_b32_e32 v118, v131
	v_mov_b32_e32 v117, v131
	v_mov_b32_e32 v116, v131
	v_mov_b32_e32 v115, v131
	v_mov_b32_e32 v114, v131
	v_mov_b32_e32 v113, v131
	v_mov_b32_e32 v112, v131
	v_mov_b32_e32 v111, v131
	v_mov_b32_e32 v110, v131
	v_mov_b32_e32 v109, v131
	v_mov_b32_e32 v108, v131
	v_mov_b32_e32 v107, v131
	v_mov_b32_e32 v106, v131
	v_mov_b32_e32 v105, v131
	v_mov_b32_e32 v104, v131
	v_mov_b32_e32 v63, v131
	v_mov_b32_e32 v62, v131
	v_mov_b32_e32 v61, v131
	v_mov_b32_e32 v60, v131
	v_mov_b32_e32 v59, v131
	v_mov_b32_e32 v58, v131
	v_mov_b32_e32 v57, v131
	v_mov_b32_e32 v56, v131
	v_mov_b32_e32 v55, v131
	v_mov_b32_e32 v54, v131
	v_mov_b32_e32 v53, v131
	v_mov_b32_e32 v52, v131
	v_mov_b32_e32 v51, v131
	v_mov_b32_e32 v50, v131
	v_mov_b32_e32 v49, v131
	v_mov_b32_e32 v48, v131
	v_mov_b32_e32 v47, v131
	v_mov_b32_e32 v46, v131
	v_mov_b32_e32 v45, v131
	v_mov_b32_e32 v44, v131
	v_mov_b32_e32 v43, v131
	v_mov_b32_e32 v42, v131
	v_mov_b32_e32 v41, v131
	v_mov_b32_e32 v40, v131
	v_mov_b32_e32 v39, v131
	v_mov_b32_e32 v38, v131
	v_mov_b32_e32 v37, v131
	v_mov_b32_e32 v36, v131
	v_mov_b32_e32 v35, v131
	v_mov_b32_e32 v34, v131
	v_mov_b32_e32 v33, v131
	v_mov_b32_e32 v32, v131
	v_mov_b32_e32 v103, v131
	v_mov_b32_e32 v102, v131
	v_mov_b32_e32 v101, v131
	v_mov_b32_e32 v100, v131
	v_mov_b32_e32 v99, v131
	v_mov_b32_e32 v98, v131
	v_mov_b32_e32 v97, v131
	v_mov_b32_e32 v96, v131
	v_mov_b32_e32 v87, v131
	v_mov_b32_e32 v86, v131
	v_mov_b32_e32 v85, v131
	v_mov_b32_e32 v84, v131
	v_mov_b32_e32 v83, v131
	v_mov_b32_e32 v82, v131
	v_mov_b32_e32 v81, v131
	v_mov_b32_e32 v80, v131
	v_mov_b32_e32 v79, v131
	v_mov_b32_e32 v78, v131
	v_mov_b32_e32 v77, v131
	v_mov_b32_e32 v76, v131
	v_mov_b32_e32 v75, v131
	v_mov_b32_e32 v74, v131
	v_mov_b32_e32 v73, v131
	v_mov_b32_e32 v72, v131
	v_mov_b32_e32 v71, v131
	v_mov_b32_e32 v70, v131
	v_mov_b32_e32 v69, v131
	v_mov_b32_e32 v68, v131
	v_mov_b32_e32 v67, v131
	v_mov_b32_e32 v66, v131
	v_mov_b32_e32 v65, v131
	v_mov_b32_e32 v64, v131
	v_mov_b32_e32 v31, v131
	v_mov_b32_e32 v30, v131
	v_mov_b32_e32 v29, v131
	v_mov_b32_e32 v28, v131
	v_mov_b32_e32 v27, v131
	v_mov_b32_e32 v26, v131
	v_mov_b32_e32 v25, v131
	v_mov_b32_e32 v24, v131
	v_mov_b32_e32 v23, v131
	v_mov_b32_e32 v22, v131
	v_mov_b32_e32 v21, v131
	v_mov_b32_e32 v20, v131
	v_mov_b32_e32 v19, v131
	v_mov_b32_e32 v18, v131
	v_mov_b32_e32 v17, v131
	v_mov_b32_e32 v16, v131
	v_mov_b32_e32 v15, v131
	v_mov_b32_e32 v14, v131
	v_mov_b32_e32 v13, v131
	v_mov_b32_e32 v12, v131
	v_mov_b32_e32 v11, v131
	v_mov_b32_e32 v10, v131
	v_mov_b32_e32 v9, v131
	v_mov_b32_e32 v8, v131
	v_mov_b32_e32 v7, v131
	v_mov_b32_e32 v6, v131
	v_mov_b32_e32 v5, v131
	v_mov_b32_e32 v4, v131
	v_mov_b32_e32 v3, v131
	v_mov_b32_e32 v2, v131
	v_mov_b32_e32 v1, v131
	v_mov_b32_e32 v0, v131
	s_cbranch_vccnz .LBB0_445
	s_add_u32 s0, s0, 0x80
	s_addc_u32 s1, s1, 0
	s_add_u32 s6, s2, 0x100
	v_mov_b32_e32 v0, 0
	s_addc_u32 s7, s3, 0
	s_mov_b32 s2, 0
	v_mov_b32_e32 v1, v0
	v_mov_b32_e32 v2, v0
	v_mov_b32_e32 v3, v0
	v_mov_b32_e32 v4, v0
	v_mov_b32_e32 v5, v0
	v_mov_b32_e32 v6, v0
	v_mov_b32_e32 v7, v0
	v_mov_b32_e32 v8, v0
	v_mov_b32_e32 v9, v0
	v_mov_b32_e32 v10, v0
	v_mov_b32_e32 v11, v0
	v_mov_b32_e32 v12, v0
	v_mov_b32_e32 v13, v0
	v_mov_b32_e32 v14, v0
	v_mov_b32_e32 v15, v0
	v_mov_b32_e32 v16, v0
	v_mov_b32_e32 v17, v0
	v_mov_b32_e32 v18, v0
	v_mov_b32_e32 v19, v0
	v_mov_b32_e32 v20, v0
	v_mov_b32_e32 v21, v0
	v_mov_b32_e32 v22, v0
	v_mov_b32_e32 v23, v0
	v_mov_b32_e32 v24, v0
	v_mov_b32_e32 v25, v0
	v_mov_b32_e32 v26, v0
	v_mov_b32_e32 v27, v0
	v_mov_b32_e32 v28, v0
	v_mov_b32_e32 v29, v0
	v_mov_b32_e32 v30, v0
	v_mov_b32_e32 v31, v0
	v_mov_b32_e32 v64, v0
	v_mov_b32_e32 v65, v0
	v_mov_b32_e32 v66, v0
	v_mov_b32_e32 v67, v0
	v_mov_b32_e32 v68, v0
	v_mov_b32_e32 v69, v0
	v_mov_b32_e32 v70, v0
	v_mov_b32_e32 v71, v0
	v_mov_b32_e32 v72, v0
	v_mov_b32_e32 v73, v0
	v_mov_b32_e32 v74, v0
	v_mov_b32_e32 v75, v0
	v_mov_b32_e32 v76, v0
	v_mov_b32_e32 v77, v0
	v_mov_b32_e32 v78, v0
	v_mov_b32_e32 v79, v0
	v_mov_b32_e32 v80, v0
	v_mov_b32_e32 v81, v0
	v_mov_b32_e32 v82, v0
	v_mov_b32_e32 v83, v0
	v_mov_b32_e32 v84, v0
	v_mov_b32_e32 v85, v0
	v_mov_b32_e32 v86, v0
	v_mov_b32_e32 v87, v0
	v_mov_b32_e32 v96, v0
	v_mov_b32_e32 v97, v0
	v_mov_b32_e32 v98, v0
	v_mov_b32_e32 v99, v0
	v_mov_b32_e32 v100, v0
	v_mov_b32_e32 v101, v0
	v_mov_b32_e32 v102, v0
	v_mov_b32_e32 v103, v0
	v_mov_b32_e32 v32, v0
	v_mov_b32_e32 v33, v0
	v_mov_b32_e32 v34, v0
	v_mov_b32_e32 v35, v0
	v_mov_b32_e32 v36, v0
	v_mov_b32_e32 v37, v0
	v_mov_b32_e32 v38, v0
	v_mov_b32_e32 v39, v0
	v_mov_b32_e32 v40, v0
	v_mov_b32_e32 v41, v0
	v_mov_b32_e32 v42, v0
	v_mov_b32_e32 v43, v0
	v_mov_b32_e32 v44, v0
	v_mov_b32_e32 v45, v0
	v_mov_b32_e32 v46, v0
	v_mov_b32_e32 v47, v0
	v_mov_b32_e32 v48, v0
	v_mov_b32_e32 v49, v0
	v_mov_b32_e32 v50, v0
	v_mov_b32_e32 v51, v0
	v_mov_b32_e32 v52, v0
	v_mov_b32_e32 v53, v0
	v_mov_b32_e32 v54, v0
	v_mov_b32_e32 v55, v0
	v_mov_b32_e32 v56, v0
	v_mov_b32_e32 v57, v0
	v_mov_b32_e32 v58, v0
	v_mov_b32_e32 v59, v0
	v_mov_b32_e32 v60, v0
	v_mov_b32_e32 v61, v0
	v_mov_b32_e32 v62, v0
	v_mov_b32_e32 v63, v0
	v_mov_b32_e32 v104, v0
	v_mov_b32_e32 v105, v0
	v_mov_b32_e32 v106, v0
	v_mov_b32_e32 v107, v0
	v_mov_b32_e32 v108, v0
	v_mov_b32_e32 v109, v0
	v_mov_b32_e32 v110, v0
	v_mov_b32_e32 v111, v0
	v_mov_b32_e32 v112, v0
	v_mov_b32_e32 v113, v0
	v_mov_b32_e32 v114, v0
	v_mov_b32_e32 v115, v0
	v_mov_b32_e32 v116, v0
	v_mov_b32_e32 v117, v0
	v_mov_b32_e32 v118, v0
	v_mov_b32_e32 v119, v0
	v_mov_b32_e32 v120, v0
	v_mov_b32_e32 v121, v0
	v_mov_b32_e32 v122, v0
	v_mov_b32_e32 v123, v0
	v_mov_b32_e32 v124, v0
	v_mov_b32_e32 v125, v0
	v_mov_b32_e32 v126, v0
	v_mov_b32_e32 v127, v0
	v_mov_b32_e32 v132, v0
	v_mov_b32_e32 v133, v0
	v_mov_b32_e32 v134, v0
	v_mov_b32_e32 v135, v0
	v_mov_b32_e32 v128, v0
	v_mov_b32_e32 v129, v0
	v_mov_b32_e32 v130, v0
	v_mov_b32_e32 v131, v0
	v_readfirstlane_b32 s100, v211
	s_cmp_ge_u32 s100, 0x100
	s_cbranch_scc0 .Lprio_skip6
	s_setprio 1
; #define PG8_STAGE(bufoff, gbase, voff) do { _Pragma("unroll") for (int _i = 0; _i < 2; ++_i) \
;         __builtin_amdgcn_global_load_lds((const unsigned*)((const char*)(gbase) + (voff)[_i]), (PG8_LAS unsigned*)(lds + (bufoff) + ldsw + _i * 8192), 16, 0, 0); } while (0)
; #define PG8_LDA(dst, b, h) do { _Pragma("unroll") for (int m = 0; m < 4; ++m) _Pragma("unroll") for (int k = 0; k < 2; ++k) dst[m][k] = *(const PG8_LAS bf16x8*)(lds + PG8_SA(b, h) + aoff + m * 2048 + k * 1024); } while (0)
; #define PG8_LDB(dst, b, h) do { _Pragma("unroll") for (int n = 0; n < 2; ++n) _Pragma("unroll") for (int k = 0; k < 2; ++k) dst[n][k] = *(const PG8_LAS bf16x8*)(lds + PG8_SB(b, h) + boff + n * 2048 + k * 1024); } while (0)
; #define PG8_MMA(ai, bj, At, Bt) do { __builtin_amdgcn_s_setprio(1); _Pragma("unroll") for (int m = 0; m < 4; ++m) _Pragma("unroll") for (int n = 0; n < 2; ++n) _Pragma("unroll") for (int k = 0; k < 2; ++k) \
;         acc[ai][bj][m][n] = __builtin_amdgcn_mfma_f32_16x16x32_bf16(Bt[n][k], At[m][k], acc[ai][bj][m][n], 0, 0, 0); __builtin_amdgcn_s_setprio(0); } while (0)
; #define PG8_WAIT_V(n) asm volatile("s_waitcnt vmcnt(" #n ")" ::: "memory")
; #define PG8_WAIT_L(n) asm volatile("s_waitcnt lgkmcnt(" #n ")" ::: "memory")
; template <class Epi, class Sched, bool ALIGN_EPI = false, bool SP2 = false>
; __device__ __forceinline__ void gemm_phase(PG8_LAS unsigned char* lds, const Gemm g, const Sched& S, const Epi& E) {
;     ...
;             const bool last = (t == nt - 2);
;             const char* a1 = cA + (size_t)(t + 1) * kstep;
;             const char* a2 = last ? nA : cA + (size_t)(t + 2) * kstep; const char* b2 = last ? nB : cB + (size_t)(t + 2) * kstep;
;             const char* a3 = a2 + kstep; const char* b3 = b2 + kstep;
;             if (last && has_next) S.a_ready(nxt);
;             if constexpr (SP2) {
;             PG8_LDB(B0, 0, 0); PG8_LDB(B1, 0, 1); PG8_SCHED; PG8_LDA(At, 0, 0); PG8_STAGE(PG8_SA(1, 1), a1 + hstep, voffA);
;             PG8_WAIT_V(8); PG8_WAIT_L(0); PG8_BAR; PG8_MMA(0, 0, At, B0); PG8_MMA(0, 1, At, B1); PG8_BAR; PG8_SCHED;
;             PG8_LDA(At, 0, 1); PG8_STAGE(PG8_SB(0, 0), b2, voffB); PG8_STAGE(PG8_SB(0, 1), b2 + hstep, voffB); PG8_STAGE(PG8_SA(0, 0), a2, voffA);
;             PG8_WAIT_V(8); PG8_WAIT_L(0); PG8_BAR; PG8_MMA(1, 0, At, B0); PG8_MMA(1, 1, At, B1); PG8_BAR; PG8_SCHED;
.Lprio_skip6:
.LBB0_444:
	s_add_i32 s12, s2, 2
	s_add_u32 s13, s0, 0x80
	s_addc_u32 s3, s1, 0
	s_add_i32 s40, 0, 0x10000
	s_cmp_eq_u32 s34, s2
	s_cselect_b32 s3, s17, s3
	s_cselect_b32 s2, s16, s13
	v_add_u32_e32 v152, s40, v172
	s_cselect_b32 s39, s75, s7
	s_cselect_b32 s38, s74, s6
	s_add_i32 s13, 0, 0x14000
	ds_read_b128 v[88:91], v152
	ds_read_b128 v[92:95], v152 offset:1024
	ds_read_b128 v[148:151], v152 offset:2048
	ds_read_b128 v[168:171], v152 offset:3072
	v_add_u32_e32 v152, s13, v172
	ds_read_b128 v[176:179], v152
	ds_read_b128 v[180:183], v152 offset:1024
	ds_read_b128 v[184:187], v152 offset:2048
	ds_read_b128 v[188:191], v152 offset:3072
	v_lshl_add_u64 v[158:159], s[0:1], 0, v[144:145]
	s_add_i32 m0, s23, 0xc000
	ds_read_b128 v[192:195], v174
	ds_read_b128 v[196:199], v174 offset:1024
	ds_read_b128 v[200:203], v174 offset:2048
	ds_read_b128 v[204:207], v174 offset:3072
	ds_read_b128 v[212:215], v174 offset:4096
	ds_read_b128 v[230:233], v174 offset:5120
	ds_read_b128 v[234:237], v174 offset:6144
	ds_read_b128 v[238:241], v174 offset:7168
	global_load_lds_dwordx4 v[158:159], off
	v_lshl_add_u64 v[158:159], s[0:1], 0, v[146:147]
	s_add_i32 m0, s23, 0xe000
	s_nop 0
	global_load_lds_dwordx4 v[158:159], off
	s_waitcnt vmcnt(8)
	s_waitcnt lgkmcnt(0)
	s_barrier
	s_waitcnt lgkmcnt(0)
	v_mfma_f32_16x16x32_bf16 v[128:131], v[88:91], v[192:195], v[128:131]
	v_mfma_f32_16x16x32_bf16 v[132:135], v[148:151], v[192:195], v[132:135]
	v_mfma_f32_16x16x32_bf16 v[124:127], v[88:91], v[200:203], v[124:127]
	v_mfma_f32_16x16x32_bf16 v[120:123], v[148:151], v[200:203], v[120:123]
	v_mfma_f32_16x16x32_bf16 v[116:119], v[88:91], v[212:215], v[116:119]
	v_mfma_f32_16x16x32_bf16 v[112:115], v[148:151], v[212:215], v[112:115]
	v_mfma_f32_16x16x32_bf16 v[108:111], v[88:91], v[234:237], v[108:111]
	v_mfma_f32_16x16x32_bf16 v[104:107], v[148:151], v[234:237], v[104:107]
	v_mfma_f32_16x16x32_bf16 v[128:131], v[92:95], v[196:199], v[128:131]
	v_mfma_f32_16x16x32_bf16 v[132:135], v[168:171], v[196:199], v[132:135]
	v_mfma_f32_16x16x32_bf16 v[124:127], v[92:95], v[204:207], v[124:127]
	v_mfma_f32_16x16x32_bf16 v[120:123], v[168:171], v[204:207], v[120:123]
	v_mfma_f32_16x16x32_bf16 v[116:119], v[92:95], v[230:233], v[116:119]
	v_mfma_f32_16x16x32_bf16 v[112:115], v[168:171], v[230:233], v[112:115]
	v_mfma_f32_16x16x32_bf16 v[108:111], v[92:95], v[238:241], v[108:111]
	v_mfma_f32_16x16x32_bf16 v[104:107], v[168:171], v[238:241], v[104:107]
	v_mfma_f32_16x16x32_bf16 v[60:63], v[176:179], v[192:195], v[60:63]
	v_mfma_f32_16x16x32_bf16 v[56:59], v[184:187], v[192:195], v[56:59]
	v_mfma_f32_16x16x32_bf16 v[52:55], v[176:179], v[200:203], v[52:55]
	v_mfma_f32_16x16x32_bf16 v[48:51], v[184:187], v[200:203], v[48:51]
	v_mfma_f32_16x16x32_bf16 v[44:47], v[176:179], v[212:215], v[44:47]
	v_mfma_f32_16x16x32_bf16 v[40:43], v[184:187], v[212:215], v[40:43]
	v_mfma_f32_16x16x32_bf16 v[36:39], v[176:179], v[234:237], v[36:39]
	v_mfma_f32_16x16x32_bf16 v[32:35], v[184:187], v[234:237], v[32:35]
	v_mfma_f32_16x16x32_bf16 v[60:63], v[180:183], v[196:199], v[60:63]
	v_mfma_f32_16x16x32_bf16 v[56:59], v[188:191], v[196:199], v[56:59]
	v_mfma_f32_16x16x32_bf16 v[52:55], v[180:183], v[204:207], v[52:55]
	v_mfma_f32_16x16x32_bf16 v[48:51], v[188:191], v[204:207], v[48:51]
	v_mfma_f32_16x16x32_bf16 v[44:47], v[180:183], v[230:233], v[44:47]
	v_mfma_f32_16x16x32_bf16 v[40:43], v[188:191], v[230:233], v[40:43]
	v_mfma_f32_16x16x32_bf16 v[36:39], v[180:183], v[238:241], v[36:39]
	v_mfma_f32_16x16x32_bf16 v[32:35], v[188:191], v[238:241], v[32:35]
	s_barrier
	s_add_i32 s40, s40, s22
	v_lshl_add_u64 v[158:159], s[38:39], 0, v[140:141]
	s_mov_b32 m0, s40
	ds_read_b128 v[192:195], v174 offset:16384
	ds_read_b128 v[196:199], v174 offset:17408
	ds_read_b128 v[200:203], v174 offset:18432
	ds_read_b128 v[204:207], v174 offset:19456
	ds_read_b128 v[212:215], v174 offset:20480
	ds_read_b128 v[230:233], v174 offset:21504
	ds_read_b128 v[234:237], v174 offset:22528
	ds_read_b128 v[238:241], v174 offset:23552
	global_load_lds_dwordx4 v[158:159], off
	s_add_i32 m0, s40, 0x2000
	v_lshl_add_u64 v[160:161], s[38:39], 0, v[136:137]
	s_add_u32 s38, s38, s14
	s_addc_u32 s39, s39, s15
	s_add_i32 s13, s13, s22
	global_load_lds_dwordx4 v[160:161], off
	v_lshl_add_u64 v[162:163], s[38:39], 0, v[140:141]
	s_mov_b32 m0, s13
	v_lshl_add_u64 v[164:165], s[38:39], 0, v[136:137]
	global_load_lds_dwordx4 v[162:163], off
	s_add_i32 m0, s13, 0x2000
	v_lshl_add_u64 v[208:209], s[2:3], 0, v[142:143]
	global_load_lds_dwordx4 v[164:165], off
	s_mov_b32 m0, s23
	v_lshl_add_u64 v[216:217], s[2:3], 0, v[138:139]
	global_load_lds_dwordx4 v[208:209], off
	s_mov_b32 m0, s24
	s_nop 0
	global_load_lds_dwordx4 v[216:217], off
	s_waitcnt vmcnt(8)
	s_waitcnt lgkmcnt(0)
	s_barrier
; #define PG8_STAGE(bufoff, gbase, voff) do { _Pragma("unroll") for (int _i = 0; _i < 2; ++_i) \
;         __builtin_amdgcn_global_load_lds((const unsigned*)((const char*)(gbase) + (voff)[_i]), (PG8_LAS unsigned*)(lds + (bufoff) + ldsw + _i * 8192), 16, 0, 0); } while (0)
; #define PG8_LDA(dst, b, h) do { _Pragma("unroll") for (int m = 0; m < 4; ++m) _Pragma("unroll") for (int k = 0; k < 2; ++k) dst[m][k] = *(const PG8_LAS bf16x8*)(lds + PG8_SA(b, h) + aoff + m * 2048 + k * 1024); } while (0)
; #define PG8_LDB(dst, b, h) do { _Pragma("unroll") for (int n = 0; n < 2; ++n) _Pragma("unroll") for (int k = 0; k < 2; ++k) dst[n][k] = *(const PG8_LAS bf16x8*)(lds + PG8_SB(b, h) + boff + n * 2048 + k * 1024); } while (0)
; #define PG8_MMA(ai, bj, At, Bt) do { __builtin_amdgcn_s_setprio(1); _Pragma("unroll") for (int m = 0; m < 4; ++m) _Pragma("unroll") for (int n = 0; n < 2; ++n) _Pragma("unroll") for (int k = 0; k < 2; ++k) \
;         acc[ai][bj][m][n] = __builtin_amdgcn_mfma_f32_16x16x32_bf16(Bt[n][k], At[m][k], acc[ai][bj][m][n], 0, 0, 0); __builtin_amdgcn_s_setprio(0); } while (0)
; #define PG8_WAIT_V(n) asm volatile("s_waitcnt vmcnt(" #n ")" ::: "memory")
; #define PG8_WAIT_L(n) asm volatile("s_waitcnt lgkmcnt(" #n ")" ::: "memory")
; #define PG8_BAR __builtin_amdgcn_s_barrier()
; #define PG8_SCHED __builtin_amdgcn_sched_barrier(0)
; template <class Epi, class Sched, bool ALIGN_EPI = false, bool SP2 = false>
; __device__ __forceinline__ void gemm_phase(PG8_LAS unsigned char* lds, const Gemm g, const Sched& S, const Epi& E) {
;     ...
;             PG8_WAIT_V(8); PG8_WAIT_L(0); PG8_BAR; PG8_MMA(1, 0, At, B0); PG8_MMA(1, 1, At, B1); PG8_BAR; PG8_SCHED;
;             PG8_LDB(B0, 1, 0); PG8_LDB(B1, 1, 1); PG8_SCHED; PG8_LDA(At, 1, 0); PG8_STAGE(PG8_SA(0, 1), a2 + hstep, voffA);
;             PG8_WAIT_V(8); PG8_WAIT_L(0); PG8_BAR; PG8_MMA(0, 0, At, B0); PG8_MMA(0, 1, At, B1); PG8_BAR; PG8_SCHED;
	s_waitcnt lgkmcnt(0)
	v_mfma_f32_16x16x32_bf16 v[100:103], v[88:91], v[192:195], v[100:103]
	v_mfma_f32_16x16x32_bf16 v[96:99], v[148:151], v[192:195], v[96:99]
	v_mfma_f32_16x16x32_bf16 v[84:87], v[88:91], v[200:203], v[84:87]
	v_mfma_f32_16x16x32_bf16 v[80:83], v[148:151], v[200:203], v[80:83]
	v_mfma_f32_16x16x32_bf16 v[76:79], v[88:91], v[212:215], v[76:79]
	v_mfma_f32_16x16x32_bf16 v[72:75], v[148:151], v[212:215], v[72:75]
	v_mfma_f32_16x16x32_bf16 v[68:71], v[88:91], v[234:237], v[68:71]
	v_mfma_f32_16x16x32_bf16 v[64:67], v[148:151], v[234:237], v[64:67]
	v_mfma_f32_16x16x32_bf16 v[100:103], v[92:95], v[196:199], v[100:103]
	v_mfma_f32_16x16x32_bf16 v[96:99], v[168:171], v[196:199], v[96:99]
	v_mfma_f32_16x16x32_bf16 v[84:87], v[92:95], v[204:207], v[84:87]
	v_mfma_f32_16x16x32_bf16 v[80:83], v[168:171], v[204:207], v[80:83]
	v_mfma_f32_16x16x32_bf16 v[76:79], v[92:95], v[230:233], v[76:79]
	v_mfma_f32_16x16x32_bf16 v[72:75], v[168:171], v[230:233], v[72:75]
	v_mfma_f32_16x16x32_bf16 v[68:71], v[92:95], v[238:241], v[68:71]
	v_mfma_f32_16x16x32_bf16 v[64:67], v[168:171], v[238:241], v[64:67]
	v_mfma_f32_16x16x32_bf16 v[28:31], v[176:179], v[192:195], v[28:31]
	v_mfma_f32_16x16x32_bf16 v[24:27], v[184:187], v[192:195], v[24:27]
	v_mfma_f32_16x16x32_bf16 v[20:23], v[176:179], v[200:203], v[20:23]
	v_mfma_f32_16x16x32_bf16 v[16:19], v[184:187], v[200:203], v[16:19]
	v_mfma_f32_16x16x32_bf16 v[12:15], v[176:179], v[212:215], v[12:15]
	v_mfma_f32_16x16x32_bf16 v[8:11], v[184:187], v[212:215], v[8:11]
	v_mfma_f32_16x16x32_bf16 v[4:7], v[176:179], v[234:237], v[4:7]
	v_mfma_f32_16x16x32_bf16 v[0:3], v[184:187], v[234:237], v[0:3]
	v_mfma_f32_16x16x32_bf16 v[28:31], v[180:183], v[196:199], v[28:31]
	v_mfma_f32_16x16x32_bf16 v[24:27], v[188:191], v[196:199], v[24:27]
	v_mfma_f32_16x16x32_bf16 v[20:23], v[180:183], v[204:207], v[20:23]
	v_mfma_f32_16x16x32_bf16 v[16:19], v[188:191], v[204:207], v[16:19]
	v_mfma_f32_16x16x32_bf16 v[12:15], v[180:183], v[230:233], v[12:15]
	v_mfma_f32_16x16x32_bf16 v[8:11], v[188:191], v[230:233], v[8:11]
	v_mfma_f32_16x16x32_bf16 v[4:7], v[180:183], v[238:241], v[4:7]
	v_mfma_f32_16x16x32_bf16 v[0:3], v[188:191], v[238:241], v[0:3]
	s_barrier
	s_add_i32 s13, 0, 0x18000
	v_add_u32_e32 v152, s13, v172
	s_add_i32 s38, 0, 0x1c000
	ds_read_b128 v[88:91], v152
	ds_read_b128 v[92:95], v152 offset:1024
	ds_read_b128 v[148:151], v152 offset:2048
	ds_read_b128 v[168:171], v152 offset:3072
	v_add_u32_e32 v152, s38, v172
	ds_read_b128 v[176:179], v152
	ds_read_b128 v[180:183], v152 offset:1024
	ds_read_b128 v[184:187], v152 offset:2048
	ds_read_b128 v[188:191], v152 offset:3072
	s_add_u32 s2, s2, s14
	s_addc_u32 s3, s3, s15
	s_mov_b32 m0, s25
	v_lshl_add_u64 v[242:243], s[2:3], 0, v[142:143]
	ds_read_b128 v[192:195], v174 offset:32768
	ds_read_b128 v[196:199], v174 offset:33792
	ds_read_b128 v[200:203], v174 offset:34816
	ds_read_b128 v[204:207], v174 offset:35840
	ds_read_b128 v[212:215], v174 offset:36864
	ds_read_b128 v[230:233], v174 offset:37888
	ds_read_b128 v[234:237], v174 offset:38912
	ds_read_b128 v[238:241], v174 offset:39936
	global_load_lds_dwordx4 v[242:243], off
	v_lshl_add_u64 v[242:243], s[2:3], 0, v[138:139]
	s_mov_b32 m0, s28
	s_nop 0
	global_load_lds_dwordx4 v[242:243], off
	s_waitcnt vmcnt(8)
	s_waitcnt lgkmcnt(0)
	s_barrier
	s_waitcnt lgkmcnt(0)
	v_mfma_f32_16x16x32_bf16 v[128:131], v[88:91], v[192:195], v[128:131]
	v_mfma_f32_16x16x32_bf16 v[132:135], v[148:151], v[192:195], v[132:135]
	v_mfma_f32_16x16x32_bf16 v[124:127], v[88:91], v[200:203], v[124:127]
	v_mfma_f32_16x16x32_bf16 v[120:123], v[148:151], v[200:203], v[120:123]
	v_mfma_f32_16x16x32_bf16 v[116:119], v[88:91], v[212:215], v[116:119]
	v_mfma_f32_16x16x32_bf16 v[112:115], v[148:151], v[212:215], v[112:115]
	v_mfma_f32_16x16x32_bf16 v[108:111], v[88:91], v[234:237], v[108:111]
	v_mfma_f32_16x16x32_bf16 v[104:107], v[148:151], v[234:237], v[104:107]
	v_mfma_f32_16x16x32_bf16 v[128:131], v[92:95], v[196:199], v[128:131]
	v_mfma_f32_16x16x32_bf16 v[132:135], v[168:171], v[196:199], v[132:135]
	v_mfma_f32_16x16x32_bf16 v[124:127], v[92:95], v[204:207], v[124:127]
	v_mfma_f32_16x16x32_bf16 v[120:123], v[168:171], v[204:207], v[120:123]
	v_mfma_f32_16x16x32_bf16 v[116:119], v[92:95], v[230:233], v[116:119]
	v_mfma_f32_16x16x32_bf16 v[112:115], v[168:171], v[230:233], v[112:115]
	v_mfma_f32_16x16x32_bf16 v[108:111], v[92:95], v[238:241], v[108:111]
	v_mfma_f32_16x16x32_bf16 v[104:107], v[168:171], v[238:241], v[104:107]
	v_mfma_f32_16x16x32_bf16 v[60:63], v[176:179], v[192:195], v[60:63]
	v_mfma_f32_16x16x32_bf16 v[56:59], v[184:187], v[192:195], v[56:59]
	v_mfma_f32_16x16x32_bf16 v[52:55], v[176:179], v[200:203], v[52:55]
	v_mfma_f32_16x16x32_bf16 v[48:51], v[184:187], v[200:203], v[48:51]
	v_mfma_f32_16x16x32_bf16 v[44:47], v[176:179], v[212:215], v[44:47]
	v_mfma_f32_16x16x32_bf16 v[40:43], v[184:187], v[212:215], v[40:43]
	v_mfma_f32_16x16x32_bf16 v[36:39], v[176:179], v[234:237], v[36:39]
	v_mfma_f32_16x16x32_bf16 v[32:35], v[184:187], v[234:237], v[32:35]
	v_mfma_f32_16x16x32_bf16 v[60:63], v[180:183], v[196:199], v[60:63]
	v_mfma_f32_16x16x32_bf16 v[56:59], v[188:191], v[196:199], v[56:59]
	v_mfma_f32_16x16x32_bf16 v[52:55], v[180:183], v[204:207], v[52:55]
	v_mfma_f32_16x16x32_bf16 v[48:51], v[188:191], v[204:207], v[48:51]
	v_mfma_f32_16x16x32_bf16 v[44:47], v[180:183], v[230:233], v[44:47]
	v_mfma_f32_16x16x32_bf16 v[40:43], v[188:191], v[230:233], v[40:43]
	v_mfma_f32_16x16x32_bf16 v[36:39], v[180:183], v[238:241], v[36:39]
	v_mfma_f32_16x16x32_bf16 v[32:35], v[188:191], v[238:241], v[32:35]
	s_barrier
; #define PG8_STAGE(bufoff, gbase, voff) do { _Pragma("unroll") for (int _i = 0; _i < 2; ++_i) \
;         __builtin_amdgcn_global_load_lds((const unsigned*)((const char*)(gbase) + (voff)[_i]), (PG8_LAS unsigned*)(lds + (bufoff) + ldsw + _i * 8192), 16, 0, 0); } while (0)
; #define PG8_LDA(dst, b, h) do { _Pragma("unroll") for (int m = 0; m < 4; ++m) _Pragma("unroll") for (int k = 0; k < 2; ++k) dst[m][k] = *(const PG8_LAS bf16x8*)(lds + PG8_SA(b, h) + aoff + m * 2048 + k * 1024); } while (0)
; #define PG8_MMA(ai, bj, At, Bt) do { __builtin_amdgcn_s_setprio(1); _Pragma("unroll") for (int m = 0; m < 4; ++m) _Pragma("unroll") for (int n = 0; n < 2; ++n) _Pragma("unroll") for (int k = 0; k < 2; ++k) \
;         acc[ai][bj][m][n] = __builtin_amdgcn_mfma_f32_16x16x32_bf16(Bt[n][k], At[m][k], acc[ai][bj][m][n], 0, 0, 0); __builtin_amdgcn_s_setprio(0); } while (0)
; #define PG8_WAIT_V(n) asm volatile("s_waitcnt vmcnt(" #n ")" ::: "memory")
; #define PG8_WAIT_L(n) asm volatile("s_waitcnt lgkmcnt(" #n ")" ::: "memory")
; #define PG8_BAR __builtin_amdgcn_s_barrier()
; #define PG8_SCHED __builtin_amdgcn_sched_barrier(0)
; template <class Epi, class Sched, bool ALIGN_EPI = false, bool SP2 = false>
; __device__ __forceinline__ void gemm_phase(PG8_LAS unsigned char* lds, const Gemm g, const Sched& S, const Epi& E) {
;     ...
;         for (int t = 0; t < nt; t += 2) {
;             const bool last = (t == nt - 2);
;     ...
;             PG8_LDA(At, 1, 1); PG8_STAGE(PG8_SB(1, 0), b3, voffB); PG8_STAGE(PG8_SB(1, 1), b3 + hstep, voffB); PG8_STAGE(PG8_SA(1, 0), a3, voffA);
;             PG8_WAIT_V(8); PG8_WAIT_L(0); PG8_BAR; PG8_MMA(1, 0, At, B0); PG8_MMA(1, 1, At, B1); PG8_BAR; PG8_SCHED;
	s_add_i32 s2, s13, s22
	v_lshl_add_u64 v[158:159], v[158:159], 0, s[82:83]
	s_mov_b32 m0, s2
	ds_read_b128 v[192:195], v174 offset:49152
	ds_read_b128 v[196:199], v174 offset:50176
	ds_read_b128 v[200:203], v174 offset:51200
	ds_read_b128 v[204:207], v174 offset:52224
	ds_read_b128 v[212:215], v174 offset:53248
	ds_read_b128 v[230:233], v174 offset:54272
	ds_read_b128 v[234:237], v174 offset:55296
	ds_read_b128 v[238:241], v174 offset:56320
	global_load_lds_dwordx4 v[158:159], off
	v_lshl_add_u64 v[158:159], v[160:161], 0, s[82:83]
	s_add_i32 m0, s2, 0x2000
	s_add_i32 s2, s38, s22
	global_load_lds_dwordx4 v[158:159], off
	v_lshl_add_u64 v[158:159], v[162:163], 0, s[82:83]
	s_mov_b32 m0, s2
	s_nop 0
	global_load_lds_dwordx4 v[158:159], off
	v_lshl_add_u64 v[158:159], v[164:165], 0, s[82:83]
	s_add_i32 m0, s2, 0x2000
	s_nop 0
	global_load_lds_dwordx4 v[158:159], off
	v_lshl_add_u64 v[158:159], v[208:209], 0, s[82:83]
	s_mov_b32 m0, s29
	s_nop 0
	global_load_lds_dwordx4 v[158:159], off
	v_lshl_add_u64 v[158:159], v[216:217], 0, s[82:83]
	s_mov_b32 m0, s30
	s_nop 0
	global_load_lds_dwordx4 v[158:159], off
	s_waitcnt vmcnt(8)
	s_waitcnt lgkmcnt(0)
	s_barrier
	s_waitcnt lgkmcnt(0)
	v_mfma_f32_16x16x32_bf16 v[100:103], v[88:91], v[192:195], v[100:103]
	v_mfma_f32_16x16x32_bf16 v[96:99], v[148:151], v[192:195], v[96:99]
	v_mfma_f32_16x16x32_bf16 v[84:87], v[88:91], v[200:203], v[84:87]
	v_mfma_f32_16x16x32_bf16 v[80:83], v[148:151], v[200:203], v[80:83]
	v_mfma_f32_16x16x32_bf16 v[76:79], v[88:91], v[212:215], v[76:79]
	v_mfma_f32_16x16x32_bf16 v[72:75], v[148:151], v[212:215], v[72:75]
	v_mfma_f32_16x16x32_bf16 v[68:71], v[88:91], v[234:237], v[68:71]
	v_mfma_f32_16x16x32_bf16 v[64:67], v[148:151], v[234:237], v[64:67]
	v_mfma_f32_16x16x32_bf16 v[100:103], v[92:95], v[196:199], v[100:103]
	v_mfma_f32_16x16x32_bf16 v[96:99], v[168:171], v[196:199], v[96:99]
	v_mfma_f32_16x16x32_bf16 v[84:87], v[92:95], v[204:207], v[84:87]
	v_mfma_f32_16x16x32_bf16 v[80:83], v[168:171], v[204:207], v[80:83]
	v_mfma_f32_16x16x32_bf16 v[76:79], v[92:95], v[230:233], v[76:79]
	v_mfma_f32_16x16x32_bf16 v[72:75], v[168:171], v[230:233], v[72:75]
	v_mfma_f32_16x16x32_bf16 v[68:71], v[92:95], v[238:241], v[68:71]
	v_mfma_f32_16x16x32_bf16 v[64:67], v[168:171], v[238:241], v[64:67]
	v_mfma_f32_16x16x32_bf16 v[28:31], v[176:179], v[192:195], v[28:31]
	v_mfma_f32_16x16x32_bf16 v[24:27], v[184:187], v[192:195], v[24:27]
	v_mfma_f32_16x16x32_bf16 v[20:23], v[176:179], v[200:203], v[20:23]
	v_mfma_f32_16x16x32_bf16 v[16:19], v[184:187], v[200:203], v[16:19]
	v_mfma_f32_16x16x32_bf16 v[12:15], v[176:179], v[212:215], v[12:15]
	v_mfma_f32_16x16x32_bf16 v[8:11], v[184:187], v[212:215], v[8:11]
	v_mfma_f32_16x16x32_bf16 v[4:7], v[176:179], v[234:237], v[4:7]
	v_mfma_f32_16x16x32_bf16 v[0:3], v[184:187], v[234:237], v[0:3]
	v_mfma_f32_16x16x32_bf16 v[28:31], v[180:183], v[196:199], v[28:31]
	v_mfma_f32_16x16x32_bf16 v[24:27], v[188:191], v[196:199], v[24:27]
	v_mfma_f32_16x16x32_bf16 v[20:23], v[180:183], v[204:207], v[20:23]
	v_mfma_f32_16x16x32_bf16 v[16:19], v[188:191], v[204:207], v[16:19]
	v_mfma_f32_16x16x32_bf16 v[12:15], v[180:183], v[230:233], v[12:15]
	v_mfma_f32_16x16x32_bf16 v[8:11], v[188:191], v[230:233], v[8:11]
	v_mfma_f32_16x16x32_bf16 v[4:7], v[180:183], v[238:241], v[4:7]
	v_mfma_f32_16x16x32_bf16 v[0:3], v[188:191], v[238:241], v[0:3]
	s_barrier
	s_add_u32 s0, s0, 0x100
	s_addc_u32 s1, s1, 0
	s_add_u32 s6, s6, 0x100
	s_addc_u32 s7, s7, 0
	s_cmp_ge_i32 s12, s31
	s_mov_b32 s2, s12
	s_cbranch_scc0 .LBB0_444
	s_setprio 0

; template <class Epi, class Sched, bool ALIGN_EPI = false, bool SP2 = false>
; __device__ __forceinline__ void gemm_phase(PG8_LAS unsigned char* lds, const Gemm g, const Sched& S, const Epi& E) {
;     ...
;         for (int t = 0; t < nt; t += 2) {
;             const bool last = (t == nt - 2);
;     ...
; #pragma unroll
;         for (int a = 0; a < 2; ++a)
; #pragma unroll
;             for (int b = 0; b < 2; ++b)
; #pragma unroll
;                 for (int m = 0; m < 4; ++m)
; #pragma unroll
;                     for (int n = 0; n < 2; ++n) acc[a][b][m][n] = (f32x4){0.f, 0.f, 0.f, 0.f};
;         cur = nxt; cA = nA; cB = nB; ++ui;
.LBB0_564:
	v_mov_b32_e32 v123, 0
	s_andn2_b64 vcc, exec, s[10:11]
	v_mov_b32_e32 v122, v123
	v_mov_b32_e32 v121, v123
	v_mov_b32_e32 v120, v123
	v_mov_b32_e32 v127, v123
	v_mov_b32_e32 v126, v123
	v_mov_b32_e32 v125, v123
	v_mov_b32_e32 v124, v123
	v_mov_b32_e32 v111, v123
	v_mov_b32_e32 v110, v123
	v_mov_b32_e32 v109, v123
	v_mov_b32_e32 v108, v123
	v_mov_b32_e32 v107, v123
	v_mov_b32_e32 v106, v123
	v_mov_b32_e32 v105, v123
	v_mov_b32_e32 v104, v123
	v_mov_b32_e32 v95, v123
	v_mov_b32_e32 v94, v123
	v_mov_b32_e32 v93, v123
	v_mov_b32_e32 v92, v123
	v_mov_b32_e32 v91, v123
	v_mov_b32_e32 v90, v123
	v_mov_b32_e32 v89, v123
	v_mov_b32_e32 v88, v123
	v_mov_b32_e32 v79, v123
	v_mov_b32_e32 v78, v123
	v_mov_b32_e32 v77, v123
	v_mov_b32_e32 v76, v123
	v_mov_b32_e32 v75, v123
	v_mov_b32_e32 v74, v123
	v_mov_b32_e32 v73, v123
	v_mov_b32_e32 v72, v123
	v_mov_b32_e32 v119, v123
	v_mov_b32_e32 v118, v123
	v_mov_b32_e32 v117, v123
	v_mov_b32_e32 v116, v123
	v_mov_b32_e32 v115, v123
	v_mov_b32_e32 v114, v123
	v_mov_b32_e32 v113, v123
	v_mov_b32_e32 v112, v123
	v_mov_b32_e32 v103, v123
	v_mov_b32_e32 v102, v123
	v_mov_b32_e32 v101, v123
	v_mov_b32_e32 v100, v123
	v_mov_b32_e32 v99, v123
	v_mov_b32_e32 v98, v123
	v_mov_b32_e32 v97, v123
	v_mov_b32_e32 v96, v123
	v_mov_b32_e32 v87, v123
	v_mov_b32_e32 v86, v123
	v_mov_b32_e32 v85, v123
	v_mov_b32_e32 v84, v123
	v_mov_b32_e32 v83, v123
	v_mov_b32_e32 v82, v123
	v_mov_b32_e32 v81, v123
	v_mov_b32_e32 v80, v123
	v_mov_b32_e32 v71, v123
	v_mov_b32_e32 v70, v123
	v_mov_b32_e32 v69, v123
	v_mov_b32_e32 v68, v123
	v_mov_b32_e32 v67, v123
	v_mov_b32_e32 v66, v123
	v_mov_b32_e32 v65, v123
	v_mov_b32_e32 v64, v123
	v_mov_b32_e32 v63, v123
	v_mov_b32_e32 v62, v123
	v_mov_b32_e32 v61, v123
	v_mov_b32_e32 v60, v123
	v_mov_b32_e32 v59, v123
	v_mov_b32_e32 v58, v123
	v_mov_b32_e32 v57, v123
	v_mov_b32_e32 v56, v123
	v_mov_b32_e32 v47, v123
	v_mov_b32_e32 v46, v123
	v_mov_b32_e32 v45, v123
	v_mov_b32_e32 v44, v123
	v_mov_b32_e32 v43, v123
	v_mov_b32_e32 v42, v123
	v_mov_b32_e32 v41, v123
	v_mov_b32_e32 v40, v123
	v_mov_b32_e32 v31, v123
	v_mov_b32_e32 v30, v123
	v_mov_b32_e32 v29, v123
	v_mov_b32_e32 v28, v123
	v_mov_b32_e32 v27, v123
	v_mov_b32_e32 v26, v123
	v_mov_b32_e32 v25, v123
	v_mov_b32_e32 v24, v123
	v_mov_b32_e32 v15, v123
	v_mov_b32_e32 v14, v123
	v_mov_b32_e32 v13, v123
	v_mov_b32_e32 v12, v123
	v_mov_b32_e32 v11, v123
	v_mov_b32_e32 v10, v123
	v_mov_b32_e32 v9, v123
	v_mov_b32_e32 v8, v123
	v_mov_b32_e32 v55, v123
	v_mov_b32_e32 v54, v123
	v_mov_b32_e32 v53, v123
	v_mov_b32_e32 v52, v123
	v_mov_b32_e32 v51, v123
	v_mov_b32_e32 v50, v123
	v_mov_b32_e32 v49, v123
	v_mov_b32_e32 v48, v123
	v_mov_b32_e32 v39, v123
	v_mov_b32_e32 v38, v123
	v_mov_b32_e32 v37, v123
	v_mov_b32_e32 v36, v123
	v_mov_b32_e32 v35, v123
	v_mov_b32_e32 v34, v123
	v_mov_b32_e32 v33, v123
	v_mov_b32_e32 v32, v123
	v_mov_b32_e32 v23, v123
	v_mov_b32_e32 v22, v123
	v_mov_b32_e32 v21, v123
	v_mov_b32_e32 v20, v123
	v_mov_b32_e32 v19, v123
	v_mov_b32_e32 v18, v123
	v_mov_b32_e32 v17, v123
	v_mov_b32_e32 v16, v123
	v_mov_b32_e32 v7, v123
	v_mov_b32_e32 v6, v123
	v_mov_b32_e32 v5, v123
	v_mov_b32_e32 v4, v123
	v_mov_b32_e32 v3, v123
	v_mov_b32_e32 v2, v123
	v_mov_b32_e32 v1, v123
	v_mov_b32_e32 v0, v123
	s_cbranch_vccnz .LBB0_567
	s_add_u32 s20, s20, 0x80
	s_addc_u32 s21, s21, 0
	s_add_u32 s42, s22, 0x100
	v_mov_b32_e32 v0, 0
	s_addc_u32 s43, s23, 0
	s_mov_b32 s22, 0
	v_mov_b32_e32 v1, v0
	v_mov_b32_e32 v2, v0
	v_mov_b32_e32 v3, v0
	v_mov_b32_e32 v4, v0
	v_mov_b32_e32 v5, v0
	v_mov_b32_e32 v6, v0
	v_mov_b32_e32 v7, v0
	v_mov_b32_e32 v16, v0
	v_mov_b32_e32 v17, v0
	v_mov_b32_e32 v18, v0
	v_mov_b32_e32 v19, v0
	v_mov_b32_e32 v20, v0
	v_mov_b32_e32 v21, v0
	v_mov_b32_e32 v22, v0
	v_mov_b32_e32 v23, v0
	v_mov_b32_e32 v32, v0
	v_mov_b32_e32 v33, v0
	v_mov_b32_e32 v34, v0
	v_mov_b32_e32 v35, v0
	v_mov_b32_e32 v36, v0
	v_mov_b32_e32 v37, v0
	v_mov_b32_e32 v38, v0
	v_mov_b32_e32 v39, v0
	v_mov_b32_e32 v48, v0
	v_mov_b32_e32 v49, v0
	v_mov_b32_e32 v50, v0
	v_mov_b32_e32 v51, v0
	v_mov_b32_e32 v52, v0
	v_mov_b32_e32 v53, v0
	v_mov_b32_e32 v54, v0
	v_mov_b32_e32 v55, v0
	v_mov_b32_e32 v8, v0
	v_mov_b32_e32 v9, v0
	v_mov_b32_e32 v10, v0
	v_mov_b32_e32 v11, v0
	v_mov_b32_e32 v12, v0
	v_mov_b32_e32 v13, v0
	v_mov_b32_e32 v14, v0
	v_mov_b32_e32 v15, v0
	v_mov_b32_e32 v24, v0
	v_mov_b32_e32 v25, v0
	v_mov_b32_e32 v26, v0
	v_mov_b32_e32 v27, v0
	v_mov_b32_e32 v28, v0
	v_mov_b32_e32 v29, v0
	v_mov_b32_e32 v30, v0
	v_mov_b32_e32 v31, v0
	v_mov_b32_e32 v40, v0
	v_mov_b32_e32 v41, v0
	v_mov_b32_e32 v42, v0
	v_mov_b32_e32 v43, v0
	v_mov_b32_e32 v44, v0
	v_mov_b32_e32 v45, v0
	v_mov_b32_e32 v46, v0
	v_mov_b32_e32 v47, v0
	v_mov_b32_e32 v56, v0
	v_mov_b32_e32 v57, v0
	v_mov_b32_e32 v58, v0
	v_mov_b32_e32 v59, v0
	v_mov_b32_e32 v60, v0
	v_mov_b32_e32 v61, v0
	v_mov_b32_e32 v62, v0
	v_mov_b32_e32 v63, v0
	v_mov_b32_e32 v64, v0
	v_mov_b32_e32 v65, v0
	v_mov_b32_e32 v66, v0
	v_mov_b32_e32 v67, v0
	v_mov_b32_e32 v68, v0
	v_mov_b32_e32 v69, v0
	v_mov_b32_e32 v70, v0
	v_mov_b32_e32 v71, v0
	v_mov_b32_e32 v80, v0
	v_mov_b32_e32 v81, v0
	v_mov_b32_e32 v82, v0
	v_mov_b32_e32 v83, v0
	v_mov_b32_e32 v84, v0
	v_mov_b32_e32 v85, v0
	v_mov_b32_e32 v86, v0
	v_mov_b32_e32 v87, v0
	v_mov_b32_e32 v96, v0
	v_mov_b32_e32 v97, v0
	v_mov_b32_e32 v98, v0
	v_mov_b32_e32 v99, v0
	v_mov_b32_e32 v100, v0
	v_mov_b32_e32 v101, v0
	v_mov_b32_e32 v102, v0
	v_mov_b32_e32 v103, v0
	v_mov_b32_e32 v112, v0
	v_mov_b32_e32 v113, v0
	v_mov_b32_e32 v114, v0
	v_mov_b32_e32 v115, v0
	v_mov_b32_e32 v116, v0
	v_mov_b32_e32 v117, v0
	v_mov_b32_e32 v118, v0
	v_mov_b32_e32 v119, v0
	v_mov_b32_e32 v72, v0
	v_mov_b32_e32 v73, v0
	v_mov_b32_e32 v74, v0
	v_mov_b32_e32 v75, v0
	v_mov_b32_e32 v76, v0
	v_mov_b32_e32 v77, v0
	v_mov_b32_e32 v78, v0
	v_mov_b32_e32 v79, v0
	v_mov_b32_e32 v88, v0
	v_mov_b32_e32 v89, v0
	v_mov_b32_e32 v90, v0
	v_mov_b32_e32 v91, v0
	v_mov_b32_e32 v92, v0
	v_mov_b32_e32 v93, v0
	v_mov_b32_e32 v94, v0
	v_mov_b32_e32 v95, v0
	v_mov_b32_e32 v104, v0
	v_mov_b32_e32 v105, v0
	v_mov_b32_e32 v106, v0
	v_mov_b32_e32 v107, v0
	v_mov_b32_e32 v108, v0
	v_mov_b32_e32 v109, v0
	v_mov_b32_e32 v110, v0
	v_mov_b32_e32 v111, v0
	v_mov_b32_e32 v124, v0
	v_mov_b32_e32 v125, v0
	v_mov_b32_e32 v126, v0
	v_mov_b32_e32 v127, v0
	v_mov_b32_e32 v120, v0
	v_mov_b32_e32 v121, v0
	v_mov_b32_e32 v122, v0
	v_mov_b32_e32 v123, v0
	v_readfirstlane_b32 s100, v211
	s_cmp_ge_u32 s100, 0x100
	s_cbranch_scc0 .Lprio_skip5
	s_setprio 1
; #define PG8_STAGE(bufoff, gbase, voff) do { _Pragma("unroll") for (int _i = 0; _i < 2; ++_i) \
;         __builtin_amdgcn_global_load_lds((const unsigned*)((const char*)(gbase) + (voff)[_i]), (PG8_LAS unsigned*)(lds + (bufoff) + ldsw + _i * 8192), 16, 0, 0); } while (0)
; #define PG8_LDA(dst, b, h) do { _Pragma("unroll") for (int m = 0; m < 4; ++m) _Pragma("unroll") for (int k = 0; k < 2; ++k) dst[m][k] = *(const PG8_LAS bf16x8*)(lds + PG8_SA(b, h) + aoff + m * 2048 + k * 1024); } while (0)
; #define PG8_LDB(dst, b, h) do { _Pragma("unroll") for (int n = 0; n < 2; ++n) _Pragma("unroll") for (int k = 0; k < 2; ++k) dst[n][k] = *(const PG8_LAS bf16x8*)(lds + PG8_SB(b, h) + boff + n * 2048 + k * 1024); } while (0)
; #define PG8_MMA(ai, bj, At, Bt) do { __builtin_amdgcn_s_setprio(1); _Pragma("unroll") for (int m = 0; m < 4; ++m) _Pragma("unroll") for (int n = 0; n < 2; ++n) _Pragma("unroll") for (int k = 0; k < 2; ++k) \
;         acc[ai][bj][m][n] = __builtin_amdgcn_mfma_f32_16x16x32_bf16(Bt[n][k], At[m][k], acc[ai][bj][m][n], 0, 0, 0); __builtin_amdgcn_s_setprio(0); } while (0)
; #define PG8_WAIT_V(n) asm volatile("s_waitcnt vmcnt(" #n ")" ::: "memory")
; #define PG8_WAIT_L(n) asm volatile("s_waitcnt lgkmcnt(" #n ")" ::: "memory")
; template <class Epi, class Sched, bool ALIGN_EPI = false, bool SP2 = false>
; __device__ __forceinline__ void gemm_phase(PG8_LAS unsigned char* lds, const Gemm g, const Sched& S, const Epi& E) {
;     ...
;             const bool last = (t == nt - 2);
;             const char* a1 = cA + (size_t)(t + 1) * kstep;
;             const char* a2 = last ? nA : cA + (size_t)(t + 2) * kstep; const char* b2 = last ? nB : cB + (size_t)(t + 2) * kstep;
;             const char* a3 = a2 + kstep; const char* b3 = b2 + kstep;
;             if (last && has_next) S.a_ready(nxt);
;             if constexpr (SP2) {
;             PG8_LDB(B0, 0, 0); PG8_LDB(B1, 0, 1); PG8_SCHED; PG8_LDA(At, 0, 0); PG8_STAGE(PG8_SA(1, 1), a1 + hstep, voffA);
;             PG8_WAIT_V(8); PG8_WAIT_L(0); PG8_BAR; PG8_MMA(0, 0, At, B0); PG8_MMA(0, 1, At, B1); PG8_BAR; PG8_SCHED;
;             PG8_LDA(At, 0, 1); PG8_STAGE(PG8_SB(0, 0), b2, voffB); PG8_STAGE(PG8_SB(0, 1), b2 + hstep, voffB); PG8_STAGE(PG8_SA(0, 0), a2, voffA);
;             PG8_WAIT_V(8); PG8_WAIT_L(0); PG8_BAR; PG8_MMA(1, 0, At, B0); PG8_MMA(1, 1, At, B1); PG8_BAR; PG8_SCHED;
.Lprio_skip5:
.LBB0_566:
	s_add_i32 s44, s22, 2
	s_add_u32 s45, s20, 0x80
	s_addc_u32 s23, s21, 0
	s_add_i32 s48, 0, 0x10000
	s_cmp_eq_u32 s36, s22
	s_cselect_b32 s23, s1, s23
	s_cselect_b32 s22, s0, s45
	v_add_u32_e32 v150, s48, v139
	s_cselect_b32 s47, s3, s43
	s_cselect_b32 s46, s2, s42
	s_add_i32 s45, 0, 0x14000
	ds_read_b128 v[142:145], v150
	ds_read_b128 v[146:149], v150 offset:1024
	ds_read_b128 v[168:171], v150 offset:2048
	ds_read_b128 v[172:175], v150 offset:3072
	v_add_u32_e32 v150, s45, v139
	ds_read_b128 v[176:179], v150
	ds_read_b128 v[180:183], v150 offset:1024
	ds_read_b128 v[184:187], v150 offset:2048
	ds_read_b128 v[188:191], v150 offset:3072
	v_lshl_add_u64 v[150:151], s[20:21], 0, v[134:135]
	s_add_i32 m0, s27, 0xc000
	ds_read_b128 v[192:195], v141
	ds_read_b128 v[196:199], v141 offset:1024
	ds_read_b128 v[200:203], v141 offset:2048
	ds_read_b128 v[204:207], v141 offset:3072
	ds_read_b128 v[212:215], v141 offset:4096
	ds_read_b128 v[230:233], v141 offset:5120
	ds_read_b128 v[234:237], v141 offset:6144
	ds_read_b128 v[238:241], v141 offset:7168
	global_load_lds_dwordx4 v[150:151], off
	v_lshl_add_u64 v[150:151], s[20:21], 0, v[136:137]
	s_add_i32 m0, s27, 0xe000
	s_nop 0
	global_load_lds_dwordx4 v[150:151], off
	s_waitcnt vmcnt(8)
	s_waitcnt lgkmcnt(0)
	s_barrier
	s_waitcnt lgkmcnt(0)
	v_mfma_f32_16x16x32_bf16 v[120:123], v[142:145], v[192:195], v[120:123]
	v_mfma_f32_16x16x32_bf16 v[124:127], v[168:171], v[192:195], v[124:127]
	v_mfma_f32_16x16x32_bf16 v[108:111], v[142:145], v[200:203], v[108:111]
	v_mfma_f32_16x16x32_bf16 v[104:107], v[168:171], v[200:203], v[104:107]
	v_mfma_f32_16x16x32_bf16 v[92:95], v[142:145], v[212:215], v[92:95]
	v_mfma_f32_16x16x32_bf16 v[88:91], v[168:171], v[212:215], v[88:91]
	v_mfma_f32_16x16x32_bf16 v[76:79], v[142:145], v[234:237], v[76:79]
	v_mfma_f32_16x16x32_bf16 v[72:75], v[168:171], v[234:237], v[72:75]
	v_mfma_f32_16x16x32_bf16 v[120:123], v[146:149], v[196:199], v[120:123]
	v_mfma_f32_16x16x32_bf16 v[124:127], v[172:175], v[196:199], v[124:127]
	v_mfma_f32_16x16x32_bf16 v[108:111], v[146:149], v[204:207], v[108:111]
	v_mfma_f32_16x16x32_bf16 v[104:107], v[172:175], v[204:207], v[104:107]
	v_mfma_f32_16x16x32_bf16 v[92:95], v[146:149], v[230:233], v[92:95]
	v_mfma_f32_16x16x32_bf16 v[88:91], v[172:175], v[230:233], v[88:91]
	v_mfma_f32_16x16x32_bf16 v[76:79], v[146:149], v[238:241], v[76:79]
	v_mfma_f32_16x16x32_bf16 v[72:75], v[172:175], v[238:241], v[72:75]
	v_mfma_f32_16x16x32_bf16 v[116:119], v[176:179], v[192:195], v[116:119]
	v_mfma_f32_16x16x32_bf16 v[112:115], v[184:187], v[192:195], v[112:115]
	v_mfma_f32_16x16x32_bf16 v[100:103], v[176:179], v[200:203], v[100:103]
	v_mfma_f32_16x16x32_bf16 v[96:99], v[184:187], v[200:203], v[96:99]
	v_mfma_f32_16x16x32_bf16 v[84:87], v[176:179], v[212:215], v[84:87]
	v_mfma_f32_16x16x32_bf16 v[80:83], v[184:187], v[212:215], v[80:83]
	v_mfma_f32_16x16x32_bf16 v[68:71], v[176:179], v[234:237], v[68:71]
	v_mfma_f32_16x16x32_bf16 v[64:67], v[184:187], v[234:237], v[64:67]
	v_mfma_f32_16x16x32_bf16 v[116:119], v[180:183], v[196:199], v[116:119]
	v_mfma_f32_16x16x32_bf16 v[112:115], v[188:191], v[196:199], v[112:115]
	v_mfma_f32_16x16x32_bf16 v[100:103], v[180:183], v[204:207], v[100:103]
	v_mfma_f32_16x16x32_bf16 v[96:99], v[188:191], v[204:207], v[96:99]
	v_mfma_f32_16x16x32_bf16 v[84:87], v[180:183], v[230:233], v[84:87]
	v_mfma_f32_16x16x32_bf16 v[80:83], v[188:191], v[230:233], v[80:83]
	v_mfma_f32_16x16x32_bf16 v[68:71], v[180:183], v[238:241], v[68:71]
	v_mfma_f32_16x16x32_bf16 v[64:67], v[188:191], v[238:241], v[64:67]
	s_barrier
	s_add_i32 s48, s48, s26
	v_lshl_add_u64 v[150:151], s[46:47], 0, v[152:153]
	s_mov_b32 m0, s48
	ds_read_b128 v[192:195], v141 offset:16384
	ds_read_b128 v[196:199], v141 offset:17408
	ds_read_b128 v[200:203], v141 offset:18432
	ds_read_b128 v[204:207], v141 offset:19456
	ds_read_b128 v[212:215], v141 offset:20480
	ds_read_b128 v[230:233], v141 offset:21504
	ds_read_b128 v[234:237], v141 offset:22528
	ds_read_b128 v[238:241], v141 offset:23552
	global_load_lds_dwordx4 v[150:151], off
	s_add_i32 m0, s48, 0x2000
	v_lshl_add_u64 v[158:159], s[46:47], 0, v[128:129]
	s_add_u32 s46, s46, s8
	s_addc_u32 s47, s47, s9
	s_add_i32 s45, s45, s26
	global_load_lds_dwordx4 v[158:159], off
	v_lshl_add_u64 v[160:161], s[46:47], 0, v[152:153]
	s_mov_b32 m0, s45
	v_lshl_add_u64 v[162:163], s[46:47], 0, v[128:129]
	global_load_lds_dwordx4 v[160:161], off
	s_add_i32 m0, s45, 0x2000
	v_lshl_add_u64 v[164:165], s[22:23], 0, v[132:133]
	global_load_lds_dwordx4 v[162:163], off
	s_mov_b32 m0, s27
	v_lshl_add_u64 v[208:209], s[22:23], 0, v[130:131]
	global_load_lds_dwordx4 v[164:165], off
	s_mov_b32 m0, s28
	s_nop 0
	global_load_lds_dwordx4 v[208:209], off
	s_waitcnt vmcnt(8)
	s_waitcnt lgkmcnt(0)
	s_barrier
; #define PG8_STAGE(bufoff, gbase, voff) do { _Pragma("unroll") for (int _i = 0; _i < 2; ++_i) \
;         __builtin_amdgcn_global_load_lds((const unsigned*)((const char*)(gbase) + (voff)[_i]), (PG8_LAS unsigned*)(lds + (bufoff) + ldsw + _i * 8192), 16, 0, 0); } while (0)
; #define PG8_LDA(dst, b, h) do { _Pragma("unroll") for (int m = 0; m < 4; ++m) _Pragma("unroll") for (int k = 0; k < 2; ++k) dst[m][k] = *(const PG8_LAS bf16x8*)(lds + PG8_SA(b, h) + aoff + m * 2048 + k * 1024); } while (0)
; #define PG8_LDB(dst, b, h) do { _Pragma("unroll") for (int n = 0; n < 2; ++n) _Pragma("unroll") for (int k = 0; k < 2; ++k) dst[n][k] = *(const PG8_LAS bf16x8*)(lds + PG8_SB(b, h) + boff + n * 2048 + k * 1024); } while (0)
; #define PG8_MMA(ai, bj, At, Bt) do { __builtin_amdgcn_s_setprio(1); _Pragma("unroll") for (int m = 0; m < 4; ++m) _Pragma("unroll") for (int n = 0; n < 2; ++n) _Pragma("unroll") for (int k = 0; k < 2; ++k) \
;         acc[ai][bj][m][n] = __builtin_amdgcn_mfma_f32_16x16x32_bf16(Bt[n][k], At[m][k], acc[ai][bj][m][n], 0, 0, 0); __builtin_amdgcn_s_setprio(0); } while (0)
; #define PG8_WAIT_V(n) asm volatile("s_waitcnt vmcnt(" #n ")" ::: "memory")
; #define PG8_WAIT_L(n) asm volatile("s_waitcnt lgkmcnt(" #n ")" ::: "memory")
; #define PG8_BAR __builtin_amdgcn_s_barrier()
; #define PG8_SCHED __builtin_amdgcn_sched_barrier(0)
; template <class Epi, class Sched, bool ALIGN_EPI = false, bool SP2 = false>
; __device__ __forceinline__ void gemm_phase(PG8_LAS unsigned char* lds, const Gemm g, const Sched& S, const Epi& E) {
;     ...
;             PG8_WAIT_V(8); PG8_WAIT_L(0); PG8_BAR; PG8_MMA(1, 0, At, B0); PG8_MMA(1, 1, At, B1); PG8_BAR; PG8_SCHED;
;             PG8_LDB(B0, 1, 0); PG8_LDB(B1, 1, 1); PG8_SCHED; PG8_LDA(At, 1, 0); PG8_STAGE(PG8_SA(0, 1), a2 + hstep, voffA);
;             PG8_WAIT_V(8); PG8_WAIT_L(0); PG8_BAR; PG8_MMA(0, 0, At, B0); PG8_MMA(0, 1, At, B1); PG8_BAR; PG8_SCHED;
	s_waitcnt lgkmcnt(0)
	v_mfma_f32_16x16x32_bf16 v[60:63], v[142:145], v[192:195], v[60:63]
	v_mfma_f32_16x16x32_bf16 v[56:59], v[168:171], v[192:195], v[56:59]
	v_mfma_f32_16x16x32_bf16 v[44:47], v[142:145], v[200:203], v[44:47]
	v_mfma_f32_16x16x32_bf16 v[40:43], v[168:171], v[200:203], v[40:43]
	v_mfma_f32_16x16x32_bf16 v[28:31], v[142:145], v[212:215], v[28:31]
	v_mfma_f32_16x16x32_bf16 v[24:27], v[168:171], v[212:215], v[24:27]
	v_mfma_f32_16x16x32_bf16 v[12:15], v[142:145], v[234:237], v[12:15]
	v_mfma_f32_16x16x32_bf16 v[8:11], v[168:171], v[234:237], v[8:11]
	v_mfma_f32_16x16x32_bf16 v[60:63], v[146:149], v[196:199], v[60:63]
	v_mfma_f32_16x16x32_bf16 v[56:59], v[172:175], v[196:199], v[56:59]
	v_mfma_f32_16x16x32_bf16 v[44:47], v[146:149], v[204:207], v[44:47]
	v_mfma_f32_16x16x32_bf16 v[40:43], v[172:175], v[204:207], v[40:43]
	v_mfma_f32_16x16x32_bf16 v[28:31], v[146:149], v[230:233], v[28:31]
	v_mfma_f32_16x16x32_bf16 v[24:27], v[172:175], v[230:233], v[24:27]
	v_mfma_f32_16x16x32_bf16 v[12:15], v[146:149], v[238:241], v[12:15]
	v_mfma_f32_16x16x32_bf16 v[8:11], v[172:175], v[238:241], v[8:11]
	v_mfma_f32_16x16x32_bf16 v[52:55], v[176:179], v[192:195], v[52:55]
	v_mfma_f32_16x16x32_bf16 v[48:51], v[184:187], v[192:195], v[48:51]
	v_mfma_f32_16x16x32_bf16 v[36:39], v[176:179], v[200:203], v[36:39]
	v_mfma_f32_16x16x32_bf16 v[32:35], v[184:187], v[200:203], v[32:35]
	v_mfma_f32_16x16x32_bf16 v[20:23], v[176:179], v[212:215], v[20:23]
	v_mfma_f32_16x16x32_bf16 v[16:19], v[184:187], v[212:215], v[16:19]
	v_mfma_f32_16x16x32_bf16 v[4:7], v[176:179], v[234:237], v[4:7]
	v_mfma_f32_16x16x32_bf16 v[0:3], v[184:187], v[234:237], v[0:3]
	v_mfma_f32_16x16x32_bf16 v[52:55], v[180:183], v[196:199], v[52:55]
	v_mfma_f32_16x16x32_bf16 v[48:51], v[188:191], v[196:199], v[48:51]
	v_mfma_f32_16x16x32_bf16 v[36:39], v[180:183], v[204:207], v[36:39]
	v_mfma_f32_16x16x32_bf16 v[32:35], v[188:191], v[204:207], v[32:35]
	v_mfma_f32_16x16x32_bf16 v[20:23], v[180:183], v[230:233], v[20:23]
	v_mfma_f32_16x16x32_bf16 v[16:19], v[188:191], v[230:233], v[16:19]
	v_mfma_f32_16x16x32_bf16 v[4:7], v[180:183], v[238:241], v[4:7]
	v_mfma_f32_16x16x32_bf16 v[0:3], v[188:191], v[238:241], v[0:3]
	s_barrier
	s_add_i32 s45, 0, 0x18000
	v_add_u32_e32 v167, s45, v139
	s_add_i32 s46, 0, 0x1c000
	ds_read_b128 v[142:145], v167
	ds_read_b128 v[146:149], v167 offset:1024
	ds_read_b128 v[168:171], v167 offset:2048
	ds_read_b128 v[172:175], v167 offset:3072
	v_add_u32_e32 v167, s46, v139
	ds_read_b128 v[176:179], v167
	ds_read_b128 v[180:183], v167 offset:1024
	ds_read_b128 v[184:187], v167 offset:2048
	ds_read_b128 v[188:191], v167 offset:3072
	s_add_u32 s22, s22, s8
	s_addc_u32 s23, s23, s9
	s_mov_b32 m0, s29
	v_lshl_add_u64 v[216:217], s[22:23], 0, v[132:133]
	ds_read_b128 v[192:195], v141 offset:32768
	ds_read_b128 v[196:199], v141 offset:33792
	ds_read_b128 v[200:203], v141 offset:34816
	ds_read_b128 v[204:207], v141 offset:35840
	ds_read_b128 v[212:215], v141 offset:36864
	ds_read_b128 v[230:233], v141 offset:37888
	ds_read_b128 v[234:237], v141 offset:38912
	ds_read_b128 v[238:241], v141 offset:39936
	global_load_lds_dwordx4 v[216:217], off
	v_lshl_add_u64 v[216:217], s[22:23], 0, v[130:131]
	s_mov_b32 m0, s30
	s_nop 0
	global_load_lds_dwordx4 v[216:217], off
	s_waitcnt vmcnt(8)
	s_waitcnt lgkmcnt(0)
	s_barrier
	s_waitcnt lgkmcnt(0)
	v_mfma_f32_16x16x32_bf16 v[120:123], v[142:145], v[192:195], v[120:123]
	v_mfma_f32_16x16x32_bf16 v[124:127], v[168:171], v[192:195], v[124:127]
	v_mfma_f32_16x16x32_bf16 v[108:111], v[142:145], v[200:203], v[108:111]
	v_mfma_f32_16x16x32_bf16 v[104:107], v[168:171], v[200:203], v[104:107]
	v_mfma_f32_16x16x32_bf16 v[92:95], v[142:145], v[212:215], v[92:95]
	v_mfma_f32_16x16x32_bf16 v[88:91], v[168:171], v[212:215], v[88:91]
	v_mfma_f32_16x16x32_bf16 v[76:79], v[142:145], v[234:237], v[76:79]
	v_mfma_f32_16x16x32_bf16 v[72:75], v[168:171], v[234:237], v[72:75]
	v_mfma_f32_16x16x32_bf16 v[120:123], v[146:149], v[196:199], v[120:123]
	v_mfma_f32_16x16x32_bf16 v[124:127], v[172:175], v[196:199], v[124:127]
	v_mfma_f32_16x16x32_bf16 v[108:111], v[146:149], v[204:207], v[108:111]
	v_mfma_f32_16x16x32_bf16 v[104:107], v[172:175], v[204:207], v[104:107]
	v_mfma_f32_16x16x32_bf16 v[92:95], v[146:149], v[230:233], v[92:95]
	v_mfma_f32_16x16x32_bf16 v[88:91], v[172:175], v[230:233], v[88:91]
	v_mfma_f32_16x16x32_bf16 v[76:79], v[146:149], v[238:241], v[76:79]
	v_mfma_f32_16x16x32_bf16 v[72:75], v[172:175], v[238:241], v[72:75]
	v_mfma_f32_16x16x32_bf16 v[116:119], v[176:179], v[192:195], v[116:119]
	v_mfma_f32_16x16x32_bf16 v[112:115], v[184:187], v[192:195], v[112:115]
	v_mfma_f32_16x16x32_bf16 v[100:103], v[176:179], v[200:203], v[100:103]
	v_mfma_f32_16x16x32_bf16 v[96:99], v[184:187], v[200:203], v[96:99]
	v_mfma_f32_16x16x32_bf16 v[84:87], v[176:179], v[212:215], v[84:87]
	v_mfma_f32_16x16x32_bf16 v[80:83], v[184:187], v[212:215], v[80:83]
	v_mfma_f32_16x16x32_bf16 v[68:71], v[176:179], v[234:237], v[68:71]
	v_mfma_f32_16x16x32_bf16 v[64:67], v[184:187], v[234:237], v[64:67]
	v_mfma_f32_16x16x32_bf16 v[116:119], v[180:183], v[196:199], v[116:119]
	v_mfma_f32_16x16x32_bf16 v[112:115], v[188:191], v[196:199], v[112:115]
	v_mfma_f32_16x16x32_bf16 v[100:103], v[180:183], v[204:207], v[100:103]
	v_mfma_f32_16x16x32_bf16 v[96:99], v[188:191], v[204:207], v[96:99]
	v_mfma_f32_16x16x32_bf16 v[84:87], v[180:183], v[230:233], v[84:87]
	v_mfma_f32_16x16x32_bf16 v[80:83], v[188:191], v[230:233], v[80:83]
	v_mfma_f32_16x16x32_bf16 v[68:71], v[180:183], v[238:241], v[68:71]
	v_mfma_f32_16x16x32_bf16 v[64:67], v[188:191], v[238:241], v[64:67]
	s_barrier
; #define PG8_STAGE(bufoff, gbase, voff) do { _Pragma("unroll") for (int _i = 0; _i < 2; ++_i) \
;         __builtin_amdgcn_global_load_lds((const unsigned*)((const char*)(gbase) + (voff)[_i]), (PG8_LAS unsigned*)(lds + (bufoff) + ldsw + _i * 8192), 16, 0, 0); } while (0)
; #define PG8_LDA(dst, b, h) do { _Pragma("unroll") for (int m = 0; m < 4; ++m) _Pragma("unroll") for (int k = 0; k < 2; ++k) dst[m][k] = *(const PG8_LAS bf16x8*)(lds + PG8_SA(b, h) + aoff + m * 2048 + k * 1024); } while (0)
; #define PG8_MMA(ai, bj, At, Bt) do { __builtin_amdgcn_s_setprio(1); _Pragma("unroll") for (int m = 0; m < 4; ++m) _Pragma("unroll") for (int n = 0; n < 2; ++n) _Pragma("unroll") for (int k = 0; k < 2; ++k) \
;         acc[ai][bj][m][n] = __builtin_amdgcn_mfma_f32_16x16x32_bf16(Bt[n][k], At[m][k], acc[ai][bj][m][n], 0, 0, 0); __builtin_amdgcn_s_setprio(0); } while (0)
; #define PG8_WAIT_V(n) asm volatile("s_waitcnt vmcnt(" #n ")" ::: "memory")
; #define PG8_WAIT_L(n) asm volatile("s_waitcnt lgkmcnt(" #n ")" ::: "memory")
; #define PG8_BAR __builtin_amdgcn_s_barrier()
; #define PG8_SCHED __builtin_amdgcn_sched_barrier(0)
; template <class Epi, class Sched, bool ALIGN_EPI = false, bool SP2 = false>
; __device__ __forceinline__ void gemm_phase(PG8_LAS unsigned char* lds, const Gemm g, const Sched& S, const Epi& E) {
;     ...
;         for (int t = 0; t < nt; t += 2) {
;             const bool last = (t == nt - 2);
;     ...
;             PG8_LDA(At, 1, 1); PG8_STAGE(PG8_SB(1, 0), b3, voffB); PG8_STAGE(PG8_SB(1, 1), b3 + hstep, voffB); PG8_STAGE(PG8_SA(1, 0), a3, voffA);
;             PG8_WAIT_V(8); PG8_WAIT_L(0); PG8_BAR; PG8_MMA(1, 0, At, B0); PG8_MMA(1, 1, At, B1); PG8_BAR; PG8_SCHED;
	s_add_i32 s22, s45, s26
	v_lshl_add_u64 v[150:151], v[150:151], 0, s[82:83]
	s_mov_b32 m0, s22
	ds_read_b128 v[192:195], v141 offset:49152
	ds_read_b128 v[196:199], v141 offset:50176
	ds_read_b128 v[200:203], v141 offset:51200
	ds_read_b128 v[204:207], v141 offset:52224
	ds_read_b128 v[212:215], v141 offset:53248
	ds_read_b128 v[230:233], v141 offset:54272
	ds_read_b128 v[234:237], v141 offset:55296
	ds_read_b128 v[238:241], v141 offset:56320
	global_load_lds_dwordx4 v[150:151], off
	v_lshl_add_u64 v[150:151], v[158:159], 0, s[82:83]
	s_add_i32 m0, s22, 0x2000
	s_add_i32 s22, s46, s26
	global_load_lds_dwordx4 v[150:151], off
	v_lshl_add_u64 v[150:151], v[160:161], 0, s[82:83]
	s_mov_b32 m0, s22
	s_nop 0
	global_load_lds_dwordx4 v[150:151], off
	v_lshl_add_u64 v[150:151], v[162:163], 0, s[82:83]
	s_add_i32 m0, s22, 0x2000
	s_nop 0
	global_load_lds_dwordx4 v[150:151], off
	v_lshl_add_u64 v[150:151], v[164:165], 0, s[82:83]
	s_mov_b32 m0, s34
	s_nop 0
	global_load_lds_dwordx4 v[150:151], off
	v_lshl_add_u64 v[150:151], v[208:209], 0, s[82:83]
	s_mov_b32 m0, s35
	s_nop 0
	global_load_lds_dwordx4 v[150:151], off
	s_waitcnt vmcnt(8)
	s_waitcnt lgkmcnt(0)
	s_barrier
	s_waitcnt lgkmcnt(0)
	v_mfma_f32_16x16x32_bf16 v[60:63], v[142:145], v[192:195], v[60:63]
	v_mfma_f32_16x16x32_bf16 v[56:59], v[168:171], v[192:195], v[56:59]
	v_mfma_f32_16x16x32_bf16 v[44:47], v[142:145], v[200:203], v[44:47]
	v_mfma_f32_16x16x32_bf16 v[40:43], v[168:171], v[200:203], v[40:43]
	v_mfma_f32_16x16x32_bf16 v[28:31], v[142:145], v[212:215], v[28:31]
	v_mfma_f32_16x16x32_bf16 v[24:27], v[168:171], v[212:215], v[24:27]
	v_mfma_f32_16x16x32_bf16 v[12:15], v[142:145], v[234:237], v[12:15]
	v_mfma_f32_16x16x32_bf16 v[8:11], v[168:171], v[234:237], v[8:11]
	v_mfma_f32_16x16x32_bf16 v[60:63], v[146:149], v[196:199], v[60:63]
	v_mfma_f32_16x16x32_bf16 v[56:59], v[172:175], v[196:199], v[56:59]
	v_mfma_f32_16x16x32_bf16 v[44:47], v[146:149], v[204:207], v[44:47]
	v_mfma_f32_16x16x32_bf16 v[40:43], v[172:175], v[204:207], v[40:43]
	v_mfma_f32_16x16x32_bf16 v[28:31], v[146:149], v[230:233], v[28:31]
	v_mfma_f32_16x16x32_bf16 v[24:27], v[172:175], v[230:233], v[24:27]
	v_mfma_f32_16x16x32_bf16 v[12:15], v[146:149], v[238:241], v[12:15]
	v_mfma_f32_16x16x32_bf16 v[8:11], v[172:175], v[238:241], v[8:11]
	v_mfma_f32_16x16x32_bf16 v[52:55], v[176:179], v[192:195], v[52:55]
	v_mfma_f32_16x16x32_bf16 v[48:51], v[184:187], v[192:195], v[48:51]
	v_mfma_f32_16x16x32_bf16 v[36:39], v[176:179], v[200:203], v[36:39]
	v_mfma_f32_16x16x32_bf16 v[32:35], v[184:187], v[200:203], v[32:35]
	v_mfma_f32_16x16x32_bf16 v[20:23], v[176:179], v[212:215], v[20:23]
	v_mfma_f32_16x16x32_bf16 v[16:19], v[184:187], v[212:215], v[16:19]
	v_mfma_f32_16x16x32_bf16 v[4:7], v[176:179], v[234:237], v[4:7]
	v_mfma_f32_16x16x32_bf16 v[0:3], v[184:187], v[234:237], v[0:3]
	v_mfma_f32_16x16x32_bf16 v[52:55], v[180:183], v[196:199], v[52:55]
	v_mfma_f32_16x16x32_bf16 v[48:51], v[188:191], v[196:199], v[48:51]
	v_mfma_f32_16x16x32_bf16 v[36:39], v[180:183], v[204:207], v[36:39]
	v_mfma_f32_16x16x32_bf16 v[32:35], v[188:191], v[204:207], v[32:35]
	v_mfma_f32_16x16x32_bf16 v[20:23], v[180:183], v[230:233], v[20:23]
	v_mfma_f32_16x16x32_bf16 v[16:19], v[188:191], v[230:233], v[16:19]
	v_mfma_f32_16x16x32_bf16 v[4:7], v[180:183], v[238:241], v[4:7]
	v_mfma_f32_16x16x32_bf16 v[0:3], v[188:191], v[238:241], v[0:3]
	s_barrier
	s_add_u32 s20, s20, 0x100
	s_addc_u32 s21, s21, 0
	s_add_u32 s42, s42, 0x100
	s_addc_u32 s43, s43, 0
	s_cmp_ge_i32 s44, s31
	s_mov_b32 s22, s44
	s_cbranch_scc0 .LBB0_566
	s_setprio 0

; template <class Epi, class Sched, bool ALIGN_EPI = false, bool SP2 = false>
; __device__ __forceinline__ void gemm_phase(PG8_LAS unsigned char* lds, const Gemm g, const Sched& S, const Epi& E) {
;     ...
;         for (int t = 0; t < nt; t += 2) {
;             const bool last = (t == nt - 2);
;     ...
; #pragma unroll
;         for (int a = 0; a < 2; ++a)
; #pragma unroll
;             for (int b = 0; b < 2; ++b)
; #pragma unroll
;                 for (int m = 0; m < 4; ++m)
; #pragma unroll
;                     for (int n = 0; n < 2; ++n) acc[a][b][m][n] = (f32x4){0.f, 0.f, 0.f, 0.f};
;         cur = nxt; cA = nA; cB = nB; ++ui;
.LBB0_628:
	v_mov_b32_e32 v123, 0
	s_andn2_b64 vcc, exec, s[10:11]
	v_mov_b32_e32 v122, v123
	v_mov_b32_e32 v121, v123
	v_mov_b32_e32 v120, v123
	v_mov_b32_e32 v127, v123
	v_mov_b32_e32 v126, v123
	v_mov_b32_e32 v125, v123
	v_mov_b32_e32 v124, v123
	v_mov_b32_e32 v111, v123
	v_mov_b32_e32 v110, v123
	v_mov_b32_e32 v109, v123
	v_mov_b32_e32 v108, v123
	v_mov_b32_e32 v107, v123
	v_mov_b32_e32 v106, v123
	v_mov_b32_e32 v105, v123
	v_mov_b32_e32 v104, v123
	v_mov_b32_e32 v95, v123
	v_mov_b32_e32 v94, v123
	v_mov_b32_e32 v93, v123
	v_mov_b32_e32 v92, v123
	v_mov_b32_e32 v91, v123
	v_mov_b32_e32 v90, v123
	v_mov_b32_e32 v89, v123
	v_mov_b32_e32 v88, v123
	v_mov_b32_e32 v79, v123
	v_mov_b32_e32 v78, v123
	v_mov_b32_e32 v77, v123
	v_mov_b32_e32 v76, v123
	v_mov_b32_e32 v75, v123
	v_mov_b32_e32 v74, v123
	v_mov_b32_e32 v73, v123
	v_mov_b32_e32 v72, v123
	v_mov_b32_e32 v119, v123
	v_mov_b32_e32 v118, v123
	v_mov_b32_e32 v117, v123
	v_mov_b32_e32 v116, v123
	v_mov_b32_e32 v115, v123
	v_mov_b32_e32 v114, v123
	v_mov_b32_e32 v113, v123
	v_mov_b32_e32 v112, v123
	v_mov_b32_e32 v103, v123
	v_mov_b32_e32 v102, v123
	v_mov_b32_e32 v101, v123
	v_mov_b32_e32 v100, v123
	v_mov_b32_e32 v99, v123
	v_mov_b32_e32 v98, v123
	v_mov_b32_e32 v97, v123
	v_mov_b32_e32 v96, v123
	v_mov_b32_e32 v87, v123
	v_mov_b32_e32 v86, v123
	v_mov_b32_e32 v85, v123
	v_mov_b32_e32 v84, v123
	v_mov_b32_e32 v83, v123
	v_mov_b32_e32 v82, v123
	v_mov_b32_e32 v81, v123
	v_mov_b32_e32 v80, v123
	v_mov_b32_e32 v71, v123
	v_mov_b32_e32 v70, v123
	v_mov_b32_e32 v69, v123
	v_mov_b32_e32 v68, v123
	v_mov_b32_e32 v67, v123
	v_mov_b32_e32 v66, v123
	v_mov_b32_e32 v65, v123
	v_mov_b32_e32 v64, v123
	v_mov_b32_e32 v63, v123
	v_mov_b32_e32 v62, v123
	v_mov_b32_e32 v61, v123
	v_mov_b32_e32 v60, v123
	v_mov_b32_e32 v59, v123
	v_mov_b32_e32 v58, v123
	v_mov_b32_e32 v57, v123
	v_mov_b32_e32 v56, v123
	v_mov_b32_e32 v47, v123
	v_mov_b32_e32 v46, v123
	v_mov_b32_e32 v45, v123
	v_mov_b32_e32 v44, v123
	v_mov_b32_e32 v43, v123
	v_mov_b32_e32 v42, v123
	v_mov_b32_e32 v41, v123
	v_mov_b32_e32 v40, v123
	v_mov_b32_e32 v31, v123
	v_mov_b32_e32 v30, v123
	v_mov_b32_e32 v29, v123
	v_mov_b32_e32 v28, v123
	v_mov_b32_e32 v27, v123
	v_mov_b32_e32 v26, v123
	v_mov_b32_e32 v25, v123
	v_mov_b32_e32 v24, v123
	v_mov_b32_e32 v15, v123
	v_mov_b32_e32 v14, v123
	v_mov_b32_e32 v13, v123
	v_mov_b32_e32 v12, v123
	v_mov_b32_e32 v11, v123
	v_mov_b32_e32 v10, v123
	v_mov_b32_e32 v9, v123
	v_mov_b32_e32 v8, v123
	v_mov_b32_e32 v55, v123
	v_mov_b32_e32 v54, v123
	v_mov_b32_e32 v53, v123
	v_mov_b32_e32 v52, v123
	v_mov_b32_e32 v51, v123
	v_mov_b32_e32 v50, v123
	v_mov_b32_e32 v49, v123
	v_mov_b32_e32 v48, v123
	v_mov_b32_e32 v39, v123
	v_mov_b32_e32 v38, v123
	v_mov_b32_e32 v37, v123
	v_mov_b32_e32 v36, v123
	v_mov_b32_e32 v35, v123
	v_mov_b32_e32 v34, v123
	v_mov_b32_e32 v33, v123
	v_mov_b32_e32 v32, v123
	v_mov_b32_e32 v23, v123
	v_mov_b32_e32 v22, v123
	v_mov_b32_e32 v21, v123
	v_mov_b32_e32 v20, v123
	v_mov_b32_e32 v19, v123
	v_mov_b32_e32 v18, v123
	v_mov_b32_e32 v17, v123
	v_mov_b32_e32 v16, v123
	v_mov_b32_e32 v7, v123
	v_mov_b32_e32 v6, v123
	v_mov_b32_e32 v5, v123
	v_mov_b32_e32 v4, v123
	v_mov_b32_e32 v3, v123
	v_mov_b32_e32 v2, v123
	v_mov_b32_e32 v1, v123
	v_mov_b32_e32 v0, v123
	s_cbranch_vccnz .LBB0_631
	s_add_u32 s6, s20, 0x80
	s_addc_u32 s7, s21, 0
	s_add_u32 s20, s18, 0x100
	v_mov_b32_e32 v0, 0
	s_addc_u32 s21, s19, 0
	s_mov_b32 s18, 0
	v_mov_b32_e32 v1, v0
	v_mov_b32_e32 v2, v0
	v_mov_b32_e32 v3, v0
	v_mov_b32_e32 v4, v0
	v_mov_b32_e32 v5, v0
	v_mov_b32_e32 v6, v0
	v_mov_b32_e32 v7, v0
	v_mov_b32_e32 v16, v0
	v_mov_b32_e32 v17, v0
	v_mov_b32_e32 v18, v0
	v_mov_b32_e32 v19, v0
	v_mov_b32_e32 v20, v0
	v_mov_b32_e32 v21, v0
	v_mov_b32_e32 v22, v0
	v_mov_b32_e32 v23, v0
	v_mov_b32_e32 v32, v0
	v_mov_b32_e32 v33, v0
	v_mov_b32_e32 v34, v0
	v_mov_b32_e32 v35, v0
	v_mov_b32_e32 v36, v0
	v_mov_b32_e32 v37, v0
	v_mov_b32_e32 v38, v0
	v_mov_b32_e32 v39, v0
	v_mov_b32_e32 v48, v0
	v_mov_b32_e32 v49, v0
	v_mov_b32_e32 v50, v0
	v_mov_b32_e32 v51, v0
	v_mov_b32_e32 v52, v0
	v_mov_b32_e32 v53, v0
	v_mov_b32_e32 v54, v0
	v_mov_b32_e32 v55, v0
	v_mov_b32_e32 v8, v0
	v_mov_b32_e32 v9, v0
	v_mov_b32_e32 v10, v0
	v_mov_b32_e32 v11, v0
	v_mov_b32_e32 v12, v0
	v_mov_b32_e32 v13, v0
	v_mov_b32_e32 v14, v0
	v_mov_b32_e32 v15, v0
	v_mov_b32_e32 v24, v0
	v_mov_b32_e32 v25, v0
	v_mov_b32_e32 v26, v0
	v_mov_b32_e32 v27, v0
	v_mov_b32_e32 v28, v0
	v_mov_b32_e32 v29, v0
	v_mov_b32_e32 v30, v0
	v_mov_b32_e32 v31, v0
	v_mov_b32_e32 v40, v0
	v_mov_b32_e32 v41, v0
	v_mov_b32_e32 v42, v0
	v_mov_b32_e32 v43, v0
	v_mov_b32_e32 v44, v0
	v_mov_b32_e32 v45, v0
	v_mov_b32_e32 v46, v0
	v_mov_b32_e32 v47, v0
	v_mov_b32_e32 v56, v0
	v_mov_b32_e32 v57, v0
	v_mov_b32_e32 v58, v0
	v_mov_b32_e32 v59, v0
	v_mov_b32_e32 v60, v0
	v_mov_b32_e32 v61, v0
	v_mov_b32_e32 v62, v0
	v_mov_b32_e32 v63, v0
	v_mov_b32_e32 v64, v0
	v_mov_b32_e32 v65, v0
	v_mov_b32_e32 v66, v0
	v_mov_b32_e32 v67, v0
	v_mov_b32_e32 v68, v0
	v_mov_b32_e32 v69, v0
	v_mov_b32_e32 v70, v0
	v_mov_b32_e32 v71, v0
	v_mov_b32_e32 v80, v0
	v_mov_b32_e32 v81, v0
	v_mov_b32_e32 v82, v0
	v_mov_b32_e32 v83, v0
	v_mov_b32_e32 v84, v0
	v_mov_b32_e32 v85, v0
	v_mov_b32_e32 v86, v0
	v_mov_b32_e32 v87, v0
	v_mov_b32_e32 v96, v0
	v_mov_b32_e32 v97, v0
	v_mov_b32_e32 v98, v0
	v_mov_b32_e32 v99, v0
	v_mov_b32_e32 v100, v0
	v_mov_b32_e32 v101, v0
	v_mov_b32_e32 v102, v0
	v_mov_b32_e32 v103, v0
	v_mov_b32_e32 v112, v0
	v_mov_b32_e32 v113, v0
	v_mov_b32_e32 v114, v0
	v_mov_b32_e32 v115, v0
	v_mov_b32_e32 v116, v0
	v_mov_b32_e32 v117, v0
	v_mov_b32_e32 v118, v0
	v_mov_b32_e32 v119, v0
	v_mov_b32_e32 v72, v0
	v_mov_b32_e32 v73, v0
	v_mov_b32_e32 v74, v0
	v_mov_b32_e32 v75, v0
	v_mov_b32_e32 v76, v0
	v_mov_b32_e32 v77, v0
	v_mov_b32_e32 v78, v0
	v_mov_b32_e32 v79, v0
	v_mov_b32_e32 v88, v0
	v_mov_b32_e32 v89, v0
	v_mov_b32_e32 v90, v0
	v_mov_b32_e32 v91, v0
	v_mov_b32_e32 v92, v0
	v_mov_b32_e32 v93, v0
	v_mov_b32_e32 v94, v0
	v_mov_b32_e32 v95, v0
	v_mov_b32_e32 v104, v0
	v_mov_b32_e32 v105, v0
	v_mov_b32_e32 v106, v0
	v_mov_b32_e32 v107, v0
	v_mov_b32_e32 v108, v0
	v_mov_b32_e32 v109, v0
	v_mov_b32_e32 v110, v0
	v_mov_b32_e32 v111, v0
	v_mov_b32_e32 v124, v0
	v_mov_b32_e32 v125, v0
	v_mov_b32_e32 v126, v0
	v_mov_b32_e32 v127, v0
	v_mov_b32_e32 v120, v0
	v_mov_b32_e32 v121, v0
	v_mov_b32_e32 v122, v0
	v_mov_b32_e32 v123, v0
	v_readfirstlane_b32 s100, v211
	s_cmp_ge_u32 s100, 0x100
	s_cbranch_scc0 .Lprio_skip4
	s_setprio 1
; #define PG8_STAGE(bufoff, gbase, voff) do { _Pragma("unroll") for (int _i = 0; _i < 2; ++_i) \
;         __builtin_amdgcn_global_load_lds((const unsigned*)((const char*)(gbase) + (voff)[_i]), (PG8_LAS unsigned*)(lds + (bufoff) + ldsw + _i * 8192), 16, 0, 0); } while (0)
; #define PG8_LDA(dst, b, h) do { _Pragma("unroll") for (int m = 0; m < 4; ++m) _Pragma("unroll") for (int k = 0; k < 2; ++k) dst[m][k] = *(const PG8_LAS bf16x8*)(lds + PG8_SA(b, h) + aoff + m * 2048 + k * 1024); } while (0)
; #define PG8_LDB(dst, b, h) do { _Pragma("unroll") for (int n = 0; n < 2; ++n) _Pragma("unroll") for (int k = 0; k < 2; ++k) dst[n][k] = *(const PG8_LAS bf16x8*)(lds + PG8_SB(b, h) + boff + n * 2048 + k * 1024); } while (0)
; #define PG8_MMA(ai, bj, At, Bt) do { __builtin_amdgcn_s_setprio(1); _Pragma("unroll") for (int m = 0; m < 4; ++m) _Pragma("unroll") for (int n = 0; n < 2; ++n) _Pragma("unroll") for (int k = 0; k < 2; ++k) \
;         acc[ai][bj][m][n] = __builtin_amdgcn_mfma_f32_16x16x32_bf16(Bt[n][k], At[m][k], acc[ai][bj][m][n], 0, 0, 0); __builtin_amdgcn_s_setprio(0); } while (0)
; #define PG8_WAIT_V(n) asm volatile("s_waitcnt vmcnt(" #n ")" ::: "memory")
; #define PG8_WAIT_L(n) asm volatile("s_waitcnt lgkmcnt(" #n ")" ::: "memory")
; template <class Epi, class Sched, bool ALIGN_EPI = false, bool SP2 = false>
; __device__ __forceinline__ void gemm_phase(PG8_LAS unsigned char* lds, const Gemm g, const Sched& S, const Epi& E) {
;     ...
;             const bool last = (t == nt - 2);
;             const char* a1 = cA + (size_t)(t + 1) * kstep;
;             const char* a2 = last ? nA : cA + (size_t)(t + 2) * kstep; const char* b2 = last ? nB : cB + (size_t)(t + 2) * kstep;
;             const char* a3 = a2 + kstep; const char* b3 = b2 + kstep;
;             if (last && has_next) S.a_ready(nxt);
;             if constexpr (SP2) {
;             PG8_LDB(B0, 0, 0); PG8_LDB(B1, 0, 1); PG8_SCHED; PG8_LDA(At, 0, 0); PG8_STAGE(PG8_SA(1, 1), a1 + hstep, voffA);
;             PG8_WAIT_V(8); PG8_WAIT_L(0); PG8_BAR; PG8_MMA(0, 0, At, B0); PG8_MMA(0, 1, At, B1); PG8_BAR; PG8_SCHED;
;             PG8_LDA(At, 0, 1); PG8_STAGE(PG8_SB(0, 0), b2, voffB); PG8_STAGE(PG8_SB(0, 1), b2 + hstep, voffB); PG8_STAGE(PG8_SA(0, 0), a2, voffA);
;             PG8_WAIT_V(8); PG8_WAIT_L(0); PG8_BAR; PG8_MMA(1, 0, At, B0); PG8_MMA(1, 1, At, B1); PG8_BAR; PG8_SCHED;
.Lprio_skip4:
.LBB0_630:
	s_add_i32 s38, s18, 2
	s_add_u32 s39, s6, 0x80
	s_addc_u32 s19, s7, 0
	s_add_i32 s42, 0, 0x10000
	s_cmp_eq_u32 s30, s18
	s_cselect_b32 s19, s1, s19
	s_cselect_b32 s18, s0, s39
	v_add_u32_e32 v150, s42, v139
	s_cselect_b32 s41, s3, s21
	s_cselect_b32 s40, s2, s20
	s_add_i32 s39, 0, 0x14000
	ds_read_b128 v[142:145], v150
	ds_read_b128 v[146:149], v150 offset:1024
	ds_read_b128 v[168:171], v150 offset:2048
	ds_read_b128 v[172:175], v150 offset:3072
	v_add_u32_e32 v150, s39, v139
	ds_read_b128 v[176:179], v150
	ds_read_b128 v[180:183], v150 offset:1024
	ds_read_b128 v[184:187], v150 offset:2048
	ds_read_b128 v[188:191], v150 offset:3072
	v_lshl_add_u64 v[150:151], s[6:7], 0, v[134:135]
	s_add_i32 m0, s23, 0xc000
	ds_read_b128 v[192:195], v141
	ds_read_b128 v[196:199], v141 offset:1024
	ds_read_b128 v[200:203], v141 offset:2048
	ds_read_b128 v[204:207], v141 offset:3072
	ds_read_b128 v[212:215], v141 offset:4096
	ds_read_b128 v[230:233], v141 offset:5120
	ds_read_b128 v[234:237], v141 offset:6144
	ds_read_b128 v[238:241], v141 offset:7168
	global_load_lds_dwordx4 v[150:151], off
	v_lshl_add_u64 v[150:151], s[6:7], 0, v[136:137]
	s_add_i32 m0, s23, 0xe000
	s_nop 0
	global_load_lds_dwordx4 v[150:151], off
	s_waitcnt vmcnt(8)
	s_waitcnt lgkmcnt(0)
	s_barrier
	s_waitcnt lgkmcnt(0)
	v_mfma_f32_16x16x32_bf16 v[120:123], v[142:145], v[192:195], v[120:123]
	v_mfma_f32_16x16x32_bf16 v[124:127], v[168:171], v[192:195], v[124:127]
	v_mfma_f32_16x16x32_bf16 v[108:111], v[142:145], v[200:203], v[108:111]
	v_mfma_f32_16x16x32_bf16 v[104:107], v[168:171], v[200:203], v[104:107]
	v_mfma_f32_16x16x32_bf16 v[92:95], v[142:145], v[212:215], v[92:95]
	v_mfma_f32_16x16x32_bf16 v[88:91], v[168:171], v[212:215], v[88:91]
	v_mfma_f32_16x16x32_bf16 v[76:79], v[142:145], v[234:237], v[76:79]
	v_mfma_f32_16x16x32_bf16 v[72:75], v[168:171], v[234:237], v[72:75]
	v_mfma_f32_16x16x32_bf16 v[120:123], v[146:149], v[196:199], v[120:123]
	v_mfma_f32_16x16x32_bf16 v[124:127], v[172:175], v[196:199], v[124:127]
	v_mfma_f32_16x16x32_bf16 v[108:111], v[146:149], v[204:207], v[108:111]
	v_mfma_f32_16x16x32_bf16 v[104:107], v[172:175], v[204:207], v[104:107]
	v_mfma_f32_16x16x32_bf16 v[92:95], v[146:149], v[230:233], v[92:95]
	v_mfma_f32_16x16x32_bf16 v[88:91], v[172:175], v[230:233], v[88:91]
	v_mfma_f32_16x16x32_bf16 v[76:79], v[146:149], v[238:241], v[76:79]
	v_mfma_f32_16x16x32_bf16 v[72:75], v[172:175], v[238:241], v[72:75]
	v_mfma_f32_16x16x32_bf16 v[116:119], v[176:179], v[192:195], v[116:119]
	v_mfma_f32_16x16x32_bf16 v[112:115], v[184:187], v[192:195], v[112:115]
	v_mfma_f32_16x16x32_bf16 v[100:103], v[176:179], v[200:203], v[100:103]
	v_mfma_f32_16x16x32_bf16 v[96:99], v[184:187], v[200:203], v[96:99]
	v_mfma_f32_16x16x32_bf16 v[84:87], v[176:179], v[212:215], v[84:87]
	v_mfma_f32_16x16x32_bf16 v[80:83], v[184:187], v[212:215], v[80:83]
	v_mfma_f32_16x16x32_bf16 v[68:71], v[176:179], v[234:237], v[68:71]
	v_mfma_f32_16x16x32_bf16 v[64:67], v[184:187], v[234:237], v[64:67]
	v_mfma_f32_16x16x32_bf16 v[116:119], v[180:183], v[196:199], v[116:119]
	v_mfma_f32_16x16x32_bf16 v[112:115], v[188:191], v[196:199], v[112:115]
	v_mfma_f32_16x16x32_bf16 v[100:103], v[180:183], v[204:207], v[100:103]
	v_mfma_f32_16x16x32_bf16 v[96:99], v[188:191], v[204:207], v[96:99]
	v_mfma_f32_16x16x32_bf16 v[84:87], v[180:183], v[230:233], v[84:87]
	v_mfma_f32_16x16x32_bf16 v[80:83], v[188:191], v[230:233], v[80:83]
	v_mfma_f32_16x16x32_bf16 v[68:71], v[180:183], v[238:241], v[68:71]
	v_mfma_f32_16x16x32_bf16 v[64:67], v[188:191], v[238:241], v[64:67]
	s_barrier
	s_add_i32 s42, s42, s22
	v_lshl_add_u64 v[150:151], s[40:41], 0, v[152:153]
	s_mov_b32 m0, s42
	ds_read_b128 v[192:195], v141 offset:16384
	ds_read_b128 v[196:199], v141 offset:17408
	ds_read_b128 v[200:203], v141 offset:18432
	ds_read_b128 v[204:207], v141 offset:19456
	ds_read_b128 v[212:215], v141 offset:20480
	ds_read_b128 v[230:233], v141 offset:21504
	ds_read_b128 v[234:237], v141 offset:22528
	ds_read_b128 v[238:241], v141 offset:23552
	global_load_lds_dwordx4 v[150:151], off
	s_add_i32 m0, s42, 0x2000
	v_lshl_add_u64 v[158:159], s[40:41], 0, v[128:129]
	s_add_u32 s40, s40, s8
	s_addc_u32 s41, s41, s9
	s_add_i32 s39, s39, s22
	global_load_lds_dwordx4 v[158:159], off
	v_lshl_add_u64 v[160:161], s[40:41], 0, v[152:153]
	s_mov_b32 m0, s39
	v_lshl_add_u64 v[162:163], s[40:41], 0, v[128:129]
	global_load_lds_dwordx4 v[160:161], off
	s_add_i32 m0, s39, 0x2000
	v_lshl_add_u64 v[164:165], s[18:19], 0, v[132:133]
	global_load_lds_dwordx4 v[162:163], off
	s_mov_b32 m0, s23
	v_lshl_add_u64 v[208:209], s[18:19], 0, v[130:131]
	global_load_lds_dwordx4 v[164:165], off
	s_mov_b32 m0, s24
	s_nop 0
	global_load_lds_dwordx4 v[208:209], off
	s_waitcnt vmcnt(8)
	s_waitcnt lgkmcnt(0)
	s_barrier
; #define PG8_STAGE(bufoff, gbase, voff) do { _Pragma("unroll") for (int _i = 0; _i < 2; ++_i) \
;         __builtin_amdgcn_global_load_lds((const unsigned*)((const char*)(gbase) + (voff)[_i]), (PG8_LAS unsigned*)(lds + (bufoff) + ldsw + _i * 8192), 16, 0, 0); } while (0)
; #define PG8_LDA(dst, b, h) do { _Pragma("unroll") for (int m = 0; m < 4; ++m) _Pragma("unroll") for (int k = 0; k < 2; ++k) dst[m][k] = *(const PG8_LAS bf16x8*)(lds + PG8_SA(b, h) + aoff + m * 2048 + k * 1024); } while (0)
; #define PG8_LDB(dst, b, h) do { _Pragma("unroll") for (int n = 0; n < 2; ++n) _Pragma("unroll") for (int k = 0; k < 2; ++k) dst[n][k] = *(const PG8_LAS bf16x8*)(lds + PG8_SB(b, h) + boff + n * 2048 + k * 1024); } while (0)
; #define PG8_MMA(ai, bj, At, Bt) do { __builtin_amdgcn_s_setprio(1); _Pragma("unroll") for (int m = 0; m < 4; ++m) _Pragma("unroll") for (int n = 0; n < 2; ++n) _Pragma("unroll") for (int k = 0; k < 2; ++k) \
;         acc[ai][bj][m][n] = __builtin_amdgcn_mfma_f32_16x16x32_bf16(Bt[n][k], At[m][k], acc[ai][bj][m][n], 0, 0, 0); __builtin_amdgcn_s_setprio(0); } while (0)
; #define PG8_WAIT_V(n) asm volatile("s_waitcnt vmcnt(" #n ")" ::: "memory")
; #define PG8_WAIT_L(n) asm volatile("s_waitcnt lgkmcnt(" #n ")" ::: "memory")
; #define PG8_BAR __builtin_amdgcn_s_barrier()
; #define PG8_SCHED __builtin_amdgcn_sched_barrier(0)
; template <class Epi, class Sched, bool ALIGN_EPI = false, bool SP2 = false>
; __device__ __forceinline__ void gemm_phase(PG8_LAS unsigned char* lds, const Gemm g, const Sched& S, const Epi& E) {
;     ...
;             PG8_WAIT_V(8); PG8_WAIT_L(0); PG8_BAR; PG8_MMA(1, 0, At, B0); PG8_MMA(1, 1, At, B1); PG8_BAR; PG8_SCHED;
;             PG8_LDB(B0, 1, 0); PG8_LDB(B1, 1, 1); PG8_SCHED; PG8_LDA(At, 1, 0); PG8_STAGE(PG8_SA(0, 1), a2 + hstep, voffA);
;             PG8_WAIT_V(8); PG8_WAIT_L(0); PG8_BAR; PG8_MMA(0, 0, At, B0); PG8_MMA(0, 1, At, B1); PG8_BAR; PG8_SCHED;
	s_waitcnt lgkmcnt(0)
	v_mfma_f32_16x16x32_bf16 v[60:63], v[142:145], v[192:195], v[60:63]
	v_mfma_f32_16x16x32_bf16 v[56:59], v[168:171], v[192:195], v[56:59]
	v_mfma_f32_16x16x32_bf16 v[44:47], v[142:145], v[200:203], v[44:47]
	v_mfma_f32_16x16x32_bf16 v[40:43], v[168:171], v[200:203], v[40:43]
	v_mfma_f32_16x16x32_bf16 v[28:31], v[142:145], v[212:215], v[28:31]
	v_mfma_f32_16x16x32_bf16 v[24:27], v[168:171], v[212:215], v[24:27]
	v_mfma_f32_16x16x32_bf16 v[12:15], v[142:145], v[234:237], v[12:15]
	v_mfma_f32_16x16x32_bf16 v[8:11], v[168:171], v[234:237], v[8:11]
	v_mfma_f32_16x16x32_bf16 v[60:63], v[146:149], v[196:199], v[60:63]
	v_mfma_f32_16x16x32_bf16 v[56:59], v[172:175], v[196:199], v[56:59]
	v_mfma_f32_16x16x32_bf16 v[44:47], v[146:149], v[204:207], v[44:47]
	v_mfma_f32_16x16x32_bf16 v[40:43], v[172:175], v[204:207], v[40:43]
	v_mfma_f32_16x16x32_bf16 v[28:31], v[146:149], v[230:233], v[28:31]
	v_mfma_f32_16x16x32_bf16 v[24:27], v[172:175], v[230:233], v[24:27]
	v_mfma_f32_16x16x32_bf16 v[12:15], v[146:149], v[238:241], v[12:15]
	v_mfma_f32_16x16x32_bf16 v[8:11], v[172:175], v[238:241], v[8:11]
	v_mfma_f32_16x16x32_bf16 v[52:55], v[176:179], v[192:195], v[52:55]
	v_mfma_f32_16x16x32_bf16 v[48:51], v[184:187], v[192:195], v[48:51]
	v_mfma_f32_16x16x32_bf16 v[36:39], v[176:179], v[200:203], v[36:39]
	v_mfma_f32_16x16x32_bf16 v[32:35], v[184:187], v[200:203], v[32:35]
	v_mfma_f32_16x16x32_bf16 v[20:23], v[176:179], v[212:215], v[20:23]
	v_mfma_f32_16x16x32_bf16 v[16:19], v[184:187], v[212:215], v[16:19]
	v_mfma_f32_16x16x32_bf16 v[4:7], v[176:179], v[234:237], v[4:7]
	v_mfma_f32_16x16x32_bf16 v[0:3], v[184:187], v[234:237], v[0:3]
	v_mfma_f32_16x16x32_bf16 v[52:55], v[180:183], v[196:199], v[52:55]
	v_mfma_f32_16x16x32_bf16 v[48:51], v[188:191], v[196:199], v[48:51]
	v_mfma_f32_16x16x32_bf16 v[36:39], v[180:183], v[204:207], v[36:39]
	v_mfma_f32_16x16x32_bf16 v[32:35], v[188:191], v[204:207], v[32:35]
	v_mfma_f32_16x16x32_bf16 v[20:23], v[180:183], v[230:233], v[20:23]
	v_mfma_f32_16x16x32_bf16 v[16:19], v[188:191], v[230:233], v[16:19]
	v_mfma_f32_16x16x32_bf16 v[4:7], v[180:183], v[238:241], v[4:7]
	v_mfma_f32_16x16x32_bf16 v[0:3], v[188:191], v[238:241], v[0:3]
	s_barrier
	s_add_i32 s39, 0, 0x18000
	v_add_u32_e32 v167, s39, v139
	s_add_i32 s40, 0, 0x1c000
	ds_read_b128 v[142:145], v167
	ds_read_b128 v[146:149], v167 offset:1024
	ds_read_b128 v[168:171], v167 offset:2048
	ds_read_b128 v[172:175], v167 offset:3072
	v_add_u32_e32 v167, s40, v139
	ds_read_b128 v[176:179], v167
	ds_read_b128 v[180:183], v167 offset:1024
	ds_read_b128 v[184:187], v167 offset:2048
	ds_read_b128 v[188:191], v167 offset:3072
	s_add_u32 s18, s18, s8
	s_addc_u32 s19, s19, s9
	s_mov_b32 m0, s25
	v_lshl_add_u64 v[216:217], s[18:19], 0, v[132:133]
	ds_read_b128 v[192:195], v141 offset:32768
	ds_read_b128 v[196:199], v141 offset:33792
	ds_read_b128 v[200:203], v141 offset:34816
	ds_read_b128 v[204:207], v141 offset:35840
	ds_read_b128 v[212:215], v141 offset:36864
	ds_read_b128 v[230:233], v141 offset:37888
	ds_read_b128 v[234:237], v141 offset:38912
	ds_read_b128 v[238:241], v141 offset:39936
	global_load_lds_dwordx4 v[216:217], off
	v_lshl_add_u64 v[216:217], s[18:19], 0, v[130:131]
	s_mov_b32 m0, s26
	s_nop 0
	global_load_lds_dwordx4 v[216:217], off
	s_waitcnt vmcnt(8)
	s_waitcnt lgkmcnt(0)
	s_barrier
	s_waitcnt lgkmcnt(0)
	v_mfma_f32_16x16x32_bf16 v[120:123], v[142:145], v[192:195], v[120:123]
	v_mfma_f32_16x16x32_bf16 v[124:127], v[168:171], v[192:195], v[124:127]
	v_mfma_f32_16x16x32_bf16 v[108:111], v[142:145], v[200:203], v[108:111]
	v_mfma_f32_16x16x32_bf16 v[104:107], v[168:171], v[200:203], v[104:107]
	v_mfma_f32_16x16x32_bf16 v[92:95], v[142:145], v[212:215], v[92:95]
	v_mfma_f32_16x16x32_bf16 v[88:91], v[168:171], v[212:215], v[88:91]
	v_mfma_f32_16x16x32_bf16 v[76:79], v[142:145], v[234:237], v[76:79]
	v_mfma_f32_16x16x32_bf16 v[72:75], v[168:171], v[234:237], v[72:75]
	v_mfma_f32_16x16x32_bf16 v[120:123], v[146:149], v[196:199], v[120:123]
	v_mfma_f32_16x16x32_bf16 v[124:127], v[172:175], v[196:199], v[124:127]
	v_mfma_f32_16x16x32_bf16 v[108:111], v[146:149], v[204:207], v[108:111]
	v_mfma_f32_16x16x32_bf16 v[104:107], v[172:175], v[204:207], v[104:107]
	v_mfma_f32_16x16x32_bf16 v[92:95], v[146:149], v[230:233], v[92:95]
	v_mfma_f32_16x16x32_bf16 v[88:91], v[172:175], v[230:233], v[88:91]
	v_mfma_f32_16x16x32_bf16 v[76:79], v[146:149], v[238:241], v[76:79]
	v_mfma_f32_16x16x32_bf16 v[72:75], v[172:175], v[238:241], v[72:75]
	v_mfma_f32_16x16x32_bf16 v[116:119], v[176:179], v[192:195], v[116:119]
	v_mfma_f32_16x16x32_bf16 v[112:115], v[184:187], v[192:195], v[112:115]
	v_mfma_f32_16x16x32_bf16 v[100:103], v[176:179], v[200:203], v[100:103]
	v_mfma_f32_16x16x32_bf16 v[96:99], v[184:187], v[200:203], v[96:99]
	v_mfma_f32_16x16x32_bf16 v[84:87], v[176:179], v[212:215], v[84:87]
	v_mfma_f32_16x16x32_bf16 v[80:83], v[184:187], v[212:215], v[80:83]
	v_mfma_f32_16x16x32_bf16 v[68:71], v[176:179], v[234:237], v[68:71]
	v_mfma_f32_16x16x32_bf16 v[64:67], v[184:187], v[234:237], v[64:67]
	v_mfma_f32_16x16x32_bf16 v[116:119], v[180:183], v[196:199], v[116:119]
	v_mfma_f32_16x16x32_bf16 v[112:115], v[188:191], v[196:199], v[112:115]
	v_mfma_f32_16x16x32_bf16 v[100:103], v[180:183], v[204:207], v[100:103]
	v_mfma_f32_16x16x32_bf16 v[96:99], v[188:191], v[204:207], v[96:99]
	v_mfma_f32_16x16x32_bf16 v[84:87], v[180:183], v[230:233], v[84:87]
	v_mfma_f32_16x16x32_bf16 v[80:83], v[188:191], v[230:233], v[80:83]
	v_mfma_f32_16x16x32_bf16 v[68:71], v[180:183], v[238:241], v[68:71]
	v_mfma_f32_16x16x32_bf16 v[64:67], v[188:191], v[238:241], v[64:67]
	s_barrier
; #define PG8_STAGE(bufoff, gbase, voff) do { _Pragma("unroll") for (int _i = 0; _i < 2; ++_i) \
;         __builtin_amdgcn_global_load_lds((const unsigned*)((const char*)(gbase) + (voff)[_i]), (PG8_LAS unsigned*)(lds + (bufoff) + ldsw + _i * 8192), 16, 0, 0); } while (0)
; #define PG8_LDA(dst, b, h) do { _Pragma("unroll") for (int m = 0; m < 4; ++m) _Pragma("unroll") for (int k = 0; k < 2; ++k) dst[m][k] = *(const PG8_LAS bf16x8*)(lds + PG8_SA(b, h) + aoff + m * 2048 + k * 1024); } while (0)
; #define PG8_MMA(ai, bj, At, Bt) do { __builtin_amdgcn_s_setprio(1); _Pragma("unroll") for (int m = 0; m < 4; ++m) _Pragma("unroll") for (int n = 0; n < 2; ++n) _Pragma("unroll") for (int k = 0; k < 2; ++k) \
;         acc[ai][bj][m][n] = __builtin_amdgcn_mfma_f32_16x16x32_bf16(Bt[n][k], At[m][k], acc[ai][bj][m][n], 0, 0, 0); __builtin_amdgcn_s_setprio(0); } while (0)
; #define PG8_WAIT_V(n) asm volatile("s_waitcnt vmcnt(" #n ")" ::: "memory")
; #define PG8_WAIT_L(n) asm volatile("s_waitcnt lgkmcnt(" #n ")" ::: "memory")
; #define PG8_BAR __builtin_amdgcn_s_barrier()
; #define PG8_SCHED __builtin_amdgcn_sched_barrier(0)
; template <class Epi, class Sched, bool ALIGN_EPI = false, bool SP2 = false>
; __device__ __forceinline__ void gemm_phase(PG8_LAS unsigned char* lds, const Gemm g, const Sched& S, const Epi& E) {
;     ...
;         for (int t = 0; t < nt; t += 2) {
;             const bool last = (t == nt - 2);
;     ...
;             PG8_LDA(At, 1, 1); PG8_STAGE(PG8_SB(1, 0), b3, voffB); PG8_STAGE(PG8_SB(1, 1), b3 + hstep, voffB); PG8_STAGE(PG8_SA(1, 0), a3, voffA);
;             PG8_WAIT_V(8); PG8_WAIT_L(0); PG8_BAR; PG8_MMA(1, 0, At, B0); PG8_MMA(1, 1, At, B1); PG8_BAR; PG8_SCHED;
	s_add_i32 s18, s39, s22
	v_lshl_add_u64 v[150:151], v[150:151], 0, s[82:83]
	s_mov_b32 m0, s18
	ds_read_b128 v[192:195], v141 offset:49152
	ds_read_b128 v[196:199], v141 offset:50176
	ds_read_b128 v[200:203], v141 offset:51200
	ds_read_b128 v[204:207], v141 offset:52224
	ds_read_b128 v[212:215], v141 offset:53248
	ds_read_b128 v[230:233], v141 offset:54272
	ds_read_b128 v[234:237], v141 offset:55296
	ds_read_b128 v[238:241], v141 offset:56320
	global_load_lds_dwordx4 v[150:151], off
	v_lshl_add_u64 v[150:151], v[158:159], 0, s[82:83]
	s_add_i32 m0, s18, 0x2000
	s_add_i32 s18, s40, s22
	global_load_lds_dwordx4 v[150:151], off
	v_lshl_add_u64 v[150:151], v[160:161], 0, s[82:83]
	s_mov_b32 m0, s18
	s_nop 0
	global_load_lds_dwordx4 v[150:151], off
	v_lshl_add_u64 v[150:151], v[162:163], 0, s[82:83]
	s_add_i32 m0, s18, 0x2000
	s_nop 0
	global_load_lds_dwordx4 v[150:151], off
	v_lshl_add_u64 v[150:151], v[164:165], 0, s[82:83]
	s_mov_b32 m0, s27
	s_nop 0
	global_load_lds_dwordx4 v[150:151], off
	v_lshl_add_u64 v[150:151], v[208:209], 0, s[82:83]
	s_mov_b32 m0, s28
	s_nop 0
	global_load_lds_dwordx4 v[150:151], off
	s_waitcnt vmcnt(8)
	s_waitcnt lgkmcnt(0)
	s_barrier
	s_waitcnt lgkmcnt(0)
	v_mfma_f32_16x16x32_bf16 v[60:63], v[142:145], v[192:195], v[60:63]
	v_mfma_f32_16x16x32_bf16 v[56:59], v[168:171], v[192:195], v[56:59]
	v_mfma_f32_16x16x32_bf16 v[44:47], v[142:145], v[200:203], v[44:47]
	v_mfma_f32_16x16x32_bf16 v[40:43], v[168:171], v[200:203], v[40:43]
	v_mfma_f32_16x16x32_bf16 v[28:31], v[142:145], v[212:215], v[28:31]
	v_mfma_f32_16x16x32_bf16 v[24:27], v[168:171], v[212:215], v[24:27]
	v_mfma_f32_16x16x32_bf16 v[12:15], v[142:145], v[234:237], v[12:15]
	v_mfma_f32_16x16x32_bf16 v[8:11], v[168:171], v[234:237], v[8:11]
	v_mfma_f32_16x16x32_bf16 v[60:63], v[146:149], v[196:199], v[60:63]
	v_mfma_f32_16x16x32_bf16 v[56:59], v[172:175], v[196:199], v[56:59]
	v_mfma_f32_16x16x32_bf16 v[44:47], v[146:149], v[204:207], v[44:47]
	v_mfma_f32_16x16x32_bf16 v[40:43], v[172:175], v[204:207], v[40:43]
	v_mfma_f32_16x16x32_bf16 v[28:31], v[146:149], v[230:233], v[28:31]
	v_mfma_f32_16x16x32_bf16 v[24:27], v[172:175], v[230:233], v[24:27]
	v_mfma_f32_16x16x32_bf16 v[12:15], v[146:149], v[238:241], v[12:15]
	v_mfma_f32_16x16x32_bf16 v[8:11], v[172:175], v[238:241], v[8:11]
	v_mfma_f32_16x16x32_bf16 v[52:55], v[176:179], v[192:195], v[52:55]
	v_mfma_f32_16x16x32_bf16 v[48:51], v[184:187], v[192:195], v[48:51]
	v_mfma_f32_16x16x32_bf16 v[36:39], v[176:179], v[200:203], v[36:39]
	v_mfma_f32_16x16x32_bf16 v[32:35], v[184:187], v[200:203], v[32:35]
	v_mfma_f32_16x16x32_bf16 v[20:23], v[176:179], v[212:215], v[20:23]
	v_mfma_f32_16x16x32_bf16 v[16:19], v[184:187], v[212:215], v[16:19]
	v_mfma_f32_16x16x32_bf16 v[4:7], v[176:179], v[234:237], v[4:7]
	v_mfma_f32_16x16x32_bf16 v[0:3], v[184:187], v[234:237], v[0:3]
	v_mfma_f32_16x16x32_bf16 v[52:55], v[180:183], v[196:199], v[52:55]
	v_mfma_f32_16x16x32_bf16 v[48:51], v[188:191], v[196:199], v[48:51]
	v_mfma_f32_16x16x32_bf16 v[36:39], v[180:183], v[204:207], v[36:39]
	v_mfma_f32_16x16x32_bf16 v[32:35], v[188:191], v[204:207], v[32:35]
	v_mfma_f32_16x16x32_bf16 v[20:23], v[180:183], v[230:233], v[20:23]
	v_mfma_f32_16x16x32_bf16 v[16:19], v[188:191], v[230:233], v[16:19]
	v_mfma_f32_16x16x32_bf16 v[4:7], v[180:183], v[238:241], v[4:7]
	v_mfma_f32_16x16x32_bf16 v[0:3], v[188:191], v[238:241], v[0:3]
	s_barrier
	s_add_u32 s6, s6, 0x100
	s_addc_u32 s7, s7, 0
	s_add_u32 s20, s20, 0x100
	s_addc_u32 s21, s21, 0
	s_cmp_ge_i32 s38, s29
	s_mov_b32 s18, s38
	s_cbranch_scc0 .LBB0_630
	s_setprio 0

; template <class Epi, class Sched, bool ALIGN_EPI = false, bool SP2 = false>
; __device__ __forceinline__ void gemm_phase(PG8_LAS unsigned char* lds, const Gemm g, const Sched& S, const Epi& E) {
;     ...
;         for (int t = 0; t < nt; t += 2) {
;             const bool last = (t == nt - 2);
;     ...
; #pragma unroll
;         for (int a = 0; a < 2; ++a)
; #pragma unroll
;             for (int b = 0; b < 2; ++b)
; #pragma unroll
;                 for (int m = 0; m < 4; ++m)
; #pragma unroll
;                     for (int n = 0; n < 2; ++n) acc[a][b][m][n] = (f32x4){0.f, 0.f, 0.f, 0.f};
;         cur = nxt; cA = nA; cB = nB; ++ui;
.LBB0_811:
	v_mov_b32_e32 v135, 0
	s_andn2_b64 vcc, exec, s[18:19]
	v_mov_b32_e32 v134, 0
	v_mov_b32_e32 v137, 0
	v_mov_b32_e32 v136, 0
	v_mov_b32_e32 v127, 0
	v_mov_b32_e32 v126, 0
	v_mov_b32_e32 v125, 0
	v_mov_b32_e32 v124, 0
	v_mov_b32_e32 v119, 0
	v_mov_b32_e32 v118, 0
	v_mov_b32_e32 v117, 0
	v_mov_b32_e32 v116, 0
	v_mov_b32_e32 v111, 0
	v_mov_b32_e32 v110, 0
	v_mov_b32_e32 v109, 0
	v_mov_b32_e32 v108, 0
	v_mov_b32_e32 v103, 0
	v_mov_b32_e32 v102, 0
	v_mov_b32_e32 v101, 0
	v_mov_b32_e32 v100, 0
	v_mov_b32_e32 v95, 0
	v_mov_b32_e32 v94, 0
	v_mov_b32_e32 v93, 0
	v_mov_b32_e32 v92, 0
	v_mov_b32_e32 v87, 0
	v_mov_b32_e32 v86, 0
	v_mov_b32_e32 v85, 0
	v_mov_b32_e32 v84, 0
	v_mov_b32_e32 v75, 0
	v_mov_b32_e32 v74, 0
	v_mov_b32_e32 v73, 0
	v_mov_b32_e32 v72, 0
	v_mov_b32_e32 v145, 0
	v_mov_b32_e32 v144, 0
	v_mov_b32_e32 v143, 0
	v_mov_b32_e32 v142, 0
	v_mov_b32_e32 v141, 0
	v_mov_b32_e32 v140, 0
	v_mov_b32_e32 v139, 0
	v_mov_b32_e32 v138, 0
	v_mov_b32_e32 v123, 0
	v_mov_b32_e32 v122, 0
	v_mov_b32_e32 v121, 0
	v_mov_b32_e32 v120, 0
	v_mov_b32_e32 v115, 0
	v_mov_b32_e32 v114, 0
	v_mov_b32_e32 v113, 0
	v_mov_b32_e32 v112, 0
	v_mov_b32_e32 v107, 0
	v_mov_b32_e32 v106, 0
	v_mov_b32_e32 v105, 0
	v_mov_b32_e32 v104, 0
	v_mov_b32_e32 v99, 0
	v_mov_b32_e32 v98, 0
	v_mov_b32_e32 v97, 0
	v_mov_b32_e32 v96, 0
	v_mov_b32_e32 v91, 0
	v_mov_b32_e32 v90, 0
	v_mov_b32_e32 v89, 0
	v_mov_b32_e32 v88, 0
	v_mov_b32_e32 v83, 0
	v_mov_b32_e32 v82, 0
	v_mov_b32_e32 v81, 0
	v_mov_b32_e32 v80, 0
	v_mov_b32_e32 v67, 0
	v_mov_b32_e32 v66, 0
	v_mov_b32_e32 v65, 0
	v_mov_b32_e32 v64, 0
	v_mov_b32_e32 v63, 0
	v_mov_b32_e32 v62, 0
	v_mov_b32_e32 v61, 0
	v_mov_b32_e32 v60, 0
	v_mov_b32_e32 v55, 0
	v_mov_b32_e32 v54, 0
	v_mov_b32_e32 v53, 0
	v_mov_b32_e32 v52, 0
	v_mov_b32_e32 v47, 0
	v_mov_b32_e32 v46, 0
	v_mov_b32_e32 v45, 0
	v_mov_b32_e32 v44, 0
	v_mov_b32_e32 v31, 0
	v_mov_b32_e32 v30, 0
	v_mov_b32_e32 v29, 0
	v_mov_b32_e32 v28, 0
	v_mov_b32_e32 v23, 0
	v_mov_b32_e32 v22, 0
	v_mov_b32_e32 v21, 0
	v_mov_b32_e32 v20, 0
	v_mov_b32_e32 v15, 0
	v_mov_b32_e32 v14, 0
	v_mov_b32_e32 v13, 0
	v_mov_b32_e32 v12, 0
	v_mov_b32_e32 v11, 0
	v_mov_b32_e32 v10, 0
	v_mov_b32_e32 v9, 0
	v_mov_b32_e32 v8, 0
	v_mov_b32_e32 v79, 0
	v_mov_b32_e32 v78, 0
	v_mov_b32_e32 v77, 0
	v_mov_b32_e32 v76, 0
	v_mov_b32_e32 v71, 0
	v_mov_b32_e32 v70, 0
	v_mov_b32_e32 v69, 0
	v_mov_b32_e32 v68, 0
	v_mov_b32_e32 v59, 0
	v_mov_b32_e32 v58, 0
	v_mov_b32_e32 v57, 0
	v_mov_b32_e32 v56, 0
	v_mov_b32_e32 v51, 0
	v_mov_b32_e32 v50, 0
	v_mov_b32_e32 v49, 0
	v_mov_b32_e32 v48, 0
	v_mov_b32_e32 v39, 0
	v_mov_b32_e32 v38, 0
	v_mov_b32_e32 v37, 0
	v_mov_b32_e32 v36, 0
	v_mov_b32_e32 v35, 0
	v_mov_b32_e32 v34, 0
	v_mov_b32_e32 v33, 0
	v_mov_b32_e32 v32, 0
	v_mov_b32_e32 v7, 0
	v_mov_b32_e32 v6, 0
	v_mov_b32_e32 v5, 0
	v_mov_b32_e32 v4, 0
	v_mov_b32_e32 v3, 0
	v_mov_b32_e32 v2, 0
	v_mov_b32_e32 v1, 0
	v_mov_b32_e32 v0, 0
	s_cbranch_vccnz .LBB0_815
	s_add_u32 s0, s0, 0x80
	s_addc_u32 s1, s1, 0
	s_add_u32 s36, s2, 0x100
	v_mov_b32_e32 v0, 0
	s_addc_u32 s37, s3, 0
	s_mov_b32 s2, 0
	v_mov_b32_e32 v1, v0
	v_mov_b32_e32 v2, v0
	v_mov_b32_e32 v3, v0
	v_mov_b32_e32 v4, v0
	v_mov_b32_e32 v5, v0
	v_mov_b32_e32 v6, v0
	v_mov_b32_e32 v7, v0
	v_mov_b32_e32 v8, v0
	v_mov_b32_e32 v9, v0
	v_mov_b32_e32 v10, v0
	v_mov_b32_e32 v11, v0
	v_mov_b32_e32 v12, v0
	v_mov_b32_e32 v13, v0
	v_mov_b32_e32 v14, v0
	v_mov_b32_e32 v15, v0
	v_mov_b32_e32 v20, v0
	v_mov_b32_e32 v21, v0
	v_mov_b32_e32 v22, v0
	v_mov_b32_e32 v23, v0
	v_mov_b32_e32 v28, v0
	v_mov_b32_e32 v29, v0
	v_mov_b32_e32 v30, v0
	v_mov_b32_e32 v31, v0
	v_mov_b32_e32 v36, v0
	v_mov_b32_e32 v37, v0
	v_mov_b32_e32 v38, v0
	v_mov_b32_e32 v39, v0
	v_mov_b32_e32 v44, v0
	v_mov_b32_e32 v45, v0
	v_mov_b32_e32 v46, v0
	v_mov_b32_e32 v47, v0
	v_mov_b32_e32 v16, v0
	v_mov_b32_e32 v17, v0
	v_mov_b32_e32 v18, v0
	v_mov_b32_e32 v19, v0
	v_mov_b32_e32 v24, v0
	v_mov_b32_e32 v25, v0
	v_mov_b32_e32 v26, v0
	v_mov_b32_e32 v27, v0
	v_mov_b32_e32 v32, v0
	v_mov_b32_e32 v33, v0
	v_mov_b32_e32 v34, v0
	v_mov_b32_e32 v35, v0
	v_mov_b32_e32 v40, v0
	v_mov_b32_e32 v41, v0
	v_mov_b32_e32 v42, v0
	v_mov_b32_e32 v43, v0
	v_mov_b32_e32 v48, v0
	v_mov_b32_e32 v49, v0
	v_mov_b32_e32 v50, v0
	v_mov_b32_e32 v51, v0
	v_mov_b32_e32 v52, v0
	v_mov_b32_e32 v53, v0
	v_mov_b32_e32 v54, v0
	v_mov_b32_e32 v55, v0
	v_mov_b32_e32 v56, v0
	v_mov_b32_e32 v57, v0
	v_mov_b32_e32 v58, v0
	v_mov_b32_e32 v59, v0
	v_mov_b32_e32 v60, v0
	v_mov_b32_e32 v61, v0
	v_mov_b32_e32 v62, v0
	v_mov_b32_e32 v63, v0
	v_mov_b32_e32 v64, v0
	v_mov_b32_e32 v65, v0
	v_mov_b32_e32 v66, v0
	v_mov_b32_e32 v67, v0
	v_mov_b32_e32 v68, v0
	v_mov_b32_e32 v69, v0
	v_mov_b32_e32 v70, v0
	v_mov_b32_e32 v71, v0
	v_mov_b32_e32 v72, v0
	v_mov_b32_e32 v73, v0
	v_mov_b32_e32 v74, v0
	v_mov_b32_e32 v75, v0
	v_mov_b32_e32 v76, v0
	v_mov_b32_e32 v77, v0
	v_mov_b32_e32 v78, v0
	v_mov_b32_e32 v79, v0
	v_mov_b32_e32 v84, v0
	v_mov_b32_e32 v85, v0
	v_mov_b32_e32 v86, v0
	v_mov_b32_e32 v87, v0
	v_mov_b32_e32 v92, v0
	v_mov_b32_e32 v93, v0
	v_mov_b32_e32 v94, v0
	v_mov_b32_e32 v95, v0
	v_mov_b32_e32 v100, v0
	v_mov_b32_e32 v101, v0
	v_mov_b32_e32 v102, v0
	v_mov_b32_e32 v103, v0
	v_mov_b32_e32 v108, v0
	v_mov_b32_e32 v109, v0
	v_mov_b32_e32 v110, v0
	v_mov_b32_e32 v111, v0
	v_mov_b32_e32 v80, v0
	v_mov_b32_e32 v81, v0
	v_mov_b32_e32 v82, v0
	v_mov_b32_e32 v83, v0
	v_mov_b32_e32 v88, v0
	v_mov_b32_e32 v89, v0
	v_mov_b32_e32 v90, v0
	v_mov_b32_e32 v91, v0
	v_mov_b32_e32 v96, v0
	v_mov_b32_e32 v97, v0
	v_mov_b32_e32 v98, v0
	v_mov_b32_e32 v99, v0
	v_mov_b32_e32 v104, v0
	v_mov_b32_e32 v105, v0
	v_mov_b32_e32 v106, v0
	v_mov_b32_e32 v107, v0
	v_mov_b32_e32 v112, v0
	v_mov_b32_e32 v113, v0
	v_mov_b32_e32 v114, v0
	v_mov_b32_e32 v115, v0
	v_mov_b32_e32 v116, v0
	v_mov_b32_e32 v117, v0
	v_mov_b32_e32 v118, v0
	v_mov_b32_e32 v119, v0
	v_mov_b32_e32 v120, v0
	v_mov_b32_e32 v121, v0
	v_mov_b32_e32 v122, v0
	v_mov_b32_e32 v123, v0
	v_mov_b32_e32 v124, v0
	v_mov_b32_e32 v125, v0
	v_mov_b32_e32 v126, v0
	v_mov_b32_e32 v127, v0
	v_readfirstlane_b32 s100, v211
	s_cmp_ge_u32 s100, 0x100
	s_cbranch_scc0 .Lprio_skip2
	s_setprio 1
; #define PG8_STAGE(bufoff, gbase, voff) do { _Pragma("unroll") for (int _i = 0; _i < 2; ++_i) \
;         __builtin_amdgcn_global_load_lds((const unsigned*)((const char*)(gbase) + (voff)[_i]), (PG8_LAS unsigned*)(lds + (bufoff) + ldsw + _i * 8192), 16, 0, 0); } while (0)
; #define PG8_LDA(dst, b, h) do { _Pragma("unroll") for (int m = 0; m < 4; ++m) _Pragma("unroll") for (int k = 0; k < 2; ++k) dst[m][k] = *(const PG8_LAS bf16x8*)(lds + PG8_SA(b, h) + aoff + m * 2048 + k * 1024); } while (0)
; #define PG8_LDB(dst, b, h) do { _Pragma("unroll") for (int n = 0; n < 2; ++n) _Pragma("unroll") for (int k = 0; k < 2; ++k) dst[n][k] = *(const PG8_LAS bf16x8*)(lds + PG8_SB(b, h) + boff + n * 2048 + k * 1024); } while (0)
; #define PG8_MMA(ai, bj, At, Bt) do { __builtin_amdgcn_s_setprio(1); _Pragma("unroll") for (int m = 0; m < 4; ++m) _Pragma("unroll") for (int n = 0; n < 2; ++n) _Pragma("unroll") for (int k = 0; k < 2; ++k) \
;         acc[ai][bj][m][n] = __builtin_amdgcn_mfma_f32_16x16x32_bf16(Bt[n][k], At[m][k], acc[ai][bj][m][n], 0, 0, 0); __builtin_amdgcn_s_setprio(0); } while (0)
; #define PG8_WAIT_V(n) asm volatile("s_waitcnt vmcnt(" #n ")" ::: "memory")
; #define PG8_WAIT_L(n) asm volatile("s_waitcnt lgkmcnt(" #n ")" ::: "memory")
; template <class Epi, class Sched, bool ALIGN_EPI = false, bool SP2 = false>
; __device__ __forceinline__ void gemm_phase(PG8_LAS unsigned char* lds, const Gemm g, const Sched& S, const Epi& E) {
;     ...
;             const bool last = (t == nt - 2);
;             const char* a1 = cA + (size_t)(t + 1) * kstep;
;             const char* a2 = last ? nA : cA + (size_t)(t + 2) * kstep; const char* b2 = last ? nB : cB + (size_t)(t + 2) * kstep;
;             const char* a3 = a2 + kstep; const char* b3 = b2 + kstep;
;             if (last && has_next) S.a_ready(nxt);
;             if constexpr (SP2) {
;             PG8_LDB(B0, 0, 0); PG8_LDB(B1, 0, 1); PG8_SCHED; PG8_LDA(At, 0, 0); PG8_STAGE(PG8_SA(1, 1), a1 + hstep, voffA);
;             PG8_WAIT_V(8); PG8_WAIT_L(0); PG8_BAR; PG8_MMA(0, 0, At, B0); PG8_MMA(0, 1, At, B1); PG8_BAR; PG8_SCHED;
;             PG8_LDA(At, 0, 1); PG8_STAGE(PG8_SB(0, 0), b2, voffB); PG8_STAGE(PG8_SB(0, 1), b2 + hstep, voffB); PG8_STAGE(PG8_SA(0, 0), a2, voffA);
;             PG8_WAIT_V(8); PG8_WAIT_L(0); PG8_BAR; PG8_MMA(1, 0, At, B0); PG8_MMA(1, 1, At, B1); PG8_BAR; PG8_SCHED;
.Lprio_skip2:
.LBB0_813:
	s_add_i32 s40, s2, 2
	s_add_u32 s41, s0, 0x80
	s_addc_u32 s3, s1, 0
	s_add_i32 s44, 0, 0x10000
	s_cmp_eq_u32 s28, s2
	s_cselect_b32 s3, s7, s3
	s_cselect_b32 s2, s6, s41
	v_add_u32_e32 v150, s44, v147
	s_cselect_b32 s43, s39, s37
	s_cselect_b32 s42, s38, s36
	s_add_i32 s41, 0, 0x14000
	ds_read_b128 v[134:137], v150
	ds_read_b128 v[138:141], v150 offset:1024
	ds_read_b128 v[142:145], v150 offset:2048
	ds_read_b128 v[168:171], v150 offset:3072
	v_add_u32_e32 v150, s41, v147
	ds_read_b128 v[172:175], v150
	ds_read_b128 v[176:179], v150 offset:1024
	ds_read_b128 v[180:183], v150 offset:2048
	ds_read_b128 v[184:187], v150 offset:3072
	v_lshl_add_u64 v[150:151], s[0:1], 0, v[130:131]
	s_add_i32 m0, s11, 0xc000
	ds_read_b128 v[188:191], v149
	ds_read_b128 v[192:195], v149 offset:1024
	ds_read_b128 v[196:199], v149 offset:2048
	ds_read_b128 v[200:203], v149 offset:3072
	ds_read_b128 v[204:207], v149 offset:4096
	ds_read_b128 v[212:215], v149 offset:5120
	ds_read_b128 v[230:233], v149 offset:6144
	ds_read_b128 v[234:237], v149 offset:7168
	global_load_lds_dwordx4 v[150:151], off
	v_lshl_add_u64 v[150:151], s[0:1], 0, v[132:133]
	s_add_i32 m0, s11, 0xe000
	s_nop 0
	global_load_lds_dwordx4 v[150:151], off
	s_waitcnt vmcnt(8)
	s_waitcnt lgkmcnt(0)
	s_barrier
	s_waitcnt lgkmcnt(0)
	v_mfma_f32_16x16x32_bf16 v[124:127], v[134:137], v[188:191], v[124:127]
	v_mfma_f32_16x16x32_bf16 v[120:123], v[142:145], v[188:191], v[120:123]
	v_mfma_f32_16x16x32_bf16 v[116:119], v[134:137], v[196:199], v[116:119]
	v_mfma_f32_16x16x32_bf16 v[112:115], v[142:145], v[196:199], v[112:115]
	v_mfma_f32_16x16x32_bf16 v[104:107], v[134:137], v[204:207], v[104:107]
	v_mfma_f32_16x16x32_bf16 v[96:99], v[142:145], v[204:207], v[96:99]
	v_mfma_f32_16x16x32_bf16 v[88:91], v[134:137], v[230:233], v[88:91]
	v_mfma_f32_16x16x32_bf16 v[80:83], v[142:145], v[230:233], v[80:83]
	v_mfma_f32_16x16x32_bf16 v[124:127], v[138:141], v[192:195], v[124:127]
	v_mfma_f32_16x16x32_bf16 v[120:123], v[168:171], v[192:195], v[120:123]
	v_mfma_f32_16x16x32_bf16 v[116:119], v[138:141], v[200:203], v[116:119]
	v_mfma_f32_16x16x32_bf16 v[112:115], v[168:171], v[200:203], v[112:115]
	v_mfma_f32_16x16x32_bf16 v[104:107], v[138:141], v[212:215], v[104:107]
	v_mfma_f32_16x16x32_bf16 v[96:99], v[168:171], v[212:215], v[96:99]
	v_mfma_f32_16x16x32_bf16 v[88:91], v[138:141], v[234:237], v[88:91]
	v_mfma_f32_16x16x32_bf16 v[80:83], v[168:171], v[234:237], v[80:83]
	v_mfma_f32_16x16x32_bf16 v[108:111], v[172:175], v[188:191], v[108:111]
	v_mfma_f32_16x16x32_bf16 v[100:103], v[180:183], v[188:191], v[100:103]
	v_mfma_f32_16x16x32_bf16 v[92:95], v[172:175], v[196:199], v[92:95]
	v_mfma_f32_16x16x32_bf16 v[84:87], v[180:183], v[196:199], v[84:87]
	v_mfma_f32_16x16x32_bf16 v[76:79], v[172:175], v[204:207], v[76:79]
	v_mfma_f32_16x16x32_bf16 v[72:75], v[180:183], v[204:207], v[72:75]
	v_mfma_f32_16x16x32_bf16 v[68:71], v[172:175], v[230:233], v[68:71]
	v_mfma_f32_16x16x32_bf16 v[64:67], v[180:183], v[230:233], v[64:67]
	v_mfma_f32_16x16x32_bf16 v[108:111], v[176:179], v[192:195], v[108:111]
	v_mfma_f32_16x16x32_bf16 v[100:103], v[184:187], v[192:195], v[100:103]
	v_mfma_f32_16x16x32_bf16 v[92:95], v[176:179], v[200:203], v[92:95]
	v_mfma_f32_16x16x32_bf16 v[84:87], v[184:187], v[200:203], v[84:87]
	v_mfma_f32_16x16x32_bf16 v[76:79], v[176:179], v[212:215], v[76:79]
	v_mfma_f32_16x16x32_bf16 v[72:75], v[184:187], v[212:215], v[72:75]
	v_mfma_f32_16x16x32_bf16 v[68:71], v[176:179], v[234:237], v[68:71]
	v_mfma_f32_16x16x32_bf16 v[64:67], v[184:187], v[234:237], v[64:67]
	s_barrier
	s_add_i32 s44, s44, s10
	v_lshl_add_u64 v[150:151], s[42:43], 0, v[152:153]
	s_mov_b32 m0, s44
	ds_read_b128 v[188:191], v149 offset:16384
	ds_read_b128 v[192:195], v149 offset:17408
	ds_read_b128 v[196:199], v149 offset:18432
	ds_read_b128 v[200:203], v149 offset:19456
	ds_read_b128 v[204:207], v149 offset:20480
	ds_read_b128 v[212:215], v149 offset:21504
	ds_read_b128 v[230:233], v149 offset:22528
	ds_read_b128 v[234:237], v149 offset:23552
	global_load_lds_dwordx4 v[150:151], off
	s_add_i32 m0, s44, 0x2000
	v_lshl_add_u64 v[158:159], s[42:43], 0, v[128:129]
	s_add_u32 s42, s42, s8
	s_addc_u32 s43, s43, s9
	s_add_i32 s41, s41, s10
	global_load_lds_dwordx4 v[158:159], off
	v_lshl_add_u64 v[160:161], s[42:43], 0, v[152:153]
	s_mov_b32 m0, s41
	v_lshl_add_u64 v[162:163], s[42:43], 0, v[128:129]
	global_load_lds_dwordx4 v[160:161], off
	s_add_i32 m0, s41, 0x2000
	v_lshl_add_u64 v[164:165], s[2:3], 0, v[152:153]
	global_load_lds_dwordx4 v[162:163], off
	s_mov_b32 m0, s11
	v_lshl_add_u64 v[208:209], s[2:3], 0, v[128:129]
	global_load_lds_dwordx4 v[164:165], off
	s_mov_b32 m0, s20
	s_nop 0
	global_load_lds_dwordx4 v[208:209], off
	s_waitcnt vmcnt(8)
	s_waitcnt lgkmcnt(0)
	s_barrier
; #define PG8_STAGE(bufoff, gbase, voff) do { _Pragma("unroll") for (int _i = 0; _i < 2; ++_i) \
;         __builtin_amdgcn_global_load_lds((const unsigned*)((const char*)(gbase) + (voff)[_i]), (PG8_LAS unsigned*)(lds + (bufoff) + ldsw + _i * 8192), 16, 0, 0); } while (0)
; #define PG8_LDA(dst, b, h) do { _Pragma("unroll") for (int m = 0; m < 4; ++m) _Pragma("unroll") for (int k = 0; k < 2; ++k) dst[m][k] = *(const PG8_LAS bf16x8*)(lds + PG8_SA(b, h) + aoff + m * 2048 + k * 1024); } while (0)
; #define PG8_LDB(dst, b, h) do { _Pragma("unroll") for (int n = 0; n < 2; ++n) _Pragma("unroll") for (int k = 0; k < 2; ++k) dst[n][k] = *(const PG8_LAS bf16x8*)(lds + PG8_SB(b, h) + boff + n * 2048 + k * 1024); } while (0)
; #define PG8_MMA(ai, bj, At, Bt) do { __builtin_amdgcn_s_setprio(1); _Pragma("unroll") for (int m = 0; m < 4; ++m) _Pragma("unroll") for (int n = 0; n < 2; ++n) _Pragma("unroll") for (int k = 0; k < 2; ++k) \
;         acc[ai][bj][m][n] = __builtin_amdgcn_mfma_f32_16x16x32_bf16(Bt[n][k], At[m][k], acc[ai][bj][m][n], 0, 0, 0); __builtin_amdgcn_s_setprio(0); } while (0)
; #define PG8_WAIT_V(n) asm volatile("s_waitcnt vmcnt(" #n ")" ::: "memory")
; #define PG8_WAIT_L(n) asm volatile("s_waitcnt lgkmcnt(" #n ")" ::: "memory")
; #define PG8_BAR __builtin_amdgcn_s_barrier()
; #define PG8_SCHED __builtin_amdgcn_sched_barrier(0)
; template <class Epi, class Sched, bool ALIGN_EPI = false, bool SP2 = false>
; __device__ __forceinline__ void gemm_phase(PG8_LAS unsigned char* lds, const Gemm g, const Sched& S, const Epi& E) {
;     ...
;             PG8_WAIT_V(8); PG8_WAIT_L(0); PG8_BAR; PG8_MMA(1, 0, At, B0); PG8_MMA(1, 1, At, B1); PG8_BAR; PG8_SCHED;
;             PG8_LDB(B0, 1, 0); PG8_LDB(B1, 1, 1); PG8_SCHED; PG8_LDA(At, 1, 0); PG8_STAGE(PG8_SA(0, 1), a2 + hstep, voffA);
;             PG8_WAIT_V(8); PG8_WAIT_L(0); PG8_BAR; PG8_MMA(0, 0, At, B0); PG8_MMA(0, 1, At, B1); PG8_BAR; PG8_SCHED;
	s_waitcnt lgkmcnt(0)
	v_mfma_f32_16x16x32_bf16 v[60:63], v[134:137], v[188:191], v[60:63]
	v_mfma_f32_16x16x32_bf16 v[56:59], v[142:145], v[188:191], v[56:59]
	v_mfma_f32_16x16x32_bf16 v[52:55], v[134:137], v[196:199], v[52:55]
	v_mfma_f32_16x16x32_bf16 v[48:51], v[142:145], v[196:199], v[48:51]
	v_mfma_f32_16x16x32_bf16 v[40:43], v[134:137], v[204:207], v[40:43]
	v_mfma_f32_16x16x32_bf16 v[32:35], v[142:145], v[204:207], v[32:35]
	v_mfma_f32_16x16x32_bf16 v[24:27], v[134:137], v[230:233], v[24:27]
	v_mfma_f32_16x16x32_bf16 v[16:19], v[142:145], v[230:233], v[16:19]
	v_mfma_f32_16x16x32_bf16 v[60:63], v[138:141], v[192:195], v[60:63]
	v_mfma_f32_16x16x32_bf16 v[56:59], v[168:171], v[192:195], v[56:59]
	v_mfma_f32_16x16x32_bf16 v[52:55], v[138:141], v[200:203], v[52:55]
	v_mfma_f32_16x16x32_bf16 v[48:51], v[168:171], v[200:203], v[48:51]
	v_mfma_f32_16x16x32_bf16 v[40:43], v[138:141], v[212:215], v[40:43]
	v_mfma_f32_16x16x32_bf16 v[32:35], v[168:171], v[212:215], v[32:35]
	v_mfma_f32_16x16x32_bf16 v[24:27], v[138:141], v[234:237], v[24:27]
	v_mfma_f32_16x16x32_bf16 v[16:19], v[168:171], v[234:237], v[16:19]
	v_mfma_f32_16x16x32_bf16 v[44:47], v[172:175], v[188:191], v[44:47]
	v_mfma_f32_16x16x32_bf16 v[36:39], v[180:183], v[188:191], v[36:39]
	v_mfma_f32_16x16x32_bf16 v[28:31], v[172:175], v[196:199], v[28:31]
	v_mfma_f32_16x16x32_bf16 v[20:23], v[180:183], v[196:199], v[20:23]
	v_mfma_f32_16x16x32_bf16 v[12:15], v[172:175], v[204:207], v[12:15]
	v_mfma_f32_16x16x32_bf16 v[8:11], v[180:183], v[204:207], v[8:11]
	v_mfma_f32_16x16x32_bf16 v[4:7], v[172:175], v[230:233], v[4:7]
	v_mfma_f32_16x16x32_bf16 v[0:3], v[180:183], v[230:233], v[0:3]
	v_mfma_f32_16x16x32_bf16 v[44:47], v[176:179], v[192:195], v[44:47]
	v_mfma_f32_16x16x32_bf16 v[36:39], v[184:187], v[192:195], v[36:39]
	v_mfma_f32_16x16x32_bf16 v[28:31], v[176:179], v[200:203], v[28:31]
	v_mfma_f32_16x16x32_bf16 v[20:23], v[184:187], v[200:203], v[20:23]
	v_mfma_f32_16x16x32_bf16 v[12:15], v[176:179], v[212:215], v[12:15]
	v_mfma_f32_16x16x32_bf16 v[8:11], v[184:187], v[212:215], v[8:11]
	v_mfma_f32_16x16x32_bf16 v[4:7], v[176:179], v[234:237], v[4:7]
	v_mfma_f32_16x16x32_bf16 v[0:3], v[184:187], v[234:237], v[0:3]
	s_barrier
	s_add_i32 s41, 0, 0x18000
	v_add_u32_e32 v167, s41, v147
	s_add_i32 s42, 0, 0x1c000
	ds_read_b128 v[134:137], v167
	ds_read_b128 v[138:141], v167 offset:1024
	ds_read_b128 v[142:145], v167 offset:2048
	ds_read_b128 v[168:171], v167 offset:3072
	v_add_u32_e32 v167, s42, v147
	ds_read_b128 v[172:175], v167
	ds_read_b128 v[176:179], v167 offset:1024
	ds_read_b128 v[180:183], v167 offset:2048
	ds_read_b128 v[184:187], v167 offset:3072
	s_add_u32 s2, s2, s8
	s_addc_u32 s3, s3, s9
	s_mov_b32 m0, s21
	v_lshl_add_u64 v[216:217], s[2:3], 0, v[152:153]
	ds_read_b128 v[188:191], v149 offset:32768
	ds_read_b128 v[192:195], v149 offset:33792
	ds_read_b128 v[196:199], v149 offset:34816
	ds_read_b128 v[200:203], v149 offset:35840
	ds_read_b128 v[204:207], v149 offset:36864
	ds_read_b128 v[212:215], v149 offset:37888
	ds_read_b128 v[230:233], v149 offset:38912
	ds_read_b128 v[234:237], v149 offset:39936
	global_load_lds_dwordx4 v[216:217], off
	v_lshl_add_u64 v[216:217], s[2:3], 0, v[128:129]
	s_mov_b32 m0, s22
	s_nop 0
	global_load_lds_dwordx4 v[216:217], off
	s_waitcnt vmcnt(8)
	s_waitcnt lgkmcnt(0)
	s_barrier
	s_waitcnt lgkmcnt(0)
	v_mfma_f32_16x16x32_bf16 v[124:127], v[134:137], v[188:191], v[124:127]
	v_mfma_f32_16x16x32_bf16 v[120:123], v[142:145], v[188:191], v[120:123]
	v_mfma_f32_16x16x32_bf16 v[116:119], v[134:137], v[196:199], v[116:119]
	v_mfma_f32_16x16x32_bf16 v[112:115], v[142:145], v[196:199], v[112:115]
	v_mfma_f32_16x16x32_bf16 v[104:107], v[134:137], v[204:207], v[104:107]
	v_mfma_f32_16x16x32_bf16 v[96:99], v[142:145], v[204:207], v[96:99]
	v_mfma_f32_16x16x32_bf16 v[88:91], v[134:137], v[230:233], v[88:91]
	v_mfma_f32_16x16x32_bf16 v[80:83], v[142:145], v[230:233], v[80:83]
	v_mfma_f32_16x16x32_bf16 v[124:127], v[138:141], v[192:195], v[124:127]
	v_mfma_f32_16x16x32_bf16 v[120:123], v[168:171], v[192:195], v[120:123]
	v_mfma_f32_16x16x32_bf16 v[116:119], v[138:141], v[200:203], v[116:119]
	v_mfma_f32_16x16x32_bf16 v[112:115], v[168:171], v[200:203], v[112:115]
	v_mfma_f32_16x16x32_bf16 v[104:107], v[138:141], v[212:215], v[104:107]
	v_mfma_f32_16x16x32_bf16 v[96:99], v[168:171], v[212:215], v[96:99]
	v_mfma_f32_16x16x32_bf16 v[88:91], v[138:141], v[234:237], v[88:91]
	v_mfma_f32_16x16x32_bf16 v[80:83], v[168:171], v[234:237], v[80:83]
	v_mfma_f32_16x16x32_bf16 v[108:111], v[172:175], v[188:191], v[108:111]
	v_mfma_f32_16x16x32_bf16 v[100:103], v[180:183], v[188:191], v[100:103]
	v_mfma_f32_16x16x32_bf16 v[92:95], v[172:175], v[196:199], v[92:95]
	v_mfma_f32_16x16x32_bf16 v[84:87], v[180:183], v[196:199], v[84:87]
	v_mfma_f32_16x16x32_bf16 v[76:79], v[172:175], v[204:207], v[76:79]
	v_mfma_f32_16x16x32_bf16 v[72:75], v[180:183], v[204:207], v[72:75]
	v_mfma_f32_16x16x32_bf16 v[68:71], v[172:175], v[230:233], v[68:71]
	v_mfma_f32_16x16x32_bf16 v[64:67], v[180:183], v[230:233], v[64:67]
	v_mfma_f32_16x16x32_bf16 v[108:111], v[176:179], v[192:195], v[108:111]
	v_mfma_f32_16x16x32_bf16 v[100:103], v[184:187], v[192:195], v[100:103]
	v_mfma_f32_16x16x32_bf16 v[92:95], v[176:179], v[200:203], v[92:95]
	v_mfma_f32_16x16x32_bf16 v[84:87], v[184:187], v[200:203], v[84:87]
	v_mfma_f32_16x16x32_bf16 v[76:79], v[176:179], v[212:215], v[76:79]
	v_mfma_f32_16x16x32_bf16 v[72:75], v[184:187], v[212:215], v[72:75]
	v_mfma_f32_16x16x32_bf16 v[68:71], v[176:179], v[234:237], v[68:71]
	v_mfma_f32_16x16x32_bf16 v[64:67], v[184:187], v[234:237], v[64:67]
	s_barrier
; #define PG8_STAGE(bufoff, gbase, voff) do { _Pragma("unroll") for (int _i = 0; _i < 2; ++_i) \
;         __builtin_amdgcn_global_load_lds((const unsigned*)((const char*)(gbase) + (voff)[_i]), (PG8_LAS unsigned*)(lds + (bufoff) + ldsw + _i * 8192), 16, 0, 0); } while (0)
; #define PG8_LDA(dst, b, h) do { _Pragma("unroll") for (int m = 0; m < 4; ++m) _Pragma("unroll") for (int k = 0; k < 2; ++k) dst[m][k] = *(const PG8_LAS bf16x8*)(lds + PG8_SA(b, h) + aoff + m * 2048 + k * 1024); } while (0)
; #define PG8_MMA(ai, bj, At, Bt) do { __builtin_amdgcn_s_setprio(1); _Pragma("unroll") for (int m = 0; m < 4; ++m) _Pragma("unroll") for (int n = 0; n < 2; ++n) _Pragma("unroll") for (int k = 0; k < 2; ++k) \
;         acc[ai][bj][m][n] = __builtin_amdgcn_mfma_f32_16x16x32_bf16(Bt[n][k], At[m][k], acc[ai][bj][m][n], 0, 0, 0); __builtin_amdgcn_s_setprio(0); } while (0)
; #define PG8_WAIT_V(n) asm volatile("s_waitcnt vmcnt(" #n ")" ::: "memory")
; #define PG8_WAIT_L(n) asm volatile("s_waitcnt lgkmcnt(" #n ")" ::: "memory")
; #define PG8_BAR __builtin_amdgcn_s_barrier()
; #define PG8_SCHED __builtin_amdgcn_sched_barrier(0)
; template <class Epi, class Sched, bool ALIGN_EPI = false, bool SP2 = false>
; __device__ __forceinline__ void gemm_phase(PG8_LAS unsigned char* lds, const Gemm g, const Sched& S, const Epi& E) {
;     ...
;         for (int t = 0; t < nt; t += 2) {
;             const bool last = (t == nt - 2);
;     ...
;             PG8_LDA(At, 1, 1); PG8_STAGE(PG8_SB(1, 0), b3, voffB); PG8_STAGE(PG8_SB(1, 1), b3 + hstep, voffB); PG8_STAGE(PG8_SA(1, 0), a3, voffA);
;             PG8_WAIT_V(8); PG8_WAIT_L(0); PG8_BAR; PG8_MMA(1, 0, At, B0); PG8_MMA(1, 1, At, B1); PG8_BAR; PG8_SCHED;
	s_add_i32 s2, s41, s10
	v_lshl_add_u64 v[150:151], v[150:151], 0, s[82:83]
	s_mov_b32 m0, s2
	ds_read_b128 v[188:191], v149 offset:49152
	ds_read_b128 v[192:195], v149 offset:50176
	ds_read_b128 v[196:199], v149 offset:51200
	ds_read_b128 v[200:203], v149 offset:52224
	ds_read_b128 v[204:207], v149 offset:53248
	ds_read_b128 v[212:215], v149 offset:54272
	ds_read_b128 v[230:233], v149 offset:55296
	ds_read_b128 v[234:237], v149 offset:56320
	global_load_lds_dwordx4 v[150:151], off
	v_lshl_add_u64 v[150:151], v[158:159], 0, s[82:83]
	s_add_i32 m0, s2, 0x2000
	s_add_i32 s2, s42, s10
	global_load_lds_dwordx4 v[150:151], off
	v_lshl_add_u64 v[150:151], v[160:161], 0, s[82:83]
	s_mov_b32 m0, s2
	s_nop 0
	global_load_lds_dwordx4 v[150:151], off
	v_lshl_add_u64 v[150:151], v[162:163], 0, s[82:83]
	s_add_i32 m0, s2, 0x2000
	s_nop 0
	global_load_lds_dwordx4 v[150:151], off
	v_lshl_add_u64 v[150:151], v[164:165], 0, s[82:83]
	s_mov_b32 m0, s23
	s_nop 0
	global_load_lds_dwordx4 v[150:151], off
	v_lshl_add_u64 v[150:151], v[208:209], 0, s[82:83]
	s_mov_b32 m0, s24
	s_nop 0
	global_load_lds_dwordx4 v[150:151], off
	s_waitcnt vmcnt(8)
	s_waitcnt lgkmcnt(0)
	s_barrier
	s_waitcnt lgkmcnt(0)
	v_mfma_f32_16x16x32_bf16 v[60:63], v[134:137], v[188:191], v[60:63]
	v_mfma_f32_16x16x32_bf16 v[56:59], v[142:145], v[188:191], v[56:59]
	v_mfma_f32_16x16x32_bf16 v[52:55], v[134:137], v[196:199], v[52:55]
	v_mfma_f32_16x16x32_bf16 v[48:51], v[142:145], v[196:199], v[48:51]
	v_mfma_f32_16x16x32_bf16 v[40:43], v[134:137], v[204:207], v[40:43]
	v_mfma_f32_16x16x32_bf16 v[32:35], v[142:145], v[204:207], v[32:35]
	v_mfma_f32_16x16x32_bf16 v[24:27], v[134:137], v[230:233], v[24:27]
	v_mfma_f32_16x16x32_bf16 v[16:19], v[142:145], v[230:233], v[16:19]
	v_mfma_f32_16x16x32_bf16 v[60:63], v[138:141], v[192:195], v[60:63]
	v_mfma_f32_16x16x32_bf16 v[56:59], v[168:171], v[192:195], v[56:59]
	v_mfma_f32_16x16x32_bf16 v[52:55], v[138:141], v[200:203], v[52:55]
	v_mfma_f32_16x16x32_bf16 v[48:51], v[168:171], v[200:203], v[48:51]
	v_mfma_f32_16x16x32_bf16 v[40:43], v[138:141], v[212:215], v[40:43]
	v_mfma_f32_16x16x32_bf16 v[32:35], v[168:171], v[212:215], v[32:35]
	v_mfma_f32_16x16x32_bf16 v[24:27], v[138:141], v[234:237], v[24:27]
	v_mfma_f32_16x16x32_bf16 v[16:19], v[168:171], v[234:237], v[16:19]
	v_mfma_f32_16x16x32_bf16 v[44:47], v[172:175], v[188:191], v[44:47]
	v_mfma_f32_16x16x32_bf16 v[36:39], v[180:183], v[188:191], v[36:39]
	v_mfma_f32_16x16x32_bf16 v[28:31], v[172:175], v[196:199], v[28:31]
	v_mfma_f32_16x16x32_bf16 v[20:23], v[180:183], v[196:199], v[20:23]
	v_mfma_f32_16x16x32_bf16 v[12:15], v[172:175], v[204:207], v[12:15]
	v_mfma_f32_16x16x32_bf16 v[8:11], v[180:183], v[204:207], v[8:11]
	v_mfma_f32_16x16x32_bf16 v[4:7], v[172:175], v[230:233], v[4:7]
	v_mfma_f32_16x16x32_bf16 v[0:3], v[180:183], v[230:233], v[0:3]
	v_mfma_f32_16x16x32_bf16 v[44:47], v[176:179], v[192:195], v[44:47]
	v_mfma_f32_16x16x32_bf16 v[36:39], v[184:187], v[192:195], v[36:39]
	v_mfma_f32_16x16x32_bf16 v[28:31], v[176:179], v[200:203], v[28:31]
	v_mfma_f32_16x16x32_bf16 v[20:23], v[184:187], v[200:203], v[20:23]
	v_mfma_f32_16x16x32_bf16 v[12:15], v[176:179], v[212:215], v[12:15]
	v_mfma_f32_16x16x32_bf16 v[8:11], v[184:187], v[212:215], v[8:11]
	v_mfma_f32_16x16x32_bf16 v[4:7], v[176:179], v[234:237], v[4:7]
	v_mfma_f32_16x16x32_bf16 v[0:3], v[184:187], v[234:237], v[0:3]
	s_barrier
	s_add_u32 s0, s0, 0x100
	s_addc_u32 s1, s1, 0
	s_add_u32 s36, s36, 0x100
	s_addc_u32 s37, s37, 0
	s_cmp_ge_i32 s40, s25
	s_mov_b32 s2, s40
	s_cbranch_scc0 .LBB0_813
;     __device__ __forceinline__ void operator()(const f32x4 (&acc)[2][2][4][2], const pg8::Unit& u, int wr, int wc, int fr, int fq) const {
;         const int row0 = u.pm * 256 + wr * 64 + fr, col0 = u.pn * 256 + wc * 32 + 4 * fq;
; #pragma unroll
;         for (int ai = 0; ai < 2; ++ai)
; #pragma unroll
;             for (int mh = 0; mh < 2; ++mh) {
;                 f32x4 xi[2][2][2];
; #pragma unroll
;                 for (int m = 0; m < 2; ++m)
; #pragma unroll
;                     for (int bj = 0; bj < 2; ++bj)
; #pragma unroll
;                         for (int n = 0; n < 2; ++n) xi[m][bj][n] = *(const f32x4*)(Xin + (size_t)(row0 + ai * 128 + (2 * mh + m) * 16) * D + col0 + bj * 128 + n * 16);
;                 __builtin_amdgcn_sched_barrier(0);
; #pragma unroll
;                 for (int m = 0; m < 2; ++m)
; #pragma unroll
;                     for (int bj = 0; bj < 2; ++bj)
; #pragma unroll
;                         for (int n = 0; n < 2; ++n) *(f32x4*)(Xout + (size_t)(row0 + ai * 128 + (2 * mh + m) * 16) * D + col0 + bj * 128 + n * 16) = xi[m][bj][n] + acc[ai][bj][2 * mh + m][n] * scale;
	s_setprio 0
	v_pk_mul_f32 v[134:135], v[126:127], 0.5 op_sel_hi:[1,0]
	v_pk_mul_f32 v[136:137], v[124:125], 0.5 op_sel_hi:[1,0]
	v_pk_mul_f32 v[126:127], v[122:123], 0.5 op_sel_hi:[1,0]
	v_pk_mul_f32 v[124:125], v[120:121], 0.5 op_sel_hi:[1,0]
	v_pk_mul_f32 v[144:145], v[110:111], 0.5 op_sel_hi:[1,0]
	v_pk_mul_f32 v[142:143], v[108:109], 0.5 op_sel_hi:[1,0]
	v_pk_mul_f32 v[140:141], v[102:103], 0.5 op_sel_hi:[1,0]
	v_pk_mul_f32 v[138:139], v[100:101], 0.5 op_sel_hi:[1,0]
	v_pk_mul_f32 v[118:119], v[118:119], 0.5 op_sel_hi:[1,0]
	v_pk_mul_f32 v[116:117], v[116:117], 0.5 op_sel_hi:[1,0]
	v_pk_mul_f32 v[110:111], v[114:115], 0.5 op_sel_hi:[1,0]
	v_pk_mul_f32 v[108:109], v[112:113], 0.5 op_sel_hi:[1,0]
	v_pk_mul_f32 v[122:123], v[94:95], 0.5 op_sel_hi:[1,0]
	v_pk_mul_f32 v[120:121], v[92:93], 0.5 op_sel_hi:[1,0]
	v_pk_mul_f32 v[114:115], v[86:87], 0.5 op_sel_hi:[1,0]
	v_pk_mul_f32 v[112:113], v[84:85], 0.5 op_sel_hi:[1,0]
	v_pk_mul_f32 v[102:103], v[106:107], 0.5 op_sel_hi:[1,0]
	v_pk_mul_f32 v[100:101], v[104:105], 0.5 op_sel_hi:[1,0]
	v_pk_mul_f32 v[94:95], v[98:99], 0.5 op_sel_hi:[1,0]
	v_pk_mul_f32 v[92:93], v[96:97], 0.5 op_sel_hi:[1,0]
	v_pk_mul_f32 v[106:107], v[78:79], 0.5 op_sel_hi:[1,0]
	v_pk_mul_f32 v[104:105], v[76:77], 0.5 op_sel_hi:[1,0]
	v_pk_mul_f32 v[98:99], v[74:75], 0.5 op_sel_hi:[1,0]
	v_pk_mul_f32 v[96:97], v[72:73], 0.5 op_sel_hi:[1,0]
	v_pk_mul_f32 v[86:87], v[90:91], 0.5 op_sel_hi:[1,0]
	v_pk_mul_f32 v[84:85], v[88:89], 0.5 op_sel_hi:[1,0]
	v_pk_mul_f32 v[74:75], v[82:83], 0.5 op_sel_hi:[1,0]
	v_pk_mul_f32 v[72:73], v[80:81], 0.5 op_sel_hi:[1,0]
	v_pk_mul_f32 v[90:91], v[70:71], 0.5 op_sel_hi:[1,0]
	v_pk_mul_f32 v[88:89], v[68:69], 0.5 op_sel_hi:[1,0]
	v_pk_mul_f32 v[82:83], v[66:67], 0.5 op_sel_hi:[1,0]
	v_pk_mul_f32 v[80:81], v[64:65], 0.5 op_sel_hi:[1,0]
	v_pk_mul_f32 v[66:67], v[62:63], 0.5 op_sel_hi:[1,0]
	v_pk_mul_f32 v[64:65], v[60:61], 0.5 op_sel_hi:[1,0]
	v_pk_mul_f32 v[62:63], v[58:59], 0.5 op_sel_hi:[1,0]
	v_pk_mul_f32 v[60:61], v[56:57], 0.5 op_sel_hi:[1,0]
	v_pk_mul_f32 v[78:79], v[46:47], 0.5 op_sel_hi:[1,0]
	v_pk_mul_f32 v[76:77], v[44:45], 0.5 op_sel_hi:[1,0]
	v_pk_mul_f32 v[70:71], v[38:39], 0.5 op_sel_hi:[1,0]
	v_pk_mul_f32 v[68:69], v[36:37], 0.5 op_sel_hi:[1,0]
	v_pk_mul_f32 v[54:55], v[54:55], 0.5 op_sel_hi:[1,0]
	v_pk_mul_f32 v[52:53], v[52:53], 0.5 op_sel_hi:[1,0]
	v_pk_mul_f32 v[46:47], v[50:51], 0.5 op_sel_hi:[1,0]
	v_pk_mul_f32 v[44:45], v[48:49], 0.5 op_sel_hi:[1,0]
	v_pk_mul_f32 v[58:59], v[30:31], 0.5 op_sel_hi:[1,0]
	v_pk_mul_f32 v[56:57], v[28:29], 0.5 op_sel_hi:[1,0]
	v_pk_mul_f32 v[50:51], v[22:23], 0.5 op_sel_hi:[1,0]
	v_pk_mul_f32 v[48:49], v[20:21], 0.5 op_sel_hi:[1,0]
	v_pk_mul_f32 v[30:31], v[42:43], 0.5 op_sel_hi:[1,0]
	v_pk_mul_f32 v[28:29], v[40:41], 0.5 op_sel_hi:[1,0]
	v_pk_mul_f32 v[22:23], v[34:35], 0.5 op_sel_hi:[1,0]
	v_pk_mul_f32 v[20:21], v[32:33], 0.5 op_sel_hi:[1,0]
	v_pk_mul_f32 v[38:39], v[14:15], 0.5 op_sel_hi:[1,0]
	v_pk_mul_f32 v[36:37], v[12:13], 0.5 op_sel_hi:[1,0]
	v_pk_mul_f32 v[34:35], v[10:11], 0.5 op_sel_hi:[1,0]
	v_pk_mul_f32 v[32:33], v[8:9], 0.5 op_sel_hi:[1,0]
	v_pk_mul_f32 v[14:15], v[26:27], 0.5 op_sel_hi:[1,0]
	v_pk_mul_f32 v[12:13], v[24:25], 0.5 op_sel_hi:[1,0]
	v_pk_mul_f32 v[10:11], v[18:19], 0.5 op_sel_hi:[1,0]
	v_pk_mul_f32 v[8:9], v[16:17], 0.5 op_sel_hi:[1,0]
	v_pk_mul_f32 v[6:7], v[6:7], 0.5 op_sel_hi:[1,0]
	v_pk_mul_f32 v[4:5], v[4:5], 0.5 op_sel_hi:[1,0]
	v_pk_mul_f32 v[2:3], v[2:3], 0.5 op_sel_hi:[1,0]
	v_pk_mul_f32 v[0:1], v[0:1], 0.5 op_sel_hi:[1,0]

; template <class Epi, class Sched, bool ALIGN_EPI = false, bool SP2 = false>
; __device__ __forceinline__ void gemm_phase(PG8_LAS unsigned char* lds, const Gemm g, const Sched& S, const Epi& E) {
;     ...
;         for (int t = 0; t < nt; t += 2) {
;             const bool last = (t == nt - 2);
;     ...
; #pragma unroll
;         for (int a = 0; a < 2; ++a)
; #pragma unroll
;             for (int b = 0; b < 2; ++b)
; #pragma unroll
;                 for (int m = 0; m < 4; ++m)
; #pragma unroll
;                     for (int n = 0; n < 2; ++n) acc[a][b][m][n] = (f32x4){0.f, 0.f, 0.f, 0.f};
;         cur = nxt; cA = nA; cB = nB; ++ui;
.LBB0_838:
	v_mov_b32_e32 v123, 0
	s_andn2_b64 vcc, exec, s[18:19]
	v_mov_b32_e32 v122, v123
	v_mov_b32_e32 v121, v123
	v_mov_b32_e32 v120, v123
	v_mov_b32_e32 v115, v123
	v_mov_b32_e32 v114, v123
	v_mov_b32_e32 v113, v123
	v_mov_b32_e32 v112, v123
	v_mov_b32_e32 v107, v123
	v_mov_b32_e32 v106, v123
	v_mov_b32_e32 v105, v123
	v_mov_b32_e32 v104, v123
	v_mov_b32_e32 v99, v123
	v_mov_b32_e32 v98, v123
	v_mov_b32_e32 v97, v123
	v_mov_b32_e32 v96, v123
	v_mov_b32_e32 v91, v123
	v_mov_b32_e32 v90, v123
	v_mov_b32_e32 v89, v123
	v_mov_b32_e32 v88, v123
	v_mov_b32_e32 v83, v123
	v_mov_b32_e32 v82, v123
	v_mov_b32_e32 v81, v123
	v_mov_b32_e32 v80, v123
	v_mov_b32_e32 v75, v123
	v_mov_b32_e32 v74, v123
	v_mov_b32_e32 v73, v123
	v_mov_b32_e32 v72, v123
	v_mov_b32_e32 v67, v123
	v_mov_b32_e32 v66, v123
	v_mov_b32_e32 v65, v123
	v_mov_b32_e32 v64, v123
	v_mov_b32_e32 v127, v123
	v_mov_b32_e32 v126, v123
	v_mov_b32_e32 v125, v123
	v_mov_b32_e32 v124, v123
	v_mov_b32_e32 v119, v123
	v_mov_b32_e32 v118, v123
	v_mov_b32_e32 v117, v123
	v_mov_b32_e32 v116, v123
	v_mov_b32_e32 v111, v123
	v_mov_b32_e32 v110, v123
	v_mov_b32_e32 v109, v123
	v_mov_b32_e32 v108, v123
	v_mov_b32_e32 v103, v123
	v_mov_b32_e32 v102, v123
	v_mov_b32_e32 v101, v123
	v_mov_b32_e32 v100, v123
	v_mov_b32_e32 v95, v123
	v_mov_b32_e32 v94, v123
	v_mov_b32_e32 v93, v123
	v_mov_b32_e32 v92, v123
	v_mov_b32_e32 v87, v123
	v_mov_b32_e32 v86, v123
	v_mov_b32_e32 v85, v123
	v_mov_b32_e32 v84, v123
	v_mov_b32_e32 v79, v123
	v_mov_b32_e32 v78, v123
	v_mov_b32_e32 v77, v123
	v_mov_b32_e32 v76, v123
	v_mov_b32_e32 v71, v123
	v_mov_b32_e32 v70, v123
	v_mov_b32_e32 v69, v123
	v_mov_b32_e32 v68, v123
	v_mov_b32_e32 v59, v123
	v_mov_b32_e32 v58, v123
	v_mov_b32_e32 v57, v123
	v_mov_b32_e32 v56, v123
	v_mov_b32_e32 v51, v123
	v_mov_b32_e32 v50, v123
	v_mov_b32_e32 v49, v123
	v_mov_b32_e32 v48, v123
	v_mov_b32_e32 v43, v123
	v_mov_b32_e32 v42, v123
	v_mov_b32_e32 v41, v123
	v_mov_b32_e32 v40, v123
	v_mov_b32_e32 v35, v123
	v_mov_b32_e32 v34, v123
	v_mov_b32_e32 v33, v123
	v_mov_b32_e32 v32, v123
	v_mov_b32_e32 v27, v123
	v_mov_b32_e32 v26, v123
	v_mov_b32_e32 v25, v123
	v_mov_b32_e32 v24, v123
	v_mov_b32_e32 v19, v123
	v_mov_b32_e32 v18, v123
	v_mov_b32_e32 v17, v123
	v_mov_b32_e32 v16, v123
	v_mov_b32_e32 v11, v123
	v_mov_b32_e32 v10, v123
	v_mov_b32_e32 v9, v123
	v_mov_b32_e32 v8, v123
	v_mov_b32_e32 v3, v123
	v_mov_b32_e32 v2, v123
	v_mov_b32_e32 v1, v123
	v_mov_b32_e32 v0, v123
	v_mov_b32_e32 v63, v123
	v_mov_b32_e32 v62, v123
	v_mov_b32_e32 v61, v123
	v_mov_b32_e32 v60, v123
	v_mov_b32_e32 v55, v123
	v_mov_b32_e32 v54, v123
	v_mov_b32_e32 v53, v123
	v_mov_b32_e32 v52, v123
	v_mov_b32_e32 v47, v123
	v_mov_b32_e32 v46, v123
	v_mov_b32_e32 v45, v123
	v_mov_b32_e32 v44, v123
	v_mov_b32_e32 v39, v123
	v_mov_b32_e32 v38, v123
	v_mov_b32_e32 v37, v123
	v_mov_b32_e32 v36, v123
	v_mov_b32_e32 v31, v123
	v_mov_b32_e32 v30, v123
	v_mov_b32_e32 v29, v123
	v_mov_b32_e32 v28, v123
	v_mov_b32_e32 v23, v123
	v_mov_b32_e32 v22, v123
	v_mov_b32_e32 v21, v123
	v_mov_b32_e32 v20, v123
	v_mov_b32_e32 v15, v123
	v_mov_b32_e32 v14, v123
	v_mov_b32_e32 v13, v123
	v_mov_b32_e32 v12, v123
	v_mov_b32_e32 v7, v123
	v_mov_b32_e32 v6, v123
	v_mov_b32_e32 v5, v123
	v_mov_b32_e32 v4, v123
	s_cbranch_vccnz .LBB0_841
	s_add_u32 s0, s0, 0x80
	s_addc_u32 s1, s1, 0
	s_add_u32 s36, s2, 0x100
	v_mov_b32_e32 v4, 0
	s_addc_u32 s37, s3, 0
	s_mov_b32 s2, 0
	v_mov_b32_e32 v5, v4
	v_mov_b32_e32 v6, v4
	v_mov_b32_e32 v7, v4
	v_mov_b32_e32 v12, v4
	v_mov_b32_e32 v13, v4
	v_mov_b32_e32 v14, v4
	v_mov_b32_e32 v15, v4
	v_mov_b32_e32 v20, v4
	v_mov_b32_e32 v21, v4
	v_mov_b32_e32 v22, v4
	v_mov_b32_e32 v23, v4
	v_mov_b32_e32 v28, v4
	v_mov_b32_e32 v29, v4
	v_mov_b32_e32 v30, v4
	v_mov_b32_e32 v31, v4
	v_mov_b32_e32 v36, v4
	v_mov_b32_e32 v37, v4
	v_mov_b32_e32 v38, v4
	v_mov_b32_e32 v39, v4
	v_mov_b32_e32 v44, v4
	v_mov_b32_e32 v45, v4
	v_mov_b32_e32 v46, v4
	v_mov_b32_e32 v47, v4
	v_mov_b32_e32 v52, v4
	v_mov_b32_e32 v53, v4
	v_mov_b32_e32 v54, v4
	v_mov_b32_e32 v55, v4
	v_mov_b32_e32 v60, v4
	v_mov_b32_e32 v61, v4
	v_mov_b32_e32 v62, v4
	v_mov_b32_e32 v63, v4
	v_mov_b32_e32 v0, v4
	v_mov_b32_e32 v1, v4
	v_mov_b32_e32 v2, v4
	v_mov_b32_e32 v3, v4
	v_mov_b32_e32 v8, v4
	v_mov_b32_e32 v9, v4
	v_mov_b32_e32 v10, v4
	v_mov_b32_e32 v11, v4
	v_mov_b32_e32 v16, v4
	v_mov_b32_e32 v17, v4
	v_mov_b32_e32 v18, v4
	v_mov_b32_e32 v19, v4
	v_mov_b32_e32 v24, v4
	v_mov_b32_e32 v25, v4
	v_mov_b32_e32 v26, v4
	v_mov_b32_e32 v27, v4
	v_mov_b32_e32 v32, v4
	v_mov_b32_e32 v33, v4
	v_mov_b32_e32 v34, v4
	v_mov_b32_e32 v35, v4
	v_mov_b32_e32 v40, v4
	v_mov_b32_e32 v41, v4
	v_mov_b32_e32 v42, v4
	v_mov_b32_e32 v43, v4
	v_mov_b32_e32 v48, v4
	v_mov_b32_e32 v49, v4
	v_mov_b32_e32 v50, v4
	v_mov_b32_e32 v51, v4
	v_mov_b32_e32 v56, v4
	v_mov_b32_e32 v57, v4
	v_mov_b32_e32 v58, v4
	v_mov_b32_e32 v59, v4
	v_mov_b32_e32 v68, v4
	v_mov_b32_e32 v69, v4
	v_mov_b32_e32 v70, v4
	v_mov_b32_e32 v71, v4
	v_mov_b32_e32 v76, v4
	v_mov_b32_e32 v77, v4
	v_mov_b32_e32 v78, v4
	v_mov_b32_e32 v79, v4
	v_mov_b32_e32 v84, v4
	v_mov_b32_e32 v85, v4
	v_mov_b32_e32 v86, v4
	v_mov_b32_e32 v87, v4
	v_mov_b32_e32 v92, v4
	v_mov_b32_e32 v93, v4
	v_mov_b32_e32 v94, v4
	v_mov_b32_e32 v95, v4
	v_mov_b32_e32 v100, v4
	v_mov_b32_e32 v101, v4
	v_mov_b32_e32 v102, v4
	v_mov_b32_e32 v103, v4
	v_mov_b32_e32 v108, v4
	v_mov_b32_e32 v109, v4
	v_mov_b32_e32 v110, v4
	v_mov_b32_e32 v111, v4
	v_mov_b32_e32 v116, v4
	v_mov_b32_e32 v117, v4
	v_mov_b32_e32 v118, v4
	v_mov_b32_e32 v119, v4
	v_mov_b32_e32 v124, v4
	v_mov_b32_e32 v125, v4
	v_mov_b32_e32 v126, v4
	v_mov_b32_e32 v127, v4
	v_mov_b32_e32 v64, v4
	v_mov_b32_e32 v65, v4
	v_mov_b32_e32 v66, v4
	v_mov_b32_e32 v67, v4
	v_mov_b32_e32 v72, v4
	v_mov_b32_e32 v73, v4
	v_mov_b32_e32 v74, v4
	v_mov_b32_e32 v75, v4
	v_mov_b32_e32 v80, v4
	v_mov_b32_e32 v81, v4
	v_mov_b32_e32 v82, v4
	v_mov_b32_e32 v83, v4
	v_mov_b32_e32 v88, v4
	v_mov_b32_e32 v89, v4
	v_mov_b32_e32 v90, v4
	v_mov_b32_e32 v91, v4
	v_mov_b32_e32 v96, v4
	v_mov_b32_e32 v97, v4
	v_mov_b32_e32 v98, v4
	v_mov_b32_e32 v99, v4
	v_mov_b32_e32 v104, v4
	v_mov_b32_e32 v105, v4
	v_mov_b32_e32 v106, v4
	v_mov_b32_e32 v107, v4
	v_mov_b32_e32 v112, v4
	v_mov_b32_e32 v113, v4
	v_mov_b32_e32 v114, v4
	v_mov_b32_e32 v115, v4
	v_mov_b32_e32 v120, v4
	v_mov_b32_e32 v121, v4
	v_mov_b32_e32 v122, v4
	v_mov_b32_e32 v123, v4
	v_readfirstlane_b32 s100, v211
	s_cmp_ge_u32 s100, 0x100
	s_cbranch_scc0 .Lprio_skip1
	s_setprio 1
; #define PG8_STAGE(bufoff, gbase, voff) do { _Pragma("unroll") for (int _i = 0; _i < 2; ++_i) \
;         __builtin_amdgcn_global_load_lds((const unsigned*)((const char*)(gbase) + (voff)[_i]), (PG8_LAS unsigned*)(lds + (bufoff) + ldsw + _i * 8192), 16, 0, 0); } while (0)
; #define PG8_LDA(dst, b, h) do { _Pragma("unroll") for (int m = 0; m < 4; ++m) _Pragma("unroll") for (int k = 0; k < 2; ++k) dst[m][k] = *(const PG8_LAS bf16x8*)(lds + PG8_SA(b, h) + aoff + m * 2048 + k * 1024); } while (0)
; #define PG8_LDB(dst, b, h) do { _Pragma("unroll") for (int n = 0; n < 2; ++n) _Pragma("unroll") for (int k = 0; k < 2; ++k) dst[n][k] = *(const PG8_LAS bf16x8*)(lds + PG8_SB(b, h) + boff + n * 2048 + k * 1024); } while (0)
; #define PG8_MMA(ai, bj, At, Bt) do { __builtin_amdgcn_s_setprio(1); _Pragma("unroll") for (int m = 0; m < 4; ++m) _Pragma("unroll") for (int n = 0; n < 2; ++n) _Pragma("unroll") for (int k = 0; k < 2; ++k) \
;         acc[ai][bj][m][n] = __builtin_amdgcn_mfma_f32_16x16x32_bf16(Bt[n][k], At[m][k], acc[ai][bj][m][n], 0, 0, 0); __builtin_amdgcn_s_setprio(0); } while (0)
; #define PG8_WAIT_V(n) asm volatile("s_waitcnt vmcnt(" #n ")" ::: "memory")
; #define PG8_WAIT_L(n) asm volatile("s_waitcnt lgkmcnt(" #n ")" ::: "memory")
; #define PG8_BAR __builtin_amdgcn_s_barrier()
; #define PG8_SCHED __builtin_amdgcn_sched_barrier(0)
; template <class Epi, class Sched, bool ALIGN_EPI = false, bool SP2 = false>
; __device__ __forceinline__ void gemm_phase(PG8_LAS unsigned char* lds, const Gemm g, const Sched& S, const Epi& E) {
;     ...
;             PG8_LDB(B0, 0, 0); PG8_LDB(B1, 0, 1); PG8_SCHED; PG8_LDA(At, 0, 0); PG8_STAGE(PG8_SA(1, 1), a1 + hstep, voffA);
;             PG8_WAIT_V(8); PG8_WAIT_L(0); PG8_BAR; PG8_MMA(0, 0, At, B0); PG8_MMA(0, 1, At, B1); PG8_BAR; PG8_SCHED;
;             PG8_LDA(At, 0, 1); PG8_STAGE(PG8_SB(0, 0), b2, voffB); PG8_STAGE(PG8_SB(0, 1), b2 + hstep, voffB); PG8_STAGE(PG8_SA(0, 0), a2, voffA);
;             PG8_WAIT_V(8); PG8_WAIT_L(0); PG8_BAR; PG8_MMA(1, 0, At, B0); PG8_MMA(1, 1, At, B1); PG8_BAR; PG8_SCHED;
.Lprio_skip1:
.LBB0_840:
	s_add_i32 s40, s2, 2
	s_add_u32 s41, s0, 0x80
	s_addc_u32 s3, s1, 0
	s_add_i32 s44, 0, 0x10000
	s_cmp_eq_u32 s28, s2
	s_cselect_b32 s3, s7, s3
	s_cselect_b32 s2, s6, s41
	v_add_u32_e32 v138, s44, v141
	s_cselect_b32 s43, s39, s37
	s_cselect_b32 s42, s38, s36
	s_add_i32 s41, 0, 0x14000
	ds_read_b128 v[144:147], v138
	ds_read_b128 v[148:151], v138 offset:1024
	ds_read_b128 v[168:171], v138 offset:2048
	ds_read_b128 v[172:175], v138 offset:3072
	v_add_u32_e32 v138, s41, v141
	ds_read_b128 v[176:179], v138
	ds_read_b128 v[180:183], v138 offset:1024
	ds_read_b128 v[184:187], v138 offset:2048
	ds_read_b128 v[188:191], v138 offset:3072
	v_lshl_add_u64 v[138:139], s[0:1], 0, v[134:135]
	s_add_i32 m0, s11, 0xc000
	ds_read_b128 v[192:195], v143
	ds_read_b128 v[196:199], v143 offset:1024
	ds_read_b128 v[200:203], v143 offset:2048
	ds_read_b128 v[204:207], v143 offset:3072
	ds_read_b128 v[212:215], v143 offset:4096
	ds_read_b128 v[230:233], v143 offset:5120
	ds_read_b128 v[234:237], v143 offset:6144
	ds_read_b128 v[238:241], v143 offset:7168
	global_load_lds_dwordx4 v[138:139], off
	v_lshl_add_u64 v[138:139], s[0:1], 0, v[136:137]
	s_add_i32 m0, s11, 0xe000
	s_nop 0
	global_load_lds_dwordx4 v[138:139], off
	s_waitcnt vmcnt(8)
	s_waitcnt lgkmcnt(0)
	s_barrier
	s_waitcnt lgkmcnt(0)
	v_mfma_f32_16x16x32_bf16 v[120:123], v[144:147], v[192:195], v[120:123]
	v_mfma_f32_16x16x32_bf16 v[112:115], v[168:171], v[192:195], v[112:115]
	v_mfma_f32_16x16x32_bf16 v[104:107], v[144:147], v[200:203], v[104:107]
	v_mfma_f32_16x16x32_bf16 v[96:99], v[168:171], v[200:203], v[96:99]
	v_mfma_f32_16x16x32_bf16 v[88:91], v[144:147], v[212:215], v[88:91]
	v_mfma_f32_16x16x32_bf16 v[80:83], v[168:171], v[212:215], v[80:83]
	v_mfma_f32_16x16x32_bf16 v[72:75], v[144:147], v[234:237], v[72:75]
	v_mfma_f32_16x16x32_bf16 v[64:67], v[168:171], v[234:237], v[64:67]
	v_mfma_f32_16x16x32_bf16 v[120:123], v[148:151], v[196:199], v[120:123]
	v_mfma_f32_16x16x32_bf16 v[112:115], v[172:175], v[196:199], v[112:115]
	v_mfma_f32_16x16x32_bf16 v[104:107], v[148:151], v[204:207], v[104:107]
	v_mfma_f32_16x16x32_bf16 v[96:99], v[172:175], v[204:207], v[96:99]
	v_mfma_f32_16x16x32_bf16 v[88:91], v[148:151], v[230:233], v[88:91]
	v_mfma_f32_16x16x32_bf16 v[80:83], v[172:175], v[230:233], v[80:83]
	v_mfma_f32_16x16x32_bf16 v[72:75], v[148:151], v[238:241], v[72:75]
	v_mfma_f32_16x16x32_bf16 v[64:67], v[172:175], v[238:241], v[64:67]
	v_mfma_f32_16x16x32_bf16 v[124:127], v[176:179], v[192:195], v[124:127]
	v_mfma_f32_16x16x32_bf16 v[116:119], v[184:187], v[192:195], v[116:119]
	v_mfma_f32_16x16x32_bf16 v[108:111], v[176:179], v[200:203], v[108:111]
	v_mfma_f32_16x16x32_bf16 v[100:103], v[184:187], v[200:203], v[100:103]
	v_mfma_f32_16x16x32_bf16 v[92:95], v[176:179], v[212:215], v[92:95]
	v_mfma_f32_16x16x32_bf16 v[84:87], v[184:187], v[212:215], v[84:87]
	v_mfma_f32_16x16x32_bf16 v[76:79], v[176:179], v[234:237], v[76:79]
	v_mfma_f32_16x16x32_bf16 v[68:71], v[184:187], v[234:237], v[68:71]
	v_mfma_f32_16x16x32_bf16 v[124:127], v[180:183], v[196:199], v[124:127]
	v_mfma_f32_16x16x32_bf16 v[116:119], v[188:191], v[196:199], v[116:119]
	v_mfma_f32_16x16x32_bf16 v[108:111], v[180:183], v[204:207], v[108:111]
	v_mfma_f32_16x16x32_bf16 v[100:103], v[188:191], v[204:207], v[100:103]
	v_mfma_f32_16x16x32_bf16 v[92:95], v[180:183], v[230:233], v[92:95]
	v_mfma_f32_16x16x32_bf16 v[84:87], v[188:191], v[230:233], v[84:87]
	v_mfma_f32_16x16x32_bf16 v[76:79], v[180:183], v[238:241], v[76:79]
	v_mfma_f32_16x16x32_bf16 v[68:71], v[188:191], v[238:241], v[68:71]
	s_barrier
	s_add_i32 s44, s44, s10
	v_lshl_add_u64 v[138:139], s[42:43], 0, v[152:153]
	s_mov_b32 m0, s44
	ds_read_b128 v[192:195], v143 offset:16384
	ds_read_b128 v[196:199], v143 offset:17408
	ds_read_b128 v[200:203], v143 offset:18432
	ds_read_b128 v[204:207], v143 offset:19456
	ds_read_b128 v[212:215], v143 offset:20480
	ds_read_b128 v[230:233], v143 offset:21504
	ds_read_b128 v[234:237], v143 offset:22528
	ds_read_b128 v[238:241], v143 offset:23552
	global_load_lds_dwordx4 v[138:139], off
	s_add_i32 m0, s44, 0x2000
	v_lshl_add_u64 v[158:159], s[42:43], 0, v[128:129]
	s_add_u32 s42, s42, s8
	s_addc_u32 s43, s43, s9
	s_add_i32 s41, s41, s10
	global_load_lds_dwordx4 v[158:159], off
	v_lshl_add_u64 v[160:161], s[42:43], 0, v[152:153]
	s_mov_b32 m0, s41
	v_lshl_add_u64 v[162:163], s[42:43], 0, v[128:129]
	global_load_lds_dwordx4 v[160:161], off
	s_add_i32 m0, s41, 0x2000
	v_lshl_add_u64 v[164:165], s[2:3], 0, v[132:133]
	global_load_lds_dwordx4 v[162:163], off
	s_mov_b32 m0, s11
	v_lshl_add_u64 v[208:209], s[2:3], 0, v[130:131]
	global_load_lds_dwordx4 v[164:165], off
	s_mov_b32 m0, s20
	s_nop 0
	global_load_lds_dwordx4 v[208:209], off
	s_waitcnt vmcnt(8)
	s_waitcnt lgkmcnt(0)
	s_barrier
; #define PG8_STAGE(bufoff, gbase, voff) do { _Pragma("unroll") for (int _i = 0; _i < 2; ++_i) \
;         __builtin_amdgcn_global_load_lds((const unsigned*)((const char*)(gbase) + (voff)[_i]), (PG8_LAS unsigned*)(lds + (bufoff) + ldsw + _i * 8192), 16, 0, 0); } while (0)
; #define PG8_LDA(dst, b, h) do { _Pragma("unroll") for (int m = 0; m < 4; ++m) _Pragma("unroll") for (int k = 0; k < 2; ++k) dst[m][k] = *(const PG8_LAS bf16x8*)(lds + PG8_SA(b, h) + aoff + m * 2048 + k * 1024); } while (0)
; #define PG8_LDB(dst, b, h) do { _Pragma("unroll") for (int n = 0; n < 2; ++n) _Pragma("unroll") for (int k = 0; k < 2; ++k) dst[n][k] = *(const PG8_LAS bf16x8*)(lds + PG8_SB(b, h) + boff + n * 2048 + k * 1024); } while (0)
; #define PG8_MMA(ai, bj, At, Bt) do { __builtin_amdgcn_s_setprio(1); _Pragma("unroll") for (int m = 0; m < 4; ++m) _Pragma("unroll") for (int n = 0; n < 2; ++n) _Pragma("unroll") for (int k = 0; k < 2; ++k) \
;         acc[ai][bj][m][n] = __builtin_amdgcn_mfma_f32_16x16x32_bf16(Bt[n][k], At[m][k], acc[ai][bj][m][n], 0, 0, 0); __builtin_amdgcn_s_setprio(0); } while (0)
; #define PG8_WAIT_V(n) asm volatile("s_waitcnt vmcnt(" #n ")" ::: "memory")
; #define PG8_WAIT_L(n) asm volatile("s_waitcnt lgkmcnt(" #n ")" ::: "memory")
; #define PG8_BAR __builtin_amdgcn_s_barrier()
; #define PG8_SCHED __builtin_amdgcn_sched_barrier(0)
; template <class Epi, class Sched, bool ALIGN_EPI = false, bool SP2 = false>
; __device__ __forceinline__ void gemm_phase(PG8_LAS unsigned char* lds, const Gemm g, const Sched& S, const Epi& E) {
;     ...
;             PG8_WAIT_V(8); PG8_WAIT_L(0); PG8_BAR; PG8_MMA(1, 0, At, B0); PG8_MMA(1, 1, At, B1); PG8_BAR; PG8_SCHED;
;             PG8_LDB(B0, 1, 0); PG8_LDB(B1, 1, 1); PG8_SCHED; PG8_LDA(At, 1, 0); PG8_STAGE(PG8_SA(0, 1), a2 + hstep, voffA);
;             PG8_WAIT_V(8); PG8_WAIT_L(0); PG8_BAR; PG8_MMA(0, 0, At, B0); PG8_MMA(0, 1, At, B1); PG8_BAR; PG8_SCHED;
;             PG8_LDA(At, 1, 1); PG8_STAGE(PG8_SB(1, 0), b3, voffB); PG8_STAGE(PG8_SB(1, 1), b3 + hstep, voffB); PG8_STAGE(PG8_SA(1, 0), a3, voffA);
	s_waitcnt lgkmcnt(0)
	v_mfma_f32_16x16x32_bf16 v[56:59], v[144:147], v[192:195], v[56:59]
	v_mfma_f32_16x16x32_bf16 v[48:51], v[168:171], v[192:195], v[48:51]
	v_mfma_f32_16x16x32_bf16 v[40:43], v[144:147], v[200:203], v[40:43]
	v_mfma_f32_16x16x32_bf16 v[32:35], v[168:171], v[200:203], v[32:35]
	v_mfma_f32_16x16x32_bf16 v[24:27], v[144:147], v[212:215], v[24:27]
	v_mfma_f32_16x16x32_bf16 v[16:19], v[168:171], v[212:215], v[16:19]
	v_mfma_f32_16x16x32_bf16 v[8:11], v[144:147], v[234:237], v[8:11]
	v_mfma_f32_16x16x32_bf16 v[0:3], v[168:171], v[234:237], v[0:3]
	v_mfma_f32_16x16x32_bf16 v[56:59], v[148:151], v[196:199], v[56:59]
	v_mfma_f32_16x16x32_bf16 v[48:51], v[172:175], v[196:199], v[48:51]
	v_mfma_f32_16x16x32_bf16 v[40:43], v[148:151], v[204:207], v[40:43]
	v_mfma_f32_16x16x32_bf16 v[32:35], v[172:175], v[204:207], v[32:35]
	v_mfma_f32_16x16x32_bf16 v[24:27], v[148:151], v[230:233], v[24:27]
	v_mfma_f32_16x16x32_bf16 v[16:19], v[172:175], v[230:233], v[16:19]
	v_mfma_f32_16x16x32_bf16 v[8:11], v[148:151], v[238:241], v[8:11]
	v_mfma_f32_16x16x32_bf16 v[0:3], v[172:175], v[238:241], v[0:3]
	v_mfma_f32_16x16x32_bf16 v[60:63], v[176:179], v[192:195], v[60:63]
	v_mfma_f32_16x16x32_bf16 v[52:55], v[184:187], v[192:195], v[52:55]
	v_mfma_f32_16x16x32_bf16 v[44:47], v[176:179], v[200:203], v[44:47]
	v_mfma_f32_16x16x32_bf16 v[36:39], v[184:187], v[200:203], v[36:39]
	v_mfma_f32_16x16x32_bf16 v[28:31], v[176:179], v[212:215], v[28:31]
	v_mfma_f32_16x16x32_bf16 v[20:23], v[184:187], v[212:215], v[20:23]
	v_mfma_f32_16x16x32_bf16 v[12:15], v[176:179], v[234:237], v[12:15]
	v_mfma_f32_16x16x32_bf16 v[4:7], v[184:187], v[234:237], v[4:7]
	v_mfma_f32_16x16x32_bf16 v[60:63], v[180:183], v[196:199], v[60:63]
	v_mfma_f32_16x16x32_bf16 v[52:55], v[188:191], v[196:199], v[52:55]
	v_mfma_f32_16x16x32_bf16 v[44:47], v[180:183], v[204:207], v[44:47]
	v_mfma_f32_16x16x32_bf16 v[36:39], v[188:191], v[204:207], v[36:39]
	v_mfma_f32_16x16x32_bf16 v[28:31], v[180:183], v[230:233], v[28:31]
	v_mfma_f32_16x16x32_bf16 v[20:23], v[188:191], v[230:233], v[20:23]
	v_mfma_f32_16x16x32_bf16 v[12:15], v[180:183], v[238:241], v[12:15]
	v_mfma_f32_16x16x32_bf16 v[4:7], v[188:191], v[238:241], v[4:7]
	s_barrier
	s_add_i32 s41, 0, 0x18000
	v_add_u32_e32 v167, s41, v141
	s_add_i32 s42, 0, 0x1c000
	ds_read_b128 v[144:147], v167
	ds_read_b128 v[148:151], v167 offset:1024
	ds_read_b128 v[168:171], v167 offset:2048
	ds_read_b128 v[172:175], v167 offset:3072
	v_add_u32_e32 v167, s42, v141
	ds_read_b128 v[176:179], v167
	ds_read_b128 v[180:183], v167 offset:1024
	ds_read_b128 v[184:187], v167 offset:2048
	ds_read_b128 v[188:191], v167 offset:3072
	s_add_u32 s2, s2, s8
	s_addc_u32 s3, s3, s9
	s_mov_b32 m0, s21
	v_lshl_add_u64 v[216:217], s[2:3], 0, v[132:133]
	ds_read_b128 v[192:195], v143 offset:32768
	ds_read_b128 v[196:199], v143 offset:33792
	ds_read_b128 v[200:203], v143 offset:34816
	ds_read_b128 v[204:207], v143 offset:35840
	ds_read_b128 v[212:215], v143 offset:36864
	ds_read_b128 v[230:233], v143 offset:37888
	ds_read_b128 v[234:237], v143 offset:38912
	ds_read_b128 v[238:241], v143 offset:39936
	global_load_lds_dwordx4 v[216:217], off
	v_lshl_add_u64 v[216:217], s[2:3], 0, v[130:131]
	s_mov_b32 m0, s22
	s_nop 0
	global_load_lds_dwordx4 v[216:217], off
	s_waitcnt vmcnt(8)
	s_waitcnt lgkmcnt(0)
	s_barrier
	s_waitcnt lgkmcnt(0)
	v_mfma_f32_16x16x32_bf16 v[120:123], v[144:147], v[192:195], v[120:123]
	v_mfma_f32_16x16x32_bf16 v[112:115], v[168:171], v[192:195], v[112:115]
	v_mfma_f32_16x16x32_bf16 v[104:107], v[144:147], v[200:203], v[104:107]
	v_mfma_f32_16x16x32_bf16 v[96:99], v[168:171], v[200:203], v[96:99]
	v_mfma_f32_16x16x32_bf16 v[88:91], v[144:147], v[212:215], v[88:91]
	v_mfma_f32_16x16x32_bf16 v[80:83], v[168:171], v[212:215], v[80:83]
	v_mfma_f32_16x16x32_bf16 v[72:75], v[144:147], v[234:237], v[72:75]
	v_mfma_f32_16x16x32_bf16 v[64:67], v[168:171], v[234:237], v[64:67]
	v_mfma_f32_16x16x32_bf16 v[120:123], v[148:151], v[196:199], v[120:123]
	v_mfma_f32_16x16x32_bf16 v[112:115], v[172:175], v[196:199], v[112:115]
	v_mfma_f32_16x16x32_bf16 v[104:107], v[148:151], v[204:207], v[104:107]
	v_mfma_f32_16x16x32_bf16 v[96:99], v[172:175], v[204:207], v[96:99]
	v_mfma_f32_16x16x32_bf16 v[88:91], v[148:151], v[230:233], v[88:91]
	v_mfma_f32_16x16x32_bf16 v[80:83], v[172:175], v[230:233], v[80:83]
	v_mfma_f32_16x16x32_bf16 v[72:75], v[148:151], v[238:241], v[72:75]
	v_mfma_f32_16x16x32_bf16 v[64:67], v[172:175], v[238:241], v[64:67]
	v_mfma_f32_16x16x32_bf16 v[124:127], v[176:179], v[192:195], v[124:127]
	v_mfma_f32_16x16x32_bf16 v[116:119], v[184:187], v[192:195], v[116:119]
	v_mfma_f32_16x16x32_bf16 v[108:111], v[176:179], v[200:203], v[108:111]
	v_mfma_f32_16x16x32_bf16 v[100:103], v[184:187], v[200:203], v[100:103]
	v_mfma_f32_16x16x32_bf16 v[92:95], v[176:179], v[212:215], v[92:95]
	v_mfma_f32_16x16x32_bf16 v[84:87], v[184:187], v[212:215], v[84:87]
	v_mfma_f32_16x16x32_bf16 v[76:79], v[176:179], v[234:237], v[76:79]
	v_mfma_f32_16x16x32_bf16 v[68:71], v[184:187], v[234:237], v[68:71]
	v_mfma_f32_16x16x32_bf16 v[124:127], v[180:183], v[196:199], v[124:127]
	v_mfma_f32_16x16x32_bf16 v[116:119], v[188:191], v[196:199], v[116:119]
	v_mfma_f32_16x16x32_bf16 v[108:111], v[180:183], v[204:207], v[108:111]
	v_mfma_f32_16x16x32_bf16 v[100:103], v[188:191], v[204:207], v[100:103]
	v_mfma_f32_16x16x32_bf16 v[92:95], v[180:183], v[230:233], v[92:95]
	v_mfma_f32_16x16x32_bf16 v[84:87], v[188:191], v[230:233], v[84:87]
	v_mfma_f32_16x16x32_bf16 v[76:79], v[180:183], v[238:241], v[76:79]
	v_mfma_f32_16x16x32_bf16 v[68:71], v[188:191], v[238:241], v[68:71]
	s_barrier
; #define PG8_STAGE(bufoff, gbase, voff) do { _Pragma("unroll") for (int _i = 0; _i < 2; ++_i) \
;         __builtin_amdgcn_global_load_lds((const unsigned*)((const char*)(gbase) + (voff)[_i]), (PG8_LAS unsigned*)(lds + (bufoff) + ldsw + _i * 8192), 16, 0, 0); } while (0)
; #define PG8_LDA(dst, b, h) do { _Pragma("unroll") for (int m = 0; m < 4; ++m) _Pragma("unroll") for (int k = 0; k < 2; ++k) dst[m][k] = *(const PG8_LAS bf16x8*)(lds + PG8_SA(b, h) + aoff + m * 2048 + k * 1024); } while (0)
; #define PG8_MMA(ai, bj, At, Bt) do { __builtin_amdgcn_s_setprio(1); _Pragma("unroll") for (int m = 0; m < 4; ++m) _Pragma("unroll") for (int n = 0; n < 2; ++n) _Pragma("unroll") for (int k = 0; k < 2; ++k) \
;         acc[ai][bj][m][n] = __builtin_amdgcn_mfma_f32_16x16x32_bf16(Bt[n][k], At[m][k], acc[ai][bj][m][n], 0, 0, 0); __builtin_amdgcn_s_setprio(0); } while (0)
; #define PG8_WAIT_V(n) asm volatile("s_waitcnt vmcnt(" #n ")" ::: "memory")
; #define PG8_WAIT_L(n) asm volatile("s_waitcnt lgkmcnt(" #n ")" ::: "memory")
; #define PG8_BAR __builtin_amdgcn_s_barrier()
; #define PG8_SCHED __builtin_amdgcn_sched_barrier(0)
; template <class Epi, class Sched, bool ALIGN_EPI = false, bool SP2 = false>
; __device__ __forceinline__ void gemm_phase(PG8_LAS unsigned char* lds, const Gemm g, const Sched& S, const Epi& E) {
;     ...
;             PG8_LDA(At, 1, 1); PG8_STAGE(PG8_SB(1, 0), b3, voffB); PG8_STAGE(PG8_SB(1, 1), b3 + hstep, voffB); PG8_STAGE(PG8_SA(1, 0), a3, voffA);
;             PG8_WAIT_V(8); PG8_WAIT_L(0); PG8_BAR; PG8_MMA(1, 0, At, B0); PG8_MMA(1, 1, At, B1); PG8_BAR; PG8_SCHED;
	s_add_i32 s2, s41, s10
	v_lshl_add_u64 v[138:139], v[138:139], 0, s[82:83]
	s_mov_b32 m0, s2
	ds_read_b128 v[192:195], v143 offset:49152
	ds_read_b128 v[196:199], v143 offset:50176
	ds_read_b128 v[200:203], v143 offset:51200
	ds_read_b128 v[204:207], v143 offset:52224
	ds_read_b128 v[212:215], v143 offset:53248
	ds_read_b128 v[230:233], v143 offset:54272
	ds_read_b128 v[234:237], v143 offset:55296
	ds_read_b128 v[238:241], v143 offset:56320
	global_load_lds_dwordx4 v[138:139], off
	v_lshl_add_u64 v[138:139], v[158:159], 0, s[82:83]
	s_add_i32 m0, s2, 0x2000
	s_add_i32 s2, s42, s10
	global_load_lds_dwordx4 v[138:139], off
	v_lshl_add_u64 v[138:139], v[160:161], 0, s[82:83]
	s_mov_b32 m0, s2
	s_nop 0
	global_load_lds_dwordx4 v[138:139], off
	v_lshl_add_u64 v[138:139], v[162:163], 0, s[82:83]
	s_add_i32 m0, s2, 0x2000
	s_nop 0
	global_load_lds_dwordx4 v[138:139], off
	v_lshl_add_u64 v[138:139], v[164:165], 0, s[82:83]
	s_mov_b32 m0, s23
	s_nop 0
	global_load_lds_dwordx4 v[138:139], off
	v_lshl_add_u64 v[138:139], v[208:209], 0, s[82:83]
	s_mov_b32 m0, s24
	s_nop 0
	global_load_lds_dwordx4 v[138:139], off
	s_waitcnt vmcnt(8)
	s_waitcnt lgkmcnt(0)
	s_barrier
	s_waitcnt lgkmcnt(0)
	v_mfma_f32_16x16x32_bf16 v[56:59], v[144:147], v[192:195], v[56:59]
	v_mfma_f32_16x16x32_bf16 v[48:51], v[168:171], v[192:195], v[48:51]
	v_mfma_f32_16x16x32_bf16 v[40:43], v[144:147], v[200:203], v[40:43]
	v_mfma_f32_16x16x32_bf16 v[32:35], v[168:171], v[200:203], v[32:35]
	v_mfma_f32_16x16x32_bf16 v[24:27], v[144:147], v[212:215], v[24:27]
	v_mfma_f32_16x16x32_bf16 v[16:19], v[168:171], v[212:215], v[16:19]
	v_mfma_f32_16x16x32_bf16 v[8:11], v[144:147], v[234:237], v[8:11]
	v_mfma_f32_16x16x32_bf16 v[0:3], v[168:171], v[234:237], v[0:3]
	v_mfma_f32_16x16x32_bf16 v[56:59], v[148:151], v[196:199], v[56:59]
	v_mfma_f32_16x16x32_bf16 v[48:51], v[172:175], v[196:199], v[48:51]
	v_mfma_f32_16x16x32_bf16 v[40:43], v[148:151], v[204:207], v[40:43]
	v_mfma_f32_16x16x32_bf16 v[32:35], v[172:175], v[204:207], v[32:35]
	v_mfma_f32_16x16x32_bf16 v[24:27], v[148:151], v[230:233], v[24:27]
	v_mfma_f32_16x16x32_bf16 v[16:19], v[172:175], v[230:233], v[16:19]
	v_mfma_f32_16x16x32_bf16 v[8:11], v[148:151], v[238:241], v[8:11]
	v_mfma_f32_16x16x32_bf16 v[0:3], v[172:175], v[238:241], v[0:3]
	v_mfma_f32_16x16x32_bf16 v[60:63], v[176:179], v[192:195], v[60:63]
	v_mfma_f32_16x16x32_bf16 v[52:55], v[184:187], v[192:195], v[52:55]
	v_mfma_f32_16x16x32_bf16 v[44:47], v[176:179], v[200:203], v[44:47]
	v_mfma_f32_16x16x32_bf16 v[36:39], v[184:187], v[200:203], v[36:39]
	v_mfma_f32_16x16x32_bf16 v[28:31], v[176:179], v[212:215], v[28:31]
	v_mfma_f32_16x16x32_bf16 v[20:23], v[184:187], v[212:215], v[20:23]
	v_mfma_f32_16x16x32_bf16 v[12:15], v[176:179], v[234:237], v[12:15]
	v_mfma_f32_16x16x32_bf16 v[4:7], v[184:187], v[234:237], v[4:7]
	v_mfma_f32_16x16x32_bf16 v[60:63], v[180:183], v[196:199], v[60:63]
	v_mfma_f32_16x16x32_bf16 v[52:55], v[188:191], v[196:199], v[52:55]
	v_mfma_f32_16x16x32_bf16 v[44:47], v[180:183], v[204:207], v[44:47]
	v_mfma_f32_16x16x32_bf16 v[36:39], v[188:191], v[204:207], v[36:39]
	v_mfma_f32_16x16x32_bf16 v[28:31], v[180:183], v[230:233], v[28:31]
	v_mfma_f32_16x16x32_bf16 v[20:23], v[188:191], v[230:233], v[20:23]
	v_mfma_f32_16x16x32_bf16 v[12:15], v[180:183], v[238:241], v[12:15]
	v_mfma_f32_16x16x32_bf16 v[4:7], v[188:191], v[238:241], v[4:7]
	s_barrier
	s_add_u32 s0, s0, 0x100
	s_addc_u32 s1, s1, 0
	s_add_u32 s36, s36, 0x100
	s_addc_u32 s37, s37, 0
	s_cmp_ge_i32 s40, s25
	s_mov_b32 s2, s40
	s_cbranch_scc0 .LBB0_840
	s_setprio 0

; __global__ void __launch_bounds__(NTHREADS, 2) mega_fwd(Params P) {
	.amdhsa_kernel _Z8mega_fwd6Params
		.amdhsa_group_segment_fixed_size 0
		.amdhsa_private_segment_fixed_size 0
		.amdhsa_kernarg_size 552
		.amdhsa_user_sgpr_count 2
		.amdhsa_user_sgpr_dispatch_ptr 0
		.amdhsa_user_sgpr_queue_ptr 0
		.amdhsa_user_sgpr_kernarg_segment_ptr 1
		.amdhsa_user_sgpr_dispatch_id 0
		.amdhsa_user_sgpr_kernarg_preload_length 0
		.amdhsa_user_sgpr_kernarg_preload_offset 0
		.amdhsa_user_sgpr_private_segment_size 0
		.amdhsa_uses_dynamic_stack 0
		.amdhsa_enable_private_segment 0
		.amdhsa_system_sgpr_workgroup_id_x 1
		.amdhsa_system_sgpr_workgroup_id_y 0
		.amdhsa_system_sgpr_workgroup_id_z 0
		.amdhsa_system_sgpr_workgroup_info 0
		.amdhsa_system_vgpr_workitem_id 2
		.amdhsa_next_free_vgpr 256
		.amdhsa_next_free_sgpr 102
		.amdhsa_accum_offset 256
		.amdhsa_reserve_vcc 1
		.amdhsa_float_round_mode_32 0
		.amdhsa_float_round_mode_16_64 0
		.amdhsa_float_denorm_mode_32 3
		.amdhsa_float_denorm_mode_16_64 3
		.amdhsa_dx10_clamp 1
		.amdhsa_ieee_mode 1
		.amdhsa_fp16_overflow 0
		.amdhsa_tg_split 0
		.amdhsa_exception_fp_ieee_invalid_op 0
		.amdhsa_exception_fp_denorm_src 0
		.amdhsa_exception_fp_ieee_div_zero 0
		.amdhsa_exception_fp_ieee_overflow 0
		.amdhsa_exception_fp_ieee_underflow 0
		.amdhsa_exception_fp_ieee_inexact 0
		.amdhsa_exception_int_div_zero 0
	.end_amdhsa_kernel

; __global__ void __launch_bounds__(NTHREADS, 2) mega_fwd(Params P) {
amdhsa.kernels:
  - .agpr_count:     0
    .args:
      - .offset:         0
        .size:           296
        .value_kind:     by_value
      - .offset:         296
        .size:           4
        .value_kind:     hidden_block_count_x
      - .offset:         300
        .size:           4
        .value_kind:     hidden_block_count_y
      - .offset:         304
        .size:           4
        .value_kind:     hidden_block_count_z
      - .offset:         308
        .size:           2
        .value_kind:     hidden_group_size_x
      - .offset:         310
        .size:           2
        .value_kind:     hidden_group_size_y
      - .offset:         312
        .size:           2
        .value_kind:     hidden_group_size_z
      - .offset:         314
        .size:           2
        .value_kind:     hidden_remainder_x
      - .offset:         316
        .size:           2
        .value_kind:     hidden_remainder_y
      - .offset:         318
        .size:           2
        .value_kind:     hidden_remainder_z
      - .offset:         336
        .size:           8
        .value_kind:     hidden_global_offset_x
      - .offset:         344
        .size:           8
        .value_kind:     hidden_global_offset_y
      - .offset:         352
        .size:           8
        .value_kind:     hidden_global_offset_z
      - .offset:         360
        .size:           2
        .value_kind:     hidden_grid_dims
      - .offset:         384
        .size:           8
        .value_kind:     hidden_multigrid_sync_arg
      - .offset:         416
        .size:           4
        .value_kind:     hidden_dynamic_lds_size
    .group_segment_fixed_size: 0
    .kernarg_segment_align: 8
    .kernarg_segment_size: 552
    .language:       OpenCL C
    .language_version:
      - 2
      - 0
    .max_flat_workgroup_size: 512
    .name:           _Z8mega_fwd6Params
    .private_segment_fixed_size: 0
    .sgpr_count:     108
    .sgpr_spill_count: 190
    .symbol:         _Z8mega_fwd6Params.kd
    .uniform_work_group_size: 1
    .uses_dynamic_stack: false
    .vgpr_count:     256
    .vgpr_spill_count: 0
    .wavefront_size: 64
